# speedup vs baseline: 1.0182x; 1.0028x over previous
; #define WAIT_L(n) asm volatile("s_waitcnt lgkmcnt(%0)" ::"n"(n) : "memory")
; #define SBAR() __builtin_amdgcn_sched_barrier(0)
; #define LDA8(dst, b, h) _Pragma("unroll") for (int m = 0; m < 4; ++m) _Pragma("unroll") for (int k = 0; k < 2; ++k) \
;     dst[m][k] = *(const bf16x8*)(abase + SAo(b, h) + m * 2048 + k * 1024)
; #define LDB8(dst, b, h) _Pragma("unroll") for (int n = 0; n < 2; ++n) _Pragma("unroll") for (int k = 0; k < 2; ++k) \
;     dst[n][k] = *(const bf16x8*)(bbase + SAo(b, h) + n * 2048 + k * 1024)
; #define BAR8 __builtin_amdgcn_s_barrier()
; __device__ __forceinline__ void gemm_main8(const u16* __restrict__ Ab, int lda, const u16* __restrict__ Bb, int ldb, int K,
;                                            char* shm, f32x4 (&acc)[2][2][4][2]) {
;     ...
;     LDB8(B0, 0, 0); SBAR(); LDA8(At, 0, 0); STG_A(1, 1, t + 1);
;     WAIT_L(8); BAR8; WAIT_L(0); MMA8(0, 0, At, B0); BAR8; SBAR();
;     LDB8(B1, 0, 1); STG_B(0, 0, t + 2);
;     BAR8; WAIT_L(0); MMA8(0, 1, At, B1); BAR8;
;     LDA8(At, 0, 1); STG_A(0, 0, t + 2);
;     BAR8; WAIT_L(0); MMA8(1, 0, At, B0); BAR8; SBAR();
.LBB0_223:
	ds_read_b128 v[152:155], v142
	ds_read_b128 v[164:167], v142 offset:1024
	ds_read_b128 v[180:183], v142 offset:2048
	ds_read_b128 v[184:187], v142 offset:3072
	ds_read_b128 v[188:191], v141
	ds_read_b128 v[192:195], v141 offset:1024
	ds_read_b128 v[196:199], v141 offset:2048
	ds_read_b128 v[200:203], v141 offset:3072
	ds_read_b128 v[204:207], v141 offset:4096
	ds_read_b128 v[208:211], v141 offset:5120
	ds_read_b128 v[212:215], v141 offset:6144
	ds_read_b128 v[216:219], v141 offset:7168
	v_lshl_add_u64 v[168:169], s[88:89], 0, v[134:135]
	v_readfirstlane_b32 s25, v179
	v_lshl_add_u64 v[220:221], v[168:169], 0, s[54:55]
	s_mov_b32 m0, s25
	v_readfirstlane_b32 s25, v178
	global_load_lds_dwordx4 v[220:221], off
	v_lshl_add_u64 v[220:221], v[168:169], 0, s[56:57]
	s_mov_b32 m0, s25
	s_nop 0
	global_load_lds_dwordx4 v[220:221], off
	s_waitcnt lgkmcnt(8)
	s_barrier
	s_waitcnt lgkmcnt(0)
	s_waitcnt lgkmcnt(0)
	v_mfma_f32_16x16x32_bf16 v[126:129], v[152:155], v[188:191], v[126:129]
	v_mfma_f32_16x16x32_bf16 v[122:125], v[180:183], v[188:191], v[122:125]
	v_mfma_f32_16x16x32_bf16 v[118:121], v[152:155], v[196:199], v[118:121]
	v_mfma_f32_16x16x32_bf16 v[114:117], v[180:183], v[196:199], v[114:117]
	v_mfma_f32_16x16x32_bf16 v[110:113], v[152:155], v[204:207], v[110:113]
	v_mfma_f32_16x16x32_bf16 v[106:109], v[180:183], v[204:207], v[106:109]
	v_mfma_f32_16x16x32_bf16 v[102:105], v[152:155], v[212:215], v[102:105]
	v_mfma_f32_16x16x32_bf16 v[98:101], v[180:183], v[212:215], v[98:101]
	v_mfma_f32_16x16x32_bf16 v[126:129], v[164:167], v[192:195], v[126:129]
	v_mfma_f32_16x16x32_bf16 v[122:125], v[184:187], v[192:195], v[122:125]
	v_mfma_f32_16x16x32_bf16 v[118:121], v[164:167], v[200:203], v[118:121]
	v_mfma_f32_16x16x32_bf16 v[114:117], v[184:187], v[200:203], v[114:117]
	v_mfma_f32_16x16x32_bf16 v[110:113], v[164:167], v[208:211], v[110:113]
	v_mfma_f32_16x16x32_bf16 v[106:109], v[184:187], v[208:211], v[106:109]
	v_mfma_f32_16x16x32_bf16 v[102:105], v[164:167], v[216:219], v[102:105]
	v_mfma_f32_16x16x32_bf16 v[98:101], v[184:187], v[216:219], v[98:101]
	s_barrier
	ds_read_b128 v[220:223], v142 offset:16384
	ds_read_b128 v[224:227], v142 offset:17408
	ds_read_b128 v[228:231], v142 offset:18432
	ds_read_b128 v[232:235], v142 offset:19456
	v_lshl_add_u64 v[236:237], s[14:15], 0, v[134:135]
	s_mov_b64 s[90:91], 0x2000100
	v_readfirstlane_b32 s25, v144
	v_lshl_add_u64 v[238:239], v[236:237], 0, s[90:91]
	s_mov_b32 m0, s25
	s_mov_b64 s[90:91], 0x2040100
	v_readfirstlane_b32 s25, v145
	global_load_lds_dwordx4 v[238:239], off
	v_lshl_add_u64 v[238:239], v[236:237], 0, s[90:91]
	s_mov_b32 m0, s25
	s_nop 0
	global_load_lds_dwordx4 v[238:239], off
	s_barrier
	s_waitcnt lgkmcnt(0)
	s_waitcnt lgkmcnt(0)
	v_mfma_f32_16x16x32_bf16 v[94:97], v[220:223], v[188:191], v[94:97]
	v_mfma_f32_16x16x32_bf16 v[90:93], v[228:231], v[188:191], v[90:93]
	v_mfma_f32_16x16x32_bf16 v[86:89], v[220:223], v[196:199], v[86:89]
	v_mfma_f32_16x16x32_bf16 v[82:85], v[228:231], v[196:199], v[82:85]
	v_mfma_f32_16x16x32_bf16 v[78:81], v[220:223], v[204:207], v[78:81]
	v_mfma_f32_16x16x32_bf16 v[74:77], v[228:231], v[204:207], v[74:77]
	v_mfma_f32_16x16x32_bf16 v[70:73], v[220:223], v[212:215], v[70:73]
	v_mfma_f32_16x16x32_bf16 v[66:69], v[228:231], v[212:215], v[66:69]
	v_mfma_f32_16x16x32_bf16 v[94:97], v[224:227], v[192:195], v[94:97]
	v_mfma_f32_16x16x32_bf16 v[90:93], v[232:235], v[192:195], v[90:93]
	v_mfma_f32_16x16x32_bf16 v[86:89], v[224:227], v[200:203], v[86:89]
	v_mfma_f32_16x16x32_bf16 v[82:85], v[232:235], v[200:203], v[82:85]
	v_mfma_f32_16x16x32_bf16 v[78:81], v[224:227], v[208:211], v[78:81]
	v_mfma_f32_16x16x32_bf16 v[74:77], v[232:235], v[208:211], v[74:77]
	v_mfma_f32_16x16x32_bf16 v[70:73], v[224:227], v[216:219], v[70:73]
	v_mfma_f32_16x16x32_bf16 v[66:69], v[232:235], v[216:219], v[66:69]
	v_readfirstlane_b32 s25, v143
	v_lshl_add_u64 v[238:239], v[168:169], 0, s[58:59]
	s_mov_b32 m0, s25
	v_readfirstlane_b32 s25, v146
	s_barrier
	ds_read_b128 v[188:191], v141 offset:16384
	ds_read_b128 v[192:195], v141 offset:17408
	ds_read_b128 v[196:199], v141 offset:18432
	ds_read_b128 v[200:203], v141 offset:19456
	ds_read_b128 v[204:207], v141 offset:20480
	ds_read_b128 v[208:211], v141 offset:21504
	ds_read_b128 v[212:215], v141 offset:22528
	ds_read_b128 v[216:219], v141 offset:23552
	global_load_lds_dwordx4 v[238:239], off
	v_lshl_add_u64 v[238:239], v[168:169], 0, s[60:61]
	s_mov_b32 m0, s25
	s_nop 0
	global_load_lds_dwordx4 v[238:239], off
	s_barrier
	s_waitcnt lgkmcnt(0)
	s_waitcnt lgkmcnt(0)
	v_mfma_f32_16x16x32_bf16 v[62:65], v[152:155], v[188:191], v[62:65]
	v_mfma_f32_16x16x32_bf16 v[58:61], v[180:183], v[188:191], v[58:61]
	v_mfma_f32_16x16x32_bf16 v[54:57], v[152:155], v[196:199], v[54:57]
	v_mfma_f32_16x16x32_bf16 v[50:53], v[180:183], v[196:199], v[50:53]
	v_mfma_f32_16x16x32_bf16 v[46:49], v[152:155], v[204:207], v[46:49]
	v_mfma_f32_16x16x32_bf16 v[42:45], v[180:183], v[204:207], v[42:45]
	v_mfma_f32_16x16x32_bf16 v[38:41], v[152:155], v[212:215], v[38:41]
	v_mfma_f32_16x16x32_bf16 v[34:37], v[180:183], v[212:215], v[34:37]
	v_mfma_f32_16x16x32_bf16 v[62:65], v[164:167], v[192:195], v[62:65]
	v_mfma_f32_16x16x32_bf16 v[58:61], v[184:187], v[192:195], v[58:61]
	v_mfma_f32_16x16x32_bf16 v[54:57], v[164:167], v[200:203], v[54:57]
	v_mfma_f32_16x16x32_bf16 v[50:53], v[184:187], v[200:203], v[50:53]
	v_mfma_f32_16x16x32_bf16 v[46:49], v[164:167], v[208:211], v[46:49]
	v_mfma_f32_16x16x32_bf16 v[42:45], v[184:187], v[208:211], v[42:45]
	v_mfma_f32_16x16x32_bf16 v[38:41], v[164:167], v[216:219], v[38:41]
	v_mfma_f32_16x16x32_bf16 v[34:37], v[184:187], v[216:219], v[34:37]
	s_barrier
; #define WAIT_V(n) asm volatile("s_waitcnt vmcnt(%0)" ::"n"(n) : "memory")
; #define WAIT_L(n) asm volatile("s_waitcnt lgkmcnt(%0)" ::"n"(n) : "memory")
; #define SBAR() __builtin_amdgcn_sched_barrier(0)
; #define LDA8(dst, b, h) _Pragma("unroll") for (int m = 0; m < 4; ++m) _Pragma("unroll") for (int k = 0; k < 2; ++k) \
;     dst[m][k] = *(const bf16x8*)(abase + SAo(b, h) + m * 2048 + k * 1024)
; #define LDB8(dst, b, h) _Pragma("unroll") for (int n = 0; n < 2; ++n) _Pragma("unroll") for (int k = 0; k < 2; ++k) \
;     dst[n][k] = *(const bf16x8*)(bbase + SAo(b, h) + n * 2048 + k * 1024)
; #define BAR8 __builtin_amdgcn_s_barrier()
; __device__ __forceinline__ void gemm_main8(const u16* __restrict__ Ab, int lda, const u16* __restrict__ Bb, int ldb, int K,
;                                            char* shm, f32x4 (&acc)[2][2][4][2]) {
;     ...
;     STG_B(0, 1, t + 2);
;     WAIT_V(6); BAR8; MMA8(1, 1, At, B1); BAR8;
;     LDB8(B0, 1, 0); SBAR(); LDA8(At, 1, 0); STG_A(0, 1, t + 2);
;     WAIT_L(8); BAR8; WAIT_L(0); MMA8(0, 0, At, B0); BAR8; SBAR();
;     LDB8(B1, 1, 1); STG_B(1, 0, t + 3);
;     BAR8; WAIT_L(0); MMA8(0, 1, At, B1); BAR8;
	s_mov_b64 s[90:91], 0x2080100
	v_readfirstlane_b32 s25, v147
	v_lshl_add_u64 v[152:153], v[236:237], 0, s[90:91]
	s_mov_b32 m0, s25
	s_mov_b64 s[90:91], 0x20c0100
	v_readfirstlane_b32 s25, v148
	global_load_lds_dwordx4 v[152:153], off
	v_lshl_add_u64 v[152:153], v[236:237], 0, s[90:91]
	s_mov_b32 m0, s25
	s_nop 0
	global_load_lds_dwordx4 v[152:153], off
	s_waitcnt vmcnt(6)
	s_barrier
	v_mfma_f32_16x16x32_bf16 v[30:33], v[220:223], v[188:191], v[30:33]
	v_mfma_f32_16x16x32_bf16 v[26:29], v[228:231], v[188:191], v[26:29]
	v_mfma_f32_16x16x32_bf16 v[22:25], v[220:223], v[196:199], v[22:25]
	v_mfma_f32_16x16x32_bf16 v[18:21], v[228:231], v[196:199], v[18:21]
	v_mfma_f32_16x16x32_bf16 v[14:17], v[220:223], v[204:207], v[14:17]
	v_mfma_f32_16x16x32_bf16 v[10:13], v[228:231], v[204:207], v[10:13]
	v_mfma_f32_16x16x32_bf16 v[6:9], v[220:223], v[212:215], v[6:9]
	v_mfma_f32_16x16x32_bf16 v[2:5], v[228:231], v[212:215], v[2:5]
	v_mfma_f32_16x16x32_bf16 v[30:33], v[224:227], v[192:195], v[30:33]
	v_mfma_f32_16x16x32_bf16 v[26:29], v[232:235], v[192:195], v[26:29]
	v_mfma_f32_16x16x32_bf16 v[22:25], v[224:227], v[200:203], v[22:25]
	v_mfma_f32_16x16x32_bf16 v[18:21], v[232:235], v[200:203], v[18:21]
	v_mfma_f32_16x16x32_bf16 v[14:17], v[224:227], v[208:211], v[14:17]
	v_mfma_f32_16x16x32_bf16 v[10:13], v[232:235], v[208:211], v[10:13]
	v_mfma_f32_16x16x32_bf16 v[6:9], v[224:227], v[216:219], v[6:9]
	v_mfma_f32_16x16x32_bf16 v[2:5], v[232:235], v[216:219], v[2:5]
	s_barrier
	ds_read_b128 v[152:155], v142 offset:32768
	ds_read_b128 v[164:167], v142 offset:33792
	ds_read_b128 v[180:183], v142 offset:34816
	ds_read_b128 v[184:187], v142 offset:35840
	ds_read_b128 v[188:191], v141 offset:32768
	ds_read_b128 v[192:195], v141 offset:33792
	ds_read_b128 v[196:199], v141 offset:34816
	ds_read_b128 v[200:203], v141 offset:35840
	ds_read_b128 v[204:207], v141 offset:36864
	ds_read_b128 v[208:211], v141 offset:37888
	ds_read_b128 v[212:215], v141 offset:38912
	ds_read_b128 v[216:219], v141 offset:39936
	v_readfirstlane_b32 s25, v149
	v_lshl_add_u64 v[220:221], v[168:169], 0, s[62:63]
	s_mov_b32 m0, s25
	v_readfirstlane_b32 s25, v171
	global_load_lds_dwordx4 v[220:221], off
	v_lshl_add_u64 v[220:221], v[168:169], 0, s[64:65]
	s_mov_b32 m0, s25
	s_nop 0
	global_load_lds_dwordx4 v[220:221], off
	s_waitcnt lgkmcnt(8)
	s_barrier
	s_waitcnt lgkmcnt(0)
	s_waitcnt lgkmcnt(0)
	v_mfma_f32_16x16x32_bf16 v[126:129], v[152:155], v[188:191], v[126:129]
	v_mfma_f32_16x16x32_bf16 v[122:125], v[180:183], v[188:191], v[122:125]
	v_mfma_f32_16x16x32_bf16 v[118:121], v[152:155], v[196:199], v[118:121]
	v_mfma_f32_16x16x32_bf16 v[114:117], v[180:183], v[196:199], v[114:117]
	v_mfma_f32_16x16x32_bf16 v[110:113], v[152:155], v[204:207], v[110:113]
	v_mfma_f32_16x16x32_bf16 v[106:109], v[180:183], v[204:207], v[106:109]
	v_mfma_f32_16x16x32_bf16 v[102:105], v[152:155], v[212:215], v[102:105]
	v_mfma_f32_16x16x32_bf16 v[98:101], v[180:183], v[212:215], v[98:101]
	v_mfma_f32_16x16x32_bf16 v[126:129], v[164:167], v[192:195], v[126:129]
	v_mfma_f32_16x16x32_bf16 v[122:125], v[184:187], v[192:195], v[122:125]
	v_mfma_f32_16x16x32_bf16 v[118:121], v[164:167], v[200:203], v[118:121]
	v_mfma_f32_16x16x32_bf16 v[114:117], v[184:187], v[200:203], v[114:117]
	v_mfma_f32_16x16x32_bf16 v[110:113], v[164:167], v[208:211], v[110:113]
	v_mfma_f32_16x16x32_bf16 v[106:109], v[184:187], v[208:211], v[106:109]
	v_mfma_f32_16x16x32_bf16 v[102:105], v[164:167], v[216:219], v[102:105]
	v_mfma_f32_16x16x32_bf16 v[98:101], v[184:187], v[216:219], v[98:101]
	s_barrier
	ds_read_b128 v[220:223], v142 offset:49152
	ds_read_b128 v[224:227], v142 offset:50176
	ds_read_b128 v[228:231], v142 offset:51200
	ds_read_b128 v[232:235], v142 offset:52224
	s_mov_b64 s[90:91], 0x2000180
	v_readfirstlane_b32 s25, v172
	v_lshl_add_u64 v[238:239], v[236:237], 0, s[90:91]
	s_mov_b32 m0, s25
	s_mov_b64 s[90:91], 0x2040180
	v_readfirstlane_b32 s25, v173
	global_load_lds_dwordx4 v[238:239], off
	v_lshl_add_u64 v[238:239], v[236:237], 0, s[90:91]
	s_mov_b32 m0, s25
	s_nop 0
	global_load_lds_dwordx4 v[238:239], off
	s_barrier
	s_waitcnt lgkmcnt(0)
	s_waitcnt lgkmcnt(0)
	v_mfma_f32_16x16x32_bf16 v[94:97], v[220:223], v[188:191], v[94:97]
	v_mfma_f32_16x16x32_bf16 v[90:93], v[228:231], v[188:191], v[90:93]
	v_mfma_f32_16x16x32_bf16 v[86:89], v[220:223], v[196:199], v[86:89]
	v_mfma_f32_16x16x32_bf16 v[82:85], v[228:231], v[196:199], v[82:85]
	v_mfma_f32_16x16x32_bf16 v[78:81], v[220:223], v[204:207], v[78:81]
	v_mfma_f32_16x16x32_bf16 v[74:77], v[228:231], v[204:207], v[74:77]
	v_mfma_f32_16x16x32_bf16 v[70:73], v[220:223], v[212:215], v[70:73]
	v_mfma_f32_16x16x32_bf16 v[66:69], v[228:231], v[212:215], v[66:69]
	v_mfma_f32_16x16x32_bf16 v[94:97], v[224:227], v[192:195], v[94:97]
	v_mfma_f32_16x16x32_bf16 v[90:93], v[232:235], v[192:195], v[90:93]
	v_mfma_f32_16x16x32_bf16 v[86:89], v[224:227], v[200:203], v[86:89]
	v_mfma_f32_16x16x32_bf16 v[82:85], v[232:235], v[200:203], v[82:85]
	v_mfma_f32_16x16x32_bf16 v[78:81], v[224:227], v[208:211], v[78:81]
	v_mfma_f32_16x16x32_bf16 v[74:77], v[232:235], v[208:211], v[74:77]
	v_mfma_f32_16x16x32_bf16 v[70:73], v[224:227], v[216:219], v[70:73]
	v_mfma_f32_16x16x32_bf16 v[66:69], v[232:235], v[216:219], v[66:69]
	v_readfirstlane_b32 s25, v174
	v_lshl_add_u64 v[238:239], v[168:169], 0, s[66:67]
	s_mov_b32 m0, s25
	v_readfirstlane_b32 s25, v175
	s_barrier
; #define WAIT_V(n) asm volatile("s_waitcnt vmcnt(%0)" ::"n"(n) : "memory")
; #define WAIT_L(n) asm volatile("s_waitcnt lgkmcnt(%0)" ::"n"(n) : "memory")
; #define SBAR() __builtin_amdgcn_sched_barrier(0)
; #define LDA8(dst, b, h) _Pragma("unroll") for (int m = 0; m < 4; ++m) _Pragma("unroll") for (int k = 0; k < 2; ++k) \
;     dst[m][k] = *(const bf16x8*)(abase + SAo(b, h) + m * 2048 + k * 1024)
; #define LDB8(dst, b, h) _Pragma("unroll") for (int n = 0; n < 2; ++n) _Pragma("unroll") for (int k = 0; k < 2; ++k) \
;     dst[n][k] = *(const bf16x8*)(bbase + SAo(b, h) + n * 2048 + k * 1024)
; #define BAR8 __builtin_amdgcn_s_barrier()
; __device__ __forceinline__ void gemm_main8(const u16* __restrict__ Ab, int lda, const u16* __restrict__ Bb, int ldb, int K,
;                                            char* shm, f32x4 (&acc)[2][2][4][2]) {
;     ...
;     LDA8(At, 1, 1); STG_A(1, 0, t + 3);
;     BAR8; WAIT_L(0); MMA8(1, 0, At, B0); BAR8; SBAR();
;     STG_B(1, 1, t + 3);
;     WAIT_V(6); BAR8; MMA8(1, 1, At, B1); BAR8;
;   }
;   { LDB8(B0, 0, 0); LDA8(At, 0, 0); STG_A(1, 1, nt - 1);
;     BAR8; WAIT_L(0); MMA8(0, 0, At, B0); BAR8;
;     LDB8(B1, 0, 1); BAR8; WAIT_L(0); MMA8(0, 1, At, B1); BAR8;
	ds_read_b128 v[188:191], v141 offset:49152
	ds_read_b128 v[192:195], v141 offset:50176
	ds_read_b128 v[196:199], v141 offset:51200
	ds_read_b128 v[200:203], v141 offset:52224
	ds_read_b128 v[204:207], v141 offset:53248
	ds_read_b128 v[208:211], v141 offset:54272
	ds_read_b128 v[212:215], v141 offset:55296
	ds_read_b128 v[216:219], v141 offset:56320
	global_load_lds_dwordx4 v[238:239], off
	v_lshl_add_u64 v[168:169], v[168:169], 0, s[68:69]
	s_mov_b32 m0, s25
	s_nop 0
	global_load_lds_dwordx4 v[168:169], off
	s_barrier
	s_waitcnt lgkmcnt(0)
	s_waitcnt lgkmcnt(0)
	v_mfma_f32_16x16x32_bf16 v[62:65], v[152:155], v[188:191], v[62:65]
	v_mfma_f32_16x16x32_bf16 v[58:61], v[180:183], v[188:191], v[58:61]
	v_mfma_f32_16x16x32_bf16 v[54:57], v[152:155], v[196:199], v[54:57]
	v_mfma_f32_16x16x32_bf16 v[50:53], v[180:183], v[196:199], v[50:53]
	v_mfma_f32_16x16x32_bf16 v[46:49], v[152:155], v[204:207], v[46:49]
	v_mfma_f32_16x16x32_bf16 v[42:45], v[180:183], v[204:207], v[42:45]
	v_mfma_f32_16x16x32_bf16 v[38:41], v[152:155], v[212:215], v[38:41]
	v_mfma_f32_16x16x32_bf16 v[34:37], v[180:183], v[212:215], v[34:37]
	v_mfma_f32_16x16x32_bf16 v[62:65], v[164:167], v[192:195], v[62:65]
	v_mfma_f32_16x16x32_bf16 v[58:61], v[184:187], v[192:195], v[58:61]
	v_mfma_f32_16x16x32_bf16 v[54:57], v[164:167], v[200:203], v[54:57]
	v_mfma_f32_16x16x32_bf16 v[50:53], v[184:187], v[200:203], v[50:53]
	v_mfma_f32_16x16x32_bf16 v[46:49], v[164:167], v[208:211], v[46:49]
	v_mfma_f32_16x16x32_bf16 v[42:45], v[184:187], v[208:211], v[42:45]
	v_mfma_f32_16x16x32_bf16 v[38:41], v[164:167], v[216:219], v[38:41]
	v_mfma_f32_16x16x32_bf16 v[34:37], v[184:187], v[216:219], v[34:37]
	s_barrier
	s_mov_b64 s[90:91], 0x2080180
	v_readfirstlane_b32 s25, v176
	v_lshl_add_u64 v[152:153], v[236:237], 0, s[90:91]
	s_mov_b32 m0, s25
	s_mov_b64 s[90:91], 0x20c0180
	v_readfirstlane_b32 s25, v177
	global_load_lds_dwordx4 v[152:153], off
	v_lshl_add_u64 v[152:153], v[236:237], 0, s[90:91]
	s_mov_b32 m0, s25
	s_nop 0
	global_load_lds_dwordx4 v[152:153], off
	s_waitcnt vmcnt(6)
	s_barrier
	v_mfma_f32_16x16x32_bf16 v[30:33], v[220:223], v[188:191], v[30:33]
	v_mfma_f32_16x16x32_bf16 v[26:29], v[228:231], v[188:191], v[26:29]
	v_mfma_f32_16x16x32_bf16 v[22:25], v[220:223], v[196:199], v[22:25]
	v_mfma_f32_16x16x32_bf16 v[18:21], v[228:231], v[196:199], v[18:21]
	v_mfma_f32_16x16x32_bf16 v[14:17], v[220:223], v[204:207], v[14:17]
	v_mfma_f32_16x16x32_bf16 v[10:13], v[228:231], v[204:207], v[10:13]
	v_mfma_f32_16x16x32_bf16 v[6:9], v[220:223], v[212:215], v[6:9]
	v_mfma_f32_16x16x32_bf16 v[2:5], v[228:231], v[212:215], v[2:5]
	v_mfma_f32_16x16x32_bf16 v[30:33], v[224:227], v[192:195], v[30:33]
	v_mfma_f32_16x16x32_bf16 v[26:29], v[232:235], v[192:195], v[26:29]
	v_mfma_f32_16x16x32_bf16 v[22:25], v[224:227], v[200:203], v[22:25]
	v_mfma_f32_16x16x32_bf16 v[18:21], v[232:235], v[200:203], v[18:21]
	v_mfma_f32_16x16x32_bf16 v[14:17], v[224:227], v[208:211], v[14:17]
	v_mfma_f32_16x16x32_bf16 v[10:13], v[232:235], v[208:211], v[10:13]
	v_mfma_f32_16x16x32_bf16 v[6:9], v[224:227], v[216:219], v[6:9]
	v_mfma_f32_16x16x32_bf16 v[2:5], v[232:235], v[216:219], v[2:5]
	s_add_i32 s5, s5, 2
	s_add_u32 s14, s14, 0x100
	s_addc_u32 s15, s15, 0
	s_add_u32 s88, s88, 0x100
	s_addc_u32 s89, s89, 0
	s_cmp_lt_u32 s5, 28
	s_barrier
	s_cbranch_scc1 .LBB0_223
	s_mov_b64 s[14:15], 0x80f80
	v_readfirstlane_b32 s5, v179
	v_lshl_add_u64 v[134:135], v[132:133], 0, s[14:15]
	s_mov_b32 m0, s5
	s_mov_b64 s[14:15], 0xc0f80
	v_readfirstlane_b32 s5, v178
	ds_read_b128 v[144:147], v142
	ds_read_b128 v[152:155], v142 offset:1024
	ds_read_b128 v[164:167], v142 offset:2048
	ds_read_b128 v[168:171], v142 offset:3072
	ds_read_b128 v[172:175], v141
	ds_read_b128 v[180:183], v141 offset:1024
	ds_read_b128 v[184:187], v141 offset:2048
	ds_read_b128 v[188:191], v141 offset:3072
	ds_read_b128 v[192:195], v141 offset:4096
	ds_read_b128 v[196:199], v141 offset:5120
	ds_read_b128 v[200:203], v141 offset:6144
	ds_read_b128 v[204:207], v141 offset:7168
	global_load_lds_dwordx4 v[134:135], off
	v_lshl_add_u64 v[132:133], v[132:133], 0, s[14:15]
	s_mov_b32 m0, s5
	s_nop 0
	global_load_lds_dwordx4 v[132:133], off
	s_barrier
	s_waitcnt lgkmcnt(0)
	s_waitcnt lgkmcnt(0)
	v_mfma_f32_16x16x32_bf16 v[126:129], v[144:147], v[172:175], v[126:129]
	v_mfma_f32_16x16x32_bf16 v[122:125], v[164:167], v[172:175], v[122:125]
	v_mfma_f32_16x16x32_bf16 v[118:121], v[144:147], v[184:187], v[118:121]
	v_mfma_f32_16x16x32_bf16 v[114:117], v[164:167], v[184:187], v[114:117]
	v_mfma_f32_16x16x32_bf16 v[102:105], v[144:147], v[200:203], v[102:105]
	v_mfma_f32_16x16x32_bf16 v[98:101], v[164:167], v[200:203], v[98:101]
	v_mfma_f32_16x16x32_bf16 v[126:129], v[152:155], v[180:183], v[126:129]
	v_mfma_f32_16x16x32_bf16 v[122:125], v[168:171], v[180:183], v[122:125]
	v_mfma_f32_16x16x32_bf16 v[118:121], v[152:155], v[188:191], v[118:121]
	v_mfma_f32_16x16x32_bf16 v[114:117], v[168:171], v[188:191], v[114:117]
	v_mfma_f32_16x16x32_bf16 v[110:113], v[144:147], v[192:195], v[110:113]
	v_mfma_f32_16x16x32_bf16 v[106:109], v[164:167], v[192:195], v[106:109]
	v_mfma_f32_16x16x32_bf16 v[102:105], v[152:155], v[204:207], v[102:105]
	v_mfma_f32_16x16x32_bf16 v[98:101], v[168:171], v[204:207], v[98:101]
	v_mfma_f32_16x16x32_bf16 v[132:135], v[152:155], v[196:199], v[110:113]
	v_mfma_f32_16x16x32_bf16 v[176:179], v[168:171], v[196:199], v[106:109]
	s_barrier
	s_nop 1
	ds_read_b128 v[106:109], v142 offset:16384
	ds_read_b128 v[110:113], v142 offset:17408
	ds_read_b128 v[208:211], v142 offset:18432
	ds_read_b128 v[212:215], v142 offset:19456
	s_barrier
; #define WAIT_V(n) asm volatile("s_waitcnt vmcnt(%0)" ::"n"(n) : "memory")
; #define WAIT_L(n) asm volatile("s_waitcnt lgkmcnt(%0)" ::"n"(n) : "memory")
; #define LDA8(dst, b, h) _Pragma("unroll") for (int m = 0; m < 4; ++m) _Pragma("unroll") for (int k = 0; k < 2; ++k) \
;     dst[m][k] = *(const bf16x8*)(abase + SAo(b, h) + m * 2048 + k * 1024)
; #define LDB8(dst, b, h) _Pragma("unroll") for (int n = 0; n < 2; ++n) _Pragma("unroll") for (int k = 0; k < 2; ++k) \
;     dst[n][k] = *(const bf16x8*)(bbase + SAo(b, h) + n * 2048 + k * 1024)
; #define BAR8 __builtin_amdgcn_s_barrier()
; __device__ __forceinline__ void gemm_main8(const u16* __restrict__ Ab, int lda, const u16* __restrict__ Bb, int ldb, int K,
;                                            char* shm, f32x4 (&acc)[2][2][4][2]) {
;     ...
;     LDB8(B1, 0, 1); BAR8; WAIT_L(0); MMA8(0, 1, At, B1); BAR8;
;     LDA8(At, 0, 1); WAIT_V(4); BAR8; WAIT_L(0); MMA8(1, 0, At, B0); MMA8(1, 1, At, B1); BAR8; }
;   { LDB8(B0, 1, 0); LDA8(At, 1, 0); WAIT_V(2); BAR8; WAIT_L(0); MMA8(0, 0, At, B0); BAR8;
	s_waitcnt lgkmcnt(0)
	s_waitcnt lgkmcnt(0)
	v_mfma_f32_16x16x32_bf16 v[86:89], v[106:109], v[184:187], v[86:89]
	v_mfma_f32_16x16x32_bf16 v[82:85], v[208:211], v[184:187], v[82:85]
	v_mfma_f32_16x16x32_bf16 v[70:73], v[106:109], v[200:203], v[70:73]
	v_mfma_f32_16x16x32_bf16 v[66:69], v[208:211], v[200:203], v[66:69]
	v_mfma_f32_16x16x32_bf16 v[94:97], v[106:109], v[172:175], v[94:97]
	v_mfma_f32_16x16x32_bf16 v[90:93], v[208:211], v[172:175], v[90:93]
	v_mfma_f32_16x16x32_bf16 v[86:89], v[110:113], v[188:191], v[86:89]
	v_mfma_f32_16x16x32_bf16 v[82:85], v[212:215], v[188:191], v[82:85]
	v_mfma_f32_16x16x32_bf16 v[78:81], v[106:109], v[192:195], v[78:81]
	v_mfma_f32_16x16x32_bf16 v[74:77], v[208:211], v[192:195], v[74:77]
	v_mfma_f32_16x16x32_bf16 v[70:73], v[110:113], v[204:207], v[70:73]
	v_mfma_f32_16x16x32_bf16 v[66:69], v[212:215], v[204:207], v[66:69]
	v_mfma_f32_16x16x32_bf16 v[216:219], v[110:113], v[180:183], v[94:97]
	v_mfma_f32_16x16x32_bf16 v[172:175], v[212:215], v[180:183], v[90:93]
	v_mfma_f32_16x16x32_bf16 v[180:183], v[110:113], v[196:199], v[78:81]
	v_mfma_f32_16x16x32_bf16 v[184:187], v[212:215], v[196:199], v[74:77]
	s_barrier
	s_nop 0
	ds_read_b128 v[74:77], v141 offset:16384
	ds_read_b128 v[78:81], v141 offset:17408
	ds_read_b128 v[90:93], v141 offset:18432
	ds_read_b128 v[94:97], v141 offset:19456
	ds_read_b128 v[188:191], v141 offset:20480
	ds_read_b128 v[192:195], v141 offset:21504
	ds_read_b128 v[196:199], v141 offset:22528
	ds_read_b128 v[200:203], v141 offset:23552
	s_waitcnt vmcnt(4)
	s_barrier
	s_waitcnt lgkmcnt(0)
	s_waitcnt lgkmcnt(0)
	v_mfma_f32_16x16x32_bf16 v[62:65], v[144:147], v[74:77], v[62:65]
	v_mfma_f32_16x16x32_bf16 v[58:61], v[164:167], v[74:77], v[58:61]
	v_mfma_f32_16x16x32_bf16 v[54:57], v[144:147], v[90:93], v[54:57]
	v_mfma_f32_16x16x32_bf16 v[50:53], v[164:167], v[90:93], v[50:53]
	v_mfma_f32_16x16x32_bf16 v[38:41], v[144:147], v[196:199], v[38:41]
	v_mfma_f32_16x16x32_bf16 v[34:37], v[164:167], v[196:199], v[34:37]
	v_mfma_f32_16x16x32_bf16 v[62:65], v[152:155], v[78:81], v[62:65]
	v_mfma_f32_16x16x32_bf16 v[58:61], v[168:171], v[78:81], v[58:61]
	v_mfma_f32_16x16x32_bf16 v[54:57], v[152:155], v[94:97], v[54:57]
	v_mfma_f32_16x16x32_bf16 v[50:53], v[168:171], v[94:97], v[50:53]
	v_mfma_f32_16x16x32_bf16 v[46:49], v[144:147], v[188:191], v[46:49]
	v_mfma_f32_16x16x32_bf16 v[42:45], v[164:167], v[188:191], v[42:45]
	v_mfma_f32_16x16x32_bf16 v[38:41], v[152:155], v[200:203], v[38:41]
	v_mfma_f32_16x16x32_bf16 v[34:37], v[168:171], v[200:203], v[34:37]
	v_mfma_f32_16x16x32_bf16 v[204:207], v[152:155], v[192:195], v[46:49]
	v_mfma_f32_16x16x32_bf16 v[220:223], v[168:171], v[192:195], v[42:45]
	v_mfma_f32_16x16x32_bf16 v[22:25], v[106:109], v[90:93], v[22:25]
	v_mfma_f32_16x16x32_bf16 v[18:21], v[208:211], v[90:93], v[18:21]
	v_mfma_f32_16x16x32_bf16 v[6:9], v[106:109], v[196:199], v[6:9]
	v_mfma_f32_16x16x32_bf16 v[2:5], v[208:211], v[196:199], v[2:5]
	v_mfma_f32_16x16x32_bf16 v[30:33], v[106:109], v[74:77], v[30:33]
	v_mfma_f32_16x16x32_bf16 v[26:29], v[208:211], v[74:77], v[26:29]
	v_mfma_f32_16x16x32_bf16 v[22:25], v[110:113], v[94:97], v[22:25]
	v_mfma_f32_16x16x32_bf16 v[18:21], v[212:215], v[94:97], v[18:21]
	v_mfma_f32_16x16x32_bf16 v[14:17], v[106:109], v[188:191], v[14:17]
	v_mfma_f32_16x16x32_bf16 v[10:13], v[208:211], v[188:191], v[10:13]
	v_mfma_f32_16x16x32_bf16 v[6:9], v[110:113], v[200:203], v[6:9]
	v_mfma_f32_16x16x32_bf16 v[2:5], v[212:215], v[200:203], v[2:5]
	v_mfma_f32_16x16x32_bf16 v[144:147], v[110:113], v[78:81], v[30:33]
	v_mfma_f32_16x16x32_bf16 v[152:155], v[212:215], v[78:81], v[26:29]
	v_mfma_f32_16x16x32_bf16 v[164:167], v[110:113], v[192:195], v[14:17]
	v_mfma_f32_16x16x32_bf16 v[168:171], v[212:215], v[192:195], v[10:13]
	s_barrier
	s_nop 0
	ds_read_b128 v[10:13], v142 offset:32768
	ds_read_b128 v[14:17], v142 offset:33792
	ds_read_b128 v[188:191], v142 offset:34816
	ds_read_b128 v[192:195], v142 offset:35840
	ds_read_b128 v[26:29], v141 offset:32768
	ds_read_b128 v[30:33], v141 offset:33792
	ds_read_b128 v[42:45], v141 offset:34816
	ds_read_b128 v[46:49], v141 offset:35840
	ds_read_b128 v[196:199], v141 offset:36864
	ds_read_b128 v[200:203], v141 offset:37888
	ds_read_b128 v[208:211], v141 offset:38912
	ds_read_b128 v[212:215], v141 offset:39936
	s_waitcnt vmcnt(2)
	s_barrier
; #define WAIT_V(n) asm volatile("s_waitcnt vmcnt(%0)" ::"n"(n) : "memory")
; #define WAIT_L(n) asm volatile("s_waitcnt lgkmcnt(%0)" ::"n"(n) : "memory")
; #define LDA8(dst, b, h) _Pragma("unroll") for (int m = 0; m < 4; ++m) _Pragma("unroll") for (int k = 0; k < 2; ++k) \
;     dst[m][k] = *(const bf16x8*)(abase + SAo(b, h) + m * 2048 + k * 1024)
; #define LDB8(dst, b, h) _Pragma("unroll") for (int n = 0; n < 2; ++n) _Pragma("unroll") for (int k = 0; k < 2; ++k) \
;     dst[n][k] = *(const bf16x8*)(bbase + SAo(b, h) + n * 2048 + k * 1024)
; #define BAR8 __builtin_amdgcn_s_barrier()
; __device__ __forceinline__ void gemm_main8(const u16* __restrict__ Ab, int lda, const u16* __restrict__ Bb, int ldb, int K,
;                                            char* shm, f32x4 (&acc)[2][2][4][2]) {
;     ...
;   { LDB8(B0, 1, 0); LDA8(At, 1, 0); WAIT_V(2); BAR8; WAIT_L(0); MMA8(0, 0, At, B0); BAR8;
;     LDB8(B1, 1, 1); WAIT_V(0); BAR8; WAIT_L(0); MMA8(0, 1, At, B1); BAR8;
;     LDA8(At, 1, 1); BAR8; WAIT_L(0); MMA8(1, 0, At, B0); MMA8(1, 1, At, B1); BAR8; }
;   if (wr == 0) BAR8;
	s_waitcnt lgkmcnt(0)
	s_waitcnt lgkmcnt(0)
	v_mfma_f32_16x16x32_bf16 v[74:77], v[10:13], v[26:29], v[126:129]
	v_mfma_f32_16x16x32_bf16 v[126:129], v[14:17], v[30:33], v[74:77]
	v_mfma_f32_16x16x32_bf16 v[74:77], v[188:191], v[26:29], v[122:125]
	v_mfma_f32_16x16x32_bf16 v[122:125], v[192:195], v[30:33], v[74:77]
	v_mfma_f32_16x16x32_bf16 v[74:77], v[10:13], v[42:45], v[118:121]
	v_mfma_f32_16x16x32_bf16 v[110:113], v[14:17], v[46:49], v[74:77]
	v_mfma_f32_16x16x32_bf16 v[74:77], v[188:191], v[42:45], v[114:117]
	v_mfma_f32_16x16x32_bf16 v[106:109], v[192:195], v[46:49], v[74:77]
	v_mfma_f32_16x16x32_bf16 v[74:77], v[10:13], v[196:199], v[132:135]
	v_mfma_f32_16x16x32_bf16 v[94:97], v[14:17], v[200:203], v[74:77]
	v_mfma_f32_16x16x32_bf16 v[74:77], v[188:191], v[196:199], v[176:179]
	v_mfma_f32_16x16x32_bf16 v[90:93], v[192:195], v[200:203], v[74:77]
	v_mfma_f32_16x16x32_bf16 v[74:77], v[10:13], v[208:211], v[102:105]
	v_mfma_f32_16x16x32_bf16 v[78:81], v[14:17], v[212:215], v[74:77]
	v_mfma_f32_16x16x32_bf16 v[74:77], v[188:191], v[208:211], v[98:101]
	v_mfma_f32_16x16x32_bf16 v[74:77], v[192:195], v[212:215], v[74:77]
	s_barrier
	ds_read_b128 v[132:135], v142 offset:49152
	ds_read_b128 v[176:179], v142 offset:50176
	ds_read_b128 v[224:227], v142 offset:51200
	ds_read_b128 v[228:231], v142 offset:52224
	s_waitcnt vmcnt(0)
	s_barrier
	s_waitcnt lgkmcnt(0)
	s_waitcnt lgkmcnt(0)
	v_mfma_f32_16x16x32_bf16 v[98:101], v[132:135], v[26:29], v[216:219]
	v_mfma_f32_16x16x32_bf16 v[26:29], v[224:227], v[26:29], v[172:175]
	v_mfma_f32_16x16x32_bf16 v[114:117], v[228:231], v[30:33], v[26:29]
	v_mfma_f32_16x16x32_bf16 v[26:29], v[132:135], v[42:45], v[86:89]
	v_mfma_f32_16x16x32_bf16 v[102:105], v[176:179], v[46:49], v[26:29]
	v_mfma_f32_16x16x32_bf16 v[26:29], v[224:227], v[42:45], v[82:85]
	v_mfma_f32_16x16x32_bf16 v[118:121], v[176:179], v[30:33], v[98:101]
	v_mfma_f32_16x16x32_bf16 v[98:101], v[228:231], v[46:49], v[26:29]
	v_mfma_f32_16x16x32_bf16 v[26:29], v[132:135], v[196:199], v[180:183]
	v_mfma_f32_16x16x32_bf16 v[86:89], v[176:179], v[200:203], v[26:29]
	v_mfma_f32_16x16x32_bf16 v[26:29], v[224:227], v[196:199], v[184:187]
	v_mfma_f32_16x16x32_bf16 v[82:85], v[228:231], v[200:203], v[26:29]
	v_mfma_f32_16x16x32_bf16 v[26:29], v[132:135], v[208:211], v[70:73]
	v_mfma_f32_16x16x32_bf16 v[70:73], v[176:179], v[212:215], v[26:29]
	v_mfma_f32_16x16x32_bf16 v[26:29], v[224:227], v[208:211], v[66:69]
	v_mfma_f32_16x16x32_bf16 v[66:69], v[228:231], v[212:215], v[26:29]
	s_barrier
	ds_read_b128 v[172:175], v141 offset:49152
	ds_read_b128 v[180:183], v141 offset:50176
	ds_read_b128 v[184:187], v141 offset:51200
	ds_read_b128 v[196:199], v141 offset:52224
	ds_read_b128 v[200:203], v141 offset:53248
	ds_read_b128 v[208:211], v141 offset:54272
	ds_read_b128 v[212:215], v141 offset:55296
	ds_read_b128 v[216:219], v141 offset:56320
	s_barrier
	s_waitcnt lgkmcnt(0)
	s_waitcnt lgkmcnt(0)
	v_mfma_f32_16x16x32_bf16 v[26:29], v[10:13], v[172:175], v[62:65]
	v_mfma_f32_16x16x32_bf16 v[62:65], v[14:17], v[180:183], v[26:29]
	v_mfma_f32_16x16x32_bf16 v[26:29], v[188:191], v[172:175], v[58:61]
	v_mfma_f32_16x16x32_bf16 v[58:61], v[192:195], v[180:183], v[26:29]
	v_mfma_f32_16x16x32_bf16 v[26:29], v[10:13], v[184:187], v[54:57]
	v_mfma_f32_16x16x32_bf16 v[46:49], v[14:17], v[196:199], v[26:29]
	v_mfma_f32_16x16x32_bf16 v[26:29], v[188:191], v[184:187], v[50:53]
	v_mfma_f32_16x16x32_bf16 v[42:45], v[192:195], v[196:199], v[26:29]
	v_mfma_f32_16x16x32_bf16 v[26:29], v[10:13], v[200:203], v[204:207]
	v_mfma_f32_16x16x32_bf16 v[10:13], v[10:13], v[212:215], v[38:41]
	v_mfma_f32_16x16x32_bf16 v[30:33], v[14:17], v[208:211], v[26:29]
	v_mfma_f32_16x16x32_bf16 v[26:29], v[188:191], v[200:203], v[220:223]
	v_mfma_f32_16x16x32_bf16 v[14:17], v[14:17], v[216:219], v[10:13]
	v_mfma_f32_16x16x32_bf16 v[10:13], v[188:191], v[212:215], v[34:37]
	v_mfma_f32_16x16x32_bf16 v[26:29], v[192:195], v[208:211], v[26:29]
	v_mfma_f32_16x16x32_bf16 v[10:13], v[192:195], v[216:219], v[10:13]
	v_mfma_f32_16x16x32_bf16 v[34:37], v[132:135], v[172:175], v[144:147]
	v_mfma_f32_16x16x32_bf16 v[54:57], v[176:179], v[180:183], v[34:37]
	v_mfma_f32_16x16x32_bf16 v[34:37], v[224:227], v[172:175], v[152:155]
	v_mfma_f32_16x16x32_bf16 v[18:21], v[224:227], v[184:187], v[18:21]
	v_mfma_f32_16x16x32_bf16 v[50:53], v[228:231], v[180:183], v[34:37]
	v_mfma_f32_16x16x32_bf16 v[22:25], v[132:135], v[184:187], v[22:25]
	v_mfma_f32_16x16x32_bf16 v[34:37], v[228:231], v[196:199], v[18:21]
	v_mfma_f32_16x16x32_bf16 v[18:21], v[132:135], v[200:203], v[164:167]
	v_mfma_f32_16x16x32_bf16 v[38:41], v[176:179], v[196:199], v[22:25]
	v_mfma_f32_16x16x32_bf16 v[22:25], v[176:179], v[208:211], v[18:21]
	v_mfma_f32_16x16x32_bf16 v[18:21], v[224:227], v[200:203], v[168:171]
	v_mfma_f32_16x16x32_bf16 v[6:9], v[132:135], v[212:215], v[6:9]
	v_mfma_f32_16x16x32_bf16 v[2:5], v[224:227], v[212:215], v[2:5]
	v_mfma_f32_16x16x32_bf16 v[18:21], v[228:231], v[208:211], v[18:21]
	v_mfma_f32_16x16x32_bf16 v[6:9], v[176:179], v[216:219], v[6:9]
	v_mfma_f32_16x16x32_bf16 v[2:5], v[228:231], v[216:219], v[2:5]
	v_cmp_gt_u32_e32 vcc, s97, v131
	s_barrier
	s_and_saveexec_b64 s[14:15], vcc
	s_cbranch_execz .LBB0_226
	s_barrier

; #define WAIT_L(n) asm volatile("s_waitcnt lgkmcnt(%0)" ::"n"(n) : "memory")
; #define SBAR() __builtin_amdgcn_sched_barrier(0)
; #define LDA8(dst, b, h) _Pragma("unroll") for (int m = 0; m < 4; ++m) _Pragma("unroll") for (int k = 0; k < 2; ++k) \
;     dst[m][k] = *(const bf16x8*)(abase + SAo(b, h) + m * 2048 + k * 1024)
; #define LDB8(dst, b, h) _Pragma("unroll") for (int n = 0; n < 2; ++n) _Pragma("unroll") for (int k = 0; k < 2; ++k) \
;     dst[n][k] = *(const bf16x8*)(bbase + SAo(b, h) + n * 2048 + k * 1024)
; #define BAR8 __builtin_amdgcn_s_barrier()
; __device__ __forceinline__ void gemm_main8(const u16* __restrict__ Ab, int lda, const u16* __restrict__ Bb, int ldb, int K,
;                                            char* shm, f32x4 (&acc)[2][2][4][2]) {
;     ...
;     LDB8(B0, 0, 0); SBAR(); LDA8(At, 0, 0); STG_A(1, 1, t + 1);
;     WAIT_L(8); BAR8; WAIT_L(0); MMA8(0, 0, At, B0); BAR8; SBAR();
;     LDB8(B1, 0, 1); STG_B(0, 0, t + 2);
;     BAR8; WAIT_L(0); MMA8(0, 1, At, B1); BAR8;
;     LDA8(At, 0, 1); STG_A(0, 0, t + 2);
;     BAR8; WAIT_L(0); MMA8(1, 0, At, B0); BAR8; SBAR();
.LBB0_368:
	ds_read_b128 v[152:155], v137
	ds_read_b128 v[164:167], v137 offset:1024
	ds_read_b128 v[176:179], v137 offset:2048
	ds_read_b128 v[180:183], v137 offset:3072
	ds_read_b128 v[184:187], v136
	ds_read_b128 v[188:191], v136 offset:1024
	ds_read_b128 v[192:195], v136 offset:2048
	ds_read_b128 v[196:199], v136 offset:3072
	ds_read_b128 v[200:203], v136 offset:4096
	ds_read_b128 v[204:207], v136 offset:5120
	ds_read_b128 v[208:211], v136 offset:6144
	ds_read_b128 v[212:215], v136 offset:7168
	v_add_u32_e32 v173, 0xc000, v138
	v_lshl_add_u64 v[168:169], s[20:21], 0, v[0:1]
	v_readfirstlane_b32 s15, v173
	v_lshl_add_u64 v[174:175], v[168:169], 0, s[54:55]
	s_mov_b32 m0, s15
	global_load_lds_dwordx4 v[174:175], off
	v_add_u32_e32 v174, 0xe000, v138
	v_lshl_add_u64 v[216:217], v[168:169], 0, s[56:57]
	v_readfirstlane_b32 s15, v174
	s_mov_b32 m0, s15
	s_nop 0
	global_load_lds_dwordx4 v[216:217], off
	s_waitcnt lgkmcnt(8)
	s_barrier
	s_waitcnt lgkmcnt(0)
	s_waitcnt lgkmcnt(0)
	v_mfma_f32_16x16x32_bf16 v[126:129], v[152:155], v[184:187], v[126:129]
	v_mfma_f32_16x16x32_bf16 v[122:125], v[176:179], v[184:187], v[122:125]
	v_mfma_f32_16x16x32_bf16 v[118:121], v[152:155], v[192:195], v[118:121]
	v_mfma_f32_16x16x32_bf16 v[114:117], v[176:179], v[192:195], v[114:117]
	v_mfma_f32_16x16x32_bf16 v[110:113], v[152:155], v[200:203], v[110:113]
	v_mfma_f32_16x16x32_bf16 v[106:109], v[176:179], v[200:203], v[106:109]
	v_mfma_f32_16x16x32_bf16 v[102:105], v[152:155], v[208:211], v[102:105]
	v_mfma_f32_16x16x32_bf16 v[98:101], v[176:179], v[208:211], v[98:101]
	v_mfma_f32_16x16x32_bf16 v[126:129], v[164:167], v[188:191], v[126:129]
	v_mfma_f32_16x16x32_bf16 v[122:125], v[180:183], v[188:191], v[122:125]
	v_mfma_f32_16x16x32_bf16 v[118:121], v[164:167], v[196:199], v[118:121]
	v_mfma_f32_16x16x32_bf16 v[114:117], v[180:183], v[196:199], v[114:117]
	v_mfma_f32_16x16x32_bf16 v[110:113], v[164:167], v[204:207], v[110:113]
	v_mfma_f32_16x16x32_bf16 v[106:109], v[180:183], v[204:207], v[106:109]
	v_mfma_f32_16x16x32_bf16 v[102:105], v[164:167], v[212:215], v[102:105]
	v_mfma_f32_16x16x32_bf16 v[98:101], v[180:183], v[212:215], v[98:101]
	s_barrier
	ds_read_b128 v[216:219], v137 offset:16384
	ds_read_b128 v[220:223], v137 offset:17408
	ds_read_b128 v[224:227], v137 offset:18432
	ds_read_b128 v[228:231], v137 offset:19456
	v_lshl_add_u64 v[232:233], s[18:19], 0, v[0:1]
	s_mov_b64 s[24:25], 0x3800100
	v_readfirstlane_b32 s15, v139
	v_lshl_add_u64 v[234:235], v[232:233], 0, s[24:25]
	s_mov_b32 m0, s15
	s_mov_b64 s[24:25], 0x3840100
	v_readfirstlane_b32 s15, v140
	global_load_lds_dwordx4 v[234:235], off
	v_lshl_add_u64 v[234:235], v[232:233], 0, s[24:25]
	s_mov_b32 m0, s15
	s_nop 0
	global_load_lds_dwordx4 v[234:235], off
	s_barrier
	s_waitcnt lgkmcnt(0)
	s_waitcnt lgkmcnt(0)
	v_mfma_f32_16x16x32_bf16 v[94:97], v[216:219], v[184:187], v[94:97]
	v_mfma_f32_16x16x32_bf16 v[90:93], v[224:227], v[184:187], v[90:93]
	v_mfma_f32_16x16x32_bf16 v[86:89], v[216:219], v[192:195], v[86:89]
	v_mfma_f32_16x16x32_bf16 v[82:85], v[224:227], v[192:195], v[82:85]
	v_mfma_f32_16x16x32_bf16 v[78:81], v[216:219], v[200:203], v[78:81]
	v_mfma_f32_16x16x32_bf16 v[74:77], v[224:227], v[200:203], v[74:77]
	v_mfma_f32_16x16x32_bf16 v[70:73], v[216:219], v[208:211], v[70:73]
	v_mfma_f32_16x16x32_bf16 v[66:69], v[224:227], v[208:211], v[66:69]
	v_mfma_f32_16x16x32_bf16 v[94:97], v[220:223], v[188:191], v[94:97]
	v_mfma_f32_16x16x32_bf16 v[90:93], v[228:231], v[188:191], v[90:93]
	v_mfma_f32_16x16x32_bf16 v[86:89], v[220:223], v[196:199], v[86:89]
	v_mfma_f32_16x16x32_bf16 v[82:85], v[228:231], v[196:199], v[82:85]
	v_mfma_f32_16x16x32_bf16 v[78:81], v[220:223], v[204:207], v[78:81]
	v_mfma_f32_16x16x32_bf16 v[74:77], v[228:231], v[204:207], v[74:77]
	v_mfma_f32_16x16x32_bf16 v[70:73], v[220:223], v[212:215], v[70:73]
	v_mfma_f32_16x16x32_bf16 v[66:69], v[228:231], v[212:215], v[66:69]
	v_readfirstlane_b32 s15, v138
	v_lshl_add_u64 v[234:235], v[168:169], 0, s[58:59]
	s_mov_b32 m0, s15
	v_readfirstlane_b32 s15, v141
	s_barrier
	ds_read_b128 v[184:187], v136 offset:16384
	ds_read_b128 v[188:191], v136 offset:17408
	ds_read_b128 v[192:195], v136 offset:18432
	ds_read_b128 v[196:199], v136 offset:19456
	ds_read_b128 v[200:203], v136 offset:20480
	ds_read_b128 v[204:207], v136 offset:21504
	ds_read_b128 v[208:211], v136 offset:22528
	ds_read_b128 v[212:215], v136 offset:23552
	global_load_lds_dwordx4 v[234:235], off
	v_lshl_add_u64 v[234:235], v[168:169], 0, s[60:61]
	s_mov_b32 m0, s15
	s_nop 0
	global_load_lds_dwordx4 v[234:235], off
	s_barrier
	s_waitcnt lgkmcnt(0)
	s_waitcnt lgkmcnt(0)
	v_mfma_f32_16x16x32_bf16 v[62:65], v[152:155], v[184:187], v[62:65]
	v_mfma_f32_16x16x32_bf16 v[58:61], v[176:179], v[184:187], v[58:61]
	v_mfma_f32_16x16x32_bf16 v[54:57], v[152:155], v[192:195], v[54:57]
	v_mfma_f32_16x16x32_bf16 v[50:53], v[176:179], v[192:195], v[50:53]
	v_mfma_f32_16x16x32_bf16 v[46:49], v[152:155], v[200:203], v[46:49]
	v_mfma_f32_16x16x32_bf16 v[42:45], v[176:179], v[200:203], v[42:45]
	v_mfma_f32_16x16x32_bf16 v[38:41], v[152:155], v[208:211], v[38:41]
	v_mfma_f32_16x16x32_bf16 v[34:37], v[176:179], v[208:211], v[34:37]
	v_mfma_f32_16x16x32_bf16 v[62:65], v[164:167], v[188:191], v[62:65]
	v_mfma_f32_16x16x32_bf16 v[58:61], v[180:183], v[188:191], v[58:61]
	v_mfma_f32_16x16x32_bf16 v[54:57], v[164:167], v[196:199], v[54:57]
	v_mfma_f32_16x16x32_bf16 v[50:53], v[180:183], v[196:199], v[50:53]
	v_mfma_f32_16x16x32_bf16 v[46:49], v[164:167], v[204:207], v[46:49]
	v_mfma_f32_16x16x32_bf16 v[42:45], v[180:183], v[204:207], v[42:45]
	v_mfma_f32_16x16x32_bf16 v[38:41], v[164:167], v[212:215], v[38:41]
	v_mfma_f32_16x16x32_bf16 v[34:37], v[180:183], v[212:215], v[34:37]
	s_barrier
; #define WAIT_V(n) asm volatile("s_waitcnt vmcnt(%0)" ::"n"(n) : "memory")
; #define WAIT_L(n) asm volatile("s_waitcnt lgkmcnt(%0)" ::"n"(n) : "memory")
; #define SBAR() __builtin_amdgcn_sched_barrier(0)
; #define LDA8(dst, b, h) _Pragma("unroll") for (int m = 0; m < 4; ++m) _Pragma("unroll") for (int k = 0; k < 2; ++k) \
;     dst[m][k] = *(const bf16x8*)(abase + SAo(b, h) + m * 2048 + k * 1024)
; #define LDB8(dst, b, h) _Pragma("unroll") for (int n = 0; n < 2; ++n) _Pragma("unroll") for (int k = 0; k < 2; ++k) \
;     dst[n][k] = *(const bf16x8*)(bbase + SAo(b, h) + n * 2048 + k * 1024)
; #define BAR8 __builtin_amdgcn_s_barrier()
; __device__ __forceinline__ void gemm_main8(const u16* __restrict__ Ab, int lda, const u16* __restrict__ Bb, int ldb, int K,
;                                            char* shm, f32x4 (&acc)[2][2][4][2]) {
;     ...
;     STG_B(0, 1, t + 2);
;     WAIT_V(6); BAR8; MMA8(1, 1, At, B1); BAR8;
;     LDB8(B0, 1, 0); SBAR(); LDA8(At, 1, 0); STG_A(0, 1, t + 2);
;     WAIT_L(8); BAR8; WAIT_L(0); MMA8(0, 0, At, B0); BAR8; SBAR();
;     LDB8(B1, 1, 1); STG_B(1, 0, t + 3);
;     BAR8; WAIT_L(0); MMA8(0, 1, At, B1); BAR8;
	s_mov_b64 s[24:25], 0x3880100
	v_readfirstlane_b32 s15, v142
	v_lshl_add_u64 v[152:153], v[232:233], 0, s[24:25]
	s_mov_b32 m0, s15
	s_mov_b64 s[24:25], 0x38c0100
	v_readfirstlane_b32 s15, v143
	global_load_lds_dwordx4 v[152:153], off
	v_lshl_add_u64 v[152:153], v[232:233], 0, s[24:25]
	s_mov_b32 m0, s15
	s_nop 0
	global_load_lds_dwordx4 v[152:153], off
	s_waitcnt vmcnt(6)
	s_barrier
	v_mfma_f32_16x16x32_bf16 v[30:33], v[216:219], v[184:187], v[30:33]
	v_mfma_f32_16x16x32_bf16 v[26:29], v[224:227], v[184:187], v[26:29]
	v_mfma_f32_16x16x32_bf16 v[22:25], v[216:219], v[192:195], v[22:25]
	v_mfma_f32_16x16x32_bf16 v[18:21], v[224:227], v[192:195], v[18:21]
	v_mfma_f32_16x16x32_bf16 v[14:17], v[216:219], v[200:203], v[14:17]
	v_mfma_f32_16x16x32_bf16 v[10:13], v[224:227], v[200:203], v[10:13]
	v_mfma_f32_16x16x32_bf16 v[6:9], v[216:219], v[208:211], v[6:9]
	v_mfma_f32_16x16x32_bf16 v[2:5], v[224:227], v[208:211], v[2:5]
	v_mfma_f32_16x16x32_bf16 v[30:33], v[220:223], v[188:191], v[30:33]
	v_mfma_f32_16x16x32_bf16 v[26:29], v[228:231], v[188:191], v[26:29]
	v_mfma_f32_16x16x32_bf16 v[22:25], v[220:223], v[196:199], v[22:25]
	v_mfma_f32_16x16x32_bf16 v[18:21], v[228:231], v[196:199], v[18:21]
	v_mfma_f32_16x16x32_bf16 v[14:17], v[220:223], v[204:207], v[14:17]
	v_mfma_f32_16x16x32_bf16 v[10:13], v[228:231], v[204:207], v[10:13]
	v_mfma_f32_16x16x32_bf16 v[6:9], v[220:223], v[212:215], v[6:9]
	v_mfma_f32_16x16x32_bf16 v[2:5], v[228:231], v[212:215], v[2:5]
	s_barrier
	ds_read_b128 v[152:155], v137 offset:32768
	ds_read_b128 v[164:167], v137 offset:33792
	ds_read_b128 v[176:179], v137 offset:34816
	ds_read_b128 v[180:183], v137 offset:35840
	ds_read_b128 v[184:187], v136 offset:32768
	ds_read_b128 v[188:191], v136 offset:33792
	ds_read_b128 v[192:195], v136 offset:34816
	ds_read_b128 v[196:199], v136 offset:35840
	ds_read_b128 v[200:203], v136 offset:36864
	ds_read_b128 v[204:207], v136 offset:37888
	ds_read_b128 v[208:211], v136 offset:38912
	ds_read_b128 v[212:215], v136 offset:39936
	v_readfirstlane_b32 s15, v144
	v_lshl_add_u64 v[216:217], v[168:169], 0, s[62:63]
	s_mov_b32 m0, s15
	v_readfirstlane_b32 s15, v145
	global_load_lds_dwordx4 v[216:217], off
	v_lshl_add_u64 v[216:217], v[168:169], 0, s[64:65]
	s_mov_b32 m0, s15
	s_nop 0
	global_load_lds_dwordx4 v[216:217], off
	s_waitcnt lgkmcnt(8)
	s_barrier
	s_waitcnt lgkmcnt(0)
	s_waitcnt lgkmcnt(0)
	v_mfma_f32_16x16x32_bf16 v[126:129], v[152:155], v[184:187], v[126:129]
	v_mfma_f32_16x16x32_bf16 v[122:125], v[176:179], v[184:187], v[122:125]
	v_mfma_f32_16x16x32_bf16 v[118:121], v[152:155], v[192:195], v[118:121]
	v_mfma_f32_16x16x32_bf16 v[114:117], v[176:179], v[192:195], v[114:117]
	v_mfma_f32_16x16x32_bf16 v[110:113], v[152:155], v[200:203], v[110:113]
	v_mfma_f32_16x16x32_bf16 v[106:109], v[176:179], v[200:203], v[106:109]
	v_mfma_f32_16x16x32_bf16 v[102:105], v[152:155], v[208:211], v[102:105]
	v_mfma_f32_16x16x32_bf16 v[98:101], v[176:179], v[208:211], v[98:101]
	v_mfma_f32_16x16x32_bf16 v[126:129], v[164:167], v[188:191], v[126:129]
	v_mfma_f32_16x16x32_bf16 v[122:125], v[180:183], v[188:191], v[122:125]
	v_mfma_f32_16x16x32_bf16 v[118:121], v[164:167], v[196:199], v[118:121]
	v_mfma_f32_16x16x32_bf16 v[114:117], v[180:183], v[196:199], v[114:117]
	v_mfma_f32_16x16x32_bf16 v[110:113], v[164:167], v[204:207], v[110:113]
	v_mfma_f32_16x16x32_bf16 v[106:109], v[180:183], v[204:207], v[106:109]
	v_mfma_f32_16x16x32_bf16 v[102:105], v[164:167], v[212:215], v[102:105]
	v_mfma_f32_16x16x32_bf16 v[98:101], v[180:183], v[212:215], v[98:101]
	s_barrier
	ds_read_b128 v[216:219], v137 offset:49152
	ds_read_b128 v[220:223], v137 offset:50176
	ds_read_b128 v[224:227], v137 offset:51200
	ds_read_b128 v[228:231], v137 offset:52224
	s_mov_b64 s[24:25], 0x3800180
	v_readfirstlane_b32 s15, v146
	v_lshl_add_u64 v[234:235], v[232:233], 0, s[24:25]
	s_mov_b32 m0, s15
	s_mov_b64 s[24:25], 0x3840180
	v_readfirstlane_b32 s15, v147
	global_load_lds_dwordx4 v[234:235], off
	v_lshl_add_u64 v[234:235], v[232:233], 0, s[24:25]
	s_mov_b32 m0, s15
	s_nop 0
	global_load_lds_dwordx4 v[234:235], off
	s_barrier
	s_waitcnt lgkmcnt(0)
	s_waitcnt lgkmcnt(0)
	v_mfma_f32_16x16x32_bf16 v[94:97], v[216:219], v[184:187], v[94:97]
	v_mfma_f32_16x16x32_bf16 v[90:93], v[224:227], v[184:187], v[90:93]
	v_mfma_f32_16x16x32_bf16 v[86:89], v[216:219], v[192:195], v[86:89]
	v_mfma_f32_16x16x32_bf16 v[82:85], v[224:227], v[192:195], v[82:85]
	v_mfma_f32_16x16x32_bf16 v[78:81], v[216:219], v[200:203], v[78:81]
	v_mfma_f32_16x16x32_bf16 v[74:77], v[224:227], v[200:203], v[74:77]
	v_mfma_f32_16x16x32_bf16 v[70:73], v[216:219], v[208:211], v[70:73]
	v_mfma_f32_16x16x32_bf16 v[66:69], v[224:227], v[208:211], v[66:69]
	v_mfma_f32_16x16x32_bf16 v[94:97], v[220:223], v[188:191], v[94:97]
	v_mfma_f32_16x16x32_bf16 v[90:93], v[228:231], v[188:191], v[90:93]
	v_mfma_f32_16x16x32_bf16 v[86:89], v[220:223], v[196:199], v[86:89]
	v_mfma_f32_16x16x32_bf16 v[82:85], v[228:231], v[196:199], v[82:85]
	v_mfma_f32_16x16x32_bf16 v[78:81], v[220:223], v[204:207], v[78:81]
	v_mfma_f32_16x16x32_bf16 v[74:77], v[228:231], v[204:207], v[74:77]
	v_mfma_f32_16x16x32_bf16 v[70:73], v[220:223], v[212:215], v[70:73]
	v_mfma_f32_16x16x32_bf16 v[66:69], v[228:231], v[212:215], v[66:69]
	v_readfirstlane_b32 s15, v148
	v_lshl_add_u64 v[234:235], v[168:169], 0, s[66:67]
	s_mov_b32 m0, s15
	v_readfirstlane_b32 s15, v149
	s_barrier
; #define WAIT_V(n) asm volatile("s_waitcnt vmcnt(%0)" ::"n"(n) : "memory")
; #define WAIT_L(n) asm volatile("s_waitcnt lgkmcnt(%0)" ::"n"(n) : "memory")
; #define SBAR() __builtin_amdgcn_sched_barrier(0)
; #define LDA8(dst, b, h) _Pragma("unroll") for (int m = 0; m < 4; ++m) _Pragma("unroll") for (int k = 0; k < 2; ++k) \
;     dst[m][k] = *(const bf16x8*)(abase + SAo(b, h) + m * 2048 + k * 1024)
; #define LDB8(dst, b, h) _Pragma("unroll") for (int n = 0; n < 2; ++n) _Pragma("unroll") for (int k = 0; k < 2; ++k) \
;     dst[n][k] = *(const bf16x8*)(bbase + SAo(b, h) + n * 2048 + k * 1024)
; #define BAR8 __builtin_amdgcn_s_barrier()
; __device__ __forceinline__ void gemm_main8(const u16* __restrict__ Ab, int lda, const u16* __restrict__ Bb, int ldb, int K,
;                                            char* shm, f32x4 (&acc)[2][2][4][2]) {
;     ...
;     LDA8(At, 1, 1); STG_A(1, 0, t + 3);
;     BAR8; WAIT_L(0); MMA8(1, 0, At, B0); BAR8; SBAR();
;     STG_B(1, 1, t + 3);
;     WAIT_V(6); BAR8; MMA8(1, 1, At, B1); BAR8;
;   }
;   { LDB8(B0, 0, 0); LDA8(At, 0, 0); STG_A(1, 1, nt - 1);
;     BAR8; WAIT_L(0); MMA8(0, 0, At, B0); BAR8;
;     LDB8(B1, 0, 1); BAR8; WAIT_L(0); MMA8(0, 1, At, B1); BAR8;
	ds_read_b128 v[184:187], v136 offset:49152
	ds_read_b128 v[188:191], v136 offset:50176
	ds_read_b128 v[192:195], v136 offset:51200
	ds_read_b128 v[196:199], v136 offset:52224
	ds_read_b128 v[200:203], v136 offset:53248
	ds_read_b128 v[204:207], v136 offset:54272
	ds_read_b128 v[208:211], v136 offset:55296
	ds_read_b128 v[212:215], v136 offset:56320
	global_load_lds_dwordx4 v[234:235], off
	v_lshl_add_u64 v[168:169], v[168:169], 0, s[68:69]
	s_mov_b32 m0, s15
	s_nop 0
	global_load_lds_dwordx4 v[168:169], off
	s_barrier
	s_waitcnt lgkmcnt(0)
	s_waitcnt lgkmcnt(0)
	v_mfma_f32_16x16x32_bf16 v[62:65], v[152:155], v[184:187], v[62:65]
	v_mfma_f32_16x16x32_bf16 v[58:61], v[176:179], v[184:187], v[58:61]
	v_mfma_f32_16x16x32_bf16 v[54:57], v[152:155], v[192:195], v[54:57]
	v_mfma_f32_16x16x32_bf16 v[50:53], v[176:179], v[192:195], v[50:53]
	v_mfma_f32_16x16x32_bf16 v[46:49], v[152:155], v[200:203], v[46:49]
	v_mfma_f32_16x16x32_bf16 v[42:45], v[176:179], v[200:203], v[42:45]
	v_mfma_f32_16x16x32_bf16 v[38:41], v[152:155], v[208:211], v[38:41]
	v_mfma_f32_16x16x32_bf16 v[34:37], v[176:179], v[208:211], v[34:37]
	v_mfma_f32_16x16x32_bf16 v[62:65], v[164:167], v[188:191], v[62:65]
	v_mfma_f32_16x16x32_bf16 v[58:61], v[180:183], v[188:191], v[58:61]
	v_mfma_f32_16x16x32_bf16 v[54:57], v[164:167], v[196:199], v[54:57]
	v_mfma_f32_16x16x32_bf16 v[50:53], v[180:183], v[196:199], v[50:53]
	v_mfma_f32_16x16x32_bf16 v[46:49], v[164:167], v[204:207], v[46:49]
	v_mfma_f32_16x16x32_bf16 v[42:45], v[180:183], v[204:207], v[42:45]
	v_mfma_f32_16x16x32_bf16 v[38:41], v[164:167], v[212:215], v[38:41]
	v_mfma_f32_16x16x32_bf16 v[34:37], v[180:183], v[212:215], v[34:37]
	s_barrier
	s_mov_b64 s[24:25], 0x3880180
	v_readfirstlane_b32 s15, v171
	v_lshl_add_u64 v[152:153], v[232:233], 0, s[24:25]
	s_mov_b32 m0, s15
	s_mov_b64 s[24:25], 0x38c0180
	v_readfirstlane_b32 s15, v172
	global_load_lds_dwordx4 v[152:153], off
	v_lshl_add_u64 v[152:153], v[232:233], 0, s[24:25]
	s_mov_b32 m0, s15
	s_nop 0
	global_load_lds_dwordx4 v[152:153], off
	s_waitcnt vmcnt(6)
	s_barrier
	v_mfma_f32_16x16x32_bf16 v[30:33], v[216:219], v[184:187], v[30:33]
	v_mfma_f32_16x16x32_bf16 v[26:29], v[224:227], v[184:187], v[26:29]
	v_mfma_f32_16x16x32_bf16 v[22:25], v[216:219], v[192:195], v[22:25]
	v_mfma_f32_16x16x32_bf16 v[18:21], v[224:227], v[192:195], v[18:21]
	v_mfma_f32_16x16x32_bf16 v[14:17], v[216:219], v[200:203], v[14:17]
	v_mfma_f32_16x16x32_bf16 v[10:13], v[224:227], v[200:203], v[10:13]
	v_mfma_f32_16x16x32_bf16 v[6:9], v[216:219], v[208:211], v[6:9]
	v_mfma_f32_16x16x32_bf16 v[2:5], v[224:227], v[208:211], v[2:5]
	v_mfma_f32_16x16x32_bf16 v[30:33], v[220:223], v[188:191], v[30:33]
	v_mfma_f32_16x16x32_bf16 v[26:29], v[228:231], v[188:191], v[26:29]
	v_mfma_f32_16x16x32_bf16 v[22:25], v[220:223], v[196:199], v[22:25]
	v_mfma_f32_16x16x32_bf16 v[18:21], v[228:231], v[196:199], v[18:21]
	v_mfma_f32_16x16x32_bf16 v[14:17], v[220:223], v[204:207], v[14:17]
	v_mfma_f32_16x16x32_bf16 v[10:13], v[228:231], v[204:207], v[10:13]
	v_mfma_f32_16x16x32_bf16 v[6:9], v[220:223], v[212:215], v[6:9]
	v_mfma_f32_16x16x32_bf16 v[2:5], v[228:231], v[212:215], v[2:5]
	s_add_i32 s13, s13, 2
	s_add_u32 s18, s18, 0x100
	s_addc_u32 s19, s19, 0
	s_add_u32 s20, s20, 0x100
	s_addc_u32 s21, s21, 0
	s_cmp_lt_u32 s13, 28
	s_barrier
	s_cbranch_scc1 .LBB0_368
	s_mov_b64 s[18:19], 0x80f80
	v_readfirstlane_b32 s13, v173
	v_lshl_add_u64 v[200:201], v[130:131], 0, s[18:19]
	s_mov_b32 m0, s13
	s_mov_b64 s[18:19], 0xc0f80
	v_readfirstlane_b32 s13, v174
	ds_read_b128 v[138:141], v137
	ds_read_b128 v[142:145], v137 offset:1024
	ds_read_b128 v[146:149], v137 offset:2048
	ds_read_b128 v[152:155], v137 offset:3072
	ds_read_b128 v[164:167], v136
	ds_read_b128 v[168:171], v136 offset:1024
	ds_read_b128 v[176:179], v136 offset:2048
	ds_read_b128 v[180:183], v136 offset:3072
	ds_read_b128 v[184:187], v136 offset:4096
	ds_read_b128 v[188:191], v136 offset:5120
	ds_read_b128 v[192:195], v136 offset:6144
	ds_read_b128 v[196:199], v136 offset:7168
	global_load_lds_dwordx4 v[200:201], off
	v_lshl_add_u64 v[130:131], v[130:131], 0, s[18:19]
	s_mov_b32 m0, s13
	s_nop 0
	global_load_lds_dwordx4 v[130:131], off
	s_barrier
	s_waitcnt lgkmcnt(0)
	s_waitcnt lgkmcnt(0)
	v_mfma_f32_16x16x32_bf16 v[126:129], v[138:141], v[164:167], v[126:129]
	v_mfma_f32_16x16x32_bf16 v[118:121], v[138:141], v[176:179], v[118:121]
	v_mfma_f32_16x16x32_bf16 v[110:113], v[138:141], v[184:187], v[110:113]
	v_mfma_f32_16x16x32_bf16 v[102:105], v[138:141], v[192:195], v[102:105]
	v_mfma_f32_16x16x32_bf16 v[126:129], v[142:145], v[168:171], v[126:129]
	v_mfma_f32_16x16x32_bf16 v[122:125], v[146:149], v[164:167], v[122:125]
	v_mfma_f32_16x16x32_bf16 v[118:121], v[142:145], v[180:183], v[118:121]
	v_mfma_f32_16x16x32_bf16 v[114:117], v[146:149], v[176:179], v[114:117]
	v_mfma_f32_16x16x32_bf16 v[110:113], v[142:145], v[188:191], v[110:113]
	v_mfma_f32_16x16x32_bf16 v[106:109], v[146:149], v[184:187], v[106:109]
	v_mfma_f32_16x16x32_bf16 v[102:105], v[142:145], v[196:199], v[102:105]
	v_mfma_f32_16x16x32_bf16 v[98:101], v[146:149], v[192:195], v[98:101]
	v_mfma_f32_16x16x32_bf16 v[172:175], v[152:155], v[168:171], v[122:125]
	v_mfma_f32_16x16x32_bf16 v[200:203], v[152:155], v[180:183], v[114:117]
	v_mfma_f32_16x16x32_bf16 v[204:207], v[152:155], v[188:191], v[106:109]
	v_mfma_f32_16x16x32_bf16 v[208:211], v[152:155], v[196:199], v[98:101]
	s_barrier
	s_nop 1
	ds_read_b128 v[98:101], v137 offset:16384
	ds_read_b128 v[106:109], v137 offset:17408
	ds_read_b128 v[114:117], v137 offset:18432
	ds_read_b128 v[122:125], v137 offset:19456
	s_barrier
; #define WAIT_V(n) asm volatile("s_waitcnt vmcnt(%0)" ::"n"(n) : "memory")
; #define WAIT_L(n) asm volatile("s_waitcnt lgkmcnt(%0)" ::"n"(n) : "memory")
; #define LDA8(dst, b, h) _Pragma("unroll") for (int m = 0; m < 4; ++m) _Pragma("unroll") for (int k = 0; k < 2; ++k) \
;     dst[m][k] = *(const bf16x8*)(abase + SAo(b, h) + m * 2048 + k * 1024)
; #define LDB8(dst, b, h) _Pragma("unroll") for (int n = 0; n < 2; ++n) _Pragma("unroll") for (int k = 0; k < 2; ++k) \
;     dst[n][k] = *(const bf16x8*)(bbase + SAo(b, h) + n * 2048 + k * 1024)
; #define BAR8 __builtin_amdgcn_s_barrier()
; __device__ __forceinline__ void gemm_main8(const u16* __restrict__ Ab, int lda, const u16* __restrict__ Bb, int ldb, int K,
;                                            char* shm, f32x4 (&acc)[2][2][4][2]) {
;     ...
;     LDB8(B1, 0, 1); BAR8; WAIT_L(0); MMA8(0, 1, At, B1); BAR8;
;     LDA8(At, 0, 1); WAIT_V(4); BAR8; WAIT_L(0); MMA8(1, 0, At, B0); MMA8(1, 1, At, B1); BAR8; }
;   { LDB8(B0, 1, 0); LDA8(At, 1, 0); WAIT_V(2); BAR8; WAIT_L(0); MMA8(0, 0, At, B0); BAR8;
	s_waitcnt lgkmcnt(0)
	s_waitcnt lgkmcnt(0)
	v_mfma_f32_16x16x32_bf16 v[94:97], v[98:101], v[164:167], v[94:97]
	v_mfma_f32_16x16x32_bf16 v[86:89], v[98:101], v[176:179], v[86:89]
	v_mfma_f32_16x16x32_bf16 v[78:81], v[98:101], v[184:187], v[78:81]
	v_mfma_f32_16x16x32_bf16 v[70:73], v[98:101], v[192:195], v[70:73]
	v_mfma_f32_16x16x32_bf16 v[94:97], v[106:109], v[168:171], v[94:97]
	v_mfma_f32_16x16x32_bf16 v[90:93], v[114:117], v[164:167], v[90:93]
	v_mfma_f32_16x16x32_bf16 v[86:89], v[106:109], v[180:183], v[86:89]
	v_mfma_f32_16x16x32_bf16 v[82:85], v[114:117], v[176:179], v[82:85]
	v_mfma_f32_16x16x32_bf16 v[78:81], v[106:109], v[188:191], v[78:81]
	v_mfma_f32_16x16x32_bf16 v[74:77], v[114:117], v[184:187], v[74:77]
	v_mfma_f32_16x16x32_bf16 v[70:73], v[106:109], v[196:199], v[70:73]
	v_mfma_f32_16x16x32_bf16 v[66:69], v[114:117], v[192:195], v[66:69]
	v_mfma_f32_16x16x32_bf16 v[164:167], v[122:125], v[168:171], v[90:93]
	v_mfma_f32_16x16x32_bf16 v[168:171], v[122:125], v[180:183], v[82:85]
	v_mfma_f32_16x16x32_bf16 v[176:179], v[122:125], v[188:191], v[74:77]
	v_mfma_f32_16x16x32_bf16 v[180:183], v[122:125], v[196:199], v[66:69]
	s_barrier
	s_nop 1
	ds_read_b128 v[66:69], v136 offset:16384
	ds_read_b128 v[74:77], v136 offset:17408
	ds_read_b128 v[82:85], v136 offset:18432
	ds_read_b128 v[90:93], v136 offset:19456
	ds_read_b128 v[184:187], v136 offset:20480
	ds_read_b128 v[188:191], v136 offset:21504
	ds_read_b128 v[192:195], v136 offset:22528
	ds_read_b128 v[196:199], v136 offset:23552
	s_waitcnt vmcnt(4)
	s_barrier
	s_waitcnt lgkmcnt(0)
	s_waitcnt lgkmcnt(0)
	v_mfma_f32_16x16x32_bf16 v[62:65], v[138:141], v[66:69], v[62:65]
	v_mfma_f32_16x16x32_bf16 v[58:61], v[146:149], v[66:69], v[58:61]
	v_mfma_f32_16x16x32_bf16 v[50:53], v[146:149], v[82:85], v[50:53]
	v_mfma_f32_16x16x32_bf16 v[42:45], v[146:149], v[184:187], v[42:45]
	v_mfma_f32_16x16x32_bf16 v[34:37], v[146:149], v[192:195], v[34:37]
	v_mfma_f32_16x16x32_bf16 v[62:65], v[142:145], v[74:77], v[62:65]
	v_mfma_f32_16x16x32_bf16 v[58:61], v[152:155], v[74:77], v[58:61]
	v_mfma_f32_16x16x32_bf16 v[54:57], v[138:141], v[82:85], v[54:57]
	v_mfma_f32_16x16x32_bf16 v[50:53], v[152:155], v[90:93], v[50:53]
	v_mfma_f32_16x16x32_bf16 v[46:49], v[138:141], v[184:187], v[46:49]
	v_mfma_f32_16x16x32_bf16 v[42:45], v[152:155], v[188:191], v[42:45]
	v_mfma_f32_16x16x32_bf16 v[38:41], v[138:141], v[192:195], v[38:41]
	v_mfma_f32_16x16x32_bf16 v[34:37], v[152:155], v[196:199], v[34:37]
	v_mfma_f32_16x16x32_bf16 v[212:215], v[142:145], v[90:93], v[54:57]
	v_mfma_f32_16x16x32_bf16 v[216:219], v[142:145], v[188:191], v[46:49]
	v_mfma_f32_16x16x32_bf16 v[138:141], v[142:145], v[196:199], v[38:41]
	v_mfma_f32_16x16x32_bf16 v[26:29], v[114:117], v[66:69], v[26:29]
	v_mfma_f32_16x16x32_bf16 v[18:21], v[114:117], v[82:85], v[18:21]
	v_mfma_f32_16x16x32_bf16 v[10:13], v[114:117], v[184:187], v[10:13]
	v_mfma_f32_16x16x32_bf16 v[2:5], v[114:117], v[192:195], v[2:5]
	v_mfma_f32_16x16x32_bf16 v[30:33], v[98:101], v[66:69], v[30:33]
	v_mfma_f32_16x16x32_bf16 v[26:29], v[122:125], v[74:77], v[26:29]
	v_mfma_f32_16x16x32_bf16 v[22:25], v[98:101], v[82:85], v[22:25]
	v_mfma_f32_16x16x32_bf16 v[18:21], v[122:125], v[90:93], v[18:21]
	v_mfma_f32_16x16x32_bf16 v[14:17], v[98:101], v[184:187], v[14:17]
	v_mfma_f32_16x16x32_bf16 v[10:13], v[122:125], v[188:191], v[10:13]
	v_mfma_f32_16x16x32_bf16 v[6:9], v[98:101], v[192:195], v[6:9]
	v_mfma_f32_16x16x32_bf16 v[2:5], v[122:125], v[196:199], v[2:5]
	v_mfma_f32_16x16x32_bf16 v[142:145], v[106:109], v[74:77], v[30:33]
	v_mfma_f32_16x16x32_bf16 v[146:149], v[106:109], v[90:93], v[22:25]
	v_mfma_f32_16x16x32_bf16 v[152:155], v[106:109], v[188:191], v[14:17]
	v_mfma_f32_16x16x32_bf16 v[184:187], v[106:109], v[196:199], v[6:9]
	s_barrier
	s_nop 0
	ds_read_b128 v[6:9], v137 offset:32768
	ds_read_b128 v[14:17], v137 offset:33792
	ds_read_b128 v[188:191], v137 offset:34816
	ds_read_b128 v[192:195], v137 offset:35840
	ds_read_b128 v[22:25], v136 offset:32768
	ds_read_b128 v[30:33], v136 offset:33792
	ds_read_b128 v[38:41], v136 offset:34816
	ds_read_b128 v[46:49], v136 offset:35840
	ds_read_b128 v[54:57], v136 offset:36864
	ds_read_b128 v[196:199], v136 offset:37888
	ds_read_b128 v[220:223], v136 offset:38912
	ds_read_b128 v[224:227], v136 offset:39936
	s_waitcnt vmcnt(2)
	s_barrier
; #define WAIT_V(n) asm volatile("s_waitcnt vmcnt(%0)" ::"n"(n) : "memory")
; #define WAIT_L(n) asm volatile("s_waitcnt lgkmcnt(%0)" ::"n"(n) : "memory")
; #define LDA8(dst, b, h) _Pragma("unroll") for (int m = 0; m < 4; ++m) _Pragma("unroll") for (int k = 0; k < 2; ++k) \
;     dst[m][k] = *(const bf16x8*)(abase + SAo(b, h) + m * 2048 + k * 1024)
; #define LDB8(dst, b, h) _Pragma("unroll") for (int n = 0; n < 2; ++n) _Pragma("unroll") for (int k = 0; k < 2; ++k) \
;     dst[n][k] = *(const bf16x8*)(bbase + SAo(b, h) + n * 2048 + k * 1024)
; #define BAR8 __builtin_amdgcn_s_barrier()
; __device__ __forceinline__ void gemm_main8(const u16* __restrict__ Ab, int lda, const u16* __restrict__ Bb, int ldb, int K,
;                                            char* shm, f32x4 (&acc)[2][2][4][2]) {
;     ...
;   { LDB8(B0, 1, 0); LDA8(At, 1, 0); WAIT_V(2); BAR8; WAIT_L(0); MMA8(0, 0, At, B0); BAR8;
;     LDB8(B1, 1, 1); WAIT_V(0); BAR8; WAIT_L(0); MMA8(0, 1, At, B1); BAR8;
;     LDA8(At, 1, 1); BAR8; WAIT_L(0); MMA8(1, 0, At, B0); MMA8(1, 1, At, B1); BAR8; }
;   if (wr == 0) BAR8;
	s_waitcnt lgkmcnt(0)
	s_waitcnt lgkmcnt(0)
	v_mfma_f32_16x16x32_bf16 v[66:69], v[6:9], v[22:25], v[126:129]
	v_mfma_f32_16x16x32_bf16 v[122:125], v[14:17], v[30:33], v[66:69]
	v_mfma_f32_16x16x32_bf16 v[66:69], v[188:191], v[22:25], v[172:175]
	v_mfma_f32_16x16x32_bf16 v[114:117], v[192:195], v[30:33], v[66:69]
	v_mfma_f32_16x16x32_bf16 v[66:69], v[6:9], v[38:41], v[118:121]
	v_mfma_f32_16x16x32_bf16 v[106:109], v[14:17], v[46:49], v[66:69]
	v_mfma_f32_16x16x32_bf16 v[66:69], v[188:191], v[38:41], v[200:203]
	v_mfma_f32_16x16x32_bf16 v[98:101], v[192:195], v[46:49], v[66:69]
	v_mfma_f32_16x16x32_bf16 v[66:69], v[6:9], v[54:57], v[110:113]
	v_mfma_f32_16x16x32_bf16 v[90:93], v[14:17], v[196:199], v[66:69]
	v_mfma_f32_16x16x32_bf16 v[66:69], v[188:191], v[54:57], v[204:207]
	v_mfma_f32_16x16x32_bf16 v[82:85], v[192:195], v[196:199], v[66:69]
	v_mfma_f32_16x16x32_bf16 v[66:69], v[6:9], v[220:223], v[102:105]
	v_mfma_f32_16x16x32_bf16 v[74:77], v[14:17], v[224:227], v[66:69]
	v_mfma_f32_16x16x32_bf16 v[66:69], v[188:191], v[220:223], v[208:211]
	v_mfma_f32_16x16x32_bf16 v[66:69], v[192:195], v[224:227], v[66:69]
	s_barrier
	ds_read_b128 v[172:175], v137 offset:49152
	ds_read_b128 v[200:203], v137 offset:50176
	ds_read_b128 v[204:207], v137 offset:51200
	ds_read_b128 v[208:211], v137 offset:52224
	s_waitcnt vmcnt(0)
	s_barrier
	s_waitcnt lgkmcnt(0)
	s_waitcnt lgkmcnt(0)
	v_mfma_f32_16x16x32_bf16 v[94:97], v[172:175], v[22:25], v[94:97]
	v_mfma_f32_16x16x32_bf16 v[22:25], v[204:207], v[22:25], v[164:167]
	v_mfma_f32_16x16x32_bf16 v[118:121], v[208:211], v[30:33], v[22:25]
	v_mfma_f32_16x16x32_bf16 v[22:25], v[172:175], v[38:41], v[86:89]
	v_mfma_f32_16x16x32_bf16 v[110:113], v[200:203], v[46:49], v[22:25]
	v_mfma_f32_16x16x32_bf16 v[22:25], v[204:207], v[38:41], v[168:171]
	v_mfma_f32_16x16x32_bf16 v[102:105], v[208:211], v[46:49], v[22:25]
	v_mfma_f32_16x16x32_bf16 v[22:25], v[172:175], v[54:57], v[78:81]
	v_mfma_f32_16x16x32_bf16 v[126:129], v[200:203], v[30:33], v[94:97]
	v_mfma_f32_16x16x32_bf16 v[94:97], v[200:203], v[196:199], v[22:25]
	v_mfma_f32_16x16x32_bf16 v[22:25], v[204:207], v[54:57], v[176:179]
	v_mfma_f32_16x16x32_bf16 v[86:89], v[208:211], v[196:199], v[22:25]
	v_mfma_f32_16x16x32_bf16 v[22:25], v[172:175], v[220:223], v[70:73]
	v_mfma_f32_16x16x32_bf16 v[78:81], v[200:203], v[224:227], v[22:25]
	v_mfma_f32_16x16x32_bf16 v[22:25], v[204:207], v[220:223], v[180:183]
	v_mfma_f32_16x16x32_bf16 v[70:73], v[208:211], v[224:227], v[22:25]
	s_barrier
	ds_read_b128 v[164:167], v136 offset:49152
	ds_read_b128 v[168:171], v136 offset:50176
	ds_read_b128 v[176:179], v136 offset:51200
	ds_read_b128 v[180:183], v136 offset:52224
	ds_read_b128 v[196:199], v136 offset:53248
	ds_read_b128 v[220:223], v136 offset:54272
	ds_read_b128 v[224:227], v136 offset:55296
	ds_read_b128 v[228:231], v136 offset:56320
	s_barrier
	s_waitcnt lgkmcnt(0)
	s_waitcnt lgkmcnt(0)
	v_mfma_f32_16x16x32_bf16 v[22:25], v[6:9], v[164:167], v[62:65]
	v_mfma_f32_16x16x32_bf16 v[62:65], v[14:17], v[168:171], v[22:25]
	v_mfma_f32_16x16x32_bf16 v[22:25], v[188:191], v[164:167], v[58:61]
	v_mfma_f32_16x16x32_bf16 v[54:57], v[192:195], v[168:171], v[22:25]
	v_mfma_f32_16x16x32_bf16 v[22:25], v[6:9], v[176:179], v[212:215]
	v_mfma_f32_16x16x32_bf16 v[46:49], v[14:17], v[180:183], v[22:25]
	v_mfma_f32_16x16x32_bf16 v[22:25], v[188:191], v[176:179], v[50:53]
	v_mfma_f32_16x16x32_bf16 v[38:41], v[192:195], v[180:183], v[22:25]
	v_mfma_f32_16x16x32_bf16 v[22:25], v[6:9], v[196:199], v[216:219]
	v_mfma_f32_16x16x32_bf16 v[6:9], v[6:9], v[224:227], v[138:141]
	v_mfma_f32_16x16x32_bf16 v[30:33], v[14:17], v[220:223], v[22:25]
	v_mfma_f32_16x16x32_bf16 v[22:25], v[188:191], v[196:199], v[42:45]
	v_mfma_f32_16x16x32_bf16 v[14:17], v[14:17], v[228:231], v[6:9]
	v_mfma_f32_16x16x32_bf16 v[6:9], v[188:191], v[224:227], v[34:37]
	v_mfma_f32_16x16x32_bf16 v[22:25], v[192:195], v[220:223], v[22:25]
	v_mfma_f32_16x16x32_bf16 v[6:9], v[192:195], v[228:231], v[6:9]
	v_mfma_f32_16x16x32_bf16 v[34:37], v[172:175], v[164:167], v[142:145]
	v_mfma_f32_16x16x32_bf16 v[26:29], v[204:207], v[164:167], v[26:29]
	v_mfma_f32_16x16x32_bf16 v[18:21], v[204:207], v[176:179], v[18:21]
	v_mfma_f32_16x16x32_bf16 v[58:61], v[200:203], v[168:171], v[34:37]
	v_mfma_f32_16x16x32_bf16 v[50:53], v[208:211], v[168:171], v[26:29]
	v_mfma_f32_16x16x32_bf16 v[26:29], v[172:175], v[176:179], v[146:149]
	v_mfma_f32_16x16x32_bf16 v[34:37], v[208:211], v[180:183], v[18:21]
	v_mfma_f32_16x16x32_bf16 v[18:21], v[172:175], v[196:199], v[152:155]
	v_mfma_f32_16x16x32_bf16 v[10:13], v[204:207], v[196:199], v[10:13]
	v_mfma_f32_16x16x32_bf16 v[42:45], v[200:203], v[180:183], v[26:29]
	v_mfma_f32_16x16x32_bf16 v[26:29], v[200:203], v[220:223], v[18:21]
	v_mfma_f32_16x16x32_bf16 v[18:21], v[208:211], v[220:223], v[10:13]
	v_mfma_f32_16x16x32_bf16 v[10:13], v[172:175], v[224:227], v[184:187]
	v_mfma_f32_16x16x32_bf16 v[2:5], v[204:207], v[224:227], v[2:5]
	v_mfma_f32_16x16x32_bf16 v[10:13], v[200:203], v[228:231], v[10:13]
	v_mfma_f32_16x16x32_bf16 v[2:5], v[208:211], v[228:231], v[2:5]
	v_cmp_gt_u32_e32 vcc, s97, v135
	s_barrier
	s_and_saveexec_b64 s[18:19], vcc
	s_cbranch_execz .LBB0_364
	s_barrier
	s_branch .LBB0_364

; #define WAIT_L(n) asm volatile("s_waitcnt lgkmcnt(%0)" ::"n"(n) : "memory")
; #define SBAR() __builtin_amdgcn_sched_barrier(0)
; #define LDA8(dst, b, h) _Pragma("unroll") for (int m = 0; m < 4; ++m) _Pragma("unroll") for (int k = 0; k < 2; ++k) \
;     dst[m][k] = *(const bf16x8*)(abase + SAo(b, h) + m * 2048 + k * 1024)
; #define LDB8(dst, b, h) _Pragma("unroll") for (int n = 0; n < 2; ++n) _Pragma("unroll") for (int k = 0; k < 2; ++k) \
;     dst[n][k] = *(const bf16x8*)(bbase + SAo(b, h) + n * 2048 + k * 1024)
; #define BAR8 __builtin_amdgcn_s_barrier()
; __device__ __forceinline__ void gemm_main8(const u16* __restrict__ Ab, int lda, const u16* __restrict__ Bb, int ldb, int K,
;                                            char* shm, f32x4 (&acc)[2][2][4][2]) {
;     ...
;     LDB8(B0, 0, 0); SBAR(); LDA8(At, 0, 0); STG_A(1, 1, t + 1);
;     WAIT_L(8); BAR8; WAIT_L(0); MMA8(0, 0, At, B0); BAR8; SBAR();
;     LDB8(B1, 0, 1); STG_B(0, 0, t + 2);
;     BAR8; WAIT_L(0); MMA8(0, 1, At, B1); BAR8;
;     LDA8(At, 0, 1); STG_A(0, 0, t + 2);
;     BAR8; WAIT_L(0); MMA8(1, 0, At, B0); BAR8; SBAR();
.LBB0_510:
	ds_read_b128 v[152:155], v137
	ds_read_b128 v[164:167], v137 offset:1024
	ds_read_b128 v[176:179], v137 offset:2048
	ds_read_b128 v[180:183], v137 offset:3072
	ds_read_b128 v[184:187], v136
	ds_read_b128 v[188:191], v136 offset:1024
	ds_read_b128 v[192:195], v136 offset:2048
	ds_read_b128 v[196:199], v136 offset:3072
	ds_read_b128 v[200:203], v136 offset:4096
	ds_read_b128 v[204:207], v136 offset:5120
	ds_read_b128 v[208:211], v136 offset:6144
	ds_read_b128 v[212:215], v136 offset:7168
	v_add_u32_e32 v173, 0xc000, v138
	v_lshl_add_u64 v[168:169], s[24:25], 0, v[0:1]
	s_mov_b64 s[88:89], 0x17320080
	v_readfirstlane_b32 s5, v173
	v_lshl_add_u64 v[174:175], v[168:169], 0, s[88:89]
	s_mov_b32 m0, s5
	global_load_lds_dwordx4 v[174:175], off
	v_add_u32_e32 v174, 0xe000, v138
	s_mov_b64 s[88:89], 0x17330080
	v_readfirstlane_b32 s5, v174
	v_lshl_add_u64 v[216:217], v[168:169], 0, s[88:89]
	s_mov_b32 m0, s5
	s_nop 0
	global_load_lds_dwordx4 v[216:217], off
	s_waitcnt lgkmcnt(8)
	s_barrier
	s_waitcnt lgkmcnt(0)
	s_waitcnt lgkmcnt(0)
	v_mfma_f32_16x16x32_bf16 v[126:129], v[152:155], v[184:187], v[126:129]
	v_mfma_f32_16x16x32_bf16 v[122:125], v[176:179], v[184:187], v[122:125]
	v_mfma_f32_16x16x32_bf16 v[118:121], v[152:155], v[192:195], v[118:121]
	v_mfma_f32_16x16x32_bf16 v[114:117], v[176:179], v[192:195], v[114:117]
	v_mfma_f32_16x16x32_bf16 v[110:113], v[152:155], v[200:203], v[110:113]
	v_mfma_f32_16x16x32_bf16 v[106:109], v[176:179], v[200:203], v[106:109]
	v_mfma_f32_16x16x32_bf16 v[102:105], v[152:155], v[208:211], v[102:105]
	v_mfma_f32_16x16x32_bf16 v[98:101], v[176:179], v[208:211], v[98:101]
	v_mfma_f32_16x16x32_bf16 v[126:129], v[164:167], v[188:191], v[126:129]
	v_mfma_f32_16x16x32_bf16 v[122:125], v[180:183], v[188:191], v[122:125]
	v_mfma_f32_16x16x32_bf16 v[118:121], v[164:167], v[196:199], v[118:121]
	v_mfma_f32_16x16x32_bf16 v[114:117], v[180:183], v[196:199], v[114:117]
	v_mfma_f32_16x16x32_bf16 v[110:113], v[164:167], v[204:207], v[110:113]
	v_mfma_f32_16x16x32_bf16 v[106:109], v[180:183], v[204:207], v[106:109]
	v_mfma_f32_16x16x32_bf16 v[102:105], v[164:167], v[212:215], v[102:105]
	v_mfma_f32_16x16x32_bf16 v[98:101], v[180:183], v[212:215], v[98:101]
	s_barrier
	ds_read_b128 v[216:219], v137 offset:16384
	ds_read_b128 v[220:223], v137 offset:17408
	ds_read_b128 v[224:227], v137 offset:18432
	ds_read_b128 v[228:231], v137 offset:19456
	v_lshl_add_u64 v[232:233], s[20:21], 0, v[0:1]
	s_mov_b64 s[88:89], 0x11300100
	v_readfirstlane_b32 s5, v139
	v_lshl_add_u64 v[234:235], v[232:233], 0, s[88:89]
	s_mov_b32 m0, s5
	s_mov_b64 s[88:89], 0x11310100
	v_readfirstlane_b32 s5, v140
	global_load_lds_dwordx4 v[234:235], off
	v_lshl_add_u64 v[234:235], v[232:233], 0, s[88:89]
	s_mov_b32 m0, s5
	s_nop 0
	global_load_lds_dwordx4 v[234:235], off
	s_barrier
	s_waitcnt lgkmcnt(0)
	s_waitcnt lgkmcnt(0)
	v_mfma_f32_16x16x32_bf16 v[94:97], v[216:219], v[184:187], v[94:97]
	v_mfma_f32_16x16x32_bf16 v[90:93], v[224:227], v[184:187], v[90:93]
	v_mfma_f32_16x16x32_bf16 v[86:89], v[216:219], v[192:195], v[86:89]
	v_mfma_f32_16x16x32_bf16 v[82:85], v[224:227], v[192:195], v[82:85]
	v_mfma_f32_16x16x32_bf16 v[78:81], v[216:219], v[200:203], v[78:81]
	v_mfma_f32_16x16x32_bf16 v[74:77], v[224:227], v[200:203], v[74:77]
	v_mfma_f32_16x16x32_bf16 v[70:73], v[216:219], v[208:211], v[70:73]
	v_mfma_f32_16x16x32_bf16 v[66:69], v[224:227], v[208:211], v[66:69]
	v_mfma_f32_16x16x32_bf16 v[94:97], v[220:223], v[188:191], v[94:97]
	v_mfma_f32_16x16x32_bf16 v[90:93], v[228:231], v[188:191], v[90:93]
	v_mfma_f32_16x16x32_bf16 v[86:89], v[220:223], v[196:199], v[86:89]
	v_mfma_f32_16x16x32_bf16 v[82:85], v[228:231], v[196:199], v[82:85]
	v_mfma_f32_16x16x32_bf16 v[78:81], v[220:223], v[204:207], v[78:81]
	v_mfma_f32_16x16x32_bf16 v[74:77], v[228:231], v[204:207], v[74:77]
	v_mfma_f32_16x16x32_bf16 v[70:73], v[220:223], v[212:215], v[70:73]
	v_mfma_f32_16x16x32_bf16 v[66:69], v[228:231], v[212:215], v[66:69]
	v_readfirstlane_b32 s5, v138
	v_lshl_add_u64 v[234:235], v[168:169], 0, s[30:31]
	s_mov_b32 m0, s5
	s_mov_b64 s[88:89], 0x17310100
	v_readfirstlane_b32 s5, v141
	s_barrier
	ds_read_b128 v[184:187], v136 offset:16384
	ds_read_b128 v[188:191], v136 offset:17408
	ds_read_b128 v[192:195], v136 offset:18432
	ds_read_b128 v[196:199], v136 offset:19456
	ds_read_b128 v[200:203], v136 offset:20480
	ds_read_b128 v[204:207], v136 offset:21504
	ds_read_b128 v[208:211], v136 offset:22528
	ds_read_b128 v[212:215], v136 offset:23552
	global_load_lds_dwordx4 v[234:235], off
	v_lshl_add_u64 v[234:235], v[168:169], 0, s[88:89]
	s_mov_b32 m0, s5
	s_nop 0
	global_load_lds_dwordx4 v[234:235], off
	s_barrier
	s_waitcnt lgkmcnt(0)
	s_waitcnt lgkmcnt(0)
	v_mfma_f32_16x16x32_bf16 v[62:65], v[152:155], v[184:187], v[62:65]
	v_mfma_f32_16x16x32_bf16 v[58:61], v[176:179], v[184:187], v[58:61]
	v_mfma_f32_16x16x32_bf16 v[54:57], v[152:155], v[192:195], v[54:57]
	v_mfma_f32_16x16x32_bf16 v[50:53], v[176:179], v[192:195], v[50:53]
	v_mfma_f32_16x16x32_bf16 v[46:49], v[152:155], v[200:203], v[46:49]
	v_mfma_f32_16x16x32_bf16 v[42:45], v[176:179], v[200:203], v[42:45]
	v_mfma_f32_16x16x32_bf16 v[38:41], v[152:155], v[208:211], v[38:41]
	v_mfma_f32_16x16x32_bf16 v[34:37], v[176:179], v[208:211], v[34:37]
	v_mfma_f32_16x16x32_bf16 v[62:65], v[164:167], v[188:191], v[62:65]
	v_mfma_f32_16x16x32_bf16 v[58:61], v[180:183], v[188:191], v[58:61]
	v_mfma_f32_16x16x32_bf16 v[54:57], v[164:167], v[196:199], v[54:57]
	v_mfma_f32_16x16x32_bf16 v[50:53], v[180:183], v[196:199], v[50:53]
	v_mfma_f32_16x16x32_bf16 v[46:49], v[164:167], v[204:207], v[46:49]
	v_mfma_f32_16x16x32_bf16 v[42:45], v[180:183], v[204:207], v[42:45]
	v_mfma_f32_16x16x32_bf16 v[38:41], v[164:167], v[212:215], v[38:41]
	v_mfma_f32_16x16x32_bf16 v[34:37], v[180:183], v[212:215], v[34:37]
	s_barrier
; #define WAIT_V(n) asm volatile("s_waitcnt vmcnt(%0)" ::"n"(n) : "memory")
; #define WAIT_L(n) asm volatile("s_waitcnt lgkmcnt(%0)" ::"n"(n) : "memory")
; #define SBAR() __builtin_amdgcn_sched_barrier(0)
; #define LDA8(dst, b, h) _Pragma("unroll") for (int m = 0; m < 4; ++m) _Pragma("unroll") for (int k = 0; k < 2; ++k) \
;     dst[m][k] = *(const bf16x8*)(abase + SAo(b, h) + m * 2048 + k * 1024)
; #define LDB8(dst, b, h) _Pragma("unroll") for (int n = 0; n < 2; ++n) _Pragma("unroll") for (int k = 0; k < 2; ++k) \
;     dst[n][k] = *(const bf16x8*)(bbase + SAo(b, h) + n * 2048 + k * 1024)
; #define BAR8 __builtin_amdgcn_s_barrier()
; __device__ __forceinline__ void gemm_main8(const u16* __restrict__ Ab, int lda, const u16* __restrict__ Bb, int ldb, int K,
;                                            char* shm, f32x4 (&acc)[2][2][4][2]) {
;     ...
;     STG_B(0, 1, t + 2);
;     WAIT_V(6); BAR8; MMA8(1, 1, At, B1); BAR8;
;     LDB8(B0, 1, 0); SBAR(); LDA8(At, 1, 0); STG_A(0, 1, t + 2);
;     WAIT_L(8); BAR8; WAIT_L(0); MMA8(0, 0, At, B0); BAR8; SBAR();
;     LDB8(B1, 1, 1); STG_B(1, 0, t + 3);
;     BAR8; WAIT_L(0); MMA8(0, 1, At, B1); BAR8;
	s_mov_b64 s[88:89], 0x11320100
	v_readfirstlane_b32 s5, v142
	v_lshl_add_u64 v[152:153], v[232:233], 0, s[88:89]
	s_mov_b32 m0, s5
	s_mov_b64 s[88:89], 0x11330100
	v_readfirstlane_b32 s5, v143
	global_load_lds_dwordx4 v[152:153], off
	v_lshl_add_u64 v[152:153], v[232:233], 0, s[88:89]
	s_mov_b32 m0, s5
	s_nop 0
	global_load_lds_dwordx4 v[152:153], off
	s_waitcnt vmcnt(6)
	s_barrier
	v_mfma_f32_16x16x32_bf16 v[30:33], v[216:219], v[184:187], v[30:33]
	v_mfma_f32_16x16x32_bf16 v[26:29], v[224:227], v[184:187], v[26:29]
	v_mfma_f32_16x16x32_bf16 v[22:25], v[216:219], v[192:195], v[22:25]
	v_mfma_f32_16x16x32_bf16 v[18:21], v[224:227], v[192:195], v[18:21]
	v_mfma_f32_16x16x32_bf16 v[14:17], v[216:219], v[200:203], v[14:17]
	v_mfma_f32_16x16x32_bf16 v[10:13], v[224:227], v[200:203], v[10:13]
	v_mfma_f32_16x16x32_bf16 v[6:9], v[216:219], v[208:211], v[6:9]
	v_mfma_f32_16x16x32_bf16 v[2:5], v[224:227], v[208:211], v[2:5]
	v_mfma_f32_16x16x32_bf16 v[30:33], v[220:223], v[188:191], v[30:33]
	v_mfma_f32_16x16x32_bf16 v[26:29], v[228:231], v[188:191], v[26:29]
	v_mfma_f32_16x16x32_bf16 v[22:25], v[220:223], v[196:199], v[22:25]
	v_mfma_f32_16x16x32_bf16 v[18:21], v[228:231], v[196:199], v[18:21]
	v_mfma_f32_16x16x32_bf16 v[14:17], v[220:223], v[204:207], v[14:17]
	v_mfma_f32_16x16x32_bf16 v[10:13], v[228:231], v[204:207], v[10:13]
	v_mfma_f32_16x16x32_bf16 v[6:9], v[220:223], v[212:215], v[6:9]
	v_mfma_f32_16x16x32_bf16 v[2:5], v[228:231], v[212:215], v[2:5]
	s_barrier
	ds_read_b128 v[152:155], v137 offset:32768
	ds_read_b128 v[164:167], v137 offset:33792
	ds_read_b128 v[176:179], v137 offset:34816
	ds_read_b128 v[180:183], v137 offset:35840
	ds_read_b128 v[184:187], v136 offset:32768
	ds_read_b128 v[188:191], v136 offset:33792
	ds_read_b128 v[192:195], v136 offset:34816
	ds_read_b128 v[196:199], v136 offset:35840
	ds_read_b128 v[200:203], v136 offset:36864
	ds_read_b128 v[204:207], v136 offset:37888
	ds_read_b128 v[208:211], v136 offset:38912
	ds_read_b128 v[212:215], v136 offset:39936
	s_mov_b64 s[88:89], 0x17320100
	v_readfirstlane_b32 s5, v144
	v_lshl_add_u64 v[216:217], v[168:169], 0, s[88:89]
	s_mov_b32 m0, s5
	s_mov_b64 s[88:89], 0x17330100
	v_readfirstlane_b32 s5, v145
	global_load_lds_dwordx4 v[216:217], off
	v_lshl_add_u64 v[216:217], v[168:169], 0, s[88:89]
	s_mov_b32 m0, s5
	s_nop 0
	global_load_lds_dwordx4 v[216:217], off
	s_waitcnt lgkmcnt(8)
	s_barrier
	s_waitcnt lgkmcnt(0)
	s_waitcnt lgkmcnt(0)
	v_mfma_f32_16x16x32_bf16 v[126:129], v[152:155], v[184:187], v[126:129]
	v_mfma_f32_16x16x32_bf16 v[122:125], v[176:179], v[184:187], v[122:125]
	v_mfma_f32_16x16x32_bf16 v[118:121], v[152:155], v[192:195], v[118:121]
	v_mfma_f32_16x16x32_bf16 v[114:117], v[176:179], v[192:195], v[114:117]
	v_mfma_f32_16x16x32_bf16 v[110:113], v[152:155], v[200:203], v[110:113]
	v_mfma_f32_16x16x32_bf16 v[106:109], v[176:179], v[200:203], v[106:109]
	v_mfma_f32_16x16x32_bf16 v[102:105], v[152:155], v[208:211], v[102:105]
	v_mfma_f32_16x16x32_bf16 v[98:101], v[176:179], v[208:211], v[98:101]
	v_mfma_f32_16x16x32_bf16 v[126:129], v[164:167], v[188:191], v[126:129]
	v_mfma_f32_16x16x32_bf16 v[122:125], v[180:183], v[188:191], v[122:125]
	v_mfma_f32_16x16x32_bf16 v[118:121], v[164:167], v[196:199], v[118:121]
	v_mfma_f32_16x16x32_bf16 v[114:117], v[180:183], v[196:199], v[114:117]
	v_mfma_f32_16x16x32_bf16 v[110:113], v[164:167], v[204:207], v[110:113]
	v_mfma_f32_16x16x32_bf16 v[106:109], v[180:183], v[204:207], v[106:109]
	v_mfma_f32_16x16x32_bf16 v[102:105], v[164:167], v[212:215], v[102:105]
	v_mfma_f32_16x16x32_bf16 v[98:101], v[180:183], v[212:215], v[98:101]
	s_barrier
	ds_read_b128 v[216:219], v137 offset:49152
	ds_read_b128 v[220:223], v137 offset:50176
	ds_read_b128 v[224:227], v137 offset:51200
	ds_read_b128 v[228:231], v137 offset:52224
	s_mov_b64 s[88:89], 0x11300180
	v_readfirstlane_b32 s5, v146
	v_lshl_add_u64 v[234:235], v[232:233], 0, s[88:89]
	s_mov_b32 m0, s5
	s_mov_b64 s[88:89], 0x11310180
	v_readfirstlane_b32 s5, v147
	global_load_lds_dwordx4 v[234:235], off
	v_lshl_add_u64 v[234:235], v[232:233], 0, s[88:89]
	s_mov_b32 m0, s5
	s_nop 0
	global_load_lds_dwordx4 v[234:235], off
	s_barrier
	s_waitcnt lgkmcnt(0)
	s_waitcnt lgkmcnt(0)
	v_mfma_f32_16x16x32_bf16 v[94:97], v[216:219], v[184:187], v[94:97]
	v_mfma_f32_16x16x32_bf16 v[90:93], v[224:227], v[184:187], v[90:93]
	v_mfma_f32_16x16x32_bf16 v[86:89], v[216:219], v[192:195], v[86:89]
	v_mfma_f32_16x16x32_bf16 v[82:85], v[224:227], v[192:195], v[82:85]
	v_mfma_f32_16x16x32_bf16 v[78:81], v[216:219], v[200:203], v[78:81]
	v_mfma_f32_16x16x32_bf16 v[74:77], v[224:227], v[200:203], v[74:77]
	v_mfma_f32_16x16x32_bf16 v[70:73], v[216:219], v[208:211], v[70:73]
	v_mfma_f32_16x16x32_bf16 v[66:69], v[224:227], v[208:211], v[66:69]
	v_mfma_f32_16x16x32_bf16 v[94:97], v[220:223], v[188:191], v[94:97]
	v_mfma_f32_16x16x32_bf16 v[90:93], v[228:231], v[188:191], v[90:93]
	v_mfma_f32_16x16x32_bf16 v[86:89], v[220:223], v[196:199], v[86:89]
	v_mfma_f32_16x16x32_bf16 v[82:85], v[228:231], v[196:199], v[82:85]
	v_mfma_f32_16x16x32_bf16 v[78:81], v[220:223], v[204:207], v[78:81]
	v_mfma_f32_16x16x32_bf16 v[74:77], v[228:231], v[204:207], v[74:77]
	v_mfma_f32_16x16x32_bf16 v[70:73], v[220:223], v[212:215], v[70:73]
	v_mfma_f32_16x16x32_bf16 v[66:69], v[228:231], v[212:215], v[66:69]
	v_readfirstlane_b32 s5, v148
	v_lshl_add_u64 v[234:235], v[168:169], 0, s[16:17]
	s_mov_b32 m0, s5
	s_mov_b64 s[88:89], 0x17310180
	v_readfirstlane_b32 s5, v149
	s_barrier
; #define WAIT_V(n) asm volatile("s_waitcnt vmcnt(%0)" ::"n"(n) : "memory")
; #define WAIT_L(n) asm volatile("s_waitcnt lgkmcnt(%0)" ::"n"(n) : "memory")
; #define SBAR() __builtin_amdgcn_sched_barrier(0)
; #define LDA8(dst, b, h) _Pragma("unroll") for (int m = 0; m < 4; ++m) _Pragma("unroll") for (int k = 0; k < 2; ++k) \
;     dst[m][k] = *(const bf16x8*)(abase + SAo(b, h) + m * 2048 + k * 1024)
; #define LDB8(dst, b, h) _Pragma("unroll") for (int n = 0; n < 2; ++n) _Pragma("unroll") for (int k = 0; k < 2; ++k) \
;     dst[n][k] = *(const bf16x8*)(bbase + SAo(b, h) + n * 2048 + k * 1024)
; #define BAR8 __builtin_amdgcn_s_barrier()
; __device__ __forceinline__ void gemm_main8(const u16* __restrict__ Ab, int lda, const u16* __restrict__ Bb, int ldb, int K,
;                                            char* shm, f32x4 (&acc)[2][2][4][2]) {
;     ...
;     LDA8(At, 1, 1); STG_A(1, 0, t + 3);
;     BAR8; WAIT_L(0); MMA8(1, 0, At, B0); BAR8; SBAR();
;     STG_B(1, 1, t + 3);
;     WAIT_V(6); BAR8; MMA8(1, 1, At, B1); BAR8;
;   }
;   { LDB8(B0, 0, 0); LDA8(At, 0, 0); STG_A(1, 1, nt - 1);
;     BAR8; WAIT_L(0); MMA8(0, 0, At, B0); BAR8;
	ds_read_b128 v[184:187], v136 offset:49152
	ds_read_b128 v[188:191], v136 offset:50176
	ds_read_b128 v[192:195], v136 offset:51200
	ds_read_b128 v[196:199], v136 offset:52224
	ds_read_b128 v[200:203], v136 offset:53248
	ds_read_b128 v[204:207], v136 offset:54272
	ds_read_b128 v[208:211], v136 offset:55296
	ds_read_b128 v[212:215], v136 offset:56320
	global_load_lds_dwordx4 v[234:235], off
	v_lshl_add_u64 v[168:169], v[168:169], 0, s[88:89]
	s_mov_b32 m0, s5
	s_nop 0
	global_load_lds_dwordx4 v[168:169], off
	s_barrier
	s_waitcnt lgkmcnt(0)
	s_waitcnt lgkmcnt(0)
	v_mfma_f32_16x16x32_bf16 v[62:65], v[152:155], v[184:187], v[62:65]
	v_mfma_f32_16x16x32_bf16 v[58:61], v[176:179], v[184:187], v[58:61]
	v_mfma_f32_16x16x32_bf16 v[54:57], v[152:155], v[192:195], v[54:57]
	v_mfma_f32_16x16x32_bf16 v[50:53], v[176:179], v[192:195], v[50:53]
	v_mfma_f32_16x16x32_bf16 v[46:49], v[152:155], v[200:203], v[46:49]
	v_mfma_f32_16x16x32_bf16 v[42:45], v[176:179], v[200:203], v[42:45]
	v_mfma_f32_16x16x32_bf16 v[38:41], v[152:155], v[208:211], v[38:41]
	v_mfma_f32_16x16x32_bf16 v[34:37], v[176:179], v[208:211], v[34:37]
	v_mfma_f32_16x16x32_bf16 v[62:65], v[164:167], v[188:191], v[62:65]
	v_mfma_f32_16x16x32_bf16 v[58:61], v[180:183], v[188:191], v[58:61]
	v_mfma_f32_16x16x32_bf16 v[54:57], v[164:167], v[196:199], v[54:57]
	v_mfma_f32_16x16x32_bf16 v[50:53], v[180:183], v[196:199], v[50:53]
	v_mfma_f32_16x16x32_bf16 v[46:49], v[164:167], v[204:207], v[46:49]
	v_mfma_f32_16x16x32_bf16 v[42:45], v[180:183], v[204:207], v[42:45]
	v_mfma_f32_16x16x32_bf16 v[38:41], v[164:167], v[212:215], v[38:41]
	v_mfma_f32_16x16x32_bf16 v[34:37], v[180:183], v[212:215], v[34:37]
	s_barrier
	s_mov_b64 s[88:89], 0x11320180
	v_readfirstlane_b32 s5, v171
	v_lshl_add_u64 v[152:153], v[232:233], 0, s[88:89]
	s_mov_b32 m0, s5
	s_mov_b64 s[88:89], 0x11330180
	v_readfirstlane_b32 s5, v172
	global_load_lds_dwordx4 v[152:153], off
	v_lshl_add_u64 v[152:153], v[232:233], 0, s[88:89]
	s_mov_b32 m0, s5
	s_nop 0
	global_load_lds_dwordx4 v[152:153], off
	s_waitcnt vmcnt(6)
	s_barrier
	v_mfma_f32_16x16x32_bf16 v[30:33], v[216:219], v[184:187], v[30:33]
	v_mfma_f32_16x16x32_bf16 v[26:29], v[224:227], v[184:187], v[26:29]
	v_mfma_f32_16x16x32_bf16 v[22:25], v[216:219], v[192:195], v[22:25]
	v_mfma_f32_16x16x32_bf16 v[18:21], v[224:227], v[192:195], v[18:21]
	v_mfma_f32_16x16x32_bf16 v[14:17], v[216:219], v[200:203], v[14:17]
	v_mfma_f32_16x16x32_bf16 v[10:13], v[224:227], v[200:203], v[10:13]
	v_mfma_f32_16x16x32_bf16 v[6:9], v[216:219], v[208:211], v[6:9]
	v_mfma_f32_16x16x32_bf16 v[2:5], v[224:227], v[208:211], v[2:5]
	v_mfma_f32_16x16x32_bf16 v[30:33], v[220:223], v[188:191], v[30:33]
	v_mfma_f32_16x16x32_bf16 v[26:29], v[228:231], v[188:191], v[26:29]
	v_mfma_f32_16x16x32_bf16 v[22:25], v[220:223], v[196:199], v[22:25]
	v_mfma_f32_16x16x32_bf16 v[18:21], v[228:231], v[196:199], v[18:21]
	v_mfma_f32_16x16x32_bf16 v[14:17], v[220:223], v[204:207], v[14:17]
	v_mfma_f32_16x16x32_bf16 v[10:13], v[228:231], v[204:207], v[10:13]
	v_mfma_f32_16x16x32_bf16 v[6:9], v[220:223], v[212:215], v[6:9]
	v_mfma_f32_16x16x32_bf16 v[2:5], v[228:231], v[212:215], v[2:5]
	s_add_i32 s3, s3, 2
	s_add_u32 s20, s20, 0x100
	s_addc_u32 s21, s21, 0
	s_add_u32 s24, s24, 0x100
	s_addc_u32 s25, s25, 0
	s_cmp_lt_u32 s3, 4
	s_barrier
	s_cbranch_scc1 .LBB0_510
	s_mov_b64 s[20:21], 0x20380
	v_readfirstlane_b32 s3, v173
	v_lshl_add_u64 v[200:201], v[130:131], 0, s[20:21]
	s_mov_b32 m0, s3
	s_mov_b64 s[20:21], 0x30380
	v_readfirstlane_b32 s3, v174
	ds_read_b128 v[138:141], v137
	ds_read_b128 v[142:145], v137 offset:1024
	ds_read_b128 v[146:149], v137 offset:2048
	ds_read_b128 v[152:155], v137 offset:3072
	ds_read_b128 v[164:167], v136
	ds_read_b128 v[168:171], v136 offset:1024
	ds_read_b128 v[176:179], v136 offset:2048
	ds_read_b128 v[180:183], v136 offset:3072
	ds_read_b128 v[184:187], v136 offset:4096
	ds_read_b128 v[188:191], v136 offset:5120
	ds_read_b128 v[192:195], v136 offset:6144
	ds_read_b128 v[196:199], v136 offset:7168
	global_load_lds_dwordx4 v[200:201], off
	v_lshl_add_u64 v[130:131], v[130:131], 0, s[20:21]
	s_mov_b32 m0, s3
	s_nop 0
	global_load_lds_dwordx4 v[130:131], off
	s_barrier
	s_waitcnt lgkmcnt(0)
	s_waitcnt lgkmcnt(0)
	v_mfma_f32_16x16x32_bf16 v[126:129], v[138:141], v[164:167], v[126:129]
	v_mfma_f32_16x16x32_bf16 v[122:125], v[146:149], v[164:167], v[122:125]
	v_mfma_f32_16x16x32_bf16 v[118:121], v[138:141], v[176:179], v[118:121]
	v_mfma_f32_16x16x32_bf16 v[114:117], v[146:149], v[176:179], v[114:117]
	v_mfma_f32_16x16x32_bf16 v[102:105], v[138:141], v[192:195], v[102:105]
	v_mfma_f32_16x16x32_bf16 v[98:101], v[146:149], v[192:195], v[98:101]
	v_mfma_f32_16x16x32_bf16 v[126:129], v[142:145], v[168:171], v[126:129]
	v_mfma_f32_16x16x32_bf16 v[122:125], v[152:155], v[168:171], v[122:125]
	v_mfma_f32_16x16x32_bf16 v[118:121], v[142:145], v[180:183], v[118:121]
	v_mfma_f32_16x16x32_bf16 v[114:117], v[152:155], v[180:183], v[114:117]
	v_mfma_f32_16x16x32_bf16 v[110:113], v[138:141], v[184:187], v[110:113]
	v_mfma_f32_16x16x32_bf16 v[106:109], v[146:149], v[184:187], v[106:109]
	v_mfma_f32_16x16x32_bf16 v[102:105], v[142:145], v[196:199], v[102:105]
	v_mfma_f32_16x16x32_bf16 v[98:101], v[152:155], v[196:199], v[98:101]
	v_mfma_f32_16x16x32_bf16 v[172:175], v[142:145], v[188:191], v[110:113]
	v_mfma_f32_16x16x32_bf16 v[200:203], v[152:155], v[188:191], v[106:109]
	s_barrier
	s_nop 1
	ds_read_b128 v[106:109], v137 offset:16384
	ds_read_b128 v[110:113], v137 offset:17408
	ds_read_b128 v[204:207], v137 offset:18432
	ds_read_b128 v[208:211], v137 offset:19456
	s_barrier
; #define WAIT_V(n) asm volatile("s_waitcnt vmcnt(%0)" ::"n"(n) : "memory")
; #define WAIT_L(n) asm volatile("s_waitcnt lgkmcnt(%0)" ::"n"(n) : "memory")
; #define LDA8(dst, b, h) _Pragma("unroll") for (int m = 0; m < 4; ++m) _Pragma("unroll") for (int k = 0; k < 2; ++k) \
;     dst[m][k] = *(const bf16x8*)(abase + SAo(b, h) + m * 2048 + k * 1024)
; #define LDB8(dst, b, h) _Pragma("unroll") for (int n = 0; n < 2; ++n) _Pragma("unroll") for (int k = 0; k < 2; ++k) \
;     dst[n][k] = *(const bf16x8*)(bbase + SAo(b, h) + n * 2048 + k * 1024)
; #define BAR8 __builtin_amdgcn_s_barrier()
; __device__ __forceinline__ void gemm_main8(const u16* __restrict__ Ab, int lda, const u16* __restrict__ Bb, int ldb, int K,
;                                            char* shm, f32x4 (&acc)[2][2][4][2]) {
;     ...
;     LDB8(B1, 0, 1); BAR8; WAIT_L(0); MMA8(0, 1, At, B1); BAR8;
;     LDA8(At, 0, 1); WAIT_V(4); BAR8; WAIT_L(0); MMA8(1, 0, At, B0); MMA8(1, 1, At, B1); BAR8; }
;   { LDB8(B0, 1, 0); LDA8(At, 1, 0); WAIT_V(2); BAR8; WAIT_L(0); MMA8(0, 0, At, B0); BAR8;
	s_waitcnt lgkmcnt(0)
	s_waitcnt lgkmcnt(0)
	v_mfma_f32_16x16x32_bf16 v[86:89], v[106:109], v[176:179], v[86:89]
	v_mfma_f32_16x16x32_bf16 v[82:85], v[204:207], v[176:179], v[82:85]
	v_mfma_f32_16x16x32_bf16 v[70:73], v[106:109], v[192:195], v[70:73]
	v_mfma_f32_16x16x32_bf16 v[66:69], v[204:207], v[192:195], v[66:69]
	v_mfma_f32_16x16x32_bf16 v[94:97], v[106:109], v[164:167], v[94:97]
	v_mfma_f32_16x16x32_bf16 v[90:93], v[204:207], v[164:167], v[90:93]
	v_mfma_f32_16x16x32_bf16 v[86:89], v[110:113], v[180:183], v[86:89]
	v_mfma_f32_16x16x32_bf16 v[82:85], v[208:211], v[180:183], v[82:85]
	v_mfma_f32_16x16x32_bf16 v[78:81], v[106:109], v[184:187], v[78:81]
	v_mfma_f32_16x16x32_bf16 v[74:77], v[204:207], v[184:187], v[74:77]
	v_mfma_f32_16x16x32_bf16 v[70:73], v[110:113], v[196:199], v[70:73]
	v_mfma_f32_16x16x32_bf16 v[66:69], v[208:211], v[196:199], v[66:69]
	v_mfma_f32_16x16x32_bf16 v[212:215], v[110:113], v[168:171], v[94:97]
	v_mfma_f32_16x16x32_bf16 v[164:167], v[208:211], v[168:171], v[90:93]
	v_mfma_f32_16x16x32_bf16 v[168:171], v[110:113], v[188:191], v[78:81]
	v_mfma_f32_16x16x32_bf16 v[176:179], v[208:211], v[188:191], v[74:77]
	s_barrier
	s_nop 0
	ds_read_b128 v[74:77], v136 offset:16384
	ds_read_b128 v[78:81], v136 offset:17408
	ds_read_b128 v[90:93], v136 offset:18432
	ds_read_b128 v[94:97], v136 offset:19456
	ds_read_b128 v[180:183], v136 offset:20480
	ds_read_b128 v[184:187], v136 offset:21504
	ds_read_b128 v[188:191], v136 offset:22528
	ds_read_b128 v[192:195], v136 offset:23552
	s_waitcnt vmcnt(4)
	s_barrier
	s_waitcnt lgkmcnt(0)
	s_waitcnt lgkmcnt(0)
	v_mfma_f32_16x16x32_bf16 v[62:65], v[138:141], v[74:77], v[62:65]
	v_mfma_f32_16x16x32_bf16 v[58:61], v[146:149], v[74:77], v[58:61]
	v_mfma_f32_16x16x32_bf16 v[54:57], v[138:141], v[90:93], v[54:57]
	v_mfma_f32_16x16x32_bf16 v[50:53], v[146:149], v[90:93], v[50:53]
	v_mfma_f32_16x16x32_bf16 v[38:41], v[138:141], v[188:191], v[38:41]
	v_mfma_f32_16x16x32_bf16 v[34:37], v[146:149], v[188:191], v[34:37]
	v_mfma_f32_16x16x32_bf16 v[62:65], v[142:145], v[78:81], v[62:65]
	v_mfma_f32_16x16x32_bf16 v[58:61], v[152:155], v[78:81], v[58:61]
	v_mfma_f32_16x16x32_bf16 v[54:57], v[142:145], v[94:97], v[54:57]
	v_mfma_f32_16x16x32_bf16 v[50:53], v[152:155], v[94:97], v[50:53]
	v_mfma_f32_16x16x32_bf16 v[46:49], v[138:141], v[180:183], v[46:49]
	v_mfma_f32_16x16x32_bf16 v[42:45], v[146:149], v[180:183], v[42:45]
	v_mfma_f32_16x16x32_bf16 v[38:41], v[142:145], v[192:195], v[38:41]
	v_mfma_f32_16x16x32_bf16 v[34:37], v[152:155], v[192:195], v[34:37]
	v_mfma_f32_16x16x32_bf16 v[196:199], v[142:145], v[184:187], v[46:49]
	v_mfma_f32_16x16x32_bf16 v[216:219], v[152:155], v[184:187], v[42:45]
	v_mfma_f32_16x16x32_bf16 v[22:25], v[106:109], v[90:93], v[22:25]
	v_mfma_f32_16x16x32_bf16 v[18:21], v[204:207], v[90:93], v[18:21]
	v_mfma_f32_16x16x32_bf16 v[6:9], v[106:109], v[188:191], v[6:9]
	v_mfma_f32_16x16x32_bf16 v[2:5], v[204:207], v[188:191], v[2:5]
	v_mfma_f32_16x16x32_bf16 v[30:33], v[106:109], v[74:77], v[30:33]
	v_mfma_f32_16x16x32_bf16 v[26:29], v[204:207], v[74:77], v[26:29]
	v_mfma_f32_16x16x32_bf16 v[22:25], v[110:113], v[94:97], v[22:25]
	v_mfma_f32_16x16x32_bf16 v[18:21], v[208:211], v[94:97], v[18:21]
	v_mfma_f32_16x16x32_bf16 v[14:17], v[106:109], v[180:183], v[14:17]
	v_mfma_f32_16x16x32_bf16 v[10:13], v[204:207], v[180:183], v[10:13]
	v_mfma_f32_16x16x32_bf16 v[6:9], v[110:113], v[192:195], v[6:9]
	v_mfma_f32_16x16x32_bf16 v[2:5], v[208:211], v[192:195], v[2:5]
	v_mfma_f32_16x16x32_bf16 v[138:141], v[110:113], v[78:81], v[30:33]
	v_mfma_f32_16x16x32_bf16 v[142:145], v[208:211], v[78:81], v[26:29]
	v_mfma_f32_16x16x32_bf16 v[146:149], v[110:113], v[184:187], v[14:17]
	v_mfma_f32_16x16x32_bf16 v[152:155], v[208:211], v[184:187], v[10:13]
	s_barrier
	s_nop 0
	ds_read_b128 v[10:13], v137 offset:32768
	ds_read_b128 v[14:17], v137 offset:33792
	ds_read_b128 v[180:183], v137 offset:34816
	ds_read_b128 v[184:187], v137 offset:35840
	ds_read_b128 v[26:29], v136 offset:32768
	ds_read_b128 v[30:33], v136 offset:33792
	ds_read_b128 v[42:45], v136 offset:34816
	ds_read_b128 v[46:49], v136 offset:35840
	ds_read_b128 v[188:191], v136 offset:36864
	ds_read_b128 v[192:195], v136 offset:37888
	ds_read_b128 v[204:207], v136 offset:38912
	ds_read_b128 v[208:211], v136 offset:39936
	s_waitcnt vmcnt(2)
	s_barrier
; #define WAIT_V(n) asm volatile("s_waitcnt vmcnt(%0)" ::"n"(n) : "memory")
; #define WAIT_L(n) asm volatile("s_waitcnt lgkmcnt(%0)" ::"n"(n) : "memory")
; #define LDA8(dst, b, h) _Pragma("unroll") for (int m = 0; m < 4; ++m) _Pragma("unroll") for (int k = 0; k < 2; ++k) \
;     dst[m][k] = *(const bf16x8*)(abase + SAo(b, h) + m * 2048 + k * 1024)
; #define LDB8(dst, b, h) _Pragma("unroll") for (int n = 0; n < 2; ++n) _Pragma("unroll") for (int k = 0; k < 2; ++k) \
;     dst[n][k] = *(const bf16x8*)(bbase + SAo(b, h) + n * 2048 + k * 1024)
; #define BAR8 __builtin_amdgcn_s_barrier()
; __device__ __forceinline__ void gemm_main8(const u16* __restrict__ Ab, int lda, const u16* __restrict__ Bb, int ldb, int K,
;                                            char* shm, f32x4 (&acc)[2][2][4][2]) {
;     ...
;   { LDB8(B0, 1, 0); LDA8(At, 1, 0); WAIT_V(2); BAR8; WAIT_L(0); MMA8(0, 0, At, B0); BAR8;
;     LDB8(B1, 1, 1); WAIT_V(0); BAR8; WAIT_L(0); MMA8(0, 1, At, B1); BAR8;
;     LDA8(At, 1, 1); BAR8; WAIT_L(0); MMA8(1, 0, At, B0); MMA8(1, 1, At, B1); BAR8; }
;   if (wr == 0) BAR8;
	s_waitcnt lgkmcnt(0)
	s_waitcnt lgkmcnt(0)
	v_mfma_f32_16x16x32_bf16 v[74:77], v[10:13], v[26:29], v[126:129]
	v_mfma_f32_16x16x32_bf16 v[126:129], v[14:17], v[30:33], v[74:77]
	v_mfma_f32_16x16x32_bf16 v[74:77], v[180:183], v[26:29], v[122:125]
	v_mfma_f32_16x16x32_bf16 v[122:125], v[184:187], v[30:33], v[74:77]
	v_mfma_f32_16x16x32_bf16 v[74:77], v[10:13], v[42:45], v[118:121]
	v_mfma_f32_16x16x32_bf16 v[110:113], v[14:17], v[46:49], v[74:77]
	v_mfma_f32_16x16x32_bf16 v[74:77], v[180:183], v[42:45], v[114:117]
	v_mfma_f32_16x16x32_bf16 v[106:109], v[184:187], v[46:49], v[74:77]
	v_mfma_f32_16x16x32_bf16 v[74:77], v[10:13], v[188:191], v[172:175]
	v_mfma_f32_16x16x32_bf16 v[94:97], v[14:17], v[192:195], v[74:77]
	v_mfma_f32_16x16x32_bf16 v[74:77], v[180:183], v[188:191], v[200:203]
	v_mfma_f32_16x16x32_bf16 v[90:93], v[184:187], v[192:195], v[74:77]
	v_mfma_f32_16x16x32_bf16 v[74:77], v[10:13], v[204:207], v[102:105]
	v_mfma_f32_16x16x32_bf16 v[78:81], v[14:17], v[208:211], v[74:77]
	v_mfma_f32_16x16x32_bf16 v[74:77], v[180:183], v[204:207], v[98:101]
	v_mfma_f32_16x16x32_bf16 v[74:77], v[184:187], v[208:211], v[74:77]
	s_barrier
	ds_read_b128 v[172:175], v137 offset:49152
	ds_read_b128 v[200:203], v137 offset:50176
	ds_read_b128 v[220:223], v137 offset:51200
	ds_read_b128 v[224:227], v137 offset:52224
	s_waitcnt vmcnt(0)
	s_barrier
	s_waitcnt lgkmcnt(0)
	s_waitcnt lgkmcnt(0)
	v_mfma_f32_16x16x32_bf16 v[98:101], v[172:175], v[26:29], v[212:215]
	v_mfma_f32_16x16x32_bf16 v[26:29], v[220:223], v[26:29], v[164:167]
	v_mfma_f32_16x16x32_bf16 v[114:117], v[224:227], v[30:33], v[26:29]
	v_mfma_f32_16x16x32_bf16 v[26:29], v[172:175], v[42:45], v[86:89]
	v_mfma_f32_16x16x32_bf16 v[102:105], v[200:203], v[46:49], v[26:29]
	v_mfma_f32_16x16x32_bf16 v[26:29], v[220:223], v[42:45], v[82:85]
	v_mfma_f32_16x16x32_bf16 v[118:121], v[200:203], v[30:33], v[98:101]
	v_mfma_f32_16x16x32_bf16 v[98:101], v[224:227], v[46:49], v[26:29]
	v_mfma_f32_16x16x32_bf16 v[26:29], v[172:175], v[188:191], v[168:171]
	v_mfma_f32_16x16x32_bf16 v[86:89], v[200:203], v[192:195], v[26:29]
	v_mfma_f32_16x16x32_bf16 v[26:29], v[220:223], v[188:191], v[176:179]
	v_mfma_f32_16x16x32_bf16 v[82:85], v[224:227], v[192:195], v[26:29]
	v_mfma_f32_16x16x32_bf16 v[26:29], v[172:175], v[204:207], v[70:73]
	v_mfma_f32_16x16x32_bf16 v[70:73], v[200:203], v[208:211], v[26:29]
	v_mfma_f32_16x16x32_bf16 v[26:29], v[220:223], v[204:207], v[66:69]
	v_mfma_f32_16x16x32_bf16 v[66:69], v[224:227], v[208:211], v[26:29]
	s_barrier
	ds_read_b128 v[164:167], v136 offset:49152
	ds_read_b128 v[168:171], v136 offset:50176
	ds_read_b128 v[176:179], v136 offset:51200
	ds_read_b128 v[188:191], v136 offset:52224
	ds_read_b128 v[192:195], v136 offset:53248
	ds_read_b128 v[204:207], v136 offset:54272
	ds_read_b128 v[208:211], v136 offset:55296
	ds_read_b128 v[212:215], v136 offset:56320
	s_barrier
	s_waitcnt lgkmcnt(0)
	s_waitcnt lgkmcnt(0)
	v_mfma_f32_16x16x32_bf16 v[26:29], v[10:13], v[164:167], v[62:65]
	v_mfma_f32_16x16x32_bf16 v[62:65], v[14:17], v[168:171], v[26:29]
	v_mfma_f32_16x16x32_bf16 v[26:29], v[180:183], v[164:167], v[58:61]
	v_mfma_f32_16x16x32_bf16 v[58:61], v[184:187], v[168:171], v[26:29]
	v_mfma_f32_16x16x32_bf16 v[26:29], v[10:13], v[176:179], v[54:57]
	v_mfma_f32_16x16x32_bf16 v[46:49], v[14:17], v[188:191], v[26:29]
	v_mfma_f32_16x16x32_bf16 v[26:29], v[180:183], v[176:179], v[50:53]
	v_mfma_f32_16x16x32_bf16 v[42:45], v[184:187], v[188:191], v[26:29]
	v_mfma_f32_16x16x32_bf16 v[26:29], v[10:13], v[192:195], v[196:199]
	v_mfma_f32_16x16x32_bf16 v[10:13], v[10:13], v[208:211], v[38:41]
	v_mfma_f32_16x16x32_bf16 v[30:33], v[14:17], v[204:207], v[26:29]
	v_mfma_f32_16x16x32_bf16 v[26:29], v[180:183], v[192:195], v[216:219]
	v_mfma_f32_16x16x32_bf16 v[14:17], v[14:17], v[212:215], v[10:13]
	v_mfma_f32_16x16x32_bf16 v[10:13], v[180:183], v[208:211], v[34:37]
	v_mfma_f32_16x16x32_bf16 v[26:29], v[184:187], v[204:207], v[26:29]
	v_mfma_f32_16x16x32_bf16 v[10:13], v[184:187], v[212:215], v[10:13]
	v_mfma_f32_16x16x32_bf16 v[34:37], v[172:175], v[164:167], v[138:141]
	v_mfma_f32_16x16x32_bf16 v[54:57], v[200:203], v[168:171], v[34:37]
	v_mfma_f32_16x16x32_bf16 v[34:37], v[220:223], v[164:167], v[142:145]
	v_mfma_f32_16x16x32_bf16 v[18:21], v[220:223], v[176:179], v[18:21]
	v_mfma_f32_16x16x32_bf16 v[50:53], v[224:227], v[168:171], v[34:37]
	v_mfma_f32_16x16x32_bf16 v[22:25], v[172:175], v[176:179], v[22:25]
	v_mfma_f32_16x16x32_bf16 v[34:37], v[224:227], v[188:191], v[18:21]
	v_mfma_f32_16x16x32_bf16 v[18:21], v[172:175], v[192:195], v[146:149]
	v_mfma_f32_16x16x32_bf16 v[38:41], v[200:203], v[188:191], v[22:25]
	v_mfma_f32_16x16x32_bf16 v[22:25], v[200:203], v[204:207], v[18:21]
	v_mfma_f32_16x16x32_bf16 v[18:21], v[220:223], v[192:195], v[152:155]
	v_mfma_f32_16x16x32_bf16 v[6:9], v[172:175], v[208:211], v[6:9]
	v_mfma_f32_16x16x32_bf16 v[2:5], v[220:223], v[208:211], v[2:5]
	v_mfma_f32_16x16x32_bf16 v[18:21], v[224:227], v[204:207], v[18:21]
	v_mfma_f32_16x16x32_bf16 v[6:9], v[200:203], v[212:215], v[6:9]
	v_mfma_f32_16x16x32_bf16 v[2:5], v[224:227], v[212:215], v[2:5]
	v_cmp_gt_u32_e32 vcc, s97, v135
	s_barrier
	s_and_saveexec_b64 s[20:21], vcc
	s_cbranch_execz .LBB0_506
	s_barrier
	s_branch .LBB0_506

; #define WAIT_L(n) asm volatile("s_waitcnt lgkmcnt(%0)" ::"n"(n) : "memory")
; #define SBAR() __builtin_amdgcn_sched_barrier(0)
; #define LDA8(dst, b, h) _Pragma("unroll") for (int m = 0; m < 4; ++m) _Pragma("unroll") for (int k = 0; k < 2; ++k) \
;     dst[m][k] = *(const bf16x8*)(abase + SAo(b, h) + m * 2048 + k * 1024)
; #define LDB8(dst, b, h) _Pragma("unroll") for (int n = 0; n < 2; ++n) _Pragma("unroll") for (int k = 0; k < 2; ++k) \
;     dst[n][k] = *(const bf16x8*)(bbase + SAo(b, h) + n * 2048 + k * 1024)
; #define BAR8 __builtin_amdgcn_s_barrier()
; __device__ __forceinline__ void gemm_main8(const u16* __restrict__ Ab, int lda, const u16* __restrict__ Bb, int ldb, int K,
;                                            char* shm, f32x4 (&acc)[2][2][4][2]) {
;     ...
;     LDB8(B0, 0, 0); SBAR(); LDA8(At, 0, 0); STG_A(1, 1, t + 1);
;     WAIT_L(8); BAR8; WAIT_L(0); MMA8(0, 0, At, B0); BAR8; SBAR();
;     LDB8(B1, 0, 1); STG_B(0, 0, t + 2);
;     BAR8; WAIT_L(0); MMA8(0, 1, At, B1); BAR8;
;     LDA8(At, 0, 1); STG_A(0, 0, t + 2);
;     BAR8; WAIT_L(0); MMA8(1, 0, At, B0); BAR8; SBAR();
.LBB0_556:
	ds_read_b128 v[152:155], v132
	ds_read_b128 v[164:167], v132 offset:1024
	ds_read_b128 v[176:179], v132 offset:2048
	ds_read_b128 v[180:183], v132 offset:3072
	ds_read_b128 v[184:187], v139
	ds_read_b128 v[188:191], v139 offset:1024
	ds_read_b128 v[192:195], v139 offset:2048
	ds_read_b128 v[196:199], v139 offset:3072
	ds_read_b128 v[200:203], v139 offset:4096
	ds_read_b128 v[204:207], v139 offset:5120
	ds_read_b128 v[208:211], v139 offset:6144
	ds_read_b128 v[212:215], v139 offset:7168
	v_add_u32_e32 v174, 0xc000, v133
	v_lshl_add_u64 v[168:169], s[20:21], 0, v[0:1]
	v_readfirstlane_b32 s15, v174
	v_add_u32_e32 v175, 0xe000, v133
	v_lshl_add_u64 v[216:217], v[168:169], 0, s[54:55]
	s_mov_b32 m0, s15
	v_readfirstlane_b32 s15, v175
	global_load_lds_dwordx4 v[216:217], off
	v_lshl_add_u64 v[216:217], v[168:169], 0, s[56:57]
	s_mov_b32 m0, s15
	s_nop 0
	global_load_lds_dwordx4 v[216:217], off
	s_waitcnt lgkmcnt(8)
	s_barrier
	s_waitcnt lgkmcnt(0)
	s_waitcnt lgkmcnt(0)
	v_mfma_f32_16x16x32_bf16 v[126:129], v[152:155], v[184:187], v[126:129]
	v_mfma_f32_16x16x32_bf16 v[122:125], v[176:179], v[184:187], v[122:125]
	v_mfma_f32_16x16x32_bf16 v[118:121], v[152:155], v[192:195], v[118:121]
	v_mfma_f32_16x16x32_bf16 v[114:117], v[176:179], v[192:195], v[114:117]
	v_mfma_f32_16x16x32_bf16 v[110:113], v[152:155], v[200:203], v[110:113]
	v_mfma_f32_16x16x32_bf16 v[106:109], v[176:179], v[200:203], v[106:109]
	v_mfma_f32_16x16x32_bf16 v[102:105], v[152:155], v[208:211], v[102:105]
	v_mfma_f32_16x16x32_bf16 v[98:101], v[176:179], v[208:211], v[98:101]
	v_mfma_f32_16x16x32_bf16 v[126:129], v[164:167], v[188:191], v[126:129]
	v_mfma_f32_16x16x32_bf16 v[122:125], v[180:183], v[188:191], v[122:125]
	v_mfma_f32_16x16x32_bf16 v[118:121], v[164:167], v[196:199], v[118:121]
	v_mfma_f32_16x16x32_bf16 v[114:117], v[180:183], v[196:199], v[114:117]
	v_mfma_f32_16x16x32_bf16 v[110:113], v[164:167], v[204:207], v[110:113]
	v_mfma_f32_16x16x32_bf16 v[106:109], v[180:183], v[204:207], v[106:109]
	v_mfma_f32_16x16x32_bf16 v[102:105], v[164:167], v[212:215], v[102:105]
	v_mfma_f32_16x16x32_bf16 v[98:101], v[180:183], v[212:215], v[98:101]
	s_barrier
	ds_read_b128 v[216:219], v132 offset:16384
	ds_read_b128 v[220:223], v132 offset:17408
	ds_read_b128 v[224:227], v132 offset:18432
	ds_read_b128 v[228:231], v132 offset:19456
	v_lshl_add_u64 v[232:233], s[18:19], 0, v[0:1]
	s_mov_b64 s[24:25], 0x1000100
	v_readfirstlane_b32 s15, v134
	v_lshl_add_u64 v[234:235], v[232:233], 0, s[24:25]
	s_mov_b32 m0, s15
	s_mov_b64 s[24:25], 0x1040100
	v_readfirstlane_b32 s15, v135
	global_load_lds_dwordx4 v[234:235], off
	v_lshl_add_u64 v[234:235], v[232:233], 0, s[24:25]
	s_mov_b32 m0, s15
	s_nop 0
	global_load_lds_dwordx4 v[234:235], off
	s_barrier
	s_waitcnt lgkmcnt(0)
	s_waitcnt lgkmcnt(0)
	v_mfma_f32_16x16x32_bf16 v[94:97], v[216:219], v[184:187], v[94:97]
	v_mfma_f32_16x16x32_bf16 v[90:93], v[224:227], v[184:187], v[90:93]
	v_mfma_f32_16x16x32_bf16 v[86:89], v[216:219], v[192:195], v[86:89]
	v_mfma_f32_16x16x32_bf16 v[82:85], v[224:227], v[192:195], v[82:85]
	v_mfma_f32_16x16x32_bf16 v[78:81], v[216:219], v[200:203], v[78:81]
	v_mfma_f32_16x16x32_bf16 v[74:77], v[224:227], v[200:203], v[74:77]
	v_mfma_f32_16x16x32_bf16 v[70:73], v[216:219], v[208:211], v[70:73]
	v_mfma_f32_16x16x32_bf16 v[66:69], v[224:227], v[208:211], v[66:69]
	v_mfma_f32_16x16x32_bf16 v[94:97], v[220:223], v[188:191], v[94:97]
	v_mfma_f32_16x16x32_bf16 v[90:93], v[228:231], v[188:191], v[90:93]
	v_mfma_f32_16x16x32_bf16 v[86:89], v[220:223], v[196:199], v[86:89]
	v_mfma_f32_16x16x32_bf16 v[82:85], v[228:231], v[196:199], v[82:85]
	v_mfma_f32_16x16x32_bf16 v[78:81], v[220:223], v[204:207], v[78:81]
	v_mfma_f32_16x16x32_bf16 v[74:77], v[228:231], v[204:207], v[74:77]
	v_mfma_f32_16x16x32_bf16 v[70:73], v[220:223], v[212:215], v[70:73]
	v_mfma_f32_16x16x32_bf16 v[66:69], v[228:231], v[212:215], v[66:69]
	v_readfirstlane_b32 s15, v133
	v_lshl_add_u64 v[234:235], v[168:169], 0, s[58:59]
	s_mov_b32 m0, s15
	v_readfirstlane_b32 s15, v136
	s_barrier
	ds_read_b128 v[184:187], v139 offset:16384
	ds_read_b128 v[188:191], v139 offset:17408
	ds_read_b128 v[192:195], v139 offset:18432
	ds_read_b128 v[196:199], v139 offset:19456
	ds_read_b128 v[200:203], v139 offset:20480
	ds_read_b128 v[204:207], v139 offset:21504
	ds_read_b128 v[208:211], v139 offset:22528
	ds_read_b128 v[212:215], v139 offset:23552
	global_load_lds_dwordx4 v[234:235], off
	v_lshl_add_u64 v[234:235], v[168:169], 0, s[60:61]
	s_mov_b32 m0, s15
	s_nop 0
	global_load_lds_dwordx4 v[234:235], off
	s_barrier
	s_waitcnt lgkmcnt(0)
	s_waitcnt lgkmcnt(0)
	v_mfma_f32_16x16x32_bf16 v[62:65], v[152:155], v[184:187], v[62:65]
	v_mfma_f32_16x16x32_bf16 v[58:61], v[176:179], v[184:187], v[58:61]
	v_mfma_f32_16x16x32_bf16 v[54:57], v[152:155], v[192:195], v[54:57]
	v_mfma_f32_16x16x32_bf16 v[50:53], v[176:179], v[192:195], v[50:53]
	v_mfma_f32_16x16x32_bf16 v[46:49], v[152:155], v[200:203], v[46:49]
	v_mfma_f32_16x16x32_bf16 v[42:45], v[176:179], v[200:203], v[42:45]
	v_mfma_f32_16x16x32_bf16 v[38:41], v[152:155], v[208:211], v[38:41]
	v_mfma_f32_16x16x32_bf16 v[34:37], v[176:179], v[208:211], v[34:37]
	v_mfma_f32_16x16x32_bf16 v[62:65], v[164:167], v[188:191], v[62:65]
	v_mfma_f32_16x16x32_bf16 v[58:61], v[180:183], v[188:191], v[58:61]
	v_mfma_f32_16x16x32_bf16 v[54:57], v[164:167], v[196:199], v[54:57]
	v_mfma_f32_16x16x32_bf16 v[50:53], v[180:183], v[196:199], v[50:53]
	v_mfma_f32_16x16x32_bf16 v[46:49], v[164:167], v[204:207], v[46:49]
	v_mfma_f32_16x16x32_bf16 v[42:45], v[180:183], v[204:207], v[42:45]
	v_mfma_f32_16x16x32_bf16 v[38:41], v[164:167], v[212:215], v[38:41]
	v_mfma_f32_16x16x32_bf16 v[34:37], v[180:183], v[212:215], v[34:37]
	s_barrier
; #define WAIT_V(n) asm volatile("s_waitcnt vmcnt(%0)" ::"n"(n) : "memory")
; #define WAIT_L(n) asm volatile("s_waitcnt lgkmcnt(%0)" ::"n"(n) : "memory")
; #define SBAR() __builtin_amdgcn_sched_barrier(0)
; #define LDA8(dst, b, h) _Pragma("unroll") for (int m = 0; m < 4; ++m) _Pragma("unroll") for (int k = 0; k < 2; ++k) \
;     dst[m][k] = *(const bf16x8*)(abase + SAo(b, h) + m * 2048 + k * 1024)
; #define LDB8(dst, b, h) _Pragma("unroll") for (int n = 0; n < 2; ++n) _Pragma("unroll") for (int k = 0; k < 2; ++k) \
;     dst[n][k] = *(const bf16x8*)(bbase + SAo(b, h) + n * 2048 + k * 1024)
; #define BAR8 __builtin_amdgcn_s_barrier()
; __device__ __forceinline__ void gemm_main8(const u16* __restrict__ Ab, int lda, const u16* __restrict__ Bb, int ldb, int K,
;                                            char* shm, f32x4 (&acc)[2][2][4][2]) {
;     ...
;     STG_B(0, 1, t + 2);
;     WAIT_V(6); BAR8; MMA8(1, 1, At, B1); BAR8;
;     LDB8(B0, 1, 0); SBAR(); LDA8(At, 1, 0); STG_A(0, 1, t + 2);
;     WAIT_L(8); BAR8; WAIT_L(0); MMA8(0, 0, At, B0); BAR8; SBAR();
;     LDB8(B1, 1, 1); STG_B(1, 0, t + 3);
;     BAR8; WAIT_L(0); MMA8(0, 1, At, B1); BAR8;
;     LDA8(At, 1, 1); STG_A(1, 0, t + 3);
	s_mov_b64 s[24:25], 0x1080100
	v_readfirstlane_b32 s15, v137
	v_lshl_add_u64 v[152:153], v[232:233], 0, s[24:25]
	s_mov_b32 m0, s15
	s_mov_b64 s[24:25], 0x10c0100
	v_readfirstlane_b32 s15, v140
	global_load_lds_dwordx4 v[152:153], off
	v_lshl_add_u64 v[152:153], v[232:233], 0, s[24:25]
	s_mov_b32 m0, s15
	s_nop 0
	global_load_lds_dwordx4 v[152:153], off
	s_waitcnt vmcnt(6)
	s_barrier
	v_mfma_f32_16x16x32_bf16 v[30:33], v[216:219], v[184:187], v[30:33]
	v_mfma_f32_16x16x32_bf16 v[26:29], v[224:227], v[184:187], v[26:29]
	v_mfma_f32_16x16x32_bf16 v[22:25], v[216:219], v[192:195], v[22:25]
	v_mfma_f32_16x16x32_bf16 v[18:21], v[224:227], v[192:195], v[18:21]
	v_mfma_f32_16x16x32_bf16 v[14:17], v[216:219], v[200:203], v[14:17]
	v_mfma_f32_16x16x32_bf16 v[10:13], v[224:227], v[200:203], v[10:13]
	v_mfma_f32_16x16x32_bf16 v[6:9], v[216:219], v[208:211], v[6:9]
	v_mfma_f32_16x16x32_bf16 v[2:5], v[224:227], v[208:211], v[2:5]
	v_mfma_f32_16x16x32_bf16 v[30:33], v[220:223], v[188:191], v[30:33]
	v_mfma_f32_16x16x32_bf16 v[26:29], v[228:231], v[188:191], v[26:29]
	v_mfma_f32_16x16x32_bf16 v[22:25], v[220:223], v[196:199], v[22:25]
	v_mfma_f32_16x16x32_bf16 v[18:21], v[228:231], v[196:199], v[18:21]
	v_mfma_f32_16x16x32_bf16 v[14:17], v[220:223], v[204:207], v[14:17]
	v_mfma_f32_16x16x32_bf16 v[10:13], v[228:231], v[204:207], v[10:13]
	v_mfma_f32_16x16x32_bf16 v[6:9], v[220:223], v[212:215], v[6:9]
	v_mfma_f32_16x16x32_bf16 v[2:5], v[228:231], v[212:215], v[2:5]
	s_barrier
	ds_read_b128 v[152:155], v132 offset:32768
	ds_read_b128 v[164:167], v132 offset:33792
	ds_read_b128 v[176:179], v132 offset:34816
	ds_read_b128 v[180:183], v132 offset:35840
	ds_read_b128 v[184:187], v139 offset:32768
	ds_read_b128 v[188:191], v139 offset:33792
	ds_read_b128 v[192:195], v139 offset:34816
	ds_read_b128 v[196:199], v139 offset:35840
	ds_read_b128 v[200:203], v139 offset:36864
	ds_read_b128 v[204:207], v139 offset:37888
	ds_read_b128 v[208:211], v139 offset:38912
	ds_read_b128 v[212:215], v139 offset:39936
	v_readfirstlane_b32 s15, v141
	v_lshl_add_u64 v[216:217], v[168:169], 0, s[62:63]
	s_mov_b32 m0, s15
	v_readfirstlane_b32 s15, v142
	global_load_lds_dwordx4 v[216:217], off
	v_lshl_add_u64 v[216:217], v[168:169], 0, s[64:65]
	s_mov_b32 m0, s15
	s_nop 0
	global_load_lds_dwordx4 v[216:217], off
	s_waitcnt lgkmcnt(8)
	s_barrier
	s_waitcnt lgkmcnt(0)
	s_waitcnt lgkmcnt(0)
	v_mfma_f32_16x16x32_bf16 v[126:129], v[152:155], v[184:187], v[126:129]
	v_mfma_f32_16x16x32_bf16 v[122:125], v[176:179], v[184:187], v[122:125]
	v_mfma_f32_16x16x32_bf16 v[118:121], v[152:155], v[192:195], v[118:121]
	v_mfma_f32_16x16x32_bf16 v[114:117], v[176:179], v[192:195], v[114:117]
	v_mfma_f32_16x16x32_bf16 v[110:113], v[152:155], v[200:203], v[110:113]
	v_mfma_f32_16x16x32_bf16 v[106:109], v[176:179], v[200:203], v[106:109]
	v_mfma_f32_16x16x32_bf16 v[102:105], v[152:155], v[208:211], v[102:105]
	v_mfma_f32_16x16x32_bf16 v[98:101], v[176:179], v[208:211], v[98:101]
	v_mfma_f32_16x16x32_bf16 v[126:129], v[164:167], v[188:191], v[126:129]
	v_mfma_f32_16x16x32_bf16 v[122:125], v[180:183], v[188:191], v[122:125]
	v_mfma_f32_16x16x32_bf16 v[118:121], v[164:167], v[196:199], v[118:121]
	v_mfma_f32_16x16x32_bf16 v[114:117], v[180:183], v[196:199], v[114:117]
	v_mfma_f32_16x16x32_bf16 v[110:113], v[164:167], v[204:207], v[110:113]
	v_mfma_f32_16x16x32_bf16 v[106:109], v[180:183], v[204:207], v[106:109]
	v_mfma_f32_16x16x32_bf16 v[102:105], v[164:167], v[212:215], v[102:105]
	v_mfma_f32_16x16x32_bf16 v[98:101], v[180:183], v[212:215], v[98:101]
	s_barrier
	ds_read_b128 v[216:219], v132 offset:49152
	ds_read_b128 v[220:223], v132 offset:50176
	ds_read_b128 v[224:227], v132 offset:51200
	ds_read_b128 v[228:231], v132 offset:52224
	s_mov_b64 s[24:25], 0x1000180
	v_readfirstlane_b32 s15, v143
	v_lshl_add_u64 v[234:235], v[232:233], 0, s[24:25]
	s_mov_b32 m0, s15
	s_mov_b64 s[24:25], 0x1040180
	v_readfirstlane_b32 s15, v144
	global_load_lds_dwordx4 v[234:235], off
	v_lshl_add_u64 v[234:235], v[232:233], 0, s[24:25]
	s_mov_b32 m0, s15
	s_nop 0
	global_load_lds_dwordx4 v[234:235], off
	s_barrier
	s_waitcnt lgkmcnt(0)
	s_waitcnt lgkmcnt(0)
	v_mfma_f32_16x16x32_bf16 v[94:97], v[216:219], v[184:187], v[94:97]
	v_mfma_f32_16x16x32_bf16 v[90:93], v[224:227], v[184:187], v[90:93]
	v_mfma_f32_16x16x32_bf16 v[86:89], v[216:219], v[192:195], v[86:89]
	v_mfma_f32_16x16x32_bf16 v[82:85], v[224:227], v[192:195], v[82:85]
	v_mfma_f32_16x16x32_bf16 v[78:81], v[216:219], v[200:203], v[78:81]
	v_mfma_f32_16x16x32_bf16 v[74:77], v[224:227], v[200:203], v[74:77]
	v_mfma_f32_16x16x32_bf16 v[70:73], v[216:219], v[208:211], v[70:73]
	v_mfma_f32_16x16x32_bf16 v[66:69], v[224:227], v[208:211], v[66:69]
	v_mfma_f32_16x16x32_bf16 v[94:97], v[220:223], v[188:191], v[94:97]
	v_mfma_f32_16x16x32_bf16 v[90:93], v[228:231], v[188:191], v[90:93]
	v_mfma_f32_16x16x32_bf16 v[86:89], v[220:223], v[196:199], v[86:89]
	v_mfma_f32_16x16x32_bf16 v[82:85], v[228:231], v[196:199], v[82:85]
	v_mfma_f32_16x16x32_bf16 v[78:81], v[220:223], v[204:207], v[78:81]
	v_mfma_f32_16x16x32_bf16 v[74:77], v[228:231], v[204:207], v[74:77]
	v_mfma_f32_16x16x32_bf16 v[70:73], v[220:223], v[212:215], v[70:73]
	v_mfma_f32_16x16x32_bf16 v[66:69], v[228:231], v[212:215], v[66:69]
	v_readfirstlane_b32 s15, v145
	v_lshl_add_u64 v[234:235], v[168:169], 0, s[66:67]
	s_mov_b32 m0, s15
	v_readfirstlane_b32 s15, v171
	s_barrier
; #define WAIT_V(n) asm volatile("s_waitcnt vmcnt(%0)" ::"n"(n) : "memory")
; #define WAIT_L(n) asm volatile("s_waitcnt lgkmcnt(%0)" ::"n"(n) : "memory")
; #define SBAR() __builtin_amdgcn_sched_barrier(0)
; #define LDA8(dst, b, h) _Pragma("unroll") for (int m = 0; m < 4; ++m) _Pragma("unroll") for (int k = 0; k < 2; ++k) \
;     dst[m][k] = *(const bf16x8*)(abase + SAo(b, h) + m * 2048 + k * 1024)
; #define LDB8(dst, b, h) _Pragma("unroll") for (int n = 0; n < 2; ++n) _Pragma("unroll") for (int k = 0; k < 2; ++k) \
;     dst[n][k] = *(const bf16x8*)(bbase + SAo(b, h) + n * 2048 + k * 1024)
; #define BAR8 __builtin_amdgcn_s_barrier()
; __device__ __forceinline__ void gemm_main8(const u16* __restrict__ Ab, int lda, const u16* __restrict__ Bb, int ldb, int K,
;                                            char* shm, f32x4 (&acc)[2][2][4][2]) {
;     ...
;     LDA8(At, 1, 1); STG_A(1, 0, t + 3);
;     BAR8; WAIT_L(0); MMA8(1, 0, At, B0); BAR8; SBAR();
;     STG_B(1, 1, t + 3);
;     WAIT_V(6); BAR8; MMA8(1, 1, At, B1); BAR8;
;   }
;   { LDB8(B0, 0, 0); LDA8(At, 0, 0); STG_A(1, 1, nt - 1);
;     BAR8; WAIT_L(0); MMA8(0, 0, At, B0); BAR8;
	ds_read_b128 v[184:187], v139 offset:49152
	ds_read_b128 v[188:191], v139 offset:50176
	ds_read_b128 v[192:195], v139 offset:51200
	ds_read_b128 v[196:199], v139 offset:52224
	ds_read_b128 v[200:203], v139 offset:53248
	ds_read_b128 v[204:207], v139 offset:54272
	ds_read_b128 v[208:211], v139 offset:55296
	ds_read_b128 v[212:215], v139 offset:56320
	global_load_lds_dwordx4 v[234:235], off
	v_lshl_add_u64 v[168:169], v[168:169], 0, s[68:69]
	s_mov_b32 m0, s15
	s_nop 0
	global_load_lds_dwordx4 v[168:169], off
	s_barrier
	s_waitcnt lgkmcnt(0)
	s_waitcnt lgkmcnt(0)
	v_mfma_f32_16x16x32_bf16 v[62:65], v[152:155], v[184:187], v[62:65]
	v_mfma_f32_16x16x32_bf16 v[58:61], v[176:179], v[184:187], v[58:61]
	v_mfma_f32_16x16x32_bf16 v[54:57], v[152:155], v[192:195], v[54:57]
	v_mfma_f32_16x16x32_bf16 v[50:53], v[176:179], v[192:195], v[50:53]
	v_mfma_f32_16x16x32_bf16 v[46:49], v[152:155], v[200:203], v[46:49]
	v_mfma_f32_16x16x32_bf16 v[42:45], v[176:179], v[200:203], v[42:45]
	v_mfma_f32_16x16x32_bf16 v[38:41], v[152:155], v[208:211], v[38:41]
	v_mfma_f32_16x16x32_bf16 v[34:37], v[176:179], v[208:211], v[34:37]
	v_mfma_f32_16x16x32_bf16 v[62:65], v[164:167], v[188:191], v[62:65]
	v_mfma_f32_16x16x32_bf16 v[58:61], v[180:183], v[188:191], v[58:61]
	v_mfma_f32_16x16x32_bf16 v[54:57], v[164:167], v[196:199], v[54:57]
	v_mfma_f32_16x16x32_bf16 v[50:53], v[180:183], v[196:199], v[50:53]
	v_mfma_f32_16x16x32_bf16 v[46:49], v[164:167], v[204:207], v[46:49]
	v_mfma_f32_16x16x32_bf16 v[42:45], v[180:183], v[204:207], v[42:45]
	v_mfma_f32_16x16x32_bf16 v[38:41], v[164:167], v[212:215], v[38:41]
	v_mfma_f32_16x16x32_bf16 v[34:37], v[180:183], v[212:215], v[34:37]
	s_barrier
	s_mov_b64 s[24:25], 0x1080180
	v_readfirstlane_b32 s15, v172
	v_lshl_add_u64 v[152:153], v[232:233], 0, s[24:25]
	s_mov_b32 m0, s15
	s_mov_b64 s[24:25], 0x10c0180
	v_readfirstlane_b32 s15, v173
	global_load_lds_dwordx4 v[152:153], off
	v_lshl_add_u64 v[152:153], v[232:233], 0, s[24:25]
	s_mov_b32 m0, s15
	s_nop 0
	global_load_lds_dwordx4 v[152:153], off
	s_waitcnt vmcnt(6)
	s_barrier
	v_mfma_f32_16x16x32_bf16 v[30:33], v[216:219], v[184:187], v[30:33]
	v_mfma_f32_16x16x32_bf16 v[26:29], v[224:227], v[184:187], v[26:29]
	v_mfma_f32_16x16x32_bf16 v[22:25], v[216:219], v[192:195], v[22:25]
	v_mfma_f32_16x16x32_bf16 v[18:21], v[224:227], v[192:195], v[18:21]
	v_mfma_f32_16x16x32_bf16 v[14:17], v[216:219], v[200:203], v[14:17]
	v_mfma_f32_16x16x32_bf16 v[10:13], v[224:227], v[200:203], v[10:13]
	v_mfma_f32_16x16x32_bf16 v[6:9], v[216:219], v[208:211], v[6:9]
	v_mfma_f32_16x16x32_bf16 v[2:5], v[224:227], v[208:211], v[2:5]
	v_mfma_f32_16x16x32_bf16 v[30:33], v[220:223], v[188:191], v[30:33]
	v_mfma_f32_16x16x32_bf16 v[26:29], v[228:231], v[188:191], v[26:29]
	v_mfma_f32_16x16x32_bf16 v[22:25], v[220:223], v[196:199], v[22:25]
	v_mfma_f32_16x16x32_bf16 v[18:21], v[228:231], v[196:199], v[18:21]
	v_mfma_f32_16x16x32_bf16 v[14:17], v[220:223], v[204:207], v[14:17]
	v_mfma_f32_16x16x32_bf16 v[10:13], v[228:231], v[204:207], v[10:13]
	v_mfma_f32_16x16x32_bf16 v[6:9], v[220:223], v[212:215], v[6:9]
	v_mfma_f32_16x16x32_bf16 v[2:5], v[228:231], v[212:215], v[2:5]
	s_add_i32 s13, s13, 2
	s_add_u32 s18, s18, 0x100
	s_addc_u32 s19, s19, 0
	s_add_u32 s20, s20, 0x100
	s_addc_u32 s21, s21, 0
	s_cmp_lt_u32 s13, 28
	s_barrier
	s_cbranch_scc1 .LBB0_556
	s_mov_b64 s[18:19], 0x80f80
	v_readfirstlane_b32 s13, v174
	v_lshl_add_u64 v[144:145], v[130:131], 0, s[18:19]
	s_mov_b32 m0, s13
	s_mov_b64 s[18:19], 0xc0f80
	v_readfirstlane_b32 s13, v175
	ds_read_b128 v[134:137], v132
	ds_read_b128 v[140:143], v132 offset:1024
	ds_read_b128 v[152:155], v132 offset:2048
	ds_read_b128 v[164:167], v132 offset:3072
	ds_read_b128 v[168:171], v139
	ds_read_b128 v[176:179], v139 offset:1024
	ds_read_b128 v[180:183], v139 offset:2048
	ds_read_b128 v[184:187], v139 offset:3072
	ds_read_b128 v[188:191], v139 offset:4096
	ds_read_b128 v[192:195], v139 offset:5120
	ds_read_b128 v[196:199], v139 offset:6144
	ds_read_b128 v[200:203], v139 offset:7168
	global_load_lds_dwordx4 v[144:145], off
	v_lshl_add_u64 v[130:131], v[130:131], 0, s[18:19]
	s_mov_b32 m0, s13
	s_nop 0
	global_load_lds_dwordx4 v[130:131], off
	s_barrier
	s_waitcnt lgkmcnt(0)
	s_waitcnt lgkmcnt(0)
	v_mfma_f32_16x16x32_bf16 v[126:129], v[134:137], v[168:171], v[126:129]
	v_mfma_f32_16x16x32_bf16 v[122:125], v[152:155], v[168:171], v[122:125]
	v_mfma_f32_16x16x32_bf16 v[118:121], v[134:137], v[180:183], v[118:121]
	v_mfma_f32_16x16x32_bf16 v[114:117], v[152:155], v[180:183], v[114:117]
	v_mfma_f32_16x16x32_bf16 v[102:105], v[134:137], v[196:199], v[102:105]
	v_mfma_f32_16x16x32_bf16 v[126:129], v[140:143], v[176:179], v[126:129]
	v_mfma_f32_16x16x32_bf16 v[122:125], v[164:167], v[176:179], v[122:125]
	v_mfma_f32_16x16x32_bf16 v[118:121], v[140:143], v[184:187], v[118:121]
	v_mfma_f32_16x16x32_bf16 v[114:117], v[164:167], v[184:187], v[114:117]
	v_mfma_f32_16x16x32_bf16 v[110:113], v[134:137], v[188:191], v[110:113]
	v_mfma_f32_16x16x32_bf16 v[106:109], v[152:155], v[188:191], v[106:109]
	v_mfma_f32_16x16x32_bf16 v[102:105], v[140:143], v[200:203], v[102:105]
	v_mfma_f32_16x16x32_bf16 v[98:101], v[152:155], v[196:199], v[98:101]
	v_mfma_f32_16x16x32_bf16 v[172:175], v[140:143], v[192:195], v[110:113]
	v_mfma_f32_16x16x32_bf16 v[106:109], v[164:167], v[192:195], v[106:109]
	v_mfma_f32_16x16x32_bf16 v[204:207], v[164:167], v[200:203], v[98:101]
	s_barrier
	s_nop 2
	ds_read_b128 v[98:101], v132 offset:16384
	ds_read_b128 v[110:113], v132 offset:17408
	ds_read_b128 v[208:211], v132 offset:18432
	ds_read_b128 v[212:215], v132 offset:19456
	s_barrier
; #define WAIT_V(n) asm volatile("s_waitcnt vmcnt(%0)" ::"n"(n) : "memory")
; #define WAIT_L(n) asm volatile("s_waitcnt lgkmcnt(%0)" ::"n"(n) : "memory")
; #define LDA8(dst, b, h) _Pragma("unroll") for (int m = 0; m < 4; ++m) _Pragma("unroll") for (int k = 0; k < 2; ++k) \
;     dst[m][k] = *(const bf16x8*)(abase + SAo(b, h) + m * 2048 + k * 1024)
; #define LDB8(dst, b, h) _Pragma("unroll") for (int n = 0; n < 2; ++n) _Pragma("unroll") for (int k = 0; k < 2; ++k) \
;     dst[n][k] = *(const bf16x8*)(bbase + SAo(b, h) + n * 2048 + k * 1024)
; #define BAR8 __builtin_amdgcn_s_barrier()
; __device__ __forceinline__ void gemm_main8(const u16* __restrict__ Ab, int lda, const u16* __restrict__ Bb, int ldb, int K,
;                                            char* shm, f32x4 (&acc)[2][2][4][2]) {
;     ...
;     LDB8(B1, 0, 1); BAR8; WAIT_L(0); MMA8(0, 1, At, B1); BAR8;
;     LDA8(At, 0, 1); WAIT_V(4); BAR8; WAIT_L(0); MMA8(1, 0, At, B0); MMA8(1, 1, At, B1); BAR8; }
;   { LDB8(B0, 1, 0); LDA8(At, 1, 0); WAIT_V(2); BAR8; WAIT_L(0); MMA8(0, 0, At, B0); BAR8;
	s_waitcnt lgkmcnt(0)
	s_waitcnt lgkmcnt(0)
	v_mfma_f32_16x16x32_bf16 v[90:93], v[208:211], v[168:171], v[90:93]
	v_mfma_f32_16x16x32_bf16 v[82:85], v[208:211], v[180:183], v[82:85]
	v_mfma_f32_16x16x32_bf16 v[74:77], v[208:211], v[188:191], v[74:77]
	v_mfma_f32_16x16x32_bf16 v[94:97], v[98:101], v[168:171], v[94:97]
	v_mfma_f32_16x16x32_bf16 v[90:93], v[212:215], v[176:179], v[90:93]
	v_mfma_f32_16x16x32_bf16 v[86:89], v[98:101], v[180:183], v[86:89]
	v_mfma_f32_16x16x32_bf16 v[82:85], v[212:215], v[184:187], v[82:85]
	v_mfma_f32_16x16x32_bf16 v[78:81], v[98:101], v[188:191], v[78:81]
	v_mfma_f32_16x16x32_bf16 v[74:77], v[212:215], v[192:195], v[74:77]
	v_mfma_f32_16x16x32_bf16 v[70:73], v[98:101], v[196:199], v[70:73]
	v_mfma_f32_16x16x32_bf16 v[66:69], v[208:211], v[196:199], v[66:69]
	v_mfma_f32_16x16x32_bf16 v[94:97], v[110:113], v[176:179], v[94:97]
	v_mfma_f32_16x16x32_bf16 v[168:171], v[110:113], v[184:187], v[86:89]
	v_mfma_f32_16x16x32_bf16 v[176:179], v[110:113], v[192:195], v[78:81]
	v_mfma_f32_16x16x32_bf16 v[180:183], v[110:113], v[200:203], v[70:73]
	v_mfma_f32_16x16x32_bf16 v[184:187], v[212:215], v[200:203], v[66:69]
	s_barrier
	s_nop 0
	ds_read_b128 v[66:69], v139 offset:16384
	ds_read_b128 v[70:73], v139 offset:17408
	ds_read_b128 v[78:81], v139 offset:18432
	ds_read_b128 v[86:89], v139 offset:19456
	ds_read_b128 v[188:191], v139 offset:20480
	ds_read_b128 v[192:195], v139 offset:21504
	ds_read_b128 v[196:199], v139 offset:22528
	ds_read_b128 v[200:203], v139 offset:23552
	s_waitcnt vmcnt(4)
	s_barrier
	s_waitcnt lgkmcnt(0)
	s_waitcnt lgkmcnt(0)
	v_mfma_f32_16x16x32_bf16 v[62:65], v[134:137], v[66:69], v[62:65]
	v_mfma_f32_16x16x32_bf16 v[54:57], v[134:137], v[78:81], v[54:57]
	v_mfma_f32_16x16x32_bf16 v[50:53], v[152:155], v[78:81], v[50:53]
	v_mfma_f32_16x16x32_bf16 v[38:41], v[134:137], v[196:199], v[38:41]
	v_mfma_f32_16x16x32_bf16 v[34:37], v[152:155], v[196:199], v[34:37]
	v_mfma_f32_16x16x32_bf16 v[62:65], v[140:143], v[70:73], v[62:65]
	v_mfma_f32_16x16x32_bf16 v[58:61], v[152:155], v[66:69], v[58:61]
	v_mfma_f32_16x16x32_bf16 v[54:57], v[140:143], v[86:89], v[54:57]
	v_mfma_f32_16x16x32_bf16 v[50:53], v[164:167], v[86:89], v[50:53]
	v_mfma_f32_16x16x32_bf16 v[46:49], v[134:137], v[188:191], v[46:49]
	v_mfma_f32_16x16x32_bf16 v[42:45], v[152:155], v[188:191], v[42:45]
	v_mfma_f32_16x16x32_bf16 v[38:41], v[140:143], v[200:203], v[38:41]
	v_mfma_f32_16x16x32_bf16 v[34:37], v[164:167], v[200:203], v[34:37]
	v_mfma_f32_16x16x32_bf16 v[216:219], v[164:167], v[70:73], v[58:61]
	v_mfma_f32_16x16x32_bf16 v[220:223], v[140:143], v[192:195], v[46:49]
	v_mfma_f32_16x16x32_bf16 v[224:227], v[164:167], v[192:195], v[42:45]
	v_mfma_f32_16x16x32_bf16 v[22:25], v[98:101], v[78:81], v[22:25]
	v_mfma_f32_16x16x32_bf16 v[18:21], v[208:211], v[78:81], v[18:21]
	v_mfma_f32_16x16x32_bf16 v[10:13], v[208:211], v[188:191], v[10:13]
	v_mfma_f32_16x16x32_bf16 v[30:33], v[98:101], v[66:69], v[30:33]
	v_mfma_f32_16x16x32_bf16 v[26:29], v[208:211], v[66:69], v[26:29]
	v_mfma_f32_16x16x32_bf16 v[22:25], v[110:113], v[86:89], v[22:25]
	v_mfma_f32_16x16x32_bf16 v[18:21], v[212:215], v[86:89], v[18:21]
	v_mfma_f32_16x16x32_bf16 v[14:17], v[98:101], v[188:191], v[14:17]
	v_mfma_f32_16x16x32_bf16 v[10:13], v[212:215], v[192:195], v[10:13]
	v_mfma_f32_16x16x32_bf16 v[6:9], v[98:101], v[196:199], v[6:9]
	v_mfma_f32_16x16x32_bf16 v[2:5], v[208:211], v[196:199], v[2:5]
	v_mfma_f32_16x16x32_bf16 v[140:143], v[110:113], v[70:73], v[30:33]
	v_mfma_f32_16x16x32_bf16 v[152:155], v[212:215], v[70:73], v[26:29]
	v_mfma_f32_16x16x32_bf16 v[164:167], v[110:113], v[192:195], v[14:17]
	v_mfma_f32_16x16x32_bf16 v[188:191], v[110:113], v[200:203], v[6:9]
	v_mfma_f32_16x16x32_bf16 v[192:195], v[212:215], v[200:203], v[2:5]
	s_barrier
	s_nop 0
	ds_read_b128 v[2:5], v132 offset:32768
	ds_read_b128 v[6:9], v132 offset:33792
	ds_read_b128 v[14:17], v132 offset:34816
	ds_read_b128 v[196:199], v132 offset:35840
	ds_read_b128 v[26:29], v139 offset:32768
	ds_read_b128 v[30:33], v139 offset:33792
	ds_read_b128 v[42:45], v139 offset:34816
	ds_read_b128 v[46:49], v139 offset:35840
	ds_read_b128 v[58:61], v139 offset:36864
	ds_read_b128 v[66:69], v139 offset:37888
	ds_read_b128 v[200:203], v139 offset:38912
	ds_read_b128 v[208:211], v139 offset:39936
	s_waitcnt vmcnt(2)
	s_barrier
; #define WAIT_V(n) asm volatile("s_waitcnt vmcnt(%0)" ::"n"(n) : "memory")
; #define WAIT_L(n) asm volatile("s_waitcnt lgkmcnt(%0)" ::"n"(n) : "memory")
; #define LDA8(dst, b, h) _Pragma("unroll") for (int m = 0; m < 4; ++m) _Pragma("unroll") for (int k = 0; k < 2; ++k) \
;     dst[m][k] = *(const bf16x8*)(abase + SAo(b, h) + m * 2048 + k * 1024)
; #define LDB8(dst, b, h) _Pragma("unroll") for (int n = 0; n < 2; ++n) _Pragma("unroll") for (int k = 0; k < 2; ++k) \
;     dst[n][k] = *(const bf16x8*)(bbase + SAo(b, h) + n * 2048 + k * 1024)
; #define BAR8 __builtin_amdgcn_s_barrier()
; __device__ __forceinline__ void gemm_main8(const u16* __restrict__ Ab, int lda, const u16* __restrict__ Bb, int ldb, int K,
;                                            char* shm, f32x4 (&acc)[2][2][4][2]) {
;     ...
;   { LDB8(B0, 1, 0); LDA8(At, 1, 0); WAIT_V(2); BAR8; WAIT_L(0); MMA8(0, 0, At, B0); BAR8;
;     LDB8(B1, 1, 1); WAIT_V(0); BAR8; WAIT_L(0); MMA8(0, 1, At, B1); BAR8;
;     LDA8(At, 1, 1); BAR8; WAIT_L(0); MMA8(1, 0, At, B0); MMA8(1, 1, At, B1); BAR8; }
;   if (wr == 0) BAR8;
	s_waitcnt lgkmcnt(0)
	s_waitcnt lgkmcnt(0)
	v_mfma_f32_16x16x32_bf16 v[70:73], v[2:5], v[26:29], v[126:129]
	v_mfma_f32_16x16x32_bf16 v[126:129], v[6:9], v[30:33], v[70:73]
	v_mfma_f32_16x16x32_bf16 v[70:73], v[14:17], v[26:29], v[122:125]
	v_mfma_f32_16x16x32_bf16 v[134:137], v[196:199], v[30:33], v[70:73]
	v_mfma_f32_16x16x32_bf16 v[70:73], v[2:5], v[42:45], v[118:121]
	v_mfma_f32_16x16x32_bf16 v[110:113], v[6:9], v[46:49], v[70:73]
	v_mfma_f32_16x16x32_bf16 v[70:73], v[14:17], v[42:45], v[114:117]
	v_mfma_f32_16x16x32_bf16 v[118:121], v[196:199], v[46:49], v[70:73]
	v_mfma_f32_16x16x32_bf16 v[70:73], v[2:5], v[58:61], v[172:175]
	v_mfma_f32_16x16x32_bf16 v[86:89], v[6:9], v[66:69], v[70:73]
	v_mfma_f32_16x16x32_bf16 v[70:73], v[14:17], v[58:61], v[106:109]
	v_mfma_f32_16x16x32_bf16 v[98:101], v[196:199], v[66:69], v[70:73]
	v_mfma_f32_16x16x32_bf16 v[70:73], v[2:5], v[200:203], v[102:105]
	v_mfma_f32_16x16x32_bf16 v[78:81], v[14:17], v[200:203], v[204:207]
	v_mfma_f32_16x16x32_bf16 v[70:73], v[6:9], v[208:211], v[70:73]
	v_mfma_f32_16x16x32_bf16 v[78:81], v[196:199], v[208:211], v[78:81]
	s_barrier
	ds_read_b128 v[106:109], v132 offset:49152
	ds_read_b128 v[172:175], v132 offset:50176
	ds_read_b128 v[204:207], v132 offset:51200
	ds_read_b128 v[212:215], v132 offset:52224
	s_waitcnt vmcnt(0)
	s_barrier
	s_waitcnt lgkmcnt(0)
	s_waitcnt lgkmcnt(0)
	v_mfma_f32_16x16x32_bf16 v[94:97], v[106:109], v[26:29], v[94:97]
	v_mfma_f32_16x16x32_bf16 v[26:29], v[204:207], v[26:29], v[90:93]
	v_mfma_f32_16x16x32_bf16 v[130:133], v[212:215], v[30:33], v[26:29]
	v_mfma_f32_16x16x32_bf16 v[26:29], v[106:109], v[42:45], v[168:171]
	v_mfma_f32_16x16x32_bf16 v[102:105], v[172:175], v[46:49], v[26:29]
	v_mfma_f32_16x16x32_bf16 v[26:29], v[204:207], v[42:45], v[82:85]
	v_mfma_f32_16x16x32_bf16 v[114:117], v[212:215], v[46:49], v[26:29]
	v_mfma_f32_16x16x32_bf16 v[26:29], v[106:109], v[58:61], v[176:179]
	v_mfma_f32_16x16x32_bf16 v[82:85], v[172:175], v[66:69], v[26:29]
	v_mfma_f32_16x16x32_bf16 v[26:29], v[204:207], v[58:61], v[74:77]
	v_mfma_f32_16x16x32_bf16 v[90:93], v[212:215], v[66:69], v[26:29]
	v_mfma_f32_16x16x32_bf16 v[26:29], v[106:109], v[200:203], v[180:183]
	v_mfma_f32_16x16x32_bf16 v[66:69], v[172:175], v[208:211], v[26:29]
	v_mfma_f32_16x16x32_bf16 v[26:29], v[204:207], v[200:203], v[184:187]
	v_mfma_f32_16x16x32_bf16 v[122:125], v[172:175], v[30:33], v[94:97]
	v_mfma_f32_16x16x32_bf16 v[74:77], v[212:215], v[208:211], v[26:29]
	s_barrier
	ds_read_b128 v[94:97], v139 offset:49152
	ds_read_b128 v[168:171], v139 offset:50176
	ds_read_b128 v[176:179], v139 offset:51200
	ds_read_b128 v[180:183], v139 offset:52224
	ds_read_b128 v[184:187], v139 offset:53248
	ds_read_b128 v[200:203], v139 offset:54272
	ds_read_b128 v[208:211], v139 offset:55296
	ds_read_b128 v[228:231], v139 offset:56320
	s_barrier
	s_waitcnt lgkmcnt(0)
	s_waitcnt lgkmcnt(0)
	v_mfma_f32_16x16x32_bf16 v[26:29], v[2:5], v[94:97], v[62:65]
	v_mfma_f32_16x16x32_bf16 v[58:61], v[6:9], v[168:171], v[26:29]
	v_mfma_f32_16x16x32_bf16 v[26:29], v[14:17], v[94:97], v[216:219]
	v_mfma_f32_16x16x32_bf16 v[62:65], v[196:199], v[168:171], v[26:29]
	v_mfma_f32_16x16x32_bf16 v[26:29], v[2:5], v[176:179], v[54:57]
	v_mfma_f32_16x16x32_bf16 v[42:45], v[6:9], v[180:183], v[26:29]
	v_mfma_f32_16x16x32_bf16 v[26:29], v[14:17], v[176:179], v[50:53]
	v_mfma_f32_16x16x32_bf16 v[46:49], v[196:199], v[180:183], v[26:29]
	v_mfma_f32_16x16x32_bf16 v[26:29], v[2:5], v[184:187], v[220:223]
	v_mfma_f32_16x16x32_bf16 v[2:5], v[2:5], v[208:211], v[38:41]
	v_mfma_f32_16x16x32_bf16 v[26:29], v[6:9], v[200:203], v[26:29]
	v_mfma_f32_16x16x32_bf16 v[30:33], v[14:17], v[184:187], v[224:227]
	v_mfma_f32_16x16x32_bf16 v[6:9], v[6:9], v[228:231], v[2:5]
	v_mfma_f32_16x16x32_bf16 v[2:5], v[14:17], v[208:211], v[34:37]
	v_mfma_f32_16x16x32_bf16 v[30:33], v[196:199], v[200:203], v[30:33]
	v_mfma_f32_16x16x32_bf16 v[14:17], v[196:199], v[228:231], v[2:5]
	v_mfma_f32_16x16x32_bf16 v[2:5], v[106:109], v[94:97], v[140:143]
	v_mfma_f32_16x16x32_bf16 v[50:53], v[172:175], v[168:171], v[2:5]
	v_mfma_f32_16x16x32_bf16 v[2:5], v[204:207], v[94:97], v[152:155]
	v_mfma_f32_16x16x32_bf16 v[54:57], v[212:215], v[168:171], v[2:5]
	v_mfma_f32_16x16x32_bf16 v[2:5], v[106:109], v[176:179], v[22:25]
	v_mfma_f32_16x16x32_bf16 v[34:37], v[172:175], v[180:183], v[2:5]
	v_mfma_f32_16x16x32_bf16 v[2:5], v[204:207], v[176:179], v[18:21]
	v_mfma_f32_16x16x32_bf16 v[38:41], v[212:215], v[180:183], v[2:5]
	v_mfma_f32_16x16x32_bf16 v[2:5], v[106:109], v[184:187], v[164:167]
	v_mfma_f32_16x16x32_bf16 v[18:21], v[172:175], v[200:203], v[2:5]
	v_mfma_f32_16x16x32_bf16 v[2:5], v[204:207], v[184:187], v[10:13]
	v_mfma_f32_16x16x32_bf16 v[22:25], v[212:215], v[200:203], v[2:5]
	v_mfma_f32_16x16x32_bf16 v[2:5], v[106:109], v[208:211], v[188:191]
	v_mfma_f32_16x16x32_bf16 v[10:13], v[204:207], v[208:211], v[192:195]
	v_mfma_f32_16x16x32_bf16 v[2:5], v[172:175], v[228:231], v[2:5]
	v_mfma_f32_16x16x32_bf16 v[10:13], v[212:215], v[228:231], v[10:13]
	v_cmp_gt_u32_e32 vcc, s97, v138
	s_barrier
	s_and_saveexec_b64 s[18:19], vcc
	s_cbranch_execz .LBB0_552
	s_barrier
	s_branch .LBB0_552

; #define WAIT_L(n) asm volatile("s_waitcnt lgkmcnt(%0)" ::"n"(n) : "memory")
; #define SBAR() __builtin_amdgcn_sched_barrier(0)
; #define LDA8(dst, b, h) _Pragma("unroll") for (int m = 0; m < 4; ++m) _Pragma("unroll") for (int k = 0; k < 2; ++k) \
;     dst[m][k] = *(const bf16x8*)(abase + SAo(b, h) + m * 2048 + k * 1024)
; #define LDB8(dst, b, h) _Pragma("unroll") for (int n = 0; n < 2; ++n) _Pragma("unroll") for (int k = 0; k < 2; ++k) \
;     dst[n][k] = *(const bf16x8*)(bbase + SAo(b, h) + n * 2048 + k * 1024)
; #define BAR8 __builtin_amdgcn_s_barrier()
; __device__ __forceinline__ void gemm_main8(const u16* __restrict__ Ab, int lda, const u16* __restrict__ Bb, int ldb, int K,
;                                            char* shm, f32x4 (&acc)[2][2][4][2]) {
;     ...
;     LDB8(B0, 0, 0); SBAR(); LDA8(At, 0, 0); STG_A(1, 1, t + 1);
;     WAIT_L(8); BAR8; WAIT_L(0); MMA8(0, 0, At, B0); BAR8; SBAR();
;     LDB8(B1, 0, 1); STG_B(0, 0, t + 2);
;     BAR8; WAIT_L(0); MMA8(0, 1, At, B1); BAR8;
;     LDA8(At, 0, 1); STG_A(0, 0, t + 2);
;     BAR8; WAIT_L(0); MMA8(1, 0, At, B0); BAR8; SBAR();
.LBB0_605:
	ds_read_b128 v[178:181], v140
	ds_read_b128 v[182:185], v140 offset:1024
	ds_read_b128 v[186:189], v140 offset:2048
	ds_read_b128 v[190:193], v140 offset:3072
	ds_read_b128 v[194:197], v0
	ds_read_b128 v[198:201], v0 offset:1024
	ds_read_b128 v[202:205], v0 offset:2048
	ds_read_b128 v[206:209], v0 offset:3072
	ds_read_b128 v[210:213], v0 offset:4096
	ds_read_b128 v[214:217], v0 offset:5120
	ds_read_b128 v[218:221], v0 offset:6144
	ds_read_b128 v[222:225], v0 offset:7168
	v_add_u32_e32 v176, 0xc000, v141
	v_lshl_add_u64 v[152:153], v[134:135], 0, s[24:25]
	s_mov_b64 s[88:89], 0x10220080
	v_readfirstlane_b32 s11, v176
	v_add_u32_e32 v177, 0xe000, v141
	v_lshl_add_u64 v[154:155], v[152:153], 0, s[88:89]
	s_mov_b32 m0, s11
	s_mov_b64 s[88:89], 0x10230080
	v_readfirstlane_b32 s11, v177
	global_load_lds_dwordx4 v[154:155], off
	v_lshl_add_u64 v[154:155], v[152:153], 0, s[88:89]
	s_mov_b32 m0, s11
	s_nop 0
	global_load_lds_dwordx4 v[154:155], off
	s_waitcnt lgkmcnt(8)
	s_barrier
	s_waitcnt lgkmcnt(0)
	s_waitcnt lgkmcnt(0)
	v_mfma_f32_16x16x32_bf16 v[126:129], v[178:181], v[194:197], v[126:129]
	v_mfma_f32_16x16x32_bf16 v[122:125], v[186:189], v[194:197], v[122:125]
	v_mfma_f32_16x16x32_bf16 v[118:121], v[178:181], v[202:205], v[118:121]
	v_mfma_f32_16x16x32_bf16 v[114:117], v[186:189], v[202:205], v[114:117]
	v_mfma_f32_16x16x32_bf16 v[110:113], v[178:181], v[210:213], v[110:113]
	v_mfma_f32_16x16x32_bf16 v[106:109], v[186:189], v[210:213], v[106:109]
	v_mfma_f32_16x16x32_bf16 v[102:105], v[178:181], v[218:221], v[102:105]
	v_mfma_f32_16x16x32_bf16 v[98:101], v[186:189], v[218:221], v[98:101]
	v_mfma_f32_16x16x32_bf16 v[126:129], v[182:185], v[198:201], v[126:129]
	v_mfma_f32_16x16x32_bf16 v[122:125], v[190:193], v[198:201], v[122:125]
	v_mfma_f32_16x16x32_bf16 v[118:121], v[182:185], v[206:209], v[118:121]
	v_mfma_f32_16x16x32_bf16 v[114:117], v[190:193], v[206:209], v[114:117]
	v_mfma_f32_16x16x32_bf16 v[110:113], v[182:185], v[214:217], v[110:113]
	v_mfma_f32_16x16x32_bf16 v[106:109], v[190:193], v[214:217], v[106:109]
	v_mfma_f32_16x16x32_bf16 v[102:105], v[182:185], v[222:225], v[102:105]
	v_mfma_f32_16x16x32_bf16 v[98:101], v[190:193], v[222:225], v[98:101]
	s_barrier
	ds_read_b128 v[226:229], v140 offset:16384
	ds_read_b128 v[230:233], v140 offset:17408
	ds_read_b128 v[234:237], v140 offset:18432
	ds_read_b128 v[238:241], v140 offset:19456
	v_lshl_add_u64 v[154:155], v[132:133], 0, s[24:25]
	v_readfirstlane_b32 s11, v142
	v_lshl_add_u64 v[164:165], v[154:155], 0, s[58:59]
	s_mov_b32 m0, s11
	v_readfirstlane_b32 s11, v143
	global_load_lds_dwordx4 v[164:165], off
	v_lshl_add_u64 v[164:165], v[154:155], 0, s[60:61]
	s_mov_b32 m0, s11
	s_nop 0
	global_load_lds_dwordx4 v[164:165], off
	s_barrier
	s_waitcnt lgkmcnt(0)
	s_waitcnt lgkmcnt(0)
	v_mfma_f32_16x16x32_bf16 v[94:97], v[226:229], v[194:197], v[94:97]
	v_mfma_f32_16x16x32_bf16 v[90:93], v[234:237], v[194:197], v[90:93]
	v_mfma_f32_16x16x32_bf16 v[86:89], v[226:229], v[202:205], v[86:89]
	v_mfma_f32_16x16x32_bf16 v[82:85], v[234:237], v[202:205], v[82:85]
	v_mfma_f32_16x16x32_bf16 v[78:81], v[226:229], v[210:213], v[78:81]
	v_mfma_f32_16x16x32_bf16 v[74:77], v[234:237], v[210:213], v[74:77]
	v_mfma_f32_16x16x32_bf16 v[70:73], v[226:229], v[218:221], v[70:73]
	v_mfma_f32_16x16x32_bf16 v[66:69], v[234:237], v[218:221], v[66:69]
	v_mfma_f32_16x16x32_bf16 v[94:97], v[230:233], v[198:201], v[94:97]
	v_mfma_f32_16x16x32_bf16 v[90:93], v[238:241], v[198:201], v[90:93]
	v_mfma_f32_16x16x32_bf16 v[86:89], v[230:233], v[206:209], v[86:89]
	v_mfma_f32_16x16x32_bf16 v[82:85], v[238:241], v[206:209], v[82:85]
	v_mfma_f32_16x16x32_bf16 v[78:81], v[230:233], v[214:217], v[78:81]
	v_mfma_f32_16x16x32_bf16 v[74:77], v[238:241], v[214:217], v[74:77]
	v_mfma_f32_16x16x32_bf16 v[70:73], v[230:233], v[222:225], v[70:73]
	v_mfma_f32_16x16x32_bf16 v[66:69], v[238:241], v[222:225], v[66:69]
	s_mov_b64 s[88:89], 0x10200100
	v_readfirstlane_b32 s11, v141
	v_lshl_add_u64 v[164:165], v[152:153], 0, s[88:89]
	s_mov_b32 m0, s11
	s_mov_b64 s[88:89], 0x10210100
	v_readfirstlane_b32 s11, v144
	s_barrier
	ds_read_b128 v[194:197], v0 offset:16384
	ds_read_b128 v[198:201], v0 offset:17408
	ds_read_b128 v[202:205], v0 offset:18432
	ds_read_b128 v[206:209], v0 offset:19456
	ds_read_b128 v[210:213], v0 offset:20480
	ds_read_b128 v[214:217], v0 offset:21504
	ds_read_b128 v[218:221], v0 offset:22528
	ds_read_b128 v[222:225], v0 offset:23552
	global_load_lds_dwordx4 v[164:165], off
	v_lshl_add_u64 v[164:165], v[152:153], 0, s[88:89]
	s_mov_b32 m0, s11
	s_nop 0
	global_load_lds_dwordx4 v[164:165], off
	s_barrier
	s_waitcnt lgkmcnt(0)
	s_waitcnt lgkmcnt(0)
	v_mfma_f32_16x16x32_bf16 v[62:65], v[178:181], v[194:197], v[62:65]
	v_mfma_f32_16x16x32_bf16 v[58:61], v[186:189], v[194:197], v[58:61]
	v_mfma_f32_16x16x32_bf16 v[54:57], v[178:181], v[202:205], v[54:57]
	v_mfma_f32_16x16x32_bf16 v[50:53], v[186:189], v[202:205], v[50:53]
	v_mfma_f32_16x16x32_bf16 v[46:49], v[178:181], v[210:213], v[46:49]
	v_mfma_f32_16x16x32_bf16 v[42:45], v[186:189], v[210:213], v[42:45]
	v_mfma_f32_16x16x32_bf16 v[38:41], v[178:181], v[218:221], v[38:41]
	v_mfma_f32_16x16x32_bf16 v[34:37], v[186:189], v[218:221], v[34:37]
	v_mfma_f32_16x16x32_bf16 v[62:65], v[182:185], v[198:201], v[62:65]
	v_mfma_f32_16x16x32_bf16 v[58:61], v[190:193], v[198:201], v[58:61]
	v_mfma_f32_16x16x32_bf16 v[54:57], v[182:185], v[206:209], v[54:57]
	v_mfma_f32_16x16x32_bf16 v[50:53], v[190:193], v[206:209], v[50:53]
	v_mfma_f32_16x16x32_bf16 v[46:49], v[182:185], v[214:217], v[46:49]
	v_mfma_f32_16x16x32_bf16 v[42:45], v[190:193], v[214:217], v[42:45]
	v_mfma_f32_16x16x32_bf16 v[38:41], v[182:185], v[222:225], v[38:41]
	v_mfma_f32_16x16x32_bf16 v[34:37], v[190:193], v[222:225], v[34:37]
	s_barrier
; #define WAIT_V(n) asm volatile("s_waitcnt vmcnt(%0)" ::"n"(n) : "memory")
; #define WAIT_L(n) asm volatile("s_waitcnt lgkmcnt(%0)" ::"n"(n) : "memory")
; #define SBAR() __builtin_amdgcn_sched_barrier(0)
; #define LDA8(dst, b, h) _Pragma("unroll") for (int m = 0; m < 4; ++m) _Pragma("unroll") for (int k = 0; k < 2; ++k) \
;     dst[m][k] = *(const bf16x8*)(abase + SAo(b, h) + m * 2048 + k * 1024)
; #define LDB8(dst, b, h) _Pragma("unroll") for (int n = 0; n < 2; ++n) _Pragma("unroll") for (int k = 0; k < 2; ++k) \
;     dst[n][k] = *(const bf16x8*)(bbase + SAo(b, h) + n * 2048 + k * 1024)
; #define BAR8 __builtin_amdgcn_s_barrier()
; __device__ __forceinline__ void gemm_main8(const u16* __restrict__ Ab, int lda, const u16* __restrict__ Bb, int ldb, int K,
;                                            char* shm, f32x4 (&acc)[2][2][4][2]) {
;     ...
;     STG_B(0, 1, t + 2);
;     WAIT_V(6); BAR8; MMA8(1, 1, At, B1); BAR8;
;     LDB8(B0, 1, 0); SBAR(); LDA8(At, 1, 0); STG_A(0, 1, t + 2);
;     WAIT_L(8); BAR8; WAIT_L(0); MMA8(0, 0, At, B0); BAR8; SBAR();
;     LDB8(B1, 1, 1); STG_B(1, 0, t + 3);
;     BAR8; WAIT_L(0); MMA8(0, 1, At, B1); BAR8;
;     LDA8(At, 1, 1); STG_A(1, 0, t + 3);
	v_readfirstlane_b32 s11, v145
	v_lshl_add_u64 v[164:165], v[154:155], 0, s[62:63]
	s_mov_b32 m0, s11
	v_readfirstlane_b32 s11, v146
	global_load_lds_dwordx4 v[164:165], off
	v_lshl_add_u64 v[164:165], v[154:155], 0, s[64:65]
	s_mov_b32 m0, s11
	s_nop 0
	global_load_lds_dwordx4 v[164:165], off
	s_waitcnt vmcnt(6)
	s_barrier
	v_mfma_f32_16x16x32_bf16 v[30:33], v[226:229], v[194:197], v[30:33]
	v_mfma_f32_16x16x32_bf16 v[26:29], v[234:237], v[194:197], v[26:29]
	v_mfma_f32_16x16x32_bf16 v[22:25], v[226:229], v[202:205], v[22:25]
	v_mfma_f32_16x16x32_bf16 v[18:21], v[234:237], v[202:205], v[18:21]
	v_mfma_f32_16x16x32_bf16 v[14:17], v[226:229], v[210:213], v[14:17]
	v_mfma_f32_16x16x32_bf16 v[10:13], v[234:237], v[210:213], v[10:13]
	v_mfma_f32_16x16x32_bf16 v[6:9], v[226:229], v[218:221], v[6:9]
	v_mfma_f32_16x16x32_bf16 v[2:5], v[234:237], v[218:221], v[2:5]
	v_mfma_f32_16x16x32_bf16 v[30:33], v[230:233], v[198:201], v[30:33]
	v_mfma_f32_16x16x32_bf16 v[26:29], v[238:241], v[198:201], v[26:29]
	v_mfma_f32_16x16x32_bf16 v[22:25], v[230:233], v[206:209], v[22:25]
	v_mfma_f32_16x16x32_bf16 v[18:21], v[238:241], v[206:209], v[18:21]
	v_mfma_f32_16x16x32_bf16 v[14:17], v[230:233], v[214:217], v[14:17]
	v_mfma_f32_16x16x32_bf16 v[10:13], v[238:241], v[214:217], v[10:13]
	v_mfma_f32_16x16x32_bf16 v[6:9], v[230:233], v[222:225], v[6:9]
	v_mfma_f32_16x16x32_bf16 v[2:5], v[238:241], v[222:225], v[2:5]
	s_barrier
	ds_read_b128 v[178:181], v140 offset:32768
	ds_read_b128 v[182:185], v140 offset:33792
	ds_read_b128 v[186:189], v140 offset:34816
	ds_read_b128 v[190:193], v140 offset:35840
	ds_read_b128 v[194:197], v0 offset:32768
	ds_read_b128 v[198:201], v0 offset:33792
	ds_read_b128 v[202:205], v0 offset:34816
	ds_read_b128 v[206:209], v0 offset:35840
	ds_read_b128 v[210:213], v0 offset:36864
	ds_read_b128 v[214:217], v0 offset:37888
	ds_read_b128 v[218:221], v0 offset:38912
	ds_read_b128 v[222:225], v0 offset:39936
	s_mov_b64 s[88:89], 0x10220100
	v_readfirstlane_b32 s11, v147
	v_lshl_add_u64 v[164:165], v[152:153], 0, s[88:89]
	s_mov_b32 m0, s11
	s_mov_b64 s[88:89], 0x10230100
	v_readfirstlane_b32 s11, v148
	global_load_lds_dwordx4 v[164:165], off
	v_lshl_add_u64 v[164:165], v[152:153], 0, s[88:89]
	s_mov_b32 m0, s11
	s_nop 0
	global_load_lds_dwordx4 v[164:165], off
	s_waitcnt lgkmcnt(8)
	s_barrier
	s_waitcnt lgkmcnt(0)
	s_waitcnt lgkmcnt(0)
	v_mfma_f32_16x16x32_bf16 v[126:129], v[178:181], v[194:197], v[126:129]
	v_mfma_f32_16x16x32_bf16 v[122:125], v[186:189], v[194:197], v[122:125]
	v_mfma_f32_16x16x32_bf16 v[118:121], v[178:181], v[202:205], v[118:121]
	v_mfma_f32_16x16x32_bf16 v[114:117], v[186:189], v[202:205], v[114:117]
	v_mfma_f32_16x16x32_bf16 v[110:113], v[178:181], v[210:213], v[110:113]
	v_mfma_f32_16x16x32_bf16 v[106:109], v[186:189], v[210:213], v[106:109]
	v_mfma_f32_16x16x32_bf16 v[102:105], v[178:181], v[218:221], v[102:105]
	v_mfma_f32_16x16x32_bf16 v[98:101], v[186:189], v[218:221], v[98:101]
	v_mfma_f32_16x16x32_bf16 v[126:129], v[182:185], v[198:201], v[126:129]
	v_mfma_f32_16x16x32_bf16 v[122:125], v[190:193], v[198:201], v[122:125]
	v_mfma_f32_16x16x32_bf16 v[118:121], v[182:185], v[206:209], v[118:121]
	v_mfma_f32_16x16x32_bf16 v[114:117], v[190:193], v[206:209], v[114:117]
	v_mfma_f32_16x16x32_bf16 v[110:113], v[182:185], v[214:217], v[110:113]
	v_mfma_f32_16x16x32_bf16 v[106:109], v[190:193], v[214:217], v[106:109]
	v_mfma_f32_16x16x32_bf16 v[102:105], v[182:185], v[222:225], v[102:105]
	v_mfma_f32_16x16x32_bf16 v[98:101], v[190:193], v[222:225], v[98:101]
	s_barrier
	ds_read_b128 v[226:229], v140 offset:49152
	ds_read_b128 v[230:233], v140 offset:50176
	ds_read_b128 v[234:237], v140 offset:51200
	ds_read_b128 v[238:241], v140 offset:52224
	v_readfirstlane_b32 s11, v149
	v_lshl_add_u64 v[164:165], v[154:155], 0, s[66:67]
	s_mov_b32 m0, s11
	v_readfirstlane_b32 s11, v171
	global_load_lds_dwordx4 v[164:165], off
	v_lshl_add_u64 v[164:165], v[154:155], 0, s[68:69]
	s_mov_b32 m0, s11
	s_nop 0
	global_load_lds_dwordx4 v[164:165], off
	s_barrier
	s_waitcnt lgkmcnt(0)
	s_waitcnt lgkmcnt(0)
	v_mfma_f32_16x16x32_bf16 v[94:97], v[226:229], v[194:197], v[94:97]
	v_mfma_f32_16x16x32_bf16 v[90:93], v[234:237], v[194:197], v[90:93]
	v_mfma_f32_16x16x32_bf16 v[86:89], v[226:229], v[202:205], v[86:89]
	v_mfma_f32_16x16x32_bf16 v[82:85], v[234:237], v[202:205], v[82:85]
	v_mfma_f32_16x16x32_bf16 v[78:81], v[226:229], v[210:213], v[78:81]
	v_mfma_f32_16x16x32_bf16 v[74:77], v[234:237], v[210:213], v[74:77]
	v_mfma_f32_16x16x32_bf16 v[70:73], v[226:229], v[218:221], v[70:73]
	v_mfma_f32_16x16x32_bf16 v[66:69], v[234:237], v[218:221], v[66:69]
	v_mfma_f32_16x16x32_bf16 v[94:97], v[230:233], v[198:201], v[94:97]
	v_mfma_f32_16x16x32_bf16 v[90:93], v[238:241], v[198:201], v[90:93]
	v_mfma_f32_16x16x32_bf16 v[86:89], v[230:233], v[206:209], v[86:89]
	v_mfma_f32_16x16x32_bf16 v[82:85], v[238:241], v[206:209], v[82:85]
	v_mfma_f32_16x16x32_bf16 v[78:81], v[230:233], v[214:217], v[78:81]
	v_mfma_f32_16x16x32_bf16 v[74:77], v[238:241], v[214:217], v[74:77]
	v_mfma_f32_16x16x32_bf16 v[70:73], v[230:233], v[222:225], v[70:73]
	v_mfma_f32_16x16x32_bf16 v[66:69], v[238:241], v[222:225], v[66:69]
	s_mov_b64 s[88:89], 0x10200180
	v_readfirstlane_b32 s11, v172
	v_lshl_add_u64 v[164:165], v[152:153], 0, s[88:89]
	s_mov_b32 m0, s11
	s_mov_b64 s[88:89], 0x10210180
	v_readfirstlane_b32 s11, v173
	s_barrier
; #define WAIT_V(n) asm volatile("s_waitcnt vmcnt(%0)" ::"n"(n) : "memory")
; #define WAIT_L(n) asm volatile("s_waitcnt lgkmcnt(%0)" ::"n"(n) : "memory")
; #define SBAR() __builtin_amdgcn_sched_barrier(0)
; #define LDA8(dst, b, h) _Pragma("unroll") for (int m = 0; m < 4; ++m) _Pragma("unroll") for (int k = 0; k < 2; ++k) \
;     dst[m][k] = *(const bf16x8*)(abase + SAo(b, h) + m * 2048 + k * 1024)
; #define LDB8(dst, b, h) _Pragma("unroll") for (int n = 0; n < 2; ++n) _Pragma("unroll") for (int k = 0; k < 2; ++k) \
;     dst[n][k] = *(const bf16x8*)(bbase + SAo(b, h) + n * 2048 + k * 1024)
; #define BAR8 __builtin_amdgcn_s_barrier()
; __device__ __forceinline__ void gemm_main8(const u16* __restrict__ Ab, int lda, const u16* __restrict__ Bb, int ldb, int K,
;                                            char* shm, f32x4 (&acc)[2][2][4][2]) {
;     ...
;     LDA8(At, 1, 1); STG_A(1, 0, t + 3);
;     BAR8; WAIT_L(0); MMA8(1, 0, At, B0); BAR8; SBAR();
;     STG_B(1, 1, t + 3);
;     WAIT_V(6); BAR8; MMA8(1, 1, At, B1); BAR8;
;   }
;   { LDB8(B0, 0, 0); LDA8(At, 0, 0); STG_A(1, 1, nt - 1);
;     BAR8; WAIT_L(0); MMA8(0, 0, At, B0); BAR8;
	ds_read_b128 v[194:197], v0 offset:49152
	ds_read_b128 v[198:201], v0 offset:50176
	ds_read_b128 v[202:205], v0 offset:51200
	ds_read_b128 v[206:209], v0 offset:52224
	ds_read_b128 v[210:213], v0 offset:53248
	ds_read_b128 v[214:217], v0 offset:54272
	ds_read_b128 v[218:221], v0 offset:55296
	ds_read_b128 v[222:225], v0 offset:56320
	global_load_lds_dwordx4 v[164:165], off
	v_lshl_add_u64 v[152:153], v[152:153], 0, s[88:89]
	s_mov_b32 m0, s11
	s_nop 0
	global_load_lds_dwordx4 v[152:153], off
	s_barrier
	s_waitcnt lgkmcnt(0)
	s_waitcnt lgkmcnt(0)
	v_mfma_f32_16x16x32_bf16 v[62:65], v[178:181], v[194:197], v[62:65]
	v_mfma_f32_16x16x32_bf16 v[58:61], v[186:189], v[194:197], v[58:61]
	v_mfma_f32_16x16x32_bf16 v[54:57], v[178:181], v[202:205], v[54:57]
	v_mfma_f32_16x16x32_bf16 v[50:53], v[186:189], v[202:205], v[50:53]
	v_mfma_f32_16x16x32_bf16 v[46:49], v[178:181], v[210:213], v[46:49]
	v_mfma_f32_16x16x32_bf16 v[42:45], v[186:189], v[210:213], v[42:45]
	v_mfma_f32_16x16x32_bf16 v[38:41], v[178:181], v[218:221], v[38:41]
	v_mfma_f32_16x16x32_bf16 v[34:37], v[186:189], v[218:221], v[34:37]
	v_mfma_f32_16x16x32_bf16 v[62:65], v[182:185], v[198:201], v[62:65]
	v_mfma_f32_16x16x32_bf16 v[58:61], v[190:193], v[198:201], v[58:61]
	v_mfma_f32_16x16x32_bf16 v[54:57], v[182:185], v[206:209], v[54:57]
	v_mfma_f32_16x16x32_bf16 v[50:53], v[190:193], v[206:209], v[50:53]
	v_mfma_f32_16x16x32_bf16 v[46:49], v[182:185], v[214:217], v[46:49]
	v_mfma_f32_16x16x32_bf16 v[42:45], v[190:193], v[214:217], v[42:45]
	v_mfma_f32_16x16x32_bf16 v[38:41], v[182:185], v[222:225], v[38:41]
	v_mfma_f32_16x16x32_bf16 v[34:37], v[190:193], v[222:225], v[34:37]
	s_barrier
	s_mov_b64 s[88:89], 0x13380180
	v_readfirstlane_b32 s11, v174
	v_lshl_add_u64 v[152:153], v[154:155], 0, s[88:89]
	s_mov_b32 m0, s11
	s_mov_b64 s[88:89], 0x133c0180
	v_readfirstlane_b32 s11, v175
	global_load_lds_dwordx4 v[152:153], off
	v_lshl_add_u64 v[152:153], v[154:155], 0, s[88:89]
	s_mov_b32 m0, s11
	s_nop 0
	global_load_lds_dwordx4 v[152:153], off
	s_waitcnt vmcnt(6)
	s_barrier
	v_mfma_f32_16x16x32_bf16 v[30:33], v[226:229], v[194:197], v[30:33]
	v_mfma_f32_16x16x32_bf16 v[26:29], v[234:237], v[194:197], v[26:29]
	v_mfma_f32_16x16x32_bf16 v[22:25], v[226:229], v[202:205], v[22:25]
	v_mfma_f32_16x16x32_bf16 v[18:21], v[234:237], v[202:205], v[18:21]
	v_mfma_f32_16x16x32_bf16 v[14:17], v[226:229], v[210:213], v[14:17]
	v_mfma_f32_16x16x32_bf16 v[10:13], v[234:237], v[210:213], v[10:13]
	v_mfma_f32_16x16x32_bf16 v[6:9], v[226:229], v[218:221], v[6:9]
	v_mfma_f32_16x16x32_bf16 v[2:5], v[234:237], v[218:221], v[2:5]
	v_mfma_f32_16x16x32_bf16 v[30:33], v[230:233], v[198:201], v[30:33]
	v_mfma_f32_16x16x32_bf16 v[26:29], v[238:241], v[198:201], v[26:29]
	v_mfma_f32_16x16x32_bf16 v[22:25], v[230:233], v[206:209], v[22:25]
	v_mfma_f32_16x16x32_bf16 v[18:21], v[238:241], v[206:209], v[18:21]
	v_mfma_f32_16x16x32_bf16 v[14:17], v[230:233], v[214:217], v[14:17]
	v_mfma_f32_16x16x32_bf16 v[10:13], v[238:241], v[214:217], v[10:13]
	v_mfma_f32_16x16x32_bf16 v[6:9], v[230:233], v[222:225], v[6:9]
	v_mfma_f32_16x16x32_bf16 v[2:5], v[238:241], v[222:225], v[2:5]
	s_add_i32 s10, s10, 2
	s_add_u32 s24, s24, 0x100
	s_addc_u32 s25, s25, 0
	s_cmp_lt_u32 s10, 4
	s_barrier
	s_cbranch_scc1 .LBB0_605
	s_mov_b64 s[10:11], 0x20380
	v_lshl_add_u64 v[152:153], v[130:131], 0, s[10:11]
	v_readfirstlane_b32 s10, v176
	s_mov_b32 m0, s10
	s_mov_b64 s[10:11], 0x30380
	v_lshl_add_u64 v[130:131], v[130:131], 0, s[10:11]
	v_readfirstlane_b32 s10, v177
	ds_read_b128 v[132:135], v140
	ds_read_b128 v[142:145], v140 offset:1024
	ds_read_b128 v[146:149], v140 offset:2048
	ds_read_b128 v[172:175], v140 offset:3072
	ds_read_b128 v[178:181], v0
	ds_read_b128 v[182:185], v0 offset:1024
	ds_read_b128 v[186:189], v0 offset:2048
	ds_read_b128 v[190:193], v0 offset:3072
	ds_read_b128 v[194:197], v0 offset:4096
	ds_read_b128 v[198:201], v0 offset:5120
	ds_read_b128 v[202:205], v0 offset:6144
	ds_read_b128 v[206:209], v0 offset:7168
	global_load_lds_dwordx4 v[152:153], off
	s_mov_b32 m0, s10
	s_nop 0
	global_load_lds_dwordx4 v[130:131], off
	s_barrier
	s_waitcnt lgkmcnt(0)
	s_waitcnt lgkmcnt(0)
	v_mfma_f32_16x16x32_bf16 v[126:129], v[132:135], v[178:181], v[126:129]
	v_mfma_f32_16x16x32_bf16 v[122:125], v[146:149], v[178:181], v[122:125]
	v_mfma_f32_16x16x32_bf16 v[114:117], v[146:149], v[186:189], v[114:117]
	v_mfma_f32_16x16x32_bf16 v[106:109], v[146:149], v[194:197], v[106:109]
	v_mfma_f32_16x16x32_bf16 v[98:101], v[146:149], v[202:205], v[98:101]
	v_mfma_f32_16x16x32_bf16 v[126:129], v[142:145], v[182:185], v[126:129]
	v_mfma_f32_16x16x32_bf16 v[122:125], v[172:175], v[182:185], v[122:125]
	v_mfma_f32_16x16x32_bf16 v[118:121], v[132:135], v[186:189], v[118:121]
	v_mfma_f32_16x16x32_bf16 v[114:117], v[172:175], v[190:193], v[114:117]
	v_mfma_f32_16x16x32_bf16 v[110:113], v[132:135], v[194:197], v[110:113]
	v_mfma_f32_16x16x32_bf16 v[106:109], v[172:175], v[198:201], v[106:109]
	v_mfma_f32_16x16x32_bf16 v[102:105], v[132:135], v[202:205], v[102:105]
	v_mfma_f32_16x16x32_bf16 v[98:101], v[172:175], v[206:209], v[98:101]
	v_mfma_f32_16x16x32_bf16 v[210:213], v[142:145], v[190:193], v[118:121]
	v_mfma_f32_16x16x32_bf16 v[214:217], v[142:145], v[198:201], v[110:113]
	v_mfma_f32_16x16x32_bf16 v[218:221], v[142:145], v[206:209], v[102:105]
	s_barrier
	s_nop 1
	ds_read_b128 v[102:105], v140 offset:16384
	ds_read_b128 v[110:113], v140 offset:17408
	ds_read_b128 v[118:121], v140 offset:18432
	ds_read_b128 v[222:225], v140 offset:19456
	s_barrier
; #define WAIT_V(n) asm volatile("s_waitcnt vmcnt(%0)" ::"n"(n) : "memory")
; #define WAIT_L(n) asm volatile("s_waitcnt lgkmcnt(%0)" ::"n"(n) : "memory")
; #define LDA8(dst, b, h) _Pragma("unroll") for (int m = 0; m < 4; ++m) _Pragma("unroll") for (int k = 0; k < 2; ++k) \
;     dst[m][k] = *(const bf16x8*)(abase + SAo(b, h) + m * 2048 + k * 1024)
; #define LDB8(dst, b, h) _Pragma("unroll") for (int n = 0; n < 2; ++n) _Pragma("unroll") for (int k = 0; k < 2; ++k) \
;     dst[n][k] = *(const bf16x8*)(bbase + SAo(b, h) + n * 2048 + k * 1024)
; #define BAR8 __builtin_amdgcn_s_barrier()
; __device__ __forceinline__ void gemm_main8(const u16* __restrict__ Ab, int lda, const u16* __restrict__ Bb, int ldb, int K,
;                                            char* shm, f32x4 (&acc)[2][2][4][2]) {
;     ...
;     LDB8(B1, 0, 1); BAR8; WAIT_L(0); MMA8(0, 1, At, B1); BAR8;
;     LDA8(At, 0, 1); WAIT_V(4); BAR8; WAIT_L(0); MMA8(1, 0, At, B0); MMA8(1, 1, At, B1); BAR8; }
;   { LDB8(B0, 1, 0); LDA8(At, 1, 0); WAIT_V(2); BAR8; WAIT_L(0); MMA8(0, 0, At, B0); BAR8;
	s_waitcnt lgkmcnt(0)
	s_waitcnt lgkmcnt(0)
	v_mfma_f32_16x16x32_bf16 v[90:93], v[118:121], v[178:181], v[90:93]
	v_mfma_f32_16x16x32_bf16 v[82:85], v[118:121], v[186:189], v[82:85]
	v_mfma_f32_16x16x32_bf16 v[74:77], v[118:121], v[194:197], v[74:77]
	v_mfma_f32_16x16x32_bf16 v[66:69], v[118:121], v[202:205], v[66:69]
	v_mfma_f32_16x16x32_bf16 v[94:97], v[102:105], v[178:181], v[94:97]
	v_mfma_f32_16x16x32_bf16 v[90:93], v[222:225], v[182:185], v[90:93]
	v_mfma_f32_16x16x32_bf16 v[86:89], v[102:105], v[186:189], v[86:89]
	v_mfma_f32_16x16x32_bf16 v[82:85], v[222:225], v[190:193], v[82:85]
	v_mfma_f32_16x16x32_bf16 v[78:81], v[102:105], v[194:197], v[78:81]
	v_mfma_f32_16x16x32_bf16 v[74:77], v[222:225], v[198:201], v[74:77]
	v_mfma_f32_16x16x32_bf16 v[70:73], v[102:105], v[202:205], v[70:73]
	v_mfma_f32_16x16x32_bf16 v[66:69], v[222:225], v[206:209], v[66:69]
	v_mfma_f32_16x16x32_bf16 v[226:229], v[110:113], v[182:185], v[94:97]
	v_mfma_f32_16x16x32_bf16 v[176:179], v[110:113], v[190:193], v[86:89]
	v_mfma_f32_16x16x32_bf16 v[180:183], v[110:113], v[198:201], v[78:81]
	v_mfma_f32_16x16x32_bf16 v[184:187], v[110:113], v[206:209], v[70:73]
	s_barrier
	s_nop 0
	ds_read_b128 v[70:73], v0 offset:16384
	ds_read_b128 v[78:81], v0 offset:17408
	ds_read_b128 v[86:89], v0 offset:18432
	ds_read_b128 v[94:97], v0 offset:19456
	ds_read_b128 v[188:191], v0 offset:20480
	ds_read_b128 v[192:195], v0 offset:21504
	ds_read_b128 v[196:199], v0 offset:22528
	ds_read_b128 v[200:203], v0 offset:23552
	s_waitcnt vmcnt(4)
	s_barrier
	s_waitcnt lgkmcnt(0)
	s_waitcnt lgkmcnt(0)
	v_mfma_f32_16x16x32_bf16 v[62:65], v[132:135], v[70:73], v[62:65]
	v_mfma_f32_16x16x32_bf16 v[58:61], v[146:149], v[70:73], v[58:61]
	v_mfma_f32_16x16x32_bf16 v[54:57], v[132:135], v[86:89], v[54:57]
	v_mfma_f32_16x16x32_bf16 v[50:53], v[146:149], v[86:89], v[50:53]
	v_mfma_f32_16x16x32_bf16 v[38:41], v[132:135], v[196:199], v[38:41]
	v_mfma_f32_16x16x32_bf16 v[34:37], v[146:149], v[196:199], v[34:37]
	v_mfma_f32_16x16x32_bf16 v[62:65], v[142:145], v[78:81], v[62:65]
	v_mfma_f32_16x16x32_bf16 v[58:61], v[172:175], v[78:81], v[58:61]
	v_mfma_f32_16x16x32_bf16 v[54:57], v[142:145], v[94:97], v[54:57]
	v_mfma_f32_16x16x32_bf16 v[50:53], v[172:175], v[94:97], v[50:53]
	v_mfma_f32_16x16x32_bf16 v[46:49], v[132:135], v[188:191], v[46:49]
	v_mfma_f32_16x16x32_bf16 v[42:45], v[146:149], v[188:191], v[42:45]
	v_mfma_f32_16x16x32_bf16 v[38:41], v[142:145], v[200:203], v[38:41]
	v_mfma_f32_16x16x32_bf16 v[34:37], v[172:175], v[200:203], v[34:37]
	v_mfma_f32_16x16x32_bf16 v[204:207], v[142:145], v[192:195], v[46:49]
	v_mfma_f32_16x16x32_bf16 v[230:233], v[172:175], v[192:195], v[42:45]
	v_mfma_f32_16x16x32_bf16 v[22:25], v[102:105], v[86:89], v[22:25]
	v_mfma_f32_16x16x32_bf16 v[18:21], v[118:121], v[86:89], v[18:21]
	v_mfma_f32_16x16x32_bf16 v[6:9], v[102:105], v[196:199], v[6:9]
	v_mfma_f32_16x16x32_bf16 v[2:5], v[118:121], v[196:199], v[2:5]
	v_mfma_f32_16x16x32_bf16 v[30:33], v[102:105], v[70:73], v[30:33]
	v_mfma_f32_16x16x32_bf16 v[26:29], v[118:121], v[70:73], v[26:29]
	v_mfma_f32_16x16x32_bf16 v[22:25], v[110:113], v[94:97], v[22:25]
	v_mfma_f32_16x16x32_bf16 v[18:21], v[222:225], v[94:97], v[18:21]
	v_mfma_f32_16x16x32_bf16 v[14:17], v[102:105], v[188:191], v[14:17]
	v_mfma_f32_16x16x32_bf16 v[10:13], v[118:121], v[188:191], v[10:13]
	v_mfma_f32_16x16x32_bf16 v[6:9], v[110:113], v[200:203], v[6:9]
	v_mfma_f32_16x16x32_bf16 v[2:5], v[222:225], v[200:203], v[2:5]
	v_mfma_f32_16x16x32_bf16 v[130:133], v[110:113], v[78:81], v[30:33]
	v_mfma_f32_16x16x32_bf16 v[142:145], v[222:225], v[78:81], v[26:29]
	v_mfma_f32_16x16x32_bf16 v[146:149], v[110:113], v[192:195], v[14:17]
	v_mfma_f32_16x16x32_bf16 v[172:175], v[222:225], v[192:195], v[10:13]
	s_barrier
	s_nop 0
	ds_read_b128 v[10:13], v140 offset:32768
	ds_read_b128 v[14:17], v140 offset:33792
	ds_read_b128 v[188:191], v140 offset:34816
	ds_read_b128 v[192:195], v140 offset:35840
	ds_read_b128 v[26:29], v0 offset:32768
	ds_read_b128 v[30:33], v0 offset:33792
	ds_read_b128 v[42:45], v0 offset:34816
	ds_read_b128 v[46:49], v0 offset:35840
	ds_read_b128 v[196:199], v0 offset:36864
	ds_read_b128 v[200:203], v0 offset:37888
	ds_read_b128 v[222:225], v0 offset:38912
	ds_read_b128 v[234:237], v0 offset:39936
	s_waitcnt vmcnt(2)
	s_barrier
; #define WAIT_V(n) asm volatile("s_waitcnt vmcnt(%0)" ::"n"(n) : "memory")
; #define WAIT_L(n) asm volatile("s_waitcnt lgkmcnt(%0)" ::"n"(n) : "memory")
; #define LDA8(dst, b, h) _Pragma("unroll") for (int m = 0; m < 4; ++m) _Pragma("unroll") for (int k = 0; k < 2; ++k) \
;     dst[m][k] = *(const bf16x8*)(abase + SAo(b, h) + m * 2048 + k * 1024)
; #define LDB8(dst, b, h) _Pragma("unroll") for (int n = 0; n < 2; ++n) _Pragma("unroll") for (int k = 0; k < 2; ++k) \
;     dst[n][k] = *(const bf16x8*)(bbase + SAo(b, h) + n * 2048 + k * 1024)
; #define BAR8 __builtin_amdgcn_s_barrier()
; __device__ __forceinline__ void gemm_main8(const u16* __restrict__ Ab, int lda, const u16* __restrict__ Bb, int ldb, int K,
;                                            char* shm, f32x4 (&acc)[2][2][4][2]) {
;     ...
;   { LDB8(B0, 1, 0); LDA8(At, 1, 0); WAIT_V(2); BAR8; WAIT_L(0); MMA8(0, 0, At, B0); BAR8;
;     LDB8(B1, 1, 1); WAIT_V(0); BAR8; WAIT_L(0); MMA8(0, 1, At, B1); BAR8;
;     LDA8(At, 1, 1); BAR8; WAIT_L(0); MMA8(1, 0, At, B0); MMA8(1, 1, At, B1); BAR8; }
;   if (wr == 0) BAR8;
	s_waitcnt lgkmcnt(0)
	s_waitcnt lgkmcnt(0)
	v_mfma_f32_16x16x32_bf16 v[70:73], v[10:13], v[26:29], v[126:129]
	v_mfma_f32_16x16x32_bf16 v[126:129], v[14:17], v[30:33], v[70:73]
	v_mfma_f32_16x16x32_bf16 v[70:73], v[188:191], v[26:29], v[122:125]
	v_mfma_f32_16x16x32_bf16 v[118:121], v[192:195], v[30:33], v[70:73]
	v_mfma_f32_16x16x32_bf16 v[70:73], v[10:13], v[42:45], v[210:213]
	v_mfma_f32_16x16x32_bf16 v[110:113], v[14:17], v[46:49], v[70:73]
	v_mfma_f32_16x16x32_bf16 v[70:73], v[188:191], v[42:45], v[114:117]
	v_mfma_f32_16x16x32_bf16 v[102:105], v[192:195], v[46:49], v[70:73]
	v_mfma_f32_16x16x32_bf16 v[70:73], v[10:13], v[196:199], v[214:217]
	v_mfma_f32_16x16x32_bf16 v[94:97], v[14:17], v[200:203], v[70:73]
	v_mfma_f32_16x16x32_bf16 v[70:73], v[188:191], v[196:199], v[106:109]
	v_mfma_f32_16x16x32_bf16 v[86:89], v[192:195], v[200:203], v[70:73]
	v_mfma_f32_16x16x32_bf16 v[70:73], v[10:13], v[222:225], v[218:221]
	v_mfma_f32_16x16x32_bf16 v[78:81], v[14:17], v[234:237], v[70:73]
	v_mfma_f32_16x16x32_bf16 v[70:73], v[188:191], v[222:225], v[98:101]
	v_mfma_f32_16x16x32_bf16 v[70:73], v[192:195], v[234:237], v[70:73]
	s_barrier
	ds_read_b128 v[208:211], v140 offset:49152
	ds_read_b128 v[212:215], v140 offset:50176
	ds_read_b128 v[216:219], v140 offset:51200
	ds_read_b128 v[238:241], v140 offset:52224
	s_waitcnt vmcnt(0)
	s_barrier
	s_waitcnt lgkmcnt(0)
	s_waitcnt lgkmcnt(0)
	v_mfma_f32_16x16x32_bf16 v[98:101], v[208:211], v[26:29], v[226:229]
	v_mfma_f32_16x16x32_bf16 v[26:29], v[216:219], v[26:29], v[90:93]
	v_mfma_f32_16x16x32_bf16 v[114:117], v[238:241], v[30:33], v[26:29]
	v_mfma_f32_16x16x32_bf16 v[26:29], v[208:211], v[42:45], v[176:179]
	v_mfma_f32_16x16x32_bf16 v[106:109], v[212:215], v[46:49], v[26:29]
	v_mfma_f32_16x16x32_bf16 v[26:29], v[216:219], v[42:45], v[82:85]
	v_mfma_f32_16x16x32_bf16 v[122:125], v[212:215], v[30:33], v[98:101]
	v_mfma_f32_16x16x32_bf16 v[98:101], v[238:241], v[46:49], v[26:29]
	v_mfma_f32_16x16x32_bf16 v[26:29], v[208:211], v[196:199], v[180:183]
	v_mfma_f32_16x16x32_bf16 v[90:93], v[212:215], v[200:203], v[26:29]
	v_mfma_f32_16x16x32_bf16 v[26:29], v[216:219], v[196:199], v[74:77]
	v_mfma_f32_16x16x32_bf16 v[82:85], v[238:241], v[200:203], v[26:29]
	v_mfma_f32_16x16x32_bf16 v[26:29], v[208:211], v[222:225], v[184:187]
	v_mfma_f32_16x16x32_bf16 v[74:77], v[212:215], v[234:237], v[26:29]
	v_mfma_f32_16x16x32_bf16 v[26:29], v[216:219], v[222:225], v[66:69]
	v_mfma_f32_16x16x32_bf16 v[66:69], v[238:241], v[234:237], v[26:29]
	s_barrier
	ds_read_b128 v[176:179], v0 offset:49152
	ds_read_b128 v[180:183], v0 offset:50176
	ds_read_b128 v[184:187], v0 offset:51200
	ds_read_b128 v[196:199], v0 offset:52224
	ds_read_b128 v[200:203], v0 offset:53248
	ds_read_b128 v[220:223], v0 offset:54272
	ds_read_b128 v[224:227], v0 offset:55296
	ds_read_b128 v[234:237], v0 offset:56320
	s_barrier
	s_waitcnt lgkmcnt(0)
	s_waitcnt lgkmcnt(0)
	v_mfma_f32_16x16x32_bf16 v[26:29], v[10:13], v[176:179], v[62:65]
	v_mfma_f32_16x16x32_bf16 v[62:65], v[14:17], v[180:183], v[26:29]
	v_mfma_f32_16x16x32_bf16 v[26:29], v[188:191], v[176:179], v[58:61]
	v_mfma_f32_16x16x32_bf16 v[58:61], v[192:195], v[180:183], v[26:29]
	v_mfma_f32_16x16x32_bf16 v[26:29], v[10:13], v[184:187], v[54:57]
	v_mfma_f32_16x16x32_bf16 v[46:49], v[14:17], v[196:199], v[26:29]
	v_mfma_f32_16x16x32_bf16 v[26:29], v[188:191], v[184:187], v[50:53]
	v_mfma_f32_16x16x32_bf16 v[42:45], v[192:195], v[196:199], v[26:29]
	v_mfma_f32_16x16x32_bf16 v[26:29], v[10:13], v[200:203], v[204:207]
	v_mfma_f32_16x16x32_bf16 v[10:13], v[10:13], v[224:227], v[38:41]
	v_mfma_f32_16x16x32_bf16 v[30:33], v[14:17], v[220:223], v[26:29]
	v_mfma_f32_16x16x32_bf16 v[26:29], v[188:191], v[200:203], v[230:233]
	v_mfma_f32_16x16x32_bf16 v[14:17], v[14:17], v[234:237], v[10:13]
	v_mfma_f32_16x16x32_bf16 v[10:13], v[188:191], v[224:227], v[34:37]
	v_mfma_f32_16x16x32_bf16 v[26:29], v[192:195], v[220:223], v[26:29]
	v_mfma_f32_16x16x32_bf16 v[10:13], v[192:195], v[234:237], v[10:13]
	v_mfma_f32_16x16x32_bf16 v[34:37], v[208:211], v[176:179], v[130:133]
	v_mfma_f32_16x16x32_bf16 v[54:57], v[212:215], v[180:183], v[34:37]
	v_mfma_f32_16x16x32_bf16 v[34:37], v[216:219], v[176:179], v[142:145]
	v_mfma_f32_16x16x32_bf16 v[18:21], v[216:219], v[184:187], v[18:21]
	v_mfma_f32_16x16x32_bf16 v[50:53], v[238:241], v[180:183], v[34:37]
	v_mfma_f32_16x16x32_bf16 v[22:25], v[208:211], v[184:187], v[22:25]
	v_mfma_f32_16x16x32_bf16 v[34:37], v[238:241], v[196:199], v[18:21]
	v_mfma_f32_16x16x32_bf16 v[18:21], v[208:211], v[200:203], v[146:149]
	v_mfma_f32_16x16x32_bf16 v[38:41], v[212:215], v[196:199], v[22:25]
	v_mfma_f32_16x16x32_bf16 v[22:25], v[212:215], v[220:223], v[18:21]
	v_mfma_f32_16x16x32_bf16 v[18:21], v[216:219], v[200:203], v[172:175]
	v_mfma_f32_16x16x32_bf16 v[6:9], v[208:211], v[224:227], v[6:9]
	v_mfma_f32_16x16x32_bf16 v[2:5], v[216:219], v[224:227], v[2:5]
	v_mfma_f32_16x16x32_bf16 v[18:21], v[238:241], v[220:223], v[18:21]
	v_mfma_f32_16x16x32_bf16 v[6:9], v[212:215], v[234:237], v[6:9]
	v_mfma_f32_16x16x32_bf16 v[2:5], v[238:241], v[234:237], v[2:5]
	v_cmp_gt_u32_e32 vcc, s97, v139
	s_barrier
	s_and_saveexec_b64 s[10:11], vcc
	s_cbranch_execz .LBB0_601
	s_barrier
	s_branch .LBB0_601

; #define WAIT_L(n) asm volatile("s_waitcnt lgkmcnt(%0)" ::"n"(n) : "memory")
; #define SBAR() __builtin_amdgcn_sched_barrier(0)
; #define LDA8(dst, b, h) _Pragma("unroll") for (int m = 0; m < 4; ++m) _Pragma("unroll") for (int k = 0; k < 2; ++k) \
;     dst[m][k] = *(const bf16x8*)(abase + SAo(b, h) + m * 2048 + k * 1024)
; #define LDB8(dst, b, h) _Pragma("unroll") for (int n = 0; n < 2; ++n) _Pragma("unroll") for (int k = 0; k < 2; ++k) \
;     dst[n][k] = *(const bf16x8*)(bbase + SAo(b, h) + n * 2048 + k * 1024)
; #define BAR8 __builtin_amdgcn_s_barrier()
; __device__ __forceinline__ void gemm_main8(const u16* __restrict__ Ab, int lda, const u16* __restrict__ Bb, int ldb, int K,
;                                            char* shm, f32x4 (&acc)[2][2][4][2]) {
;     ...
;     LDB8(B0, 0, 0); SBAR(); LDA8(At, 0, 0); STG_A(1, 1, t + 1);
;     WAIT_L(8); BAR8; WAIT_L(0); MMA8(0, 0, At, B0); BAR8; SBAR();
;     LDB8(B1, 0, 1); STG_B(0, 0, t + 2);
;     BAR8; WAIT_L(0); MMA8(0, 1, At, B1); BAR8;
;     LDA8(At, 0, 1); STG_A(0, 0, t + 2);
;     BAR8; WAIT_L(0); MMA8(1, 0, At, B0); BAR8; SBAR();
.LBB0_662:
	ds_read_b128 v[178:181], v140
	ds_read_b128 v[182:185], v140 offset:1024
	ds_read_b128 v[186:189], v140 offset:2048
	ds_read_b128 v[190:193], v140 offset:3072
	ds_read_b128 v[194:197], v0
	ds_read_b128 v[198:201], v0 offset:1024
	ds_read_b128 v[202:205], v0 offset:2048
	ds_read_b128 v[206:209], v0 offset:3072
	ds_read_b128 v[210:213], v0 offset:4096
	ds_read_b128 v[214:217], v0 offset:5120
	ds_read_b128 v[218:221], v0 offset:6144
	ds_read_b128 v[222:225], v0 offset:7168
	v_add_u32_e32 v176, 0xc000, v141
	v_lshl_add_u64 v[152:153], v[134:135], 0, s[20:21]
	s_mov_b64 s[24:25], 0x8400080
	v_readfirstlane_b32 s11, v176
	v_add_u32_e32 v177, 0xe000, v141
	v_lshl_add_u64 v[154:155], v[152:153], 0, s[24:25]
	s_mov_b32 m0, s11
	s_mov_b64 s[24:25], 0x8500080
	v_readfirstlane_b32 s11, v177
	global_load_lds_dwordx4 v[154:155], off
	v_lshl_add_u64 v[154:155], v[152:153], 0, s[24:25]
	s_mov_b32 m0, s11
	s_nop 0
	global_load_lds_dwordx4 v[154:155], off
	s_waitcnt lgkmcnt(8)
	s_barrier
	s_waitcnt lgkmcnt(0)
	s_waitcnt lgkmcnt(0)
	v_mfma_f32_16x16x32_bf16 v[126:129], v[178:181], v[194:197], v[126:129]
	v_mfma_f32_16x16x32_bf16 v[122:125], v[186:189], v[194:197], v[122:125]
	v_mfma_f32_16x16x32_bf16 v[118:121], v[178:181], v[202:205], v[118:121]
	v_mfma_f32_16x16x32_bf16 v[114:117], v[186:189], v[202:205], v[114:117]
	v_mfma_f32_16x16x32_bf16 v[110:113], v[178:181], v[210:213], v[110:113]
	v_mfma_f32_16x16x32_bf16 v[106:109], v[186:189], v[210:213], v[106:109]
	v_mfma_f32_16x16x32_bf16 v[102:105], v[178:181], v[218:221], v[102:105]
	v_mfma_f32_16x16x32_bf16 v[98:101], v[186:189], v[218:221], v[98:101]
	v_mfma_f32_16x16x32_bf16 v[126:129], v[182:185], v[198:201], v[126:129]
	v_mfma_f32_16x16x32_bf16 v[122:125], v[190:193], v[198:201], v[122:125]
	v_mfma_f32_16x16x32_bf16 v[118:121], v[182:185], v[206:209], v[118:121]
	v_mfma_f32_16x16x32_bf16 v[114:117], v[190:193], v[206:209], v[114:117]
	v_mfma_f32_16x16x32_bf16 v[110:113], v[182:185], v[214:217], v[110:113]
	v_mfma_f32_16x16x32_bf16 v[106:109], v[190:193], v[214:217], v[106:109]
	v_mfma_f32_16x16x32_bf16 v[102:105], v[182:185], v[222:225], v[102:105]
	v_mfma_f32_16x16x32_bf16 v[98:101], v[190:193], v[222:225], v[98:101]
	s_barrier
	ds_read_b128 v[226:229], v140 offset:16384
	ds_read_b128 v[230:233], v140 offset:17408
	ds_read_b128 v[234:237], v140 offset:18432
	ds_read_b128 v[238:241], v140 offset:19456
	v_lshl_add_u64 v[154:155], v[132:133], 0, s[20:21]
	v_readfirstlane_b32 s11, v142
	v_lshl_add_u64 v[164:165], v[154:155], 0, s[30:31]
	s_mov_b32 m0, s11
	s_mov_b64 s[24:25], 0x17500100
	v_readfirstlane_b32 s11, v143
	global_load_lds_dwordx4 v[164:165], off
	v_lshl_add_u64 v[164:165], v[154:155], 0, s[24:25]
	s_mov_b32 m0, s11
	s_nop 0
	global_load_lds_dwordx4 v[164:165], off
	s_barrier
	s_waitcnt lgkmcnt(0)
	s_waitcnt lgkmcnt(0)
	v_mfma_f32_16x16x32_bf16 v[94:97], v[226:229], v[194:197], v[94:97]
	v_mfma_f32_16x16x32_bf16 v[90:93], v[234:237], v[194:197], v[90:93]
	v_mfma_f32_16x16x32_bf16 v[86:89], v[226:229], v[202:205], v[86:89]
	v_mfma_f32_16x16x32_bf16 v[82:85], v[234:237], v[202:205], v[82:85]
	v_mfma_f32_16x16x32_bf16 v[78:81], v[226:229], v[210:213], v[78:81]
	v_mfma_f32_16x16x32_bf16 v[74:77], v[234:237], v[210:213], v[74:77]
	v_mfma_f32_16x16x32_bf16 v[70:73], v[226:229], v[218:221], v[70:73]
	v_mfma_f32_16x16x32_bf16 v[66:69], v[234:237], v[218:221], v[66:69]
	v_mfma_f32_16x16x32_bf16 v[94:97], v[230:233], v[198:201], v[94:97]
	v_mfma_f32_16x16x32_bf16 v[90:93], v[238:241], v[198:201], v[90:93]
	v_mfma_f32_16x16x32_bf16 v[86:89], v[230:233], v[206:209], v[86:89]
	v_mfma_f32_16x16x32_bf16 v[82:85], v[238:241], v[206:209], v[82:85]
	v_mfma_f32_16x16x32_bf16 v[78:81], v[230:233], v[214:217], v[78:81]
	v_mfma_f32_16x16x32_bf16 v[74:77], v[238:241], v[214:217], v[74:77]
	v_mfma_f32_16x16x32_bf16 v[70:73], v[230:233], v[222:225], v[70:73]
	v_mfma_f32_16x16x32_bf16 v[66:69], v[238:241], v[222:225], v[66:69]
	s_mov_b64 s[24:25], 0x8200100
	v_readfirstlane_b32 s11, v141
	v_lshl_add_u64 v[164:165], v[152:153], 0, s[24:25]
	s_mov_b32 m0, s11
	s_mov_b64 s[24:25], 0x8300100
	v_readfirstlane_b32 s11, v144
	s_barrier
	ds_read_b128 v[194:197], v0 offset:16384
	ds_read_b128 v[198:201], v0 offset:17408
	ds_read_b128 v[202:205], v0 offset:18432
	ds_read_b128 v[206:209], v0 offset:19456
	ds_read_b128 v[210:213], v0 offset:20480
	ds_read_b128 v[214:217], v0 offset:21504
	ds_read_b128 v[218:221], v0 offset:22528
	ds_read_b128 v[222:225], v0 offset:23552
	global_load_lds_dwordx4 v[164:165], off
	v_lshl_add_u64 v[164:165], v[152:153], 0, s[24:25]
	s_mov_b32 m0, s11
	s_nop 0
	global_load_lds_dwordx4 v[164:165], off
	s_barrier
	s_waitcnt lgkmcnt(0)
	s_waitcnt lgkmcnt(0)
	v_mfma_f32_16x16x32_bf16 v[62:65], v[178:181], v[194:197], v[62:65]
	v_mfma_f32_16x16x32_bf16 v[58:61], v[186:189], v[194:197], v[58:61]
	v_mfma_f32_16x16x32_bf16 v[54:57], v[178:181], v[202:205], v[54:57]
	v_mfma_f32_16x16x32_bf16 v[50:53], v[186:189], v[202:205], v[50:53]
	v_mfma_f32_16x16x32_bf16 v[46:49], v[178:181], v[210:213], v[46:49]
	v_mfma_f32_16x16x32_bf16 v[42:45], v[186:189], v[210:213], v[42:45]
	v_mfma_f32_16x16x32_bf16 v[38:41], v[178:181], v[218:221], v[38:41]
	v_mfma_f32_16x16x32_bf16 v[34:37], v[186:189], v[218:221], v[34:37]
	v_mfma_f32_16x16x32_bf16 v[62:65], v[182:185], v[198:201], v[62:65]
	v_mfma_f32_16x16x32_bf16 v[58:61], v[190:193], v[198:201], v[58:61]
	v_mfma_f32_16x16x32_bf16 v[54:57], v[182:185], v[206:209], v[54:57]
	v_mfma_f32_16x16x32_bf16 v[50:53], v[190:193], v[206:209], v[50:53]
	v_mfma_f32_16x16x32_bf16 v[46:49], v[182:185], v[214:217], v[46:49]
	v_mfma_f32_16x16x32_bf16 v[42:45], v[190:193], v[214:217], v[42:45]
	v_mfma_f32_16x16x32_bf16 v[38:41], v[182:185], v[222:225], v[38:41]
	v_mfma_f32_16x16x32_bf16 v[34:37], v[190:193], v[222:225], v[34:37]
	s_barrier
; #define WAIT_V(n) asm volatile("s_waitcnt vmcnt(%0)" ::"n"(n) : "memory")
; #define WAIT_L(n) asm volatile("s_waitcnt lgkmcnt(%0)" ::"n"(n) : "memory")
; #define SBAR() __builtin_amdgcn_sched_barrier(0)
; #define LDA8(dst, b, h) _Pragma("unroll") for (int m = 0; m < 4; ++m) _Pragma("unroll") for (int k = 0; k < 2; ++k) \
;     dst[m][k] = *(const bf16x8*)(abase + SAo(b, h) + m * 2048 + k * 1024)
; #define LDB8(dst, b, h) _Pragma("unroll") for (int n = 0; n < 2; ++n) _Pragma("unroll") for (int k = 0; k < 2; ++k) \
;     dst[n][k] = *(const bf16x8*)(bbase + SAo(b, h) + n * 2048 + k * 1024)
; #define BAR8 __builtin_amdgcn_s_barrier()
; __device__ __forceinline__ void gemm_main8(const u16* __restrict__ Ab, int lda, const u16* __restrict__ Bb, int ldb, int K,
;                                            char* shm, f32x4 (&acc)[2][2][4][2]) {
;     ...
;     STG_B(0, 1, t + 2);
;     WAIT_V(6); BAR8; MMA8(1, 1, At, B1); BAR8;
;     LDB8(B0, 1, 0); SBAR(); LDA8(At, 1, 0); STG_A(0, 1, t + 2);
;     WAIT_L(8); BAR8; WAIT_L(0); MMA8(0, 0, At, B0); BAR8; SBAR();
;     LDB8(B1, 1, 1); STG_B(1, 0, t + 3);
;     BAR8; WAIT_L(0); MMA8(0, 1, At, B1); BAR8;
;     LDA8(At, 1, 1); STG_A(1, 0, t + 3);
	s_mov_b64 s[24:25], 0x17700100
	v_readfirstlane_b32 s11, v145
	v_lshl_add_u64 v[164:165], v[154:155], 0, s[24:25]
	s_mov_b32 m0, s11
	s_mov_b64 s[24:25], 0x17900100
	v_readfirstlane_b32 s11, v146
	global_load_lds_dwordx4 v[164:165], off
	v_lshl_add_u64 v[164:165], v[154:155], 0, s[24:25]
	s_mov_b32 m0, s11
	s_nop 0
	global_load_lds_dwordx4 v[164:165], off
	s_waitcnt vmcnt(6)
	s_barrier
	v_mfma_f32_16x16x32_bf16 v[30:33], v[226:229], v[194:197], v[30:33]
	v_mfma_f32_16x16x32_bf16 v[26:29], v[234:237], v[194:197], v[26:29]
	v_mfma_f32_16x16x32_bf16 v[22:25], v[226:229], v[202:205], v[22:25]
	v_mfma_f32_16x16x32_bf16 v[18:21], v[234:237], v[202:205], v[18:21]
	v_mfma_f32_16x16x32_bf16 v[14:17], v[226:229], v[210:213], v[14:17]
	v_mfma_f32_16x16x32_bf16 v[10:13], v[234:237], v[210:213], v[10:13]
	v_mfma_f32_16x16x32_bf16 v[6:9], v[226:229], v[218:221], v[6:9]
	v_mfma_f32_16x16x32_bf16 v[2:5], v[234:237], v[218:221], v[2:5]
	v_mfma_f32_16x16x32_bf16 v[30:33], v[230:233], v[198:201], v[30:33]
	v_mfma_f32_16x16x32_bf16 v[26:29], v[238:241], v[198:201], v[26:29]
	v_mfma_f32_16x16x32_bf16 v[22:25], v[230:233], v[206:209], v[22:25]
	v_mfma_f32_16x16x32_bf16 v[18:21], v[238:241], v[206:209], v[18:21]
	v_mfma_f32_16x16x32_bf16 v[14:17], v[230:233], v[214:217], v[14:17]
	v_mfma_f32_16x16x32_bf16 v[10:13], v[238:241], v[214:217], v[10:13]
	v_mfma_f32_16x16x32_bf16 v[6:9], v[230:233], v[222:225], v[6:9]
	v_mfma_f32_16x16x32_bf16 v[2:5], v[238:241], v[222:225], v[2:5]
	s_barrier
	ds_read_b128 v[178:181], v140 offset:32768
	ds_read_b128 v[182:185], v140 offset:33792
	ds_read_b128 v[186:189], v140 offset:34816
	ds_read_b128 v[190:193], v140 offset:35840
	ds_read_b128 v[194:197], v0 offset:32768
	ds_read_b128 v[198:201], v0 offset:33792
	ds_read_b128 v[202:205], v0 offset:34816
	ds_read_b128 v[206:209], v0 offset:35840
	ds_read_b128 v[210:213], v0 offset:36864
	ds_read_b128 v[214:217], v0 offset:37888
	ds_read_b128 v[218:221], v0 offset:38912
	ds_read_b128 v[222:225], v0 offset:39936
	s_mov_b64 s[24:25], 0x8400100
	v_readfirstlane_b32 s11, v147
	v_lshl_add_u64 v[164:165], v[152:153], 0, s[24:25]
	s_mov_b32 m0, s11
	s_mov_b64 s[24:25], 0x8500100
	v_readfirstlane_b32 s11, v148
	global_load_lds_dwordx4 v[164:165], off
	v_lshl_add_u64 v[164:165], v[152:153], 0, s[24:25]
	s_mov_b32 m0, s11
	s_nop 0
	global_load_lds_dwordx4 v[164:165], off
	s_waitcnt lgkmcnt(8)
	s_barrier
	s_waitcnt lgkmcnt(0)
	s_waitcnt lgkmcnt(0)
	v_mfma_f32_16x16x32_bf16 v[126:129], v[178:181], v[194:197], v[126:129]
	v_mfma_f32_16x16x32_bf16 v[122:125], v[186:189], v[194:197], v[122:125]
	v_mfma_f32_16x16x32_bf16 v[118:121], v[178:181], v[202:205], v[118:121]
	v_mfma_f32_16x16x32_bf16 v[114:117], v[186:189], v[202:205], v[114:117]
	v_mfma_f32_16x16x32_bf16 v[110:113], v[178:181], v[210:213], v[110:113]
	v_mfma_f32_16x16x32_bf16 v[106:109], v[186:189], v[210:213], v[106:109]
	v_mfma_f32_16x16x32_bf16 v[102:105], v[178:181], v[218:221], v[102:105]
	v_mfma_f32_16x16x32_bf16 v[98:101], v[186:189], v[218:221], v[98:101]
	v_mfma_f32_16x16x32_bf16 v[126:129], v[182:185], v[198:201], v[126:129]
	v_mfma_f32_16x16x32_bf16 v[122:125], v[190:193], v[198:201], v[122:125]
	v_mfma_f32_16x16x32_bf16 v[118:121], v[182:185], v[206:209], v[118:121]
	v_mfma_f32_16x16x32_bf16 v[114:117], v[190:193], v[206:209], v[114:117]
	v_mfma_f32_16x16x32_bf16 v[110:113], v[182:185], v[214:217], v[110:113]
	v_mfma_f32_16x16x32_bf16 v[106:109], v[190:193], v[214:217], v[106:109]
	v_mfma_f32_16x16x32_bf16 v[102:105], v[182:185], v[222:225], v[102:105]
	v_mfma_f32_16x16x32_bf16 v[98:101], v[190:193], v[222:225], v[98:101]
	s_barrier
	ds_read_b128 v[226:229], v140 offset:49152
	ds_read_b128 v[230:233], v140 offset:50176
	ds_read_b128 v[234:237], v140 offset:51200
	ds_read_b128 v[238:241], v140 offset:52224
	v_readfirstlane_b32 s11, v149
	v_lshl_add_u64 v[164:165], v[154:155], 0, s[16:17]
	s_mov_b32 m0, s11
	s_mov_b64 s[24:25], 0x17500180
	v_readfirstlane_b32 s11, v171
	global_load_lds_dwordx4 v[164:165], off
	v_lshl_add_u64 v[164:165], v[154:155], 0, s[24:25]
	s_mov_b32 m0, s11
	s_nop 0
	global_load_lds_dwordx4 v[164:165], off
	s_barrier
	s_waitcnt lgkmcnt(0)
	s_waitcnt lgkmcnt(0)
	v_mfma_f32_16x16x32_bf16 v[94:97], v[226:229], v[194:197], v[94:97]
	v_mfma_f32_16x16x32_bf16 v[90:93], v[234:237], v[194:197], v[90:93]
	v_mfma_f32_16x16x32_bf16 v[86:89], v[226:229], v[202:205], v[86:89]
	v_mfma_f32_16x16x32_bf16 v[82:85], v[234:237], v[202:205], v[82:85]
	v_mfma_f32_16x16x32_bf16 v[78:81], v[226:229], v[210:213], v[78:81]
	v_mfma_f32_16x16x32_bf16 v[74:77], v[234:237], v[210:213], v[74:77]
	v_mfma_f32_16x16x32_bf16 v[70:73], v[226:229], v[218:221], v[70:73]
	v_mfma_f32_16x16x32_bf16 v[66:69], v[234:237], v[218:221], v[66:69]
	v_mfma_f32_16x16x32_bf16 v[94:97], v[230:233], v[198:201], v[94:97]
	v_mfma_f32_16x16x32_bf16 v[90:93], v[238:241], v[198:201], v[90:93]
	v_mfma_f32_16x16x32_bf16 v[86:89], v[230:233], v[206:209], v[86:89]
	v_mfma_f32_16x16x32_bf16 v[82:85], v[238:241], v[206:209], v[82:85]
	v_mfma_f32_16x16x32_bf16 v[78:81], v[230:233], v[214:217], v[78:81]
	v_mfma_f32_16x16x32_bf16 v[74:77], v[238:241], v[214:217], v[74:77]
	v_mfma_f32_16x16x32_bf16 v[70:73], v[230:233], v[222:225], v[70:73]
	v_mfma_f32_16x16x32_bf16 v[66:69], v[238:241], v[222:225], v[66:69]
	s_mov_b64 s[24:25], 0x8200180
	v_readfirstlane_b32 s11, v172
	v_lshl_add_u64 v[164:165], v[152:153], 0, s[24:25]
	s_mov_b32 m0, s11
	s_mov_b64 s[24:25], 0x8300180
	v_readfirstlane_b32 s11, v173
	s_barrier
; #define WAIT_V(n) asm volatile("s_waitcnt vmcnt(%0)" ::"n"(n) : "memory")
; #define WAIT_L(n) asm volatile("s_waitcnt lgkmcnt(%0)" ::"n"(n) : "memory")
; #define SBAR() __builtin_amdgcn_sched_barrier(0)
; #define LDA8(dst, b, h) _Pragma("unroll") for (int m = 0; m < 4; ++m) _Pragma("unroll") for (int k = 0; k < 2; ++k) \
;     dst[m][k] = *(const bf16x8*)(abase + SAo(b, h) + m * 2048 + k * 1024)
; #define LDB8(dst, b, h) _Pragma("unroll") for (int n = 0; n < 2; ++n) _Pragma("unroll") for (int k = 0; k < 2; ++k) \
;     dst[n][k] = *(const bf16x8*)(bbase + SAo(b, h) + n * 2048 + k * 1024)
; #define BAR8 __builtin_amdgcn_s_barrier()
; __device__ __forceinline__ void gemm_main8(const u16* __restrict__ Ab, int lda, const u16* __restrict__ Bb, int ldb, int K,
;                                            char* shm, f32x4 (&acc)[2][2][4][2]) {
;     ...
;     LDA8(At, 1, 1); STG_A(1, 0, t + 3);
;     BAR8; WAIT_L(0); MMA8(1, 0, At, B0); BAR8; SBAR();
;     STG_B(1, 1, t + 3);
;     WAIT_V(6); BAR8; MMA8(1, 1, At, B1); BAR8;
;   }
;   { LDB8(B0, 0, 0); LDA8(At, 0, 0); STG_A(1, 1, nt - 1);
;     BAR8; WAIT_L(0); MMA8(0, 0, At, B0); BAR8;
	ds_read_b128 v[194:197], v0 offset:49152
	ds_read_b128 v[198:201], v0 offset:50176
	ds_read_b128 v[202:205], v0 offset:51200
	ds_read_b128 v[206:209], v0 offset:52224
	ds_read_b128 v[210:213], v0 offset:53248
	ds_read_b128 v[214:217], v0 offset:54272
	ds_read_b128 v[218:221], v0 offset:55296
	ds_read_b128 v[222:225], v0 offset:56320
	global_load_lds_dwordx4 v[164:165], off
	v_lshl_add_u64 v[152:153], v[152:153], 0, s[24:25]
	s_mov_b32 m0, s11
	s_nop 0
	global_load_lds_dwordx4 v[152:153], off
	s_barrier
	s_waitcnt lgkmcnt(0)
	s_waitcnt lgkmcnt(0)
	v_mfma_f32_16x16x32_bf16 v[62:65], v[178:181], v[194:197], v[62:65]
	v_mfma_f32_16x16x32_bf16 v[58:61], v[186:189], v[194:197], v[58:61]
	v_mfma_f32_16x16x32_bf16 v[54:57], v[178:181], v[202:205], v[54:57]
	v_mfma_f32_16x16x32_bf16 v[50:53], v[186:189], v[202:205], v[50:53]
	v_mfma_f32_16x16x32_bf16 v[46:49], v[178:181], v[210:213], v[46:49]
	v_mfma_f32_16x16x32_bf16 v[42:45], v[186:189], v[210:213], v[42:45]
	v_mfma_f32_16x16x32_bf16 v[38:41], v[178:181], v[218:221], v[38:41]
	v_mfma_f32_16x16x32_bf16 v[34:37], v[186:189], v[218:221], v[34:37]
	v_mfma_f32_16x16x32_bf16 v[62:65], v[182:185], v[198:201], v[62:65]
	v_mfma_f32_16x16x32_bf16 v[58:61], v[190:193], v[198:201], v[58:61]
	v_mfma_f32_16x16x32_bf16 v[54:57], v[182:185], v[206:209], v[54:57]
	v_mfma_f32_16x16x32_bf16 v[50:53], v[190:193], v[206:209], v[50:53]
	v_mfma_f32_16x16x32_bf16 v[46:49], v[182:185], v[214:217], v[46:49]
	v_mfma_f32_16x16x32_bf16 v[42:45], v[190:193], v[214:217], v[42:45]
	v_mfma_f32_16x16x32_bf16 v[38:41], v[182:185], v[222:225], v[38:41]
	v_mfma_f32_16x16x32_bf16 v[34:37], v[190:193], v[222:225], v[34:37]
	s_barrier
	s_mov_b64 s[24:25], 0x17700180
	v_readfirstlane_b32 s11, v174
	v_lshl_add_u64 v[152:153], v[154:155], 0, s[24:25]
	s_mov_b32 m0, s11
	s_mov_b64 s[24:25], 0x17900180
	v_readfirstlane_b32 s11, v175
	global_load_lds_dwordx4 v[152:153], off
	v_lshl_add_u64 v[152:153], v[154:155], 0, s[24:25]
	s_mov_b32 m0, s11
	s_nop 0
	global_load_lds_dwordx4 v[152:153], off
	s_waitcnt vmcnt(6)
	s_barrier
	v_mfma_f32_16x16x32_bf16 v[30:33], v[226:229], v[194:197], v[30:33]
	v_mfma_f32_16x16x32_bf16 v[26:29], v[234:237], v[194:197], v[26:29]
	v_mfma_f32_16x16x32_bf16 v[22:25], v[226:229], v[202:205], v[22:25]
	v_mfma_f32_16x16x32_bf16 v[18:21], v[234:237], v[202:205], v[18:21]
	v_mfma_f32_16x16x32_bf16 v[14:17], v[226:229], v[210:213], v[14:17]
	v_mfma_f32_16x16x32_bf16 v[10:13], v[234:237], v[210:213], v[10:13]
	v_mfma_f32_16x16x32_bf16 v[6:9], v[226:229], v[218:221], v[6:9]
	v_mfma_f32_16x16x32_bf16 v[2:5], v[234:237], v[218:221], v[2:5]
	v_mfma_f32_16x16x32_bf16 v[30:33], v[230:233], v[198:201], v[30:33]
	v_mfma_f32_16x16x32_bf16 v[26:29], v[238:241], v[198:201], v[26:29]
	v_mfma_f32_16x16x32_bf16 v[22:25], v[230:233], v[206:209], v[22:25]
	v_mfma_f32_16x16x32_bf16 v[18:21], v[238:241], v[206:209], v[18:21]
	v_mfma_f32_16x16x32_bf16 v[14:17], v[230:233], v[214:217], v[14:17]
	v_mfma_f32_16x16x32_bf16 v[10:13], v[238:241], v[214:217], v[10:13]
	v_mfma_f32_16x16x32_bf16 v[6:9], v[230:233], v[222:225], v[6:9]
	v_mfma_f32_16x16x32_bf16 v[2:5], v[238:241], v[222:225], v[2:5]
	s_add_i32 s10, s10, 2
	s_add_u32 s20, s20, 0x100
	s_addc_u32 s21, s21, 0
	s_cmpk_lt_u32 s10, 0x7c
	s_barrier
	s_cbranch_scc1 .LBB0_662
	s_mov_b64 s[10:11], 0x203f80
	v_lshl_add_u64 v[152:153], v[130:131], 0, s[10:11]
	v_readfirstlane_b32 s10, v176
	s_mov_b32 m0, s10
	s_mov_b64 s[10:11], 0x303f80
	v_lshl_add_u64 v[130:131], v[130:131], 0, s[10:11]
	v_readfirstlane_b32 s10, v177
	ds_read_b128 v[132:135], v140
	ds_read_b128 v[142:145], v140 offset:1024
	ds_read_b128 v[146:149], v140 offset:2048
	ds_read_b128 v[172:175], v140 offset:3072
	ds_read_b128 v[178:181], v0
	ds_read_b128 v[182:185], v0 offset:1024
	ds_read_b128 v[186:189], v0 offset:2048
	ds_read_b128 v[190:193], v0 offset:3072
	ds_read_b128 v[194:197], v0 offset:4096
	ds_read_b128 v[198:201], v0 offset:5120
	ds_read_b128 v[202:205], v0 offset:6144
	ds_read_b128 v[206:209], v0 offset:7168
	global_load_lds_dwordx4 v[152:153], off
	s_mov_b32 m0, s10
	s_nop 0
	global_load_lds_dwordx4 v[130:131], off
	s_barrier
	s_waitcnt lgkmcnt(0)
	s_waitcnt lgkmcnt(0)
	v_mfma_f32_16x16x32_bf16 v[126:129], v[132:135], v[178:181], v[126:129]
	v_mfma_f32_16x16x32_bf16 v[122:125], v[146:149], v[178:181], v[122:125]
	v_mfma_f32_16x16x32_bf16 v[118:121], v[132:135], v[186:189], v[118:121]
	v_mfma_f32_16x16x32_bf16 v[114:117], v[146:149], v[186:189], v[114:117]
	v_mfma_f32_16x16x32_bf16 v[110:113], v[132:135], v[194:197], v[110:113]
	v_mfma_f32_16x16x32_bf16 v[106:109], v[146:149], v[194:197], v[106:109]
	v_mfma_f32_16x16x32_bf16 v[102:105], v[132:135], v[202:205], v[102:105]
	v_mfma_f32_16x16x32_bf16 v[98:101], v[146:149], v[202:205], v[98:101]
	v_mfma_f32_16x16x32_bf16 v[126:129], v[142:145], v[182:185], v[126:129]
	v_mfma_f32_16x16x32_bf16 v[122:125], v[172:175], v[182:185], v[122:125]
	v_mfma_f32_16x16x32_bf16 v[118:121], v[142:145], v[190:193], v[118:121]
	v_mfma_f32_16x16x32_bf16 v[114:117], v[172:175], v[190:193], v[114:117]
	v_mfma_f32_16x16x32_bf16 v[110:113], v[142:145], v[198:201], v[110:113]
	v_mfma_f32_16x16x32_bf16 v[106:109], v[172:175], v[198:201], v[106:109]
	v_mfma_f32_16x16x32_bf16 v[102:105], v[142:145], v[206:209], v[102:105]
	v_mfma_f32_16x16x32_bf16 v[98:101], v[172:175], v[206:209], v[98:101]
	s_barrier
	ds_read_b128 v[210:213], v140 offset:16384
	ds_read_b128 v[214:217], v140 offset:17408
	ds_read_b128 v[218:221], v140 offset:18432
	ds_read_b128 v[222:225], v140 offset:19456
	s_barrier
; #define WAIT_V(n) asm volatile("s_waitcnt vmcnt(%0)" ::"n"(n) : "memory")
; #define WAIT_L(n) asm volatile("s_waitcnt lgkmcnt(%0)" ::"n"(n) : "memory")
; #define LDA8(dst, b, h) _Pragma("unroll") for (int m = 0; m < 4; ++m) _Pragma("unroll") for (int k = 0; k < 2; ++k) \
;     dst[m][k] = *(const bf16x8*)(abase + SAo(b, h) + m * 2048 + k * 1024)
; #define LDB8(dst, b, h) _Pragma("unroll") for (int n = 0; n < 2; ++n) _Pragma("unroll") for (int k = 0; k < 2; ++k) \
;     dst[n][k] = *(const bf16x8*)(bbase + SAo(b, h) + n * 2048 + k * 1024)
; #define BAR8 __builtin_amdgcn_s_barrier()
; __device__ __forceinline__ void gemm_main8(const u16* __restrict__ Ab, int lda, const u16* __restrict__ Bb, int ldb, int K,
;                                            char* shm, f32x4 (&acc)[2][2][4][2]) {
;     ...
;     LDB8(B1, 0, 1); BAR8; WAIT_L(0); MMA8(0, 1, At, B1); BAR8;
;     LDA8(At, 0, 1); WAIT_V(4); BAR8; WAIT_L(0); MMA8(1, 0, At, B0); MMA8(1, 1, At, B1); BAR8; }
;   { LDB8(B0, 1, 0); LDA8(At, 1, 0); WAIT_V(2); BAR8; WAIT_L(0); MMA8(0, 0, At, B0); BAR8;
	s_waitcnt lgkmcnt(0)
	s_waitcnt lgkmcnt(0)
	v_mfma_f32_16x16x32_bf16 v[94:97], v[210:213], v[178:181], v[94:97]
	v_mfma_f32_16x16x32_bf16 v[90:93], v[218:221], v[178:181], v[90:93]
	v_mfma_f32_16x16x32_bf16 v[86:89], v[210:213], v[186:189], v[86:89]
	v_mfma_f32_16x16x32_bf16 v[82:85], v[218:221], v[186:189], v[82:85]
	v_mfma_f32_16x16x32_bf16 v[78:81], v[210:213], v[194:197], v[78:81]
	v_mfma_f32_16x16x32_bf16 v[74:77], v[218:221], v[194:197], v[74:77]
	v_mfma_f32_16x16x32_bf16 v[70:73], v[210:213], v[202:205], v[70:73]
	v_mfma_f32_16x16x32_bf16 v[66:69], v[218:221], v[202:205], v[66:69]
	v_mfma_f32_16x16x32_bf16 v[94:97], v[214:217], v[182:185], v[94:97]
	v_mfma_f32_16x16x32_bf16 v[90:93], v[222:225], v[182:185], v[90:93]
	v_mfma_f32_16x16x32_bf16 v[86:89], v[214:217], v[190:193], v[86:89]
	v_mfma_f32_16x16x32_bf16 v[82:85], v[222:225], v[190:193], v[82:85]
	v_mfma_f32_16x16x32_bf16 v[78:81], v[214:217], v[198:201], v[78:81]
	v_mfma_f32_16x16x32_bf16 v[74:77], v[222:225], v[198:201], v[74:77]
	v_mfma_f32_16x16x32_bf16 v[70:73], v[214:217], v[206:209], v[70:73]
	v_mfma_f32_16x16x32_bf16 v[66:69], v[222:225], v[206:209], v[66:69]
	s_barrier
	ds_read_b128 v[176:179], v0 offset:16384
	ds_read_b128 v[180:183], v0 offset:17408
	ds_read_b128 v[184:187], v0 offset:18432
	ds_read_b128 v[188:191], v0 offset:19456
	ds_read_b128 v[192:195], v0 offset:20480
	ds_read_b128 v[196:199], v0 offset:21504
	ds_read_b128 v[200:203], v0 offset:22528
	ds_read_b128 v[204:207], v0 offset:23552
	s_waitcnt vmcnt(4)
	s_barrier
	s_waitcnt lgkmcnt(0)
	s_waitcnt lgkmcnt(0)
	v_mfma_f32_16x16x32_bf16 v[46:49], v[132:135], v[192:195], v[46:49]
	v_mfma_f32_16x16x32_bf16 v[42:45], v[146:149], v[192:195], v[42:45]
	v_mfma_f32_16x16x32_bf16 v[62:65], v[132:135], v[176:179], v[62:65]
	v_mfma_f32_16x16x32_bf16 v[58:61], v[146:149], v[176:179], v[58:61]
	v_mfma_f32_16x16x32_bf16 v[54:57], v[132:135], v[184:187], v[54:57]
	v_mfma_f32_16x16x32_bf16 v[50:53], v[146:149], v[184:187], v[50:53]
	v_mfma_f32_16x16x32_bf16 v[46:49], v[142:145], v[196:199], v[46:49]
	v_mfma_f32_16x16x32_bf16 v[42:45], v[172:175], v[196:199], v[42:45]
	v_mfma_f32_16x16x32_bf16 v[38:41], v[132:135], v[200:203], v[38:41]
	v_mfma_f32_16x16x32_bf16 v[34:37], v[146:149], v[200:203], v[34:37]
	v_mfma_f32_16x16x32_bf16 v[226:229], v[142:145], v[180:183], v[62:65]
	v_mfma_f32_16x16x32_bf16 v[230:233], v[172:175], v[180:183], v[58:61]
	v_mfma_f32_16x16x32_bf16 v[234:237], v[142:145], v[188:191], v[54:57]
	v_mfma_f32_16x16x32_bf16 v[238:241], v[172:175], v[188:191], v[50:53]
	v_mfma_f32_16x16x32_bf16 v[130:133], v[142:145], v[204:207], v[38:41]
	v_mfma_f32_16x16x32_bf16 v[142:145], v[172:175], v[204:207], v[34:37]
	v_mfma_f32_16x16x32_bf16 v[30:33], v[210:213], v[176:179], v[30:33]
	v_mfma_f32_16x16x32_bf16 v[26:29], v[218:221], v[176:179], v[26:29]
	v_mfma_f32_16x16x32_bf16 v[22:25], v[210:213], v[184:187], v[22:25]
	v_mfma_f32_16x16x32_bf16 v[18:21], v[218:221], v[184:187], v[18:21]
	v_mfma_f32_16x16x32_bf16 v[14:17], v[210:213], v[192:195], v[14:17]
	v_mfma_f32_16x16x32_bf16 v[10:13], v[218:221], v[192:195], v[10:13]
	v_mfma_f32_16x16x32_bf16 v[6:9], v[210:213], v[200:203], v[6:9]
	v_mfma_f32_16x16x32_bf16 v[2:5], v[218:221], v[200:203], v[2:5]
	v_mfma_f32_16x16x32_bf16 v[146:149], v[214:217], v[180:183], v[30:33]
	v_mfma_f32_16x16x32_bf16 v[172:175], v[222:225], v[180:183], v[26:29]
	v_mfma_f32_16x16x32_bf16 v[176:179], v[214:217], v[188:191], v[22:25]
	v_mfma_f32_16x16x32_bf16 v[180:183], v[222:225], v[188:191], v[18:21]
	v_mfma_f32_16x16x32_bf16 v[184:187], v[214:217], v[196:199], v[14:17]
	v_mfma_f32_16x16x32_bf16 v[188:191], v[222:225], v[196:199], v[10:13]
	v_mfma_f32_16x16x32_bf16 v[192:195], v[214:217], v[204:207], v[6:9]
	v_mfma_f32_16x16x32_bf16 v[196:199], v[222:225], v[204:207], v[2:5]
	s_barrier
	ds_read_b128 v[10:13], v140 offset:32768
	ds_read_b128 v[14:17], v140 offset:33792
	ds_read_b128 v[200:203], v140 offset:34816
	ds_read_b128 v[204:207], v140 offset:35840
	ds_read_b128 v[26:29], v0 offset:32768
	ds_read_b128 v[34:37], v0 offset:33792
	ds_read_b128 v[58:61], v0 offset:34816
	ds_read_b128 v[62:65], v0 offset:35840
	ds_read_b128 v[208:211], v0 offset:36864
	ds_read_b128 v[212:215], v0 offset:37888
	ds_read_b128 v[216:219], v0 offset:38912
	ds_read_b128 v[220:223], v0 offset:39936
	s_waitcnt vmcnt(2)
	s_barrier
; #define WAIT_V(n) asm volatile("s_waitcnt vmcnt(%0)" ::"n"(n) : "memory")
; #define WAIT_L(n) asm volatile("s_waitcnt lgkmcnt(%0)" ::"n"(n) : "memory")
; #define LDA8(dst, b, h) _Pragma("unroll") for (int m = 0; m < 4; ++m) _Pragma("unroll") for (int k = 0; k < 2; ++k) \
;     dst[m][k] = *(const bf16x8*)(abase + SAo(b, h) + m * 2048 + k * 1024)
; #define LDB8(dst, b, h) _Pragma("unroll") for (int n = 0; n < 2; ++n) _Pragma("unroll") for (int k = 0; k < 2; ++k) \
;     dst[n][k] = *(const bf16x8*)(bbase + SAo(b, h) + n * 2048 + k * 1024)
; #define BAR8 __builtin_amdgcn_s_barrier()
; __device__ __forceinline__ void gemm_main8(const u16* __restrict__ Ab, int lda, const u16* __restrict__ Bb, int ldb, int K,
;                                            char* shm, f32x4 (&acc)[2][2][4][2]) {
;     ...
;   { LDB8(B0, 1, 0); LDA8(At, 1, 0); WAIT_V(2); BAR8; WAIT_L(0); MMA8(0, 0, At, B0); BAR8;
;     LDB8(B1, 1, 1); WAIT_V(0); BAR8; WAIT_L(0); MMA8(0, 1, At, B1); BAR8;
;     LDA8(At, 1, 1); BAR8; WAIT_L(0); MMA8(1, 0, At, B0); MMA8(1, 1, At, B1); BAR8; }
;   if (wr == 0) BAR8;
	s_waitcnt lgkmcnt(0)
	s_waitcnt lgkmcnt(0)
	v_mfma_f32_16x16x32_bf16 v[2:5], v[10:13], v[26:29], v[126:129]
	v_mfma_f32_16x16x32_bf16 v[50:53], v[14:17], v[34:37], v[2:5]
	v_mfma_f32_16x16x32_bf16 v[2:5], v[200:203], v[26:29], v[122:125]
	v_mfma_f32_16x16x32_bf16 v[54:57], v[204:207], v[34:37], v[2:5]
	v_mfma_f32_16x16x32_bf16 v[2:5], v[10:13], v[58:61], v[118:121]
	v_mfma_f32_16x16x32_bf16 v[30:33], v[14:17], v[62:65], v[2:5]
	v_mfma_f32_16x16x32_bf16 v[2:5], v[200:203], v[58:61], v[114:117]
	v_mfma_f32_16x16x32_bf16 v[38:41], v[204:207], v[62:65], v[2:5]
	v_mfma_f32_16x16x32_bf16 v[2:5], v[10:13], v[208:211], v[110:113]
	v_mfma_f32_16x16x32_bf16 v[18:21], v[14:17], v[212:215], v[2:5]
	v_mfma_f32_16x16x32_bf16 v[2:5], v[200:203], v[208:211], v[106:109]
	v_mfma_f32_16x16x32_bf16 v[22:25], v[204:207], v[212:215], v[2:5]
	v_mfma_f32_16x16x32_bf16 v[2:5], v[10:13], v[216:219], v[102:105]
	v_mfma_f32_16x16x32_bf16 v[6:9], v[200:203], v[216:219], v[98:101]
	v_mfma_f32_16x16x32_bf16 v[2:5], v[14:17], v[220:223], v[2:5]
	v_mfma_f32_16x16x32_bf16 v[6:9], v[204:207], v[220:223], v[6:9]
	s_barrier
	ds_read_b128 v[242:245], v140 offset:49152
	ds_read_b128 v[246:249], v140 offset:50176
	ds_read_b128 v[250:253], v140 offset:51200
	ds_read_b128 v[168:171], v140 offset:52224
	s_waitcnt vmcnt(0)
	s_barrier
	s_waitcnt lgkmcnt(0)
	s_waitcnt lgkmcnt(0)
	v_mfma_f32_16x16x32_bf16 v[94:97], v[242:245], v[26:29], v[94:97]
	v_mfma_f32_16x16x32_bf16 v[26:29], v[250:253], v[26:29], v[90:93]
	v_mfma_f32_16x16x32_bf16 v[118:121], v[168:171], v[34:37], v[26:29]
	v_mfma_f32_16x16x32_bf16 v[26:29], v[242:245], v[58:61], v[86:89]
	v_mfma_f32_16x16x32_bf16 v[98:101], v[246:249], v[62:65], v[26:29]
	v_mfma_f32_16x16x32_bf16 v[26:29], v[250:253], v[58:61], v[82:85]
	v_mfma_f32_16x16x32_bf16 v[102:105], v[168:171], v[62:65], v[26:29]
	v_mfma_f32_16x16x32_bf16 v[26:29], v[242:245], v[208:211], v[78:81]
	v_mfma_f32_16x16x32_bf16 v[82:85], v[246:249], v[212:215], v[26:29]
	v_mfma_f32_16x16x32_bf16 v[26:29], v[250:253], v[208:211], v[74:77]
	v_mfma_f32_16x16x32_bf16 v[90:93], v[168:171], v[212:215], v[26:29]
	v_mfma_f32_16x16x32_bf16 v[26:29], v[242:245], v[216:219], v[70:73]
	v_mfma_f32_16x16x32_bf16 v[58:61], v[246:249], v[220:223], v[26:29]
	v_mfma_f32_16x16x32_bf16 v[26:29], v[250:253], v[216:219], v[66:69]
	v_mfma_f32_16x16x32_bf16 v[114:117], v[246:249], v[34:37], v[94:97]
	v_mfma_f32_16x16x32_bf16 v[62:65], v[168:171], v[220:223], v[26:29]
	s_barrier
	ds_read_b128 v[74:77], v0 offset:49152
	ds_read_b128 v[78:81], v0 offset:50176
	ds_read_b128 v[110:113], v0 offset:51200
	ds_read_b128 v[208:211], v0 offset:52224
	ds_read_b128 v[212:215], v0 offset:53248
	ds_read_b128 v[216:219], v0 offset:54272
	ds_read_b128 v[220:223], v0 offset:55296
	ds_read_b128 v[152:155], v0 offset:56320
	s_barrier
	s_waitcnt lgkmcnt(0)
	s_waitcnt lgkmcnt(0)
	v_mfma_f32_16x16x32_bf16 v[26:29], v[10:13], v[74:77], v[226:229]
	v_mfma_f32_16x16x32_bf16 v[86:89], v[14:17], v[78:81], v[26:29]
	v_mfma_f32_16x16x32_bf16 v[26:29], v[200:203], v[74:77], v[230:233]
	v_mfma_f32_16x16x32_bf16 v[94:97], v[204:207], v[78:81], v[26:29]
	v_mfma_f32_16x16x32_bf16 v[26:29], v[10:13], v[110:113], v[234:237]
	v_mfma_f32_16x16x32_bf16 v[66:69], v[14:17], v[208:211], v[26:29]
	v_mfma_f32_16x16x32_bf16 v[26:29], v[200:203], v[110:113], v[238:241]
	v_mfma_f32_16x16x32_bf16 v[70:73], v[204:207], v[208:211], v[26:29]
	v_mfma_f32_16x16x32_bf16 v[26:29], v[10:13], v[212:215], v[46:49]
	v_mfma_f32_16x16x32_bf16 v[10:13], v[10:13], v[220:223], v[130:133]
	v_mfma_f32_16x16x32_bf16 v[26:29], v[14:17], v[216:219], v[26:29]
	v_mfma_f32_16x16x32_bf16 v[34:37], v[200:203], v[212:215], v[42:45]
	v_mfma_f32_16x16x32_bf16 v[10:13], v[14:17], v[152:155], v[10:13]
	v_mfma_f32_16x16x32_bf16 v[14:17], v[200:203], v[220:223], v[142:145]
	v_mfma_f32_16x16x32_bf16 v[34:37], v[204:207], v[216:219], v[34:37]
	v_mfma_f32_16x16x32_bf16 v[14:17], v[204:207], v[152:155], v[14:17]
	v_mfma_f32_16x16x32_bf16 v[42:45], v[242:245], v[74:77], v[146:149]
	v_mfma_f32_16x16x32_bf16 v[122:125], v[246:249], v[78:81], v[42:45]
	v_mfma_f32_16x16x32_bf16 v[42:45], v[250:253], v[74:77], v[172:175]
	v_mfma_f32_16x16x32_bf16 v[126:129], v[168:171], v[78:81], v[42:45]
	v_mfma_f32_16x16x32_bf16 v[42:45], v[242:245], v[110:113], v[176:179]
	v_mfma_f32_16x16x32_bf16 v[106:109], v[246:249], v[208:211], v[42:45]
	v_mfma_f32_16x16x32_bf16 v[42:45], v[250:253], v[110:113], v[180:183]
	v_mfma_f32_16x16x32_bf16 v[110:113], v[168:171], v[208:211], v[42:45]
	v_mfma_f32_16x16x32_bf16 v[42:45], v[242:245], v[212:215], v[184:187]
	v_mfma_f32_16x16x32_bf16 v[74:77], v[246:249], v[216:219], v[42:45]
	v_mfma_f32_16x16x32_bf16 v[42:45], v[250:253], v[212:215], v[188:191]
	v_mfma_f32_16x16x32_bf16 v[78:81], v[168:171], v[216:219], v[42:45]
	v_mfma_f32_16x16x32_bf16 v[42:45], v[242:245], v[220:223], v[192:195]
	v_mfma_f32_16x16x32_bf16 v[46:49], v[246:249], v[152:155], v[42:45]
	v_mfma_f32_16x16x32_bf16 v[42:45], v[250:253], v[220:223], v[196:199]
	v_mfma_f32_16x16x32_bf16 v[42:45], v[168:171], v[152:155], v[42:45]
	v_cmp_gt_u32_e32 vcc, s97, v139
	s_barrier
	s_and_saveexec_b64 s[10:11], vcc
	s_cbranch_execz .LBB0_658
	s_barrier
	s_branch .LBB0_658

; #define WAIT_L(n) asm volatile("s_waitcnt lgkmcnt(%0)" ::"n"(n) : "memory")
; #define SBAR() __builtin_amdgcn_sched_barrier(0)
; #define LDA8(dst, b, h) _Pragma("unroll") for (int m = 0; m < 4; ++m) _Pragma("unroll") for (int k = 0; k < 2; ++k) \
;     dst[m][k] = *(const bf16x8*)(abase + SAo(b, h) + m * 2048 + k * 1024)
; #define LDB8(dst, b, h) _Pragma("unroll") for (int n = 0; n < 2; ++n) _Pragma("unroll") for (int k = 0; k < 2; ++k) \
;     dst[n][k] = *(const bf16x8*)(bbase + SAo(b, h) + n * 2048 + k * 1024)
; #define BAR8 __builtin_amdgcn_s_barrier()
; __device__ __forceinline__ void gemm_main8(const u16* __restrict__ Ab, int lda, const u16* __restrict__ Bb, int ldb, int K,
;                                            char* shm, f32x4 (&acc)[2][2][4][2]) {
;     ...
;     LDB8(B0, 0, 0); SBAR(); LDA8(At, 0, 0); STG_A(1, 1, t + 1);
;     WAIT_L(8); BAR8; WAIT_L(0); MMA8(0, 0, At, B0); BAR8; SBAR();
;     LDB8(B1, 0, 1); STG_B(0, 0, t + 2);
;     BAR8; WAIT_L(0); MMA8(0, 1, At, B1); BAR8;
;     LDA8(At, 0, 1); STG_A(0, 0, t + 2);
;     BAR8; WAIT_L(0); MMA8(1, 0, At, B0); BAR8; SBAR();
.LBB0_816:
	ds_read_b128 v[152:155], v137
	ds_read_b128 v[176:179], v137 offset:1024
	ds_read_b128 v[180:183], v137 offset:2048
	ds_read_b128 v[184:187], v137 offset:3072
	ds_read_b128 v[188:191], v136
	ds_read_b128 v[192:195], v136 offset:1024
	ds_read_b128 v[196:199], v136 offset:2048
	ds_read_b128 v[200:203], v136 offset:3072
	ds_read_b128 v[204:207], v136 offset:4096
	ds_read_b128 v[208:211], v136 offset:5120
	ds_read_b128 v[212:215], v136 offset:6144
	ds_read_b128 v[216:219], v136 offset:7168
	v_add_u32_e32 v173, 0xc000, v138
	v_lshl_add_u64 v[164:165], s[24:25], 0, v[0:1]
	v_readfirstlane_b32 s11, v173
	v_add_u32_e32 v174, 0xe000, v138
	v_lshl_add_u64 v[166:167], v[164:165], 0, s[54:55]
	s_mov_b32 m0, s11
	v_readfirstlane_b32 s11, v174
	global_load_lds_dwordx4 v[166:167], off
	v_lshl_add_u64 v[166:167], v[164:165], 0, s[56:57]
	s_mov_b32 m0, s11
	s_nop 0
	global_load_lds_dwordx4 v[166:167], off
	s_waitcnt lgkmcnt(8)
	s_barrier
	s_waitcnt lgkmcnt(0)
	s_waitcnt lgkmcnt(0)
	v_mfma_f32_16x16x32_bf16 v[126:129], v[152:155], v[188:191], v[126:129]
	v_mfma_f32_16x16x32_bf16 v[122:125], v[180:183], v[188:191], v[122:125]
	v_mfma_f32_16x16x32_bf16 v[118:121], v[152:155], v[196:199], v[118:121]
	v_mfma_f32_16x16x32_bf16 v[114:117], v[180:183], v[196:199], v[114:117]
	v_mfma_f32_16x16x32_bf16 v[110:113], v[152:155], v[204:207], v[110:113]
	v_mfma_f32_16x16x32_bf16 v[106:109], v[180:183], v[204:207], v[106:109]
	v_mfma_f32_16x16x32_bf16 v[102:105], v[152:155], v[212:215], v[102:105]
	v_mfma_f32_16x16x32_bf16 v[98:101], v[180:183], v[212:215], v[98:101]
	v_mfma_f32_16x16x32_bf16 v[126:129], v[176:179], v[192:195], v[126:129]
	v_mfma_f32_16x16x32_bf16 v[122:125], v[184:187], v[192:195], v[122:125]
	v_mfma_f32_16x16x32_bf16 v[118:121], v[176:179], v[200:203], v[118:121]
	v_mfma_f32_16x16x32_bf16 v[114:117], v[184:187], v[200:203], v[114:117]
	v_mfma_f32_16x16x32_bf16 v[110:113], v[176:179], v[208:211], v[110:113]
	v_mfma_f32_16x16x32_bf16 v[106:109], v[184:187], v[208:211], v[106:109]
	v_mfma_f32_16x16x32_bf16 v[102:105], v[176:179], v[216:219], v[102:105]
	v_mfma_f32_16x16x32_bf16 v[98:101], v[184:187], v[216:219], v[98:101]
	s_barrier
	ds_read_b128 v[220:223], v137 offset:16384
	ds_read_b128 v[224:227], v137 offset:17408
	ds_read_b128 v[228:231], v137 offset:18432
	ds_read_b128 v[232:235], v137 offset:19456
	v_lshl_add_u64 v[166:167], s[20:21], 0, v[0:1]
	v_readfirstlane_b32 s11, v139
	v_lshl_add_u64 v[168:169], v[166:167], 0, s[70:71]
	s_mov_b32 m0, s11
	s_mov_b64 s[74:75], 0x40100
	v_readfirstlane_b32 s11, v140
	global_load_lds_dwordx4 v[168:169], off
	v_lshl_add_u64 v[168:169], v[166:167], 0, s[74:75]
	s_mov_b32 m0, s11
	s_nop 0
	global_load_lds_dwordx4 v[168:169], off
	s_barrier
	s_waitcnt lgkmcnt(0)
	s_waitcnt lgkmcnt(0)
	v_mfma_f32_16x16x32_bf16 v[94:97], v[220:223], v[188:191], v[94:97]
	v_mfma_f32_16x16x32_bf16 v[90:93], v[228:231], v[188:191], v[90:93]
	v_mfma_f32_16x16x32_bf16 v[86:89], v[220:223], v[196:199], v[86:89]
	v_mfma_f32_16x16x32_bf16 v[82:85], v[228:231], v[196:199], v[82:85]
	v_mfma_f32_16x16x32_bf16 v[78:81], v[220:223], v[204:207], v[78:81]
	v_mfma_f32_16x16x32_bf16 v[74:77], v[228:231], v[204:207], v[74:77]
	v_mfma_f32_16x16x32_bf16 v[70:73], v[220:223], v[212:215], v[70:73]
	v_mfma_f32_16x16x32_bf16 v[66:69], v[228:231], v[212:215], v[66:69]
	v_mfma_f32_16x16x32_bf16 v[94:97], v[224:227], v[192:195], v[94:97]
	v_mfma_f32_16x16x32_bf16 v[90:93], v[232:235], v[192:195], v[90:93]
	v_mfma_f32_16x16x32_bf16 v[86:89], v[224:227], v[200:203], v[86:89]
	v_mfma_f32_16x16x32_bf16 v[82:85], v[232:235], v[200:203], v[82:85]
	v_mfma_f32_16x16x32_bf16 v[78:81], v[224:227], v[208:211], v[78:81]
	v_mfma_f32_16x16x32_bf16 v[74:77], v[232:235], v[208:211], v[74:77]
	v_mfma_f32_16x16x32_bf16 v[70:73], v[224:227], v[216:219], v[70:73]
	v_mfma_f32_16x16x32_bf16 v[66:69], v[232:235], v[216:219], v[66:69]
	v_readfirstlane_b32 s11, v138
	v_lshl_add_u64 v[168:169], v[164:165], 0, s[58:59]
	s_mov_b32 m0, s11
	v_readfirstlane_b32 s11, v141
	s_barrier
	ds_read_b128 v[188:191], v136 offset:16384
	ds_read_b128 v[192:195], v136 offset:17408
	ds_read_b128 v[196:199], v136 offset:18432
	ds_read_b128 v[200:203], v136 offset:19456
	ds_read_b128 v[204:207], v136 offset:20480
	ds_read_b128 v[208:211], v136 offset:21504
	ds_read_b128 v[212:215], v136 offset:22528
	ds_read_b128 v[216:219], v136 offset:23552
	global_load_lds_dwordx4 v[168:169], off
	v_lshl_add_u64 v[168:169], v[164:165], 0, s[60:61]
	s_mov_b32 m0, s11
	s_nop 0
	global_load_lds_dwordx4 v[168:169], off
	s_barrier
	s_waitcnt lgkmcnt(0)
	s_waitcnt lgkmcnt(0)
	v_mfma_f32_16x16x32_bf16 v[62:65], v[152:155], v[188:191], v[62:65]
	v_mfma_f32_16x16x32_bf16 v[58:61], v[180:183], v[188:191], v[58:61]
	v_mfma_f32_16x16x32_bf16 v[54:57], v[152:155], v[196:199], v[54:57]
	v_mfma_f32_16x16x32_bf16 v[50:53], v[180:183], v[196:199], v[50:53]
	v_mfma_f32_16x16x32_bf16 v[46:49], v[152:155], v[204:207], v[46:49]
	v_mfma_f32_16x16x32_bf16 v[42:45], v[180:183], v[204:207], v[42:45]
	v_mfma_f32_16x16x32_bf16 v[38:41], v[152:155], v[212:215], v[38:41]
	v_mfma_f32_16x16x32_bf16 v[34:37], v[180:183], v[212:215], v[34:37]
	v_mfma_f32_16x16x32_bf16 v[62:65], v[176:179], v[192:195], v[62:65]
	v_mfma_f32_16x16x32_bf16 v[58:61], v[184:187], v[192:195], v[58:61]
	v_mfma_f32_16x16x32_bf16 v[54:57], v[176:179], v[200:203], v[54:57]
	v_mfma_f32_16x16x32_bf16 v[50:53], v[184:187], v[200:203], v[50:53]
	v_mfma_f32_16x16x32_bf16 v[46:49], v[176:179], v[208:211], v[46:49]
	v_mfma_f32_16x16x32_bf16 v[42:45], v[184:187], v[208:211], v[42:45]
	v_mfma_f32_16x16x32_bf16 v[38:41], v[176:179], v[216:219], v[38:41]
	v_mfma_f32_16x16x32_bf16 v[34:37], v[184:187], v[216:219], v[34:37]
	s_barrier
; #define WAIT_V(n) asm volatile("s_waitcnt vmcnt(%0)" ::"n"(n) : "memory")
; #define WAIT_L(n) asm volatile("s_waitcnt lgkmcnt(%0)" ::"n"(n) : "memory")
; #define SBAR() __builtin_amdgcn_sched_barrier(0)
; #define LDA8(dst, b, h) _Pragma("unroll") for (int m = 0; m < 4; ++m) _Pragma("unroll") for (int k = 0; k < 2; ++k) \
;     dst[m][k] = *(const bf16x8*)(abase + SAo(b, h) + m * 2048 + k * 1024)
; #define LDB8(dst, b, h) _Pragma("unroll") for (int n = 0; n < 2; ++n) _Pragma("unroll") for (int k = 0; k < 2; ++k) \
;     dst[n][k] = *(const bf16x8*)(bbase + SAo(b, h) + n * 2048 + k * 1024)
; #define BAR8 __builtin_amdgcn_s_barrier()
; __device__ __forceinline__ void gemm_main8(const u16* __restrict__ Ab, int lda, const u16* __restrict__ Bb, int ldb, int K,
;                                            char* shm, f32x4 (&acc)[2][2][4][2]) {
;     ...
;     STG_B(0, 1, t + 2);
;     WAIT_V(6); BAR8; MMA8(1, 1, At, B1); BAR8;
;     LDB8(B0, 1, 0); SBAR(); LDA8(At, 1, 0); STG_A(0, 1, t + 2);
;     WAIT_L(8); BAR8; WAIT_L(0); MMA8(0, 0, At, B0); BAR8; SBAR();
;     LDB8(B1, 1, 1); STG_B(1, 0, t + 3);
;     BAR8; WAIT_L(0); MMA8(0, 1, At, B1); BAR8;
;     LDA8(At, 1, 1); STG_A(1, 0, t + 3);
	s_mov_b64 s[74:75], 0x80100
	v_readfirstlane_b32 s11, v142
	v_lshl_add_u64 v[152:153], v[166:167], 0, s[74:75]
	s_mov_b32 m0, s11
	s_mov_b64 s[74:75], 0xc0100
	v_readfirstlane_b32 s11, v143
	global_load_lds_dwordx4 v[152:153], off
	v_lshl_add_u64 v[152:153], v[166:167], 0, s[74:75]
	s_mov_b32 m0, s11
	s_nop 0
	global_load_lds_dwordx4 v[152:153], off
	s_waitcnt vmcnt(6)
	s_barrier
	v_mfma_f32_16x16x32_bf16 v[30:33], v[220:223], v[188:191], v[30:33]
	v_mfma_f32_16x16x32_bf16 v[26:29], v[228:231], v[188:191], v[26:29]
	v_mfma_f32_16x16x32_bf16 v[22:25], v[220:223], v[196:199], v[22:25]
	v_mfma_f32_16x16x32_bf16 v[18:21], v[228:231], v[196:199], v[18:21]
	v_mfma_f32_16x16x32_bf16 v[14:17], v[220:223], v[204:207], v[14:17]
	v_mfma_f32_16x16x32_bf16 v[10:13], v[228:231], v[204:207], v[10:13]
	v_mfma_f32_16x16x32_bf16 v[6:9], v[220:223], v[212:215], v[6:9]
	v_mfma_f32_16x16x32_bf16 v[2:5], v[228:231], v[212:215], v[2:5]
	v_mfma_f32_16x16x32_bf16 v[30:33], v[224:227], v[192:195], v[30:33]
	v_mfma_f32_16x16x32_bf16 v[26:29], v[232:235], v[192:195], v[26:29]
	v_mfma_f32_16x16x32_bf16 v[22:25], v[224:227], v[200:203], v[22:25]
	v_mfma_f32_16x16x32_bf16 v[18:21], v[232:235], v[200:203], v[18:21]
	v_mfma_f32_16x16x32_bf16 v[14:17], v[224:227], v[208:211], v[14:17]
	v_mfma_f32_16x16x32_bf16 v[10:13], v[232:235], v[208:211], v[10:13]
	v_mfma_f32_16x16x32_bf16 v[6:9], v[224:227], v[216:219], v[6:9]
	v_mfma_f32_16x16x32_bf16 v[2:5], v[232:235], v[216:219], v[2:5]
	s_barrier
	ds_read_b128 v[152:155], v137 offset:32768
	ds_read_b128 v[176:179], v137 offset:33792
	ds_read_b128 v[180:183], v137 offset:34816
	ds_read_b128 v[184:187], v137 offset:35840
	ds_read_b128 v[188:191], v136 offset:32768
	ds_read_b128 v[192:195], v136 offset:33792
	ds_read_b128 v[196:199], v136 offset:34816
	ds_read_b128 v[200:203], v136 offset:35840
	ds_read_b128 v[204:207], v136 offset:36864
	ds_read_b128 v[208:211], v136 offset:37888
	ds_read_b128 v[212:215], v136 offset:38912
	ds_read_b128 v[216:219], v136 offset:39936
	v_readfirstlane_b32 s11, v144
	v_lshl_add_u64 v[168:169], v[164:165], 0, s[62:63]
	s_mov_b32 m0, s11
	v_readfirstlane_b32 s11, v145
	global_load_lds_dwordx4 v[168:169], off
	v_lshl_add_u64 v[168:169], v[164:165], 0, s[64:65]
	s_mov_b32 m0, s11
	s_nop 0
	global_load_lds_dwordx4 v[168:169], off
	s_waitcnt lgkmcnt(8)
	s_barrier
	s_waitcnt lgkmcnt(0)
	s_waitcnt lgkmcnt(0)
	v_mfma_f32_16x16x32_bf16 v[126:129], v[152:155], v[188:191], v[126:129]
	v_mfma_f32_16x16x32_bf16 v[122:125], v[180:183], v[188:191], v[122:125]
	v_mfma_f32_16x16x32_bf16 v[118:121], v[152:155], v[196:199], v[118:121]
	v_mfma_f32_16x16x32_bf16 v[114:117], v[180:183], v[196:199], v[114:117]
	v_mfma_f32_16x16x32_bf16 v[110:113], v[152:155], v[204:207], v[110:113]
	v_mfma_f32_16x16x32_bf16 v[106:109], v[180:183], v[204:207], v[106:109]
	v_mfma_f32_16x16x32_bf16 v[102:105], v[152:155], v[212:215], v[102:105]
	v_mfma_f32_16x16x32_bf16 v[98:101], v[180:183], v[212:215], v[98:101]
	v_mfma_f32_16x16x32_bf16 v[126:129], v[176:179], v[192:195], v[126:129]
	v_mfma_f32_16x16x32_bf16 v[122:125], v[184:187], v[192:195], v[122:125]
	v_mfma_f32_16x16x32_bf16 v[118:121], v[176:179], v[200:203], v[118:121]
	v_mfma_f32_16x16x32_bf16 v[114:117], v[184:187], v[200:203], v[114:117]
	v_mfma_f32_16x16x32_bf16 v[110:113], v[176:179], v[208:211], v[110:113]
	v_mfma_f32_16x16x32_bf16 v[106:109], v[184:187], v[208:211], v[106:109]
	v_mfma_f32_16x16x32_bf16 v[102:105], v[176:179], v[216:219], v[102:105]
	v_mfma_f32_16x16x32_bf16 v[98:101], v[184:187], v[216:219], v[98:101]
	s_barrier
	ds_read_b128 v[220:223], v137 offset:49152
	ds_read_b128 v[224:227], v137 offset:50176
	ds_read_b128 v[228:231], v137 offset:51200
	ds_read_b128 v[232:235], v137 offset:52224
	v_readfirstlane_b32 s11, v146
	v_lshl_add_u64 v[168:169], v[166:167], 0, s[8:9]
	s_mov_b32 m0, s11
	s_mov_b64 s[74:75], 0x40180
	v_readfirstlane_b32 s11, v147
	global_load_lds_dwordx4 v[168:169], off
	v_lshl_add_u64 v[168:169], v[166:167], 0, s[74:75]
	s_mov_b32 m0, s11
	s_nop 0
	global_load_lds_dwordx4 v[168:169], off
	s_barrier
	s_waitcnt lgkmcnt(0)
	s_waitcnt lgkmcnt(0)
	v_mfma_f32_16x16x32_bf16 v[94:97], v[220:223], v[188:191], v[94:97]
	v_mfma_f32_16x16x32_bf16 v[90:93], v[228:231], v[188:191], v[90:93]
	v_mfma_f32_16x16x32_bf16 v[86:89], v[220:223], v[196:199], v[86:89]
	v_mfma_f32_16x16x32_bf16 v[82:85], v[228:231], v[196:199], v[82:85]
	v_mfma_f32_16x16x32_bf16 v[78:81], v[220:223], v[204:207], v[78:81]
	v_mfma_f32_16x16x32_bf16 v[74:77], v[228:231], v[204:207], v[74:77]
	v_mfma_f32_16x16x32_bf16 v[70:73], v[220:223], v[212:215], v[70:73]
	v_mfma_f32_16x16x32_bf16 v[66:69], v[228:231], v[212:215], v[66:69]
	v_mfma_f32_16x16x32_bf16 v[94:97], v[224:227], v[192:195], v[94:97]
	v_mfma_f32_16x16x32_bf16 v[90:93], v[232:235], v[192:195], v[90:93]
	v_mfma_f32_16x16x32_bf16 v[86:89], v[224:227], v[200:203], v[86:89]
	v_mfma_f32_16x16x32_bf16 v[82:85], v[232:235], v[200:203], v[82:85]
	v_mfma_f32_16x16x32_bf16 v[78:81], v[224:227], v[208:211], v[78:81]
	v_mfma_f32_16x16x32_bf16 v[74:77], v[232:235], v[208:211], v[74:77]
	v_mfma_f32_16x16x32_bf16 v[70:73], v[224:227], v[216:219], v[70:73]
	v_mfma_f32_16x16x32_bf16 v[66:69], v[232:235], v[216:219], v[66:69]
	v_readfirstlane_b32 s11, v148
	v_lshl_add_u64 v[168:169], v[164:165], 0, s[66:67]
	s_mov_b32 m0, s11
	v_readfirstlane_b32 s11, v149
	s_barrier
	ds_read_b128 v[188:191], v136 offset:49152
	ds_read_b128 v[192:195], v136 offset:50176
	ds_read_b128 v[196:199], v136 offset:51200
	ds_read_b128 v[200:203], v136 offset:52224
	ds_read_b128 v[204:207], v136 offset:53248
	ds_read_b128 v[208:211], v136 offset:54272
	ds_read_b128 v[212:215], v136 offset:55296
	ds_read_b128 v[216:219], v136 offset:56320
	global_load_lds_dwordx4 v[168:169], off
	v_lshl_add_u64 v[164:165], v[164:165], 0, s[68:69]
	s_mov_b32 m0, s11
	s_nop 0
	global_load_lds_dwordx4 v[164:165], off
	s_barrier
; #define WAIT_V(n) asm volatile("s_waitcnt vmcnt(%0)" ::"n"(n) : "memory")
; #define WAIT_L(n) asm volatile("s_waitcnt lgkmcnt(%0)" ::"n"(n) : "memory")
; #define SBAR() __builtin_amdgcn_sched_barrier(0)
; #define LDA8(dst, b, h) _Pragma("unroll") for (int m = 0; m < 4; ++m) _Pragma("unroll") for (int k = 0; k < 2; ++k) \
;     dst[m][k] = *(const bf16x8*)(abase + SAo(b, h) + m * 2048 + k * 1024)
; #define LDB8(dst, b, h) _Pragma("unroll") for (int n = 0; n < 2; ++n) _Pragma("unroll") for (int k = 0; k < 2; ++k) \
;     dst[n][k] = *(const bf16x8*)(bbase + SAo(b, h) + n * 2048 + k * 1024)
; #define BAR8 __builtin_amdgcn_s_barrier()
; __device__ __forceinline__ void gemm_main8(const u16* __restrict__ Ab, int lda, const u16* __restrict__ Bb, int ldb, int K,
;                                            char* shm, f32x4 (&acc)[2][2][4][2]) {
;     ...
;     LDA8(At, 1, 1); STG_A(1, 0, t + 3);
;     BAR8; WAIT_L(0); MMA8(1, 0, At, B0); BAR8; SBAR();
;     STG_B(1, 1, t + 3);
;     WAIT_V(6); BAR8; MMA8(1, 1, At, B1); BAR8;
;   }
;   { LDB8(B0, 0, 0); LDA8(At, 0, 0); STG_A(1, 1, nt - 1);
;     BAR8; WAIT_L(0); MMA8(0, 0, At, B0); BAR8;
	s_waitcnt lgkmcnt(0)
	s_waitcnt lgkmcnt(0)
	v_mfma_f32_16x16x32_bf16 v[62:65], v[152:155], v[188:191], v[62:65]
	v_mfma_f32_16x16x32_bf16 v[58:61], v[180:183], v[188:191], v[58:61]
	v_mfma_f32_16x16x32_bf16 v[54:57], v[152:155], v[196:199], v[54:57]
	v_mfma_f32_16x16x32_bf16 v[50:53], v[180:183], v[196:199], v[50:53]
	v_mfma_f32_16x16x32_bf16 v[46:49], v[152:155], v[204:207], v[46:49]
	v_mfma_f32_16x16x32_bf16 v[42:45], v[180:183], v[204:207], v[42:45]
	v_mfma_f32_16x16x32_bf16 v[38:41], v[152:155], v[212:215], v[38:41]
	v_mfma_f32_16x16x32_bf16 v[34:37], v[180:183], v[212:215], v[34:37]
	v_mfma_f32_16x16x32_bf16 v[62:65], v[176:179], v[192:195], v[62:65]
	v_mfma_f32_16x16x32_bf16 v[58:61], v[184:187], v[192:195], v[58:61]
	v_mfma_f32_16x16x32_bf16 v[54:57], v[176:179], v[200:203], v[54:57]
	v_mfma_f32_16x16x32_bf16 v[50:53], v[184:187], v[200:203], v[50:53]
	v_mfma_f32_16x16x32_bf16 v[46:49], v[176:179], v[208:211], v[46:49]
	v_mfma_f32_16x16x32_bf16 v[42:45], v[184:187], v[208:211], v[42:45]
	v_mfma_f32_16x16x32_bf16 v[38:41], v[176:179], v[216:219], v[38:41]
	v_mfma_f32_16x16x32_bf16 v[34:37], v[184:187], v[216:219], v[34:37]
	s_barrier
	s_mov_b64 s[74:75], 0x80180
	v_readfirstlane_b32 s11, v171
	v_lshl_add_u64 v[152:153], v[166:167], 0, s[74:75]
	s_mov_b32 m0, s11
	s_mov_b64 s[74:75], 0xc0180
	v_readfirstlane_b32 s11, v172
	global_load_lds_dwordx4 v[152:153], off
	v_lshl_add_u64 v[152:153], v[166:167], 0, s[74:75]
	s_mov_b32 m0, s11
	s_nop 0
	global_load_lds_dwordx4 v[152:153], off
	s_waitcnt vmcnt(6)
	s_barrier
	v_mfma_f32_16x16x32_bf16 v[30:33], v[220:223], v[188:191], v[30:33]
	v_mfma_f32_16x16x32_bf16 v[26:29], v[228:231], v[188:191], v[26:29]
	v_mfma_f32_16x16x32_bf16 v[22:25], v[220:223], v[196:199], v[22:25]
	v_mfma_f32_16x16x32_bf16 v[18:21], v[228:231], v[196:199], v[18:21]
	v_mfma_f32_16x16x32_bf16 v[14:17], v[220:223], v[204:207], v[14:17]
	v_mfma_f32_16x16x32_bf16 v[10:13], v[228:231], v[204:207], v[10:13]
	v_mfma_f32_16x16x32_bf16 v[6:9], v[220:223], v[212:215], v[6:9]
	v_mfma_f32_16x16x32_bf16 v[2:5], v[228:231], v[212:215], v[2:5]
	v_mfma_f32_16x16x32_bf16 v[30:33], v[224:227], v[192:195], v[30:33]
	v_mfma_f32_16x16x32_bf16 v[26:29], v[232:235], v[192:195], v[26:29]
	v_mfma_f32_16x16x32_bf16 v[22:25], v[224:227], v[200:203], v[22:25]
	v_mfma_f32_16x16x32_bf16 v[18:21], v[232:235], v[200:203], v[18:21]
	v_mfma_f32_16x16x32_bf16 v[14:17], v[224:227], v[208:211], v[14:17]
	v_mfma_f32_16x16x32_bf16 v[10:13], v[232:235], v[208:211], v[10:13]
	v_mfma_f32_16x16x32_bf16 v[6:9], v[224:227], v[216:219], v[6:9]
	v_mfma_f32_16x16x32_bf16 v[2:5], v[232:235], v[216:219], v[2:5]
	s_add_i32 s10, s10, 2
	s_add_u32 s20, s20, 0x100
	s_addc_u32 s21, s21, 0
	s_add_u32 s24, s24, 0x100
	s_addc_u32 s25, s25, 0
	s_cmp_lt_u32 s10, 28
	s_barrier
	s_cbranch_scc1 .LBB0_816
	s_mov_b64 s[10:11], 0x80f80
	v_lshl_add_u64 v[164:165], v[130:131], 0, s[10:11]
	v_readfirstlane_b32 s10, v173
	s_mov_b32 m0, s10
	s_mov_b64 s[10:11], 0xc0f80
	v_lshl_add_u64 v[130:131], v[130:131], 0, s[10:11]
	v_readfirstlane_b32 s10, v174
	ds_read_b128 v[138:141], v137
	ds_read_b128 v[142:145], v137 offset:1024
	ds_read_b128 v[146:149], v137 offset:2048
	ds_read_b128 v[152:155], v137 offset:3072
	ds_read_b128 v[168:171], v136
	ds_read_b128 v[176:179], v136 offset:1024
	ds_read_b128 v[180:183], v136 offset:2048
	ds_read_b128 v[184:187], v136 offset:3072
	ds_read_b128 v[188:191], v136 offset:4096
	ds_read_b128 v[192:195], v136 offset:5120
	ds_read_b128 v[196:199], v136 offset:6144
	ds_read_b128 v[200:203], v136 offset:7168
	global_load_lds_dwordx4 v[164:165], off
	s_mov_b32 m0, s10
	s_nop 0
	global_load_lds_dwordx4 v[130:131], off
	s_barrier
	s_waitcnt lgkmcnt(0)
	s_waitcnt lgkmcnt(0)
	v_mfma_f32_16x16x32_bf16 v[126:129], v[138:141], v[168:171], v[126:129]
	v_mfma_f32_16x16x32_bf16 v[118:121], v[138:141], v[180:183], v[118:121]
	v_mfma_f32_16x16x32_bf16 v[110:113], v[138:141], v[188:191], v[110:113]
	v_mfma_f32_16x16x32_bf16 v[102:105], v[138:141], v[196:199], v[102:105]
	v_mfma_f32_16x16x32_bf16 v[126:129], v[142:145], v[176:179], v[126:129]
	v_mfma_f32_16x16x32_bf16 v[122:125], v[146:149], v[168:171], v[122:125]
	v_mfma_f32_16x16x32_bf16 v[118:121], v[142:145], v[184:187], v[118:121]
	v_mfma_f32_16x16x32_bf16 v[114:117], v[146:149], v[180:183], v[114:117]
	v_mfma_f32_16x16x32_bf16 v[110:113], v[142:145], v[192:195], v[110:113]
	v_mfma_f32_16x16x32_bf16 v[106:109], v[146:149], v[188:191], v[106:109]
	v_mfma_f32_16x16x32_bf16 v[102:105], v[142:145], v[200:203], v[102:105]
	v_mfma_f32_16x16x32_bf16 v[98:101], v[146:149], v[196:199], v[98:101]
	v_mfma_f32_16x16x32_bf16 v[172:175], v[152:155], v[176:179], v[122:125]
	v_mfma_f32_16x16x32_bf16 v[204:207], v[152:155], v[184:187], v[114:117]
	v_mfma_f32_16x16x32_bf16 v[208:211], v[152:155], v[192:195], v[106:109]
	v_mfma_f32_16x16x32_bf16 v[212:215], v[152:155], v[200:203], v[98:101]
	s_barrier
	s_nop 1
	ds_read_b128 v[98:101], v137 offset:16384
	ds_read_b128 v[106:109], v137 offset:17408
	ds_read_b128 v[114:117], v137 offset:18432
	ds_read_b128 v[122:125], v137 offset:19456
	s_barrier
; #define WAIT_V(n) asm volatile("s_waitcnt vmcnt(%0)" ::"n"(n) : "memory")
; #define WAIT_L(n) asm volatile("s_waitcnt lgkmcnt(%0)" ::"n"(n) : "memory")
; #define LDA8(dst, b, h) _Pragma("unroll") for (int m = 0; m < 4; ++m) _Pragma("unroll") for (int k = 0; k < 2; ++k) \
;     dst[m][k] = *(const bf16x8*)(abase + SAo(b, h) + m * 2048 + k * 1024)
; #define LDB8(dst, b, h) _Pragma("unroll") for (int n = 0; n < 2; ++n) _Pragma("unroll") for (int k = 0; k < 2; ++k) \
;     dst[n][k] = *(const bf16x8*)(bbase + SAo(b, h) + n * 2048 + k * 1024)
; #define BAR8 __builtin_amdgcn_s_barrier()
; __device__ __forceinline__ void gemm_main8(const u16* __restrict__ Ab, int lda, const u16* __restrict__ Bb, int ldb, int K,
;                                            char* shm, f32x4 (&acc)[2][2][4][2]) {
;     ...
;     LDB8(B1, 0, 1); BAR8; WAIT_L(0); MMA8(0, 1, At, B1); BAR8;
;     LDA8(At, 0, 1); WAIT_V(4); BAR8; WAIT_L(0); MMA8(1, 0, At, B0); MMA8(1, 1, At, B1); BAR8; }
;   { LDB8(B0, 1, 0); LDA8(At, 1, 0); WAIT_V(2); BAR8; WAIT_L(0); MMA8(0, 0, At, B0); BAR8;
	s_waitcnt lgkmcnt(0)
	s_waitcnt lgkmcnt(0)
	v_mfma_f32_16x16x32_bf16 v[94:97], v[98:101], v[168:171], v[94:97]
	v_mfma_f32_16x16x32_bf16 v[86:89], v[98:101], v[180:183], v[86:89]
	v_mfma_f32_16x16x32_bf16 v[78:81], v[98:101], v[188:191], v[78:81]
	v_mfma_f32_16x16x32_bf16 v[70:73], v[98:101], v[196:199], v[70:73]
	v_mfma_f32_16x16x32_bf16 v[94:97], v[106:109], v[176:179], v[94:97]
	v_mfma_f32_16x16x32_bf16 v[90:93], v[114:117], v[168:171], v[90:93]
	v_mfma_f32_16x16x32_bf16 v[86:89], v[106:109], v[184:187], v[86:89]
	v_mfma_f32_16x16x32_bf16 v[82:85], v[114:117], v[180:183], v[82:85]
	v_mfma_f32_16x16x32_bf16 v[78:81], v[106:109], v[192:195], v[78:81]
	v_mfma_f32_16x16x32_bf16 v[74:77], v[114:117], v[188:191], v[74:77]
	v_mfma_f32_16x16x32_bf16 v[70:73], v[106:109], v[200:203], v[70:73]
	v_mfma_f32_16x16x32_bf16 v[66:69], v[114:117], v[196:199], v[66:69]
	v_mfma_f32_16x16x32_bf16 v[168:171], v[122:125], v[176:179], v[90:93]
	v_mfma_f32_16x16x32_bf16 v[176:179], v[122:125], v[184:187], v[82:85]
	v_mfma_f32_16x16x32_bf16 v[180:183], v[122:125], v[192:195], v[74:77]
	v_mfma_f32_16x16x32_bf16 v[184:187], v[122:125], v[200:203], v[66:69]
	s_barrier
	s_nop 1
	ds_read_b128 v[66:69], v136 offset:16384
	ds_read_b128 v[74:77], v136 offset:17408
	ds_read_b128 v[82:85], v136 offset:18432
	ds_read_b128 v[90:93], v136 offset:19456
	ds_read_b128 v[188:191], v136 offset:20480
	ds_read_b128 v[192:195], v136 offset:21504
	ds_read_b128 v[196:199], v136 offset:22528
	ds_read_b128 v[200:203], v136 offset:23552
	s_waitcnt vmcnt(4)
	s_barrier
	s_waitcnt lgkmcnt(0)
	s_waitcnt lgkmcnt(0)
	v_mfma_f32_16x16x32_bf16 v[62:65], v[138:141], v[66:69], v[62:65]
	v_mfma_f32_16x16x32_bf16 v[58:61], v[146:149], v[66:69], v[58:61]
	v_mfma_f32_16x16x32_bf16 v[50:53], v[146:149], v[82:85], v[50:53]
	v_mfma_f32_16x16x32_bf16 v[42:45], v[146:149], v[188:191], v[42:45]
	v_mfma_f32_16x16x32_bf16 v[34:37], v[146:149], v[196:199], v[34:37]
	v_mfma_f32_16x16x32_bf16 v[62:65], v[142:145], v[74:77], v[62:65]
	v_mfma_f32_16x16x32_bf16 v[58:61], v[152:155], v[74:77], v[58:61]
	v_mfma_f32_16x16x32_bf16 v[54:57], v[138:141], v[82:85], v[54:57]
	v_mfma_f32_16x16x32_bf16 v[50:53], v[152:155], v[90:93], v[50:53]
	v_mfma_f32_16x16x32_bf16 v[46:49], v[138:141], v[188:191], v[46:49]
	v_mfma_f32_16x16x32_bf16 v[42:45], v[152:155], v[192:195], v[42:45]
	v_mfma_f32_16x16x32_bf16 v[38:41], v[138:141], v[196:199], v[38:41]
	v_mfma_f32_16x16x32_bf16 v[34:37], v[152:155], v[200:203], v[34:37]
	v_mfma_f32_16x16x32_bf16 v[216:219], v[142:145], v[90:93], v[54:57]
	v_mfma_f32_16x16x32_bf16 v[220:223], v[142:145], v[192:195], v[46:49]
	v_mfma_f32_16x16x32_bf16 v[138:141], v[142:145], v[200:203], v[38:41]
	v_mfma_f32_16x16x32_bf16 v[26:29], v[114:117], v[66:69], v[26:29]
	v_mfma_f32_16x16x32_bf16 v[18:21], v[114:117], v[82:85], v[18:21]
	v_mfma_f32_16x16x32_bf16 v[10:13], v[114:117], v[188:191], v[10:13]
	v_mfma_f32_16x16x32_bf16 v[2:5], v[114:117], v[196:199], v[2:5]
	v_mfma_f32_16x16x32_bf16 v[30:33], v[98:101], v[66:69], v[30:33]
	v_mfma_f32_16x16x32_bf16 v[26:29], v[122:125], v[74:77], v[26:29]
	v_mfma_f32_16x16x32_bf16 v[22:25], v[98:101], v[82:85], v[22:25]
	v_mfma_f32_16x16x32_bf16 v[18:21], v[122:125], v[90:93], v[18:21]
	v_mfma_f32_16x16x32_bf16 v[14:17], v[98:101], v[188:191], v[14:17]
	v_mfma_f32_16x16x32_bf16 v[10:13], v[122:125], v[192:195], v[10:13]
	v_mfma_f32_16x16x32_bf16 v[6:9], v[98:101], v[196:199], v[6:9]
	v_mfma_f32_16x16x32_bf16 v[2:5], v[122:125], v[200:203], v[2:5]
	v_mfma_f32_16x16x32_bf16 v[142:145], v[106:109], v[74:77], v[30:33]
	v_mfma_f32_16x16x32_bf16 v[146:149], v[106:109], v[90:93], v[22:25]
	v_mfma_f32_16x16x32_bf16 v[152:155], v[106:109], v[192:195], v[14:17]
	v_mfma_f32_16x16x32_bf16 v[188:191], v[106:109], v[200:203], v[6:9]
	s_barrier
	s_nop 0
	ds_read_b128 v[6:9], v137 offset:32768
	ds_read_b128 v[14:17], v137 offset:33792
	ds_read_b128 v[192:195], v137 offset:34816
	ds_read_b128 v[196:199], v137 offset:35840
	ds_read_b128 v[22:25], v136 offset:32768
	ds_read_b128 v[30:33], v136 offset:33792
	ds_read_b128 v[38:41], v136 offset:34816
	ds_read_b128 v[46:49], v136 offset:35840
	ds_read_b128 v[54:57], v136 offset:36864
	ds_read_b128 v[200:203], v136 offset:37888
	ds_read_b128 v[224:227], v136 offset:38912
	ds_read_b128 v[228:231], v136 offset:39936
	s_waitcnt vmcnt(2)
	s_barrier
; #define WAIT_V(n) asm volatile("s_waitcnt vmcnt(%0)" ::"n"(n) : "memory")
; #define WAIT_L(n) asm volatile("s_waitcnt lgkmcnt(%0)" ::"n"(n) : "memory")
; #define LDA8(dst, b, h) _Pragma("unroll") for (int m = 0; m < 4; ++m) _Pragma("unroll") for (int k = 0; k < 2; ++k) \
;     dst[m][k] = *(const bf16x8*)(abase + SAo(b, h) + m * 2048 + k * 1024)
; #define LDB8(dst, b, h) _Pragma("unroll") for (int n = 0; n < 2; ++n) _Pragma("unroll") for (int k = 0; k < 2; ++k) \
;     dst[n][k] = *(const bf16x8*)(bbase + SAo(b, h) + n * 2048 + k * 1024)
; #define BAR8 __builtin_amdgcn_s_barrier()
; __device__ __forceinline__ void gemm_main8(const u16* __restrict__ Ab, int lda, const u16* __restrict__ Bb, int ldb, int K,
;                                            char* shm, f32x4 (&acc)[2][2][4][2]) {
;     ...
;   { LDB8(B0, 1, 0); LDA8(At, 1, 0); WAIT_V(2); BAR8; WAIT_L(0); MMA8(0, 0, At, B0); BAR8;
;     LDB8(B1, 1, 1); WAIT_V(0); BAR8; WAIT_L(0); MMA8(0, 1, At, B1); BAR8;
;     LDA8(At, 1, 1); BAR8; WAIT_L(0); MMA8(1, 0, At, B0); MMA8(1, 1, At, B1); BAR8; }
;   if (wr == 0) BAR8;
	s_waitcnt lgkmcnt(0)
	s_waitcnt lgkmcnt(0)
	v_mfma_f32_16x16x32_bf16 v[66:69], v[6:9], v[22:25], v[126:129]
	v_mfma_f32_16x16x32_bf16 v[122:125], v[14:17], v[30:33], v[66:69]
	v_mfma_f32_16x16x32_bf16 v[66:69], v[192:195], v[22:25], v[172:175]
	v_mfma_f32_16x16x32_bf16 v[114:117], v[196:199], v[30:33], v[66:69]
	v_mfma_f32_16x16x32_bf16 v[66:69], v[6:9], v[38:41], v[118:121]
	v_mfma_f32_16x16x32_bf16 v[106:109], v[14:17], v[46:49], v[66:69]
	v_mfma_f32_16x16x32_bf16 v[66:69], v[192:195], v[38:41], v[204:207]
	v_mfma_f32_16x16x32_bf16 v[98:101], v[196:199], v[46:49], v[66:69]
	v_mfma_f32_16x16x32_bf16 v[66:69], v[6:9], v[54:57], v[110:113]
	v_mfma_f32_16x16x32_bf16 v[90:93], v[14:17], v[200:203], v[66:69]
	v_mfma_f32_16x16x32_bf16 v[66:69], v[192:195], v[54:57], v[208:211]
	v_mfma_f32_16x16x32_bf16 v[82:85], v[196:199], v[200:203], v[66:69]
	v_mfma_f32_16x16x32_bf16 v[66:69], v[6:9], v[224:227], v[102:105]
	v_mfma_f32_16x16x32_bf16 v[74:77], v[14:17], v[228:231], v[66:69]
	v_mfma_f32_16x16x32_bf16 v[66:69], v[192:195], v[224:227], v[212:215]
	v_mfma_f32_16x16x32_bf16 v[66:69], v[196:199], v[228:231], v[66:69]
	s_barrier
	ds_read_b128 v[172:175], v137 offset:49152
	ds_read_b128 v[204:207], v137 offset:50176
	ds_read_b128 v[208:211], v137 offset:51200
	ds_read_b128 v[212:215], v137 offset:52224
	s_waitcnt vmcnt(0)
	s_barrier
	s_waitcnt lgkmcnt(0)
	s_waitcnt lgkmcnt(0)
	v_mfma_f32_16x16x32_bf16 v[94:97], v[172:175], v[22:25], v[94:97]
	v_mfma_f32_16x16x32_bf16 v[22:25], v[208:211], v[22:25], v[168:171]
	v_mfma_f32_16x16x32_bf16 v[118:121], v[212:215], v[30:33], v[22:25]
	v_mfma_f32_16x16x32_bf16 v[22:25], v[172:175], v[38:41], v[86:89]
	v_mfma_f32_16x16x32_bf16 v[110:113], v[204:207], v[46:49], v[22:25]
	v_mfma_f32_16x16x32_bf16 v[22:25], v[208:211], v[38:41], v[176:179]
	v_mfma_f32_16x16x32_bf16 v[102:105], v[212:215], v[46:49], v[22:25]
	v_mfma_f32_16x16x32_bf16 v[22:25], v[172:175], v[54:57], v[78:81]
	v_mfma_f32_16x16x32_bf16 v[126:129], v[204:207], v[30:33], v[94:97]
	v_mfma_f32_16x16x32_bf16 v[94:97], v[204:207], v[200:203], v[22:25]
	v_mfma_f32_16x16x32_bf16 v[22:25], v[208:211], v[54:57], v[180:183]
	v_mfma_f32_16x16x32_bf16 v[86:89], v[212:215], v[200:203], v[22:25]
	v_mfma_f32_16x16x32_bf16 v[22:25], v[172:175], v[224:227], v[70:73]
	v_mfma_f32_16x16x32_bf16 v[78:81], v[204:207], v[228:231], v[22:25]
	v_mfma_f32_16x16x32_bf16 v[22:25], v[208:211], v[224:227], v[184:187]
	v_mfma_f32_16x16x32_bf16 v[70:73], v[212:215], v[228:231], v[22:25]
	s_barrier
	ds_read_b128 v[168:171], v136 offset:49152
	ds_read_b128 v[176:179], v136 offset:50176
	ds_read_b128 v[180:183], v136 offset:51200
	ds_read_b128 v[184:187], v136 offset:52224
	ds_read_b128 v[200:203], v136 offset:53248
	ds_read_b128 v[224:227], v136 offset:54272
	ds_read_b128 v[228:231], v136 offset:55296
	ds_read_b128 v[232:235], v136 offset:56320
	s_barrier
	s_waitcnt lgkmcnt(0)
	s_waitcnt lgkmcnt(0)
	v_mfma_f32_16x16x32_bf16 v[22:25], v[6:9], v[168:171], v[62:65]
	v_mfma_f32_16x16x32_bf16 v[62:65], v[14:17], v[176:179], v[22:25]
	v_mfma_f32_16x16x32_bf16 v[22:25], v[192:195], v[168:171], v[58:61]
	v_mfma_f32_16x16x32_bf16 v[54:57], v[196:199], v[176:179], v[22:25]
	v_mfma_f32_16x16x32_bf16 v[22:25], v[6:9], v[180:183], v[216:219]
	v_mfma_f32_16x16x32_bf16 v[46:49], v[14:17], v[184:187], v[22:25]
	v_mfma_f32_16x16x32_bf16 v[22:25], v[192:195], v[180:183], v[50:53]
	v_mfma_f32_16x16x32_bf16 v[38:41], v[196:199], v[184:187], v[22:25]
	v_mfma_f32_16x16x32_bf16 v[22:25], v[6:9], v[200:203], v[220:223]
	v_mfma_f32_16x16x32_bf16 v[6:9], v[6:9], v[228:231], v[138:141]
	v_mfma_f32_16x16x32_bf16 v[30:33], v[14:17], v[224:227], v[22:25]
	v_mfma_f32_16x16x32_bf16 v[22:25], v[192:195], v[200:203], v[42:45]
	v_mfma_f32_16x16x32_bf16 v[14:17], v[14:17], v[232:235], v[6:9]
	v_mfma_f32_16x16x32_bf16 v[6:9], v[192:195], v[228:231], v[34:37]
	v_mfma_f32_16x16x32_bf16 v[22:25], v[196:199], v[224:227], v[22:25]
	v_mfma_f32_16x16x32_bf16 v[6:9], v[196:199], v[232:235], v[6:9]
	v_mfma_f32_16x16x32_bf16 v[34:37], v[172:175], v[168:171], v[142:145]
	v_mfma_f32_16x16x32_bf16 v[26:29], v[208:211], v[168:171], v[26:29]
	v_mfma_f32_16x16x32_bf16 v[18:21], v[208:211], v[180:183], v[18:21]
	v_mfma_f32_16x16x32_bf16 v[58:61], v[204:207], v[176:179], v[34:37]
	v_mfma_f32_16x16x32_bf16 v[50:53], v[212:215], v[176:179], v[26:29]
	v_mfma_f32_16x16x32_bf16 v[26:29], v[172:175], v[180:183], v[146:149]
	v_mfma_f32_16x16x32_bf16 v[34:37], v[212:215], v[184:187], v[18:21]
	v_mfma_f32_16x16x32_bf16 v[18:21], v[172:175], v[200:203], v[152:155]
	v_mfma_f32_16x16x32_bf16 v[10:13], v[208:211], v[200:203], v[10:13]
	v_mfma_f32_16x16x32_bf16 v[42:45], v[204:207], v[184:187], v[26:29]
	v_mfma_f32_16x16x32_bf16 v[26:29], v[204:207], v[224:227], v[18:21]
	v_mfma_f32_16x16x32_bf16 v[18:21], v[212:215], v[224:227], v[10:13]
	v_mfma_f32_16x16x32_bf16 v[10:13], v[172:175], v[228:231], v[188:191]
	v_mfma_f32_16x16x32_bf16 v[2:5], v[208:211], v[228:231], v[2:5]
	v_mfma_f32_16x16x32_bf16 v[10:13], v[204:207], v[232:235], v[10:13]
	v_mfma_f32_16x16x32_bf16 v[2:5], v[212:215], v[232:235], v[2:5]
	v_cmp_gt_u32_e32 vcc, s97, v135
	s_barrier
	s_and_saveexec_b64 s[10:11], vcc
	s_cbranch_execz .LBB0_812
	s_barrier
	s_branch .LBB0_812

; #define WAIT_L(n) asm volatile("s_waitcnt lgkmcnt(%0)" ::"n"(n) : "memory")
; #define SBAR() __builtin_amdgcn_sched_barrier(0)
; #define LDA8(dst, b, h) _Pragma("unroll") for (int m = 0; m < 4; ++m) _Pragma("unroll") for (int k = 0; k < 2; ++k) \
;     dst[m][k] = *(const bf16x8*)(abase + SAo(b, h) + m * 2048 + k * 1024)
; #define LDB8(dst, b, h) _Pragma("unroll") for (int n = 0; n < 2; ++n) _Pragma("unroll") for (int k = 0; k < 2; ++k) \
;     dst[n][k] = *(const bf16x8*)(bbase + SAo(b, h) + n * 2048 + k * 1024)
; #define BAR8 __builtin_amdgcn_s_barrier()
; __device__ __forceinline__ void gemm_main8(const u16* __restrict__ Ab, int lda, const u16* __restrict__ Bb, int ldb, int K,
;                                            char* shm, f32x4 (&acc)[2][2][4][2]) {
;     ...
;     LDB8(B0, 0, 0); SBAR(); LDA8(At, 0, 0); STG_A(1, 1, t + 1);
;     WAIT_L(8); BAR8; WAIT_L(0); MMA8(0, 0, At, B0); BAR8; SBAR();
;     LDB8(B1, 0, 1); STG_B(0, 0, t + 2);
;     BAR8; WAIT_L(0); MMA8(0, 1, At, B1); BAR8;
;     LDA8(At, 0, 1); STG_A(0, 0, t + 2);
;     BAR8; WAIT_L(0); MMA8(1, 0, At, B0); BAR8; SBAR();
.LBB0_905:
	ds_read_b128 v[152:155], v138
	ds_read_b128 v[164:167], v138 offset:1024
	ds_read_b128 v[176:179], v138 offset:2048
	ds_read_b128 v[180:183], v138 offset:3072
	ds_read_b128 v[184:187], v137
	ds_read_b128 v[188:191], v137 offset:1024
	ds_read_b128 v[192:195], v137 offset:2048
	ds_read_b128 v[196:199], v137 offset:3072
	ds_read_b128 v[200:203], v137 offset:4096
	ds_read_b128 v[204:207], v137 offset:5120
	ds_read_b128 v[208:211], v137 offset:6144
	ds_read_b128 v[212:215], v137 offset:7168
	v_add_u32_e32 v174, 0xc000, v139
	v_lshl_add_u64 v[168:169], s[28:29], 0, v[0:1]
	v_readfirstlane_b32 s11, v174
	v_add_u32_e32 v175, 0xe000, v139
	v_lshl_add_u64 v[216:217], v[168:169], 0, s[54:55]
	s_mov_b32 m0, s11
	v_readfirstlane_b32 s11, v175
	global_load_lds_dwordx4 v[216:217], off
	v_lshl_add_u64 v[216:217], v[168:169], 0, s[56:57]
	s_mov_b32 m0, s11
	s_nop 0
	global_load_lds_dwordx4 v[216:217], off
	s_waitcnt lgkmcnt(8)
	s_barrier
	s_waitcnt lgkmcnt(0)
	s_waitcnt lgkmcnt(0)
	v_mfma_f32_16x16x32_bf16 v[126:129], v[152:155], v[184:187], v[126:129]
	v_mfma_f32_16x16x32_bf16 v[122:125], v[176:179], v[184:187], v[122:125]
	v_mfma_f32_16x16x32_bf16 v[118:121], v[152:155], v[192:195], v[118:121]
	v_mfma_f32_16x16x32_bf16 v[114:117], v[176:179], v[192:195], v[114:117]
	v_mfma_f32_16x16x32_bf16 v[110:113], v[152:155], v[200:203], v[110:113]
	v_mfma_f32_16x16x32_bf16 v[106:109], v[176:179], v[200:203], v[106:109]
	v_mfma_f32_16x16x32_bf16 v[102:105], v[152:155], v[208:211], v[102:105]
	v_mfma_f32_16x16x32_bf16 v[98:101], v[176:179], v[208:211], v[98:101]
	v_mfma_f32_16x16x32_bf16 v[126:129], v[164:167], v[188:191], v[126:129]
	v_mfma_f32_16x16x32_bf16 v[122:125], v[180:183], v[188:191], v[122:125]
	v_mfma_f32_16x16x32_bf16 v[118:121], v[164:167], v[196:199], v[118:121]
	v_mfma_f32_16x16x32_bf16 v[114:117], v[180:183], v[196:199], v[114:117]
	v_mfma_f32_16x16x32_bf16 v[110:113], v[164:167], v[204:207], v[110:113]
	v_mfma_f32_16x16x32_bf16 v[106:109], v[180:183], v[204:207], v[106:109]
	v_mfma_f32_16x16x32_bf16 v[102:105], v[164:167], v[212:215], v[102:105]
	v_mfma_f32_16x16x32_bf16 v[98:101], v[180:183], v[212:215], v[98:101]
	s_barrier
	ds_read_b128 v[216:219], v138 offset:16384
	ds_read_b128 v[220:223], v138 offset:17408
	ds_read_b128 v[224:227], v138 offset:18432
	ds_read_b128 v[228:231], v138 offset:19456
	v_lshl_add_u64 v[232:233], s[12:13], 0, v[0:1]
	s_mov_b64 s[78:79], 0x4000100
	v_readfirstlane_b32 s11, v140
	v_lshl_add_u64 v[234:235], v[232:233], 0, s[78:79]
	s_mov_b32 m0, s11
	s_mov_b64 s[78:79], 0x4040100
	v_readfirstlane_b32 s11, v141
	global_load_lds_dwordx4 v[234:235], off
	v_lshl_add_u64 v[234:235], v[232:233], 0, s[78:79]
	s_mov_b32 m0, s11
	s_nop 0
	global_load_lds_dwordx4 v[234:235], off
	s_barrier
	s_waitcnt lgkmcnt(0)
	s_waitcnt lgkmcnt(0)
	v_mfma_f32_16x16x32_bf16 v[94:97], v[216:219], v[184:187], v[94:97]
	v_mfma_f32_16x16x32_bf16 v[90:93], v[224:227], v[184:187], v[90:93]
	v_mfma_f32_16x16x32_bf16 v[86:89], v[216:219], v[192:195], v[86:89]
	v_mfma_f32_16x16x32_bf16 v[82:85], v[224:227], v[192:195], v[82:85]
	v_mfma_f32_16x16x32_bf16 v[78:81], v[216:219], v[200:203], v[78:81]
	v_mfma_f32_16x16x32_bf16 v[74:77], v[224:227], v[200:203], v[74:77]
	v_mfma_f32_16x16x32_bf16 v[70:73], v[216:219], v[208:211], v[70:73]
	v_mfma_f32_16x16x32_bf16 v[66:69], v[224:227], v[208:211], v[66:69]
	v_mfma_f32_16x16x32_bf16 v[94:97], v[220:223], v[188:191], v[94:97]
	v_mfma_f32_16x16x32_bf16 v[90:93], v[228:231], v[188:191], v[90:93]
	v_mfma_f32_16x16x32_bf16 v[86:89], v[220:223], v[196:199], v[86:89]
	v_mfma_f32_16x16x32_bf16 v[82:85], v[228:231], v[196:199], v[82:85]
	v_mfma_f32_16x16x32_bf16 v[78:81], v[220:223], v[204:207], v[78:81]
	v_mfma_f32_16x16x32_bf16 v[74:77], v[228:231], v[204:207], v[74:77]
	v_mfma_f32_16x16x32_bf16 v[70:73], v[220:223], v[212:215], v[70:73]
	v_mfma_f32_16x16x32_bf16 v[66:69], v[228:231], v[212:215], v[66:69]
	v_readfirstlane_b32 s11, v139
	v_lshl_add_u64 v[234:235], v[168:169], 0, s[58:59]
	s_mov_b32 m0, s11
	v_readfirstlane_b32 s11, v142
	s_barrier
	ds_read_b128 v[184:187], v137 offset:16384
	ds_read_b128 v[188:191], v137 offset:17408
	ds_read_b128 v[192:195], v137 offset:18432
	ds_read_b128 v[196:199], v137 offset:19456
	ds_read_b128 v[200:203], v137 offset:20480
	ds_read_b128 v[204:207], v137 offset:21504
	ds_read_b128 v[208:211], v137 offset:22528
	ds_read_b128 v[212:215], v137 offset:23552
	global_load_lds_dwordx4 v[234:235], off
	v_lshl_add_u64 v[234:235], v[168:169], 0, s[60:61]
	s_mov_b32 m0, s11
	s_nop 0
	global_load_lds_dwordx4 v[234:235], off
	s_barrier
	s_waitcnt lgkmcnt(0)
	s_waitcnt lgkmcnt(0)
	v_mfma_f32_16x16x32_bf16 v[62:65], v[152:155], v[184:187], v[62:65]
	v_mfma_f32_16x16x32_bf16 v[58:61], v[176:179], v[184:187], v[58:61]
	v_mfma_f32_16x16x32_bf16 v[54:57], v[152:155], v[192:195], v[54:57]
	v_mfma_f32_16x16x32_bf16 v[50:53], v[176:179], v[192:195], v[50:53]
	v_mfma_f32_16x16x32_bf16 v[46:49], v[152:155], v[200:203], v[46:49]
	v_mfma_f32_16x16x32_bf16 v[42:45], v[176:179], v[200:203], v[42:45]
	v_mfma_f32_16x16x32_bf16 v[38:41], v[152:155], v[208:211], v[38:41]
	v_mfma_f32_16x16x32_bf16 v[34:37], v[176:179], v[208:211], v[34:37]
	v_mfma_f32_16x16x32_bf16 v[62:65], v[164:167], v[188:191], v[62:65]
	v_mfma_f32_16x16x32_bf16 v[58:61], v[180:183], v[188:191], v[58:61]
	v_mfma_f32_16x16x32_bf16 v[54:57], v[164:167], v[196:199], v[54:57]
	v_mfma_f32_16x16x32_bf16 v[50:53], v[180:183], v[196:199], v[50:53]
	v_mfma_f32_16x16x32_bf16 v[46:49], v[164:167], v[204:207], v[46:49]
	v_mfma_f32_16x16x32_bf16 v[42:45], v[180:183], v[204:207], v[42:45]
	v_mfma_f32_16x16x32_bf16 v[38:41], v[164:167], v[212:215], v[38:41]
	v_mfma_f32_16x16x32_bf16 v[34:37], v[180:183], v[212:215], v[34:37]
	s_barrier
; #define WAIT_V(n) asm volatile("s_waitcnt vmcnt(%0)" ::"n"(n) : "memory")
; #define WAIT_L(n) asm volatile("s_waitcnt lgkmcnt(%0)" ::"n"(n) : "memory")
; #define SBAR() __builtin_amdgcn_sched_barrier(0)
; #define LDA8(dst, b, h) _Pragma("unroll") for (int m = 0; m < 4; ++m) _Pragma("unroll") for (int k = 0; k < 2; ++k) \
;     dst[m][k] = *(const bf16x8*)(abase + SAo(b, h) + m * 2048 + k * 1024)
; #define LDB8(dst, b, h) _Pragma("unroll") for (int n = 0; n < 2; ++n) _Pragma("unroll") for (int k = 0; k < 2; ++k) \
;     dst[n][k] = *(const bf16x8*)(bbase + SAo(b, h) + n * 2048 + k * 1024)
; #define BAR8 __builtin_amdgcn_s_barrier()
; __device__ __forceinline__ void gemm_main8(const u16* __restrict__ Ab, int lda, const u16* __restrict__ Bb, int ldb, int K,
;                                            char* shm, f32x4 (&acc)[2][2][4][2]) {
;     ...
;     STG_B(0, 1, t + 2);
;     WAIT_V(6); BAR8; MMA8(1, 1, At, B1); BAR8;
;     LDB8(B0, 1, 0); SBAR(); LDA8(At, 1, 0); STG_A(0, 1, t + 2);
;     WAIT_L(8); BAR8; WAIT_L(0); MMA8(0, 0, At, B0); BAR8; SBAR();
;     LDB8(B1, 1, 1); STG_B(1, 0, t + 3);
;     BAR8; WAIT_L(0); MMA8(0, 1, At, B1); BAR8;
	s_mov_b64 s[78:79], 0x4080100
	v_readfirstlane_b32 s11, v143
	v_lshl_add_u64 v[152:153], v[232:233], 0, s[78:79]
	s_mov_b32 m0, s11
	s_mov_b64 s[78:79], 0x40c0100
	v_readfirstlane_b32 s11, v144
	global_load_lds_dwordx4 v[152:153], off
	v_lshl_add_u64 v[152:153], v[232:233], 0, s[78:79]
	s_mov_b32 m0, s11
	s_nop 0
	global_load_lds_dwordx4 v[152:153], off
	s_waitcnt vmcnt(6)
	s_barrier
	v_mfma_f32_16x16x32_bf16 v[30:33], v[216:219], v[184:187], v[30:33]
	v_mfma_f32_16x16x32_bf16 v[26:29], v[224:227], v[184:187], v[26:29]
	v_mfma_f32_16x16x32_bf16 v[22:25], v[216:219], v[192:195], v[22:25]
	v_mfma_f32_16x16x32_bf16 v[18:21], v[224:227], v[192:195], v[18:21]
	v_mfma_f32_16x16x32_bf16 v[14:17], v[216:219], v[200:203], v[14:17]
	v_mfma_f32_16x16x32_bf16 v[10:13], v[224:227], v[200:203], v[10:13]
	v_mfma_f32_16x16x32_bf16 v[6:9], v[216:219], v[208:211], v[6:9]
	v_mfma_f32_16x16x32_bf16 v[2:5], v[224:227], v[208:211], v[2:5]
	v_mfma_f32_16x16x32_bf16 v[30:33], v[220:223], v[188:191], v[30:33]
	v_mfma_f32_16x16x32_bf16 v[26:29], v[228:231], v[188:191], v[26:29]
	v_mfma_f32_16x16x32_bf16 v[22:25], v[220:223], v[196:199], v[22:25]
	v_mfma_f32_16x16x32_bf16 v[18:21], v[228:231], v[196:199], v[18:21]
	v_mfma_f32_16x16x32_bf16 v[14:17], v[220:223], v[204:207], v[14:17]
	v_mfma_f32_16x16x32_bf16 v[10:13], v[228:231], v[204:207], v[10:13]
	v_mfma_f32_16x16x32_bf16 v[6:9], v[220:223], v[212:215], v[6:9]
	v_mfma_f32_16x16x32_bf16 v[2:5], v[228:231], v[212:215], v[2:5]
	s_barrier
	ds_read_b128 v[152:155], v138 offset:32768
	ds_read_b128 v[164:167], v138 offset:33792
	ds_read_b128 v[176:179], v138 offset:34816
	ds_read_b128 v[180:183], v138 offset:35840
	ds_read_b128 v[184:187], v137 offset:32768
	ds_read_b128 v[188:191], v137 offset:33792
	ds_read_b128 v[192:195], v137 offset:34816
	ds_read_b128 v[196:199], v137 offset:35840
	ds_read_b128 v[200:203], v137 offset:36864
	ds_read_b128 v[204:207], v137 offset:37888
	ds_read_b128 v[208:211], v137 offset:38912
	ds_read_b128 v[212:215], v137 offset:39936
	v_readfirstlane_b32 s11, v145
	v_lshl_add_u64 v[216:217], v[168:169], 0, s[62:63]
	s_mov_b32 m0, s11
	v_readfirstlane_b32 s11, v146
	global_load_lds_dwordx4 v[216:217], off
	v_lshl_add_u64 v[216:217], v[168:169], 0, s[64:65]
	s_mov_b32 m0, s11
	s_nop 0
	global_load_lds_dwordx4 v[216:217], off
	s_waitcnt lgkmcnt(8)
	s_barrier
	s_waitcnt lgkmcnt(0)
	s_waitcnt lgkmcnt(0)
	v_mfma_f32_16x16x32_bf16 v[126:129], v[152:155], v[184:187], v[126:129]
	v_mfma_f32_16x16x32_bf16 v[122:125], v[176:179], v[184:187], v[122:125]
	v_mfma_f32_16x16x32_bf16 v[118:121], v[152:155], v[192:195], v[118:121]
	v_mfma_f32_16x16x32_bf16 v[114:117], v[176:179], v[192:195], v[114:117]
	v_mfma_f32_16x16x32_bf16 v[110:113], v[152:155], v[200:203], v[110:113]
	v_mfma_f32_16x16x32_bf16 v[106:109], v[176:179], v[200:203], v[106:109]
	v_mfma_f32_16x16x32_bf16 v[102:105], v[152:155], v[208:211], v[102:105]
	v_mfma_f32_16x16x32_bf16 v[98:101], v[176:179], v[208:211], v[98:101]
	v_mfma_f32_16x16x32_bf16 v[126:129], v[164:167], v[188:191], v[126:129]
	v_mfma_f32_16x16x32_bf16 v[122:125], v[180:183], v[188:191], v[122:125]
	v_mfma_f32_16x16x32_bf16 v[118:121], v[164:167], v[196:199], v[118:121]
	v_mfma_f32_16x16x32_bf16 v[114:117], v[180:183], v[196:199], v[114:117]
	v_mfma_f32_16x16x32_bf16 v[110:113], v[164:167], v[204:207], v[110:113]
	v_mfma_f32_16x16x32_bf16 v[106:109], v[180:183], v[204:207], v[106:109]
	v_mfma_f32_16x16x32_bf16 v[102:105], v[164:167], v[212:215], v[102:105]
	v_mfma_f32_16x16x32_bf16 v[98:101], v[180:183], v[212:215], v[98:101]
	s_barrier
	ds_read_b128 v[216:219], v138 offset:49152
	ds_read_b128 v[220:223], v138 offset:50176
	ds_read_b128 v[224:227], v138 offset:51200
	ds_read_b128 v[228:231], v138 offset:52224
	s_mov_b64 s[78:79], 0x4000180
	v_readfirstlane_b32 s11, v147
	v_lshl_add_u64 v[234:235], v[232:233], 0, s[78:79]
	s_mov_b32 m0, s11
	s_mov_b64 s[78:79], 0x4040180
	v_readfirstlane_b32 s11, v148
	global_load_lds_dwordx4 v[234:235], off
	v_lshl_add_u64 v[234:235], v[232:233], 0, s[78:79]
	s_mov_b32 m0, s11
	s_nop 0
	global_load_lds_dwordx4 v[234:235], off
	s_barrier
	s_waitcnt lgkmcnt(0)
	s_waitcnt lgkmcnt(0)
	v_mfma_f32_16x16x32_bf16 v[94:97], v[216:219], v[184:187], v[94:97]
	v_mfma_f32_16x16x32_bf16 v[90:93], v[224:227], v[184:187], v[90:93]
	v_mfma_f32_16x16x32_bf16 v[86:89], v[216:219], v[192:195], v[86:89]
	v_mfma_f32_16x16x32_bf16 v[82:85], v[224:227], v[192:195], v[82:85]
	v_mfma_f32_16x16x32_bf16 v[78:81], v[216:219], v[200:203], v[78:81]
	v_mfma_f32_16x16x32_bf16 v[74:77], v[224:227], v[200:203], v[74:77]
	v_mfma_f32_16x16x32_bf16 v[70:73], v[216:219], v[208:211], v[70:73]
	v_mfma_f32_16x16x32_bf16 v[66:69], v[224:227], v[208:211], v[66:69]
	v_mfma_f32_16x16x32_bf16 v[94:97], v[220:223], v[188:191], v[94:97]
	v_mfma_f32_16x16x32_bf16 v[90:93], v[228:231], v[188:191], v[90:93]
	v_mfma_f32_16x16x32_bf16 v[86:89], v[220:223], v[196:199], v[86:89]
	v_mfma_f32_16x16x32_bf16 v[82:85], v[228:231], v[196:199], v[82:85]
	v_mfma_f32_16x16x32_bf16 v[78:81], v[220:223], v[204:207], v[78:81]
	v_mfma_f32_16x16x32_bf16 v[74:77], v[228:231], v[204:207], v[74:77]
	v_mfma_f32_16x16x32_bf16 v[70:73], v[220:223], v[212:215], v[70:73]
	v_mfma_f32_16x16x32_bf16 v[66:69], v[228:231], v[212:215], v[66:69]
	v_readfirstlane_b32 s11, v149
	v_lshl_add_u64 v[234:235], v[168:169], 0, s[66:67]
	s_mov_b32 m0, s11
	v_readfirstlane_b32 s11, v171
	s_barrier
; #define WAIT_V(n) asm volatile("s_waitcnt vmcnt(%0)" ::"n"(n) : "memory")
; #define WAIT_L(n) asm volatile("s_waitcnt lgkmcnt(%0)" ::"n"(n) : "memory")
; #define SBAR() __builtin_amdgcn_sched_barrier(0)
; #define LDA8(dst, b, h) _Pragma("unroll") for (int m = 0; m < 4; ++m) _Pragma("unroll") for (int k = 0; k < 2; ++k) \
;     dst[m][k] = *(const bf16x8*)(abase + SAo(b, h) + m * 2048 + k * 1024)
; #define LDB8(dst, b, h) _Pragma("unroll") for (int n = 0; n < 2; ++n) _Pragma("unroll") for (int k = 0; k < 2; ++k) \
;     dst[n][k] = *(const bf16x8*)(bbase + SAo(b, h) + n * 2048 + k * 1024)
; #define BAR8 __builtin_amdgcn_s_barrier()
; __device__ __forceinline__ void gemm_main8(const u16* __restrict__ Ab, int lda, const u16* __restrict__ Bb, int ldb, int K,
;                                            char* shm, f32x4 (&acc)[2][2][4][2]) {
;     ...
;     LDA8(At, 1, 1); STG_A(1, 0, t + 3);
;     BAR8; WAIT_L(0); MMA8(1, 0, At, B0); BAR8; SBAR();
;     STG_B(1, 1, t + 3);
;     WAIT_V(6); BAR8; MMA8(1, 1, At, B1); BAR8;
;   }
;   { LDB8(B0, 0, 0); LDA8(At, 0, 0); STG_A(1, 1, nt - 1);
;     BAR8; WAIT_L(0); MMA8(0, 0, At, B0); BAR8;
;     LDB8(B1, 0, 1); BAR8; WAIT_L(0); MMA8(0, 1, At, B1); BAR8;
	ds_read_b128 v[184:187], v137 offset:49152
	ds_read_b128 v[188:191], v137 offset:50176
	ds_read_b128 v[192:195], v137 offset:51200
	ds_read_b128 v[196:199], v137 offset:52224
	ds_read_b128 v[200:203], v137 offset:53248
	ds_read_b128 v[204:207], v137 offset:54272
	ds_read_b128 v[208:211], v137 offset:55296
	ds_read_b128 v[212:215], v137 offset:56320
	global_load_lds_dwordx4 v[234:235], off
	v_lshl_add_u64 v[168:169], v[168:169], 0, s[68:69]
	s_mov_b32 m0, s11
	s_nop 0
	global_load_lds_dwordx4 v[168:169], off
	s_barrier
	s_waitcnt lgkmcnt(0)
	s_waitcnt lgkmcnt(0)
	v_mfma_f32_16x16x32_bf16 v[62:65], v[152:155], v[184:187], v[62:65]
	v_mfma_f32_16x16x32_bf16 v[58:61], v[176:179], v[184:187], v[58:61]
	v_mfma_f32_16x16x32_bf16 v[54:57], v[152:155], v[192:195], v[54:57]
	v_mfma_f32_16x16x32_bf16 v[50:53], v[176:179], v[192:195], v[50:53]
	v_mfma_f32_16x16x32_bf16 v[46:49], v[152:155], v[200:203], v[46:49]
	v_mfma_f32_16x16x32_bf16 v[42:45], v[176:179], v[200:203], v[42:45]
	v_mfma_f32_16x16x32_bf16 v[38:41], v[152:155], v[208:211], v[38:41]
	v_mfma_f32_16x16x32_bf16 v[34:37], v[176:179], v[208:211], v[34:37]
	v_mfma_f32_16x16x32_bf16 v[62:65], v[164:167], v[188:191], v[62:65]
	v_mfma_f32_16x16x32_bf16 v[58:61], v[180:183], v[188:191], v[58:61]
	v_mfma_f32_16x16x32_bf16 v[54:57], v[164:167], v[196:199], v[54:57]
	v_mfma_f32_16x16x32_bf16 v[50:53], v[180:183], v[196:199], v[50:53]
	v_mfma_f32_16x16x32_bf16 v[46:49], v[164:167], v[204:207], v[46:49]
	v_mfma_f32_16x16x32_bf16 v[42:45], v[180:183], v[204:207], v[42:45]
	v_mfma_f32_16x16x32_bf16 v[38:41], v[164:167], v[212:215], v[38:41]
	v_mfma_f32_16x16x32_bf16 v[34:37], v[180:183], v[212:215], v[34:37]
	s_barrier
	s_mov_b64 s[78:79], 0x4080180
	v_readfirstlane_b32 s11, v172
	v_lshl_add_u64 v[152:153], v[232:233], 0, s[78:79]
	s_mov_b32 m0, s11
	s_mov_b64 s[78:79], 0x40c0180
	v_readfirstlane_b32 s11, v173
	global_load_lds_dwordx4 v[152:153], off
	v_lshl_add_u64 v[152:153], v[232:233], 0, s[78:79]
	s_mov_b32 m0, s11
	s_nop 0
	global_load_lds_dwordx4 v[152:153], off
	s_waitcnt vmcnt(6)
	s_barrier
	v_mfma_f32_16x16x32_bf16 v[30:33], v[216:219], v[184:187], v[30:33]
	v_mfma_f32_16x16x32_bf16 v[26:29], v[224:227], v[184:187], v[26:29]
	v_mfma_f32_16x16x32_bf16 v[22:25], v[216:219], v[192:195], v[22:25]
	v_mfma_f32_16x16x32_bf16 v[18:21], v[224:227], v[192:195], v[18:21]
	v_mfma_f32_16x16x32_bf16 v[14:17], v[216:219], v[200:203], v[14:17]
	v_mfma_f32_16x16x32_bf16 v[10:13], v[224:227], v[200:203], v[10:13]
	v_mfma_f32_16x16x32_bf16 v[6:9], v[216:219], v[208:211], v[6:9]
	v_mfma_f32_16x16x32_bf16 v[2:5], v[224:227], v[208:211], v[2:5]
	v_mfma_f32_16x16x32_bf16 v[30:33], v[220:223], v[188:191], v[30:33]
	v_mfma_f32_16x16x32_bf16 v[26:29], v[228:231], v[188:191], v[26:29]
	v_mfma_f32_16x16x32_bf16 v[22:25], v[220:223], v[196:199], v[22:25]
	v_mfma_f32_16x16x32_bf16 v[18:21], v[228:231], v[196:199], v[18:21]
	v_mfma_f32_16x16x32_bf16 v[14:17], v[220:223], v[204:207], v[14:17]
	v_mfma_f32_16x16x32_bf16 v[10:13], v[228:231], v[204:207], v[10:13]
	v_mfma_f32_16x16x32_bf16 v[6:9], v[220:223], v[212:215], v[6:9]
	v_mfma_f32_16x16x32_bf16 v[2:5], v[228:231], v[212:215], v[2:5]
	s_add_i32 s10, s10, 2
	s_add_u32 s12, s12, 0x100
	s_addc_u32 s13, s13, 0
	s_add_u32 s28, s28, 0x100
	s_addc_u32 s29, s29, 0
	s_cmp_lt_u32 s10, 28
	s_barrier
	s_cbranch_scc1 .LBB0_905
	s_mov_b64 s[10:11], 0x80f80
	v_lshl_add_u64 v[148:149], v[130:131], 0, s[10:11]
	v_readfirstlane_b32 s10, v174
	s_mov_b32 m0, s10
	s_mov_b64 s[10:11], 0xc0f80
	v_lshl_add_u64 v[130:131], v[130:131], 0, s[10:11]
	v_readfirstlane_b32 s10, v175
	ds_read_b128 v[140:143], v138
	ds_read_b128 v[144:147], v138 offset:1024
	ds_read_b128 v[152:155], v138 offset:2048
	ds_read_b128 v[164:167], v138 offset:3072
	ds_read_b128 v[168:171], v137
	ds_read_b128 v[176:179], v137 offset:1024
	ds_read_b128 v[180:183], v137 offset:2048
	ds_read_b128 v[184:187], v137 offset:3072
	ds_read_b128 v[188:191], v137 offset:4096
	ds_read_b128 v[192:195], v137 offset:5120
	ds_read_b128 v[196:199], v137 offset:6144
	ds_read_b128 v[200:203], v137 offset:7168
	global_load_lds_dwordx4 v[148:149], off
	s_mov_b32 m0, s10
	s_nop 0
	global_load_lds_dwordx4 v[130:131], off
	s_barrier
	s_waitcnt lgkmcnt(0)
	s_waitcnt lgkmcnt(0)
	v_mfma_f32_16x16x32_bf16 v[126:129], v[140:143], v[168:171], v[126:129]
	v_mfma_f32_16x16x32_bf16 v[118:121], v[140:143], v[180:183], v[118:121]
	v_mfma_f32_16x16x32_bf16 v[114:117], v[152:155], v[180:183], v[114:117]
	v_mfma_f32_16x16x32_bf16 v[102:105], v[140:143], v[196:199], v[102:105]
	v_mfma_f32_16x16x32_bf16 v[98:101], v[152:155], v[196:199], v[98:101]
	v_mfma_f32_16x16x32_bf16 v[126:129], v[144:147], v[176:179], v[126:129]
	v_mfma_f32_16x16x32_bf16 v[122:125], v[152:155], v[168:171], v[122:125]
	v_mfma_f32_16x16x32_bf16 v[118:121], v[144:147], v[184:187], v[118:121]
	v_mfma_f32_16x16x32_bf16 v[114:117], v[164:167], v[184:187], v[114:117]
	v_mfma_f32_16x16x32_bf16 v[110:113], v[140:143], v[188:191], v[110:113]
	v_mfma_f32_16x16x32_bf16 v[106:109], v[152:155], v[188:191], v[106:109]
	v_mfma_f32_16x16x32_bf16 v[102:105], v[144:147], v[200:203], v[102:105]
	v_mfma_f32_16x16x32_bf16 v[98:101], v[164:167], v[200:203], v[98:101]
	v_mfma_f32_16x16x32_bf16 v[172:175], v[164:167], v[176:179], v[122:125]
	v_mfma_f32_16x16x32_bf16 v[204:207], v[144:147], v[192:195], v[110:113]
	v_mfma_f32_16x16x32_bf16 v[208:211], v[164:167], v[192:195], v[106:109]
	s_barrier
	s_nop 0
	ds_read_b128 v[106:109], v138 offset:16384
	ds_read_b128 v[110:113], v138 offset:17408
	ds_read_b128 v[122:125], v138 offset:18432
	ds_read_b128 v[212:215], v138 offset:19456
	s_barrier
; #define WAIT_V(n) asm volatile("s_waitcnt vmcnt(%0)" ::"n"(n) : "memory")
; #define WAIT_L(n) asm volatile("s_waitcnt lgkmcnt(%0)" ::"n"(n) : "memory")
; #define LDA8(dst, b, h) _Pragma("unroll") for (int m = 0; m < 4; ++m) _Pragma("unroll") for (int k = 0; k < 2; ++k) \
;     dst[m][k] = *(const bf16x8*)(abase + SAo(b, h) + m * 2048 + k * 1024)
; #define LDB8(dst, b, h) _Pragma("unroll") for (int n = 0; n < 2; ++n) _Pragma("unroll") for (int k = 0; k < 2; ++k) \
;     dst[n][k] = *(const bf16x8*)(bbase + SAo(b, h) + n * 2048 + k * 1024)
; #define BAR8 __builtin_amdgcn_s_barrier()
; __device__ __forceinline__ void gemm_main8(const u16* __restrict__ Ab, int lda, const u16* __restrict__ Bb, int ldb, int K,
;                                            char* shm, f32x4 (&acc)[2][2][4][2]) {
;     ...
;     LDB8(B1, 0, 1); BAR8; WAIT_L(0); MMA8(0, 1, At, B1); BAR8;
;     LDA8(At, 0, 1); WAIT_V(4); BAR8; WAIT_L(0); MMA8(1, 0, At, B0); MMA8(1, 1, At, B1); BAR8; }
;   { LDB8(B0, 1, 0); LDA8(At, 1, 0); WAIT_V(2); BAR8; WAIT_L(0); MMA8(0, 0, At, B0); BAR8;
	s_waitcnt lgkmcnt(0)
	s_waitcnt lgkmcnt(0)
	v_mfma_f32_16x16x32_bf16 v[86:89], v[106:109], v[180:183], v[86:89]
	v_mfma_f32_16x16x32_bf16 v[82:85], v[122:125], v[180:183], v[82:85]
	v_mfma_f32_16x16x32_bf16 v[70:73], v[106:109], v[196:199], v[70:73]
	v_mfma_f32_16x16x32_bf16 v[94:97], v[106:109], v[168:171], v[94:97]
	v_mfma_f32_16x16x32_bf16 v[90:93], v[122:125], v[168:171], v[90:93]
	v_mfma_f32_16x16x32_bf16 v[86:89], v[110:113], v[184:187], v[86:89]
	v_mfma_f32_16x16x32_bf16 v[82:85], v[212:215], v[184:187], v[82:85]
	v_mfma_f32_16x16x32_bf16 v[78:81], v[106:109], v[188:191], v[78:81]
	v_mfma_f32_16x16x32_bf16 v[74:77], v[122:125], v[188:191], v[74:77]
	v_mfma_f32_16x16x32_bf16 v[70:73], v[110:113], v[200:203], v[70:73]
	v_mfma_f32_16x16x32_bf16 v[66:69], v[122:125], v[196:199], v[66:69]
	v_mfma_f32_16x16x32_bf16 v[216:219], v[110:113], v[176:179], v[94:97]
	v_mfma_f32_16x16x32_bf16 v[168:171], v[212:215], v[176:179], v[90:93]
	v_mfma_f32_16x16x32_bf16 v[176:179], v[110:113], v[192:195], v[78:81]
	v_mfma_f32_16x16x32_bf16 v[180:183], v[212:215], v[192:195], v[74:77]
	v_mfma_f32_16x16x32_bf16 v[184:187], v[212:215], v[200:203], v[66:69]
	s_barrier
	s_nop 0
	ds_read_b128 v[66:69], v137 offset:16384
	ds_read_b128 v[74:77], v137 offset:17408
	ds_read_b128 v[78:81], v137 offset:18432
	ds_read_b128 v[90:93], v137 offset:19456
	ds_read_b128 v[94:97], v137 offset:20480
	ds_read_b128 v[188:191], v137 offset:21504
	ds_read_b128 v[192:195], v137 offset:22528
	ds_read_b128 v[196:199], v137 offset:23552
	s_waitcnt vmcnt(4)
	s_barrier
	s_waitcnt lgkmcnt(0)
	s_waitcnt lgkmcnt(0)
	v_mfma_f32_16x16x32_bf16 v[62:65], v[140:143], v[66:69], v[62:65]
	v_mfma_f32_16x16x32_bf16 v[54:57], v[140:143], v[78:81], v[54:57]
	v_mfma_f32_16x16x32_bf16 v[50:53], v[152:155], v[78:81], v[50:53]
	v_mfma_f32_16x16x32_bf16 v[38:41], v[140:143], v[192:195], v[38:41]
	v_mfma_f32_16x16x32_bf16 v[34:37], v[152:155], v[192:195], v[34:37]
	v_mfma_f32_16x16x32_bf16 v[62:65], v[144:147], v[74:77], v[62:65]
	v_mfma_f32_16x16x32_bf16 v[58:61], v[152:155], v[66:69], v[58:61]
	v_mfma_f32_16x16x32_bf16 v[54:57], v[144:147], v[90:93], v[54:57]
	v_mfma_f32_16x16x32_bf16 v[50:53], v[164:167], v[90:93], v[50:53]
	v_mfma_f32_16x16x32_bf16 v[46:49], v[140:143], v[94:97], v[46:49]
	v_mfma_f32_16x16x32_bf16 v[42:45], v[152:155], v[94:97], v[42:45]
	v_mfma_f32_16x16x32_bf16 v[38:41], v[144:147], v[196:199], v[38:41]
	v_mfma_f32_16x16x32_bf16 v[34:37], v[164:167], v[196:199], v[34:37]
	v_mfma_f32_16x16x32_bf16 v[200:203], v[164:167], v[74:77], v[58:61]
	v_mfma_f32_16x16x32_bf16 v[220:223], v[144:147], v[188:191], v[46:49]
	v_mfma_f32_16x16x32_bf16 v[224:227], v[164:167], v[188:191], v[42:45]
	v_mfma_f32_16x16x32_bf16 v[22:25], v[106:109], v[78:81], v[22:25]
	v_mfma_f32_16x16x32_bf16 v[18:21], v[122:125], v[78:81], v[18:21]
	v_mfma_f32_16x16x32_bf16 v[6:9], v[106:109], v[192:195], v[6:9]
	v_mfma_f32_16x16x32_bf16 v[30:33], v[106:109], v[66:69], v[30:33]
	v_mfma_f32_16x16x32_bf16 v[26:29], v[122:125], v[66:69], v[26:29]
	v_mfma_f32_16x16x32_bf16 v[22:25], v[110:113], v[90:93], v[22:25]
	v_mfma_f32_16x16x32_bf16 v[18:21], v[212:215], v[90:93], v[18:21]
	v_mfma_f32_16x16x32_bf16 v[14:17], v[106:109], v[94:97], v[14:17]
	v_mfma_f32_16x16x32_bf16 v[10:13], v[122:125], v[94:97], v[10:13]
	v_mfma_f32_16x16x32_bf16 v[6:9], v[110:113], v[196:199], v[6:9]
	v_mfma_f32_16x16x32_bf16 v[2:5], v[122:125], v[192:195], v[2:5]
	v_mfma_f32_16x16x32_bf16 v[140:143], v[110:113], v[74:77], v[30:33]
	v_mfma_f32_16x16x32_bf16 v[144:147], v[212:215], v[74:77], v[26:29]
	v_mfma_f32_16x16x32_bf16 v[152:155], v[110:113], v[188:191], v[14:17]
	v_mfma_f32_16x16x32_bf16 v[164:167], v[212:215], v[188:191], v[10:13]
	v_mfma_f32_16x16x32_bf16 v[188:191], v[212:215], v[196:199], v[2:5]
	s_barrier
	s_nop 0
	ds_read_b128 v[2:5], v138 offset:32768
	ds_read_b128 v[10:13], v138 offset:33792
	ds_read_b128 v[14:17], v138 offset:34816
	ds_read_b128 v[192:195], v138 offset:35840
	ds_read_b128 v[26:29], v137 offset:32768
	ds_read_b128 v[30:33], v137 offset:33792
	ds_read_b128 v[42:45], v137 offset:34816
	ds_read_b128 v[46:49], v137 offset:35840
	ds_read_b128 v[58:61], v137 offset:36864
	ds_read_b128 v[66:69], v137 offset:37888
	ds_read_b128 v[196:199], v137 offset:38912
	ds_read_b128 v[212:215], v137 offset:39936
	s_waitcnt vmcnt(2)
	s_barrier
; #define WAIT_V(n) asm volatile("s_waitcnt vmcnt(%0)" ::"n"(n) : "memory")
; #define WAIT_L(n) asm volatile("s_waitcnt lgkmcnt(%0)" ::"n"(n) : "memory")
; #define LDA8(dst, b, h) _Pragma("unroll") for (int m = 0; m < 4; ++m) _Pragma("unroll") for (int k = 0; k < 2; ++k) \
;     dst[m][k] = *(const bf16x8*)(abase + SAo(b, h) + m * 2048 + k * 1024)
; #define LDB8(dst, b, h) _Pragma("unroll") for (int n = 0; n < 2; ++n) _Pragma("unroll") for (int k = 0; k < 2; ++k) \
;     dst[n][k] = *(const bf16x8*)(bbase + SAo(b, h) + n * 2048 + k * 1024)
; #define BAR8 __builtin_amdgcn_s_barrier()
; __device__ __forceinline__ void gemm_main8(const u16* __restrict__ Ab, int lda, const u16* __restrict__ Bb, int ldb, int K,
;                                            char* shm, f32x4 (&acc)[2][2][4][2]) {
;     ...
;   { LDB8(B0, 1, 0); LDA8(At, 1, 0); WAIT_V(2); BAR8; WAIT_L(0); MMA8(0, 0, At, B0); BAR8;
;     LDB8(B1, 1, 1); WAIT_V(0); BAR8; WAIT_L(0); MMA8(0, 1, At, B1); BAR8;
;     LDA8(At, 1, 1); BAR8; WAIT_L(0); MMA8(1, 0, At, B0); MMA8(1, 1, At, B1); BAR8; }
;   if (wr == 0) BAR8;
	s_waitcnt lgkmcnt(0)
	s_waitcnt lgkmcnt(0)
	v_mfma_f32_16x16x32_bf16 v[74:77], v[2:5], v[26:29], v[126:129]
	v_mfma_f32_16x16x32_bf16 v[122:125], v[10:13], v[30:33], v[74:77]
	v_mfma_f32_16x16x32_bf16 v[74:77], v[14:17], v[26:29], v[172:175]
	v_mfma_f32_16x16x32_bf16 v[126:129], v[192:195], v[30:33], v[74:77]
	v_mfma_f32_16x16x32_bf16 v[74:77], v[2:5], v[42:45], v[118:121]
	v_mfma_f32_16x16x32_bf16 v[106:109], v[10:13], v[46:49], v[74:77]
	v_mfma_f32_16x16x32_bf16 v[74:77], v[14:17], v[42:45], v[114:117]
	v_mfma_f32_16x16x32_bf16 v[110:113], v[192:195], v[46:49], v[74:77]
	v_mfma_f32_16x16x32_bf16 v[74:77], v[2:5], v[58:61], v[204:207]
	v_mfma_f32_16x16x32_bf16 v[90:93], v[10:13], v[66:69], v[74:77]
	v_mfma_f32_16x16x32_bf16 v[74:77], v[14:17], v[58:61], v[208:211]
	v_mfma_f32_16x16x32_bf16 v[94:97], v[192:195], v[66:69], v[74:77]
	v_mfma_f32_16x16x32_bf16 v[74:77], v[2:5], v[196:199], v[102:105]
	v_mfma_f32_16x16x32_bf16 v[78:81], v[14:17], v[196:199], v[98:101]
	v_mfma_f32_16x16x32_bf16 v[74:77], v[10:13], v[212:215], v[74:77]
	v_mfma_f32_16x16x32_bf16 v[78:81], v[192:195], v[212:215], v[78:81]
	s_barrier
	ds_read_b128 v[172:175], v138 offset:49152
	ds_read_b128 v[204:207], v138 offset:50176
	ds_read_b128 v[208:211], v138 offset:51200
	ds_read_b128 v[228:231], v138 offset:52224
	s_waitcnt vmcnt(0)
	s_barrier
	s_waitcnt lgkmcnt(0)
	s_waitcnt lgkmcnt(0)
	v_mfma_f32_16x16x32_bf16 v[98:101], v[172:175], v[26:29], v[216:219]
	v_mfma_f32_16x16x32_bf16 v[26:29], v[208:211], v[26:29], v[168:171]
	v_mfma_f32_16x16x32_bf16 v[118:121], v[228:231], v[30:33], v[26:29]
	v_mfma_f32_16x16x32_bf16 v[26:29], v[172:175], v[42:45], v[86:89]
	v_mfma_f32_16x16x32_bf16 v[114:117], v[204:207], v[30:33], v[98:101]
	v_mfma_f32_16x16x32_bf16 v[98:101], v[204:207], v[46:49], v[26:29]
	v_mfma_f32_16x16x32_bf16 v[26:29], v[208:211], v[42:45], v[82:85]
	v_mfma_f32_16x16x32_bf16 v[102:105], v[228:231], v[46:49], v[26:29]
	v_mfma_f32_16x16x32_bf16 v[26:29], v[172:175], v[58:61], v[176:179]
	v_mfma_f32_16x16x32_bf16 v[82:85], v[204:207], v[66:69], v[26:29]
	v_mfma_f32_16x16x32_bf16 v[26:29], v[208:211], v[58:61], v[180:183]
	v_mfma_f32_16x16x32_bf16 v[86:89], v[228:231], v[66:69], v[26:29]
	v_mfma_f32_16x16x32_bf16 v[26:29], v[172:175], v[196:199], v[70:73]
	v_mfma_f32_16x16x32_bf16 v[66:69], v[204:207], v[212:215], v[26:29]
	v_mfma_f32_16x16x32_bf16 v[26:29], v[208:211], v[196:199], v[184:187]
	v_mfma_f32_16x16x32_bf16 v[70:73], v[228:231], v[212:215], v[26:29]
	s_barrier
	ds_read_b128 v[168:171], v137 offset:49152
	ds_read_b128 v[176:179], v137 offset:50176
	ds_read_b128 v[180:183], v137 offset:51200
	ds_read_b128 v[184:187], v137 offset:52224
	ds_read_b128 v[196:199], v137 offset:53248
	ds_read_b128 v[212:215], v137 offset:54272
	ds_read_b128 v[216:219], v137 offset:55296
	ds_read_b128 v[232:235], v137 offset:56320
	s_barrier
	s_waitcnt lgkmcnt(0)
	s_waitcnt lgkmcnt(0)
	v_mfma_f32_16x16x32_bf16 v[26:29], v[2:5], v[168:171], v[62:65]
	v_mfma_f32_16x16x32_bf16 v[58:61], v[10:13], v[176:179], v[26:29]
	v_mfma_f32_16x16x32_bf16 v[26:29], v[14:17], v[168:171], v[200:203]
	v_mfma_f32_16x16x32_bf16 v[62:65], v[192:195], v[176:179], v[26:29]
	v_mfma_f32_16x16x32_bf16 v[26:29], v[2:5], v[180:183], v[54:57]
	v_mfma_f32_16x16x32_bf16 v[42:45], v[10:13], v[184:187], v[26:29]
	v_mfma_f32_16x16x32_bf16 v[26:29], v[14:17], v[180:183], v[50:53]
	v_mfma_f32_16x16x32_bf16 v[46:49], v[192:195], v[184:187], v[26:29]
	v_mfma_f32_16x16x32_bf16 v[26:29], v[2:5], v[196:199], v[220:223]
	v_mfma_f32_16x16x32_bf16 v[2:5], v[2:5], v[216:219], v[38:41]
	v_mfma_f32_16x16x32_bf16 v[26:29], v[10:13], v[212:215], v[26:29]
	v_mfma_f32_16x16x32_bf16 v[30:33], v[14:17], v[196:199], v[224:227]
	v_mfma_f32_16x16x32_bf16 v[10:13], v[10:13], v[232:235], v[2:5]
	v_mfma_f32_16x16x32_bf16 v[2:5], v[14:17], v[216:219], v[34:37]
	v_mfma_f32_16x16x32_bf16 v[30:33], v[192:195], v[212:215], v[30:33]
	v_mfma_f32_16x16x32_bf16 v[14:17], v[192:195], v[232:235], v[2:5]
	v_mfma_f32_16x16x32_bf16 v[2:5], v[172:175], v[168:171], v[140:143]
	v_mfma_f32_16x16x32_bf16 v[54:57], v[204:207], v[176:179], v[2:5]
	v_mfma_f32_16x16x32_bf16 v[2:5], v[208:211], v[168:171], v[144:147]
	v_mfma_f32_16x16x32_bf16 v[50:53], v[228:231], v[176:179], v[2:5]
	v_mfma_f32_16x16x32_bf16 v[2:5], v[172:175], v[180:183], v[22:25]
	v_mfma_f32_16x16x32_bf16 v[34:37], v[204:207], v[184:187], v[2:5]
	v_mfma_f32_16x16x32_bf16 v[2:5], v[208:211], v[180:183], v[18:21]
	v_mfma_f32_16x16x32_bf16 v[38:41], v[228:231], v[184:187], v[2:5]
	v_mfma_f32_16x16x32_bf16 v[2:5], v[172:175], v[196:199], v[152:155]
	v_mfma_f32_16x16x32_bf16 v[18:21], v[204:207], v[212:215], v[2:5]
	v_mfma_f32_16x16x32_bf16 v[2:5], v[208:211], v[196:199], v[164:167]
	v_mfma_f32_16x16x32_bf16 v[22:25], v[228:231], v[212:215], v[2:5]
	v_mfma_f32_16x16x32_bf16 v[2:5], v[172:175], v[216:219], v[6:9]
	v_mfma_f32_16x16x32_bf16 v[6:9], v[208:211], v[216:219], v[188:191]
	v_mfma_f32_16x16x32_bf16 v[2:5], v[204:207], v[232:235], v[2:5]
	v_mfma_f32_16x16x32_bf16 v[6:9], v[228:231], v[232:235], v[6:9]
	v_cmp_gt_u32_e64 s[12:13], s97, v136
	s_barrier
	s_and_saveexec_b64 s[10:11], s[12:13]
	s_cbranch_execz .LBB0_901
	s_barrier
	s_branch .LBB0_901

; #define WAIT_L(n) asm volatile("s_waitcnt lgkmcnt(%0)" ::"n"(n) : "memory")
; #define SBAR() __builtin_amdgcn_sched_barrier(0)
; #define LDA8(dst, b, h) _Pragma("unroll") for (int m = 0; m < 4; ++m) _Pragma("unroll") for (int k = 0; k < 2; ++k) \
;     dst[m][k] = *(const bf16x8*)(abase + SAo(b, h) + m * 2048 + k * 1024)
; #define LDB8(dst, b, h) _Pragma("unroll") for (int n = 0; n < 2; ++n) _Pragma("unroll") for (int k = 0; k < 2; ++k) \
;     dst[n][k] = *(const bf16x8*)(bbase + SAo(b, h) + n * 2048 + k * 1024)
; #define BAR8 __builtin_amdgcn_s_barrier()
; __device__ __forceinline__ void gemm_main8(const u16* __restrict__ Ab, int lda, const u16* __restrict__ Bb, int ldb, int K,
;                                            char* shm, f32x4 (&acc)[2][2][4][2]) {
;     ...
;     LDB8(B0, 0, 0); SBAR(); LDA8(At, 0, 0); STG_A(1, 1, t + 1);
;     WAIT_L(8); BAR8; WAIT_L(0); MMA8(0, 0, At, B0); BAR8; SBAR();
;     LDB8(B1, 0, 1); STG_B(0, 0, t + 2);
;     BAR8; WAIT_L(0); MMA8(0, 1, At, B1); BAR8;
;     LDA8(At, 0, 1); STG_A(0, 0, t + 2);
;     BAR8; WAIT_L(0); MMA8(1, 0, At, B0); BAR8; SBAR();
.LBB0_951:
	ds_read_b128 v[152:155], v137
	ds_read_b128 v[164:167], v137 offset:1024
	ds_read_b128 v[176:179], v137 offset:2048
	ds_read_b128 v[180:183], v137 offset:3072
	ds_read_b128 v[184:187], v136
	ds_read_b128 v[188:191], v136 offset:1024
	ds_read_b128 v[192:195], v136 offset:2048
	ds_read_b128 v[196:199], v136 offset:3072
	ds_read_b128 v[200:203], v136 offset:4096
	ds_read_b128 v[204:207], v136 offset:5120
	ds_read_b128 v[208:211], v136 offset:6144
	ds_read_b128 v[212:215], v136 offset:7168
	v_add_u32_e32 v173, 0xc000, v138
	v_lshl_add_u64 v[168:169], s[20:21], 0, v[0:1]
	s_mov_b64 s[78:79], 0x17460080
	v_readfirstlane_b32 s25, v173
	v_lshl_add_u64 v[174:175], v[168:169], 0, s[78:79]
	s_mov_b32 m0, s25
	global_load_lds_dwordx4 v[174:175], off
	v_add_u32_e32 v174, 0xe000, v138
	s_mov_b64 s[78:79], 0x17510080
	v_readfirstlane_b32 s25, v174
	v_lshl_add_u64 v[216:217], v[168:169], 0, s[78:79]
	s_mov_b32 m0, s25
	s_nop 0
	global_load_lds_dwordx4 v[216:217], off
	s_waitcnt lgkmcnt(8)
	s_barrier
	s_waitcnt lgkmcnt(0)
	s_waitcnt lgkmcnt(0)
	v_mfma_f32_16x16x32_bf16 v[126:129], v[152:155], v[184:187], v[126:129]
	v_mfma_f32_16x16x32_bf16 v[122:125], v[176:179], v[184:187], v[122:125]
	v_mfma_f32_16x16x32_bf16 v[118:121], v[152:155], v[192:195], v[118:121]
	v_mfma_f32_16x16x32_bf16 v[114:117], v[176:179], v[192:195], v[114:117]
	v_mfma_f32_16x16x32_bf16 v[110:113], v[152:155], v[200:203], v[110:113]
	v_mfma_f32_16x16x32_bf16 v[106:109], v[176:179], v[200:203], v[106:109]
	v_mfma_f32_16x16x32_bf16 v[102:105], v[152:155], v[208:211], v[102:105]
	v_mfma_f32_16x16x32_bf16 v[98:101], v[176:179], v[208:211], v[98:101]
	v_mfma_f32_16x16x32_bf16 v[126:129], v[164:167], v[188:191], v[126:129]
	v_mfma_f32_16x16x32_bf16 v[122:125], v[180:183], v[188:191], v[122:125]
	v_mfma_f32_16x16x32_bf16 v[118:121], v[164:167], v[196:199], v[118:121]
	v_mfma_f32_16x16x32_bf16 v[114:117], v[180:183], v[196:199], v[114:117]
	v_mfma_f32_16x16x32_bf16 v[110:113], v[164:167], v[204:207], v[110:113]
	v_mfma_f32_16x16x32_bf16 v[106:109], v[180:183], v[204:207], v[106:109]
	v_mfma_f32_16x16x32_bf16 v[102:105], v[164:167], v[212:215], v[102:105]
	v_mfma_f32_16x16x32_bf16 v[98:101], v[180:183], v[212:215], v[98:101]
	s_barrier
	ds_read_b128 v[216:219], v137 offset:16384
	ds_read_b128 v[220:223], v137 offset:17408
	ds_read_b128 v[224:227], v137 offset:18432
	ds_read_b128 v[228:231], v137 offset:19456
	v_lshl_add_u64 v[232:233], s[18:19], 0, v[0:1]
	s_mov_b64 s[78:79], 0x6c00100
	v_readfirstlane_b32 s25, v139
	v_lshl_add_u64 v[234:235], v[232:233], 0, s[78:79]
	s_mov_b32 m0, s25
	s_mov_b64 s[78:79], 0x6cb0100
	v_readfirstlane_b32 s25, v140
	global_load_lds_dwordx4 v[234:235], off
	v_lshl_add_u64 v[234:235], v[232:233], 0, s[78:79]
	s_mov_b32 m0, s25
	s_nop 0
	global_load_lds_dwordx4 v[234:235], off
	s_barrier
	s_waitcnt lgkmcnt(0)
	s_waitcnt lgkmcnt(0)
	v_mfma_f32_16x16x32_bf16 v[94:97], v[216:219], v[184:187], v[94:97]
	v_mfma_f32_16x16x32_bf16 v[90:93], v[224:227], v[184:187], v[90:93]
	v_mfma_f32_16x16x32_bf16 v[86:89], v[216:219], v[192:195], v[86:89]
	v_mfma_f32_16x16x32_bf16 v[82:85], v[224:227], v[192:195], v[82:85]
	v_mfma_f32_16x16x32_bf16 v[78:81], v[216:219], v[200:203], v[78:81]
	v_mfma_f32_16x16x32_bf16 v[74:77], v[224:227], v[200:203], v[74:77]
	v_mfma_f32_16x16x32_bf16 v[70:73], v[216:219], v[208:211], v[70:73]
	v_mfma_f32_16x16x32_bf16 v[66:69], v[224:227], v[208:211], v[66:69]
	v_mfma_f32_16x16x32_bf16 v[94:97], v[220:223], v[188:191], v[94:97]
	v_mfma_f32_16x16x32_bf16 v[90:93], v[228:231], v[188:191], v[90:93]
	v_mfma_f32_16x16x32_bf16 v[86:89], v[220:223], v[196:199], v[86:89]
	v_mfma_f32_16x16x32_bf16 v[82:85], v[228:231], v[196:199], v[82:85]
	v_mfma_f32_16x16x32_bf16 v[78:81], v[220:223], v[204:207], v[78:81]
	v_mfma_f32_16x16x32_bf16 v[74:77], v[228:231], v[204:207], v[74:77]
	v_mfma_f32_16x16x32_bf16 v[70:73], v[220:223], v[212:215], v[70:73]
	v_mfma_f32_16x16x32_bf16 v[66:69], v[228:231], v[212:215], v[66:69]
	v_readfirstlane_b32 s25, v138
	v_lshl_add_u64 v[234:235], v[168:169], 0, s[30:31]
	s_mov_b32 m0, s25
	s_mov_b64 s[78:79], 0x173b0100
	v_readfirstlane_b32 s25, v141
	s_barrier
	ds_read_b128 v[184:187], v136 offset:16384
	ds_read_b128 v[188:191], v136 offset:17408
	ds_read_b128 v[192:195], v136 offset:18432
	ds_read_b128 v[196:199], v136 offset:19456
	ds_read_b128 v[200:203], v136 offset:20480
	ds_read_b128 v[204:207], v136 offset:21504
	ds_read_b128 v[208:211], v136 offset:22528
	ds_read_b128 v[212:215], v136 offset:23552
	global_load_lds_dwordx4 v[234:235], off
	v_lshl_add_u64 v[234:235], v[168:169], 0, s[78:79]
	s_mov_b32 m0, s25
	s_nop 0
	global_load_lds_dwordx4 v[234:235], off
	s_barrier
	s_waitcnt lgkmcnt(0)
	s_waitcnt lgkmcnt(0)
	v_mfma_f32_16x16x32_bf16 v[62:65], v[152:155], v[184:187], v[62:65]
	v_mfma_f32_16x16x32_bf16 v[58:61], v[176:179], v[184:187], v[58:61]
	v_mfma_f32_16x16x32_bf16 v[54:57], v[152:155], v[192:195], v[54:57]
	v_mfma_f32_16x16x32_bf16 v[50:53], v[176:179], v[192:195], v[50:53]
	v_mfma_f32_16x16x32_bf16 v[46:49], v[152:155], v[200:203], v[46:49]
	v_mfma_f32_16x16x32_bf16 v[42:45], v[176:179], v[200:203], v[42:45]
	v_mfma_f32_16x16x32_bf16 v[38:41], v[152:155], v[208:211], v[38:41]
	v_mfma_f32_16x16x32_bf16 v[34:37], v[176:179], v[208:211], v[34:37]
	v_mfma_f32_16x16x32_bf16 v[62:65], v[164:167], v[188:191], v[62:65]
	v_mfma_f32_16x16x32_bf16 v[58:61], v[180:183], v[188:191], v[58:61]
	v_mfma_f32_16x16x32_bf16 v[54:57], v[164:167], v[196:199], v[54:57]
	v_mfma_f32_16x16x32_bf16 v[50:53], v[180:183], v[196:199], v[50:53]
	v_mfma_f32_16x16x32_bf16 v[46:49], v[164:167], v[204:207], v[46:49]
	v_mfma_f32_16x16x32_bf16 v[42:45], v[180:183], v[204:207], v[42:45]
	v_mfma_f32_16x16x32_bf16 v[38:41], v[164:167], v[212:215], v[38:41]
	v_mfma_f32_16x16x32_bf16 v[34:37], v[180:183], v[212:215], v[34:37]
	s_barrier
; #define WAIT_V(n) asm volatile("s_waitcnt vmcnt(%0)" ::"n"(n) : "memory")
; #define WAIT_L(n) asm volatile("s_waitcnt lgkmcnt(%0)" ::"n"(n) : "memory")
; #define SBAR() __builtin_amdgcn_sched_barrier(0)
; #define LDA8(dst, b, h) _Pragma("unroll") for (int m = 0; m < 4; ++m) _Pragma("unroll") for (int k = 0; k < 2; ++k) \
;     dst[m][k] = *(const bf16x8*)(abase + SAo(b, h) + m * 2048 + k * 1024)
; #define LDB8(dst, b, h) _Pragma("unroll") for (int n = 0; n < 2; ++n) _Pragma("unroll") for (int k = 0; k < 2; ++k) \
;     dst[n][k] = *(const bf16x8*)(bbase + SAo(b, h) + n * 2048 + k * 1024)
; #define BAR8 __builtin_amdgcn_s_barrier()
; __device__ __forceinline__ void gemm_main8(const u16* __restrict__ Ab, int lda, const u16* __restrict__ Bb, int ldb, int K,
;                                            char* shm, f32x4 (&acc)[2][2][4][2]) {
;     ...
;     STG_B(0, 1, t + 2);
;     WAIT_V(6); BAR8; MMA8(1, 1, At, B1); BAR8;
;     LDB8(B0, 1, 0); SBAR(); LDA8(At, 1, 0); STG_A(0, 1, t + 2);
;     WAIT_L(8); BAR8; WAIT_L(0); MMA8(0, 0, At, B0); BAR8; SBAR();
;     LDB8(B1, 1, 1); STG_B(1, 0, t + 3);
;     BAR8; WAIT_L(0); MMA8(0, 1, At, B1); BAR8;
	s_mov_b64 s[78:79], 0x6d60100
	v_readfirstlane_b32 s25, v142
	v_lshl_add_u64 v[152:153], v[232:233], 0, s[78:79]
	s_mov_b32 m0, s25
	s_mov_b64 s[78:79], 0x6e10100
	v_readfirstlane_b32 s25, v143
	global_load_lds_dwordx4 v[152:153], off
	v_lshl_add_u64 v[152:153], v[232:233], 0, s[78:79]
	s_mov_b32 m0, s25
	s_nop 0
	global_load_lds_dwordx4 v[152:153], off
	s_waitcnt vmcnt(6)
	s_barrier
	v_mfma_f32_16x16x32_bf16 v[30:33], v[216:219], v[184:187], v[30:33]
	v_mfma_f32_16x16x32_bf16 v[26:29], v[224:227], v[184:187], v[26:29]
	v_mfma_f32_16x16x32_bf16 v[22:25], v[216:219], v[192:195], v[22:25]
	v_mfma_f32_16x16x32_bf16 v[18:21], v[224:227], v[192:195], v[18:21]
	v_mfma_f32_16x16x32_bf16 v[14:17], v[216:219], v[200:203], v[14:17]
	v_mfma_f32_16x16x32_bf16 v[10:13], v[224:227], v[200:203], v[10:13]
	v_mfma_f32_16x16x32_bf16 v[6:9], v[216:219], v[208:211], v[6:9]
	v_mfma_f32_16x16x32_bf16 v[2:5], v[224:227], v[208:211], v[2:5]
	v_mfma_f32_16x16x32_bf16 v[30:33], v[220:223], v[188:191], v[30:33]
	v_mfma_f32_16x16x32_bf16 v[26:29], v[228:231], v[188:191], v[26:29]
	v_mfma_f32_16x16x32_bf16 v[22:25], v[220:223], v[196:199], v[22:25]
	v_mfma_f32_16x16x32_bf16 v[18:21], v[228:231], v[196:199], v[18:21]
	v_mfma_f32_16x16x32_bf16 v[14:17], v[220:223], v[204:207], v[14:17]
	v_mfma_f32_16x16x32_bf16 v[10:13], v[228:231], v[204:207], v[10:13]
	v_mfma_f32_16x16x32_bf16 v[6:9], v[220:223], v[212:215], v[6:9]
	v_mfma_f32_16x16x32_bf16 v[2:5], v[228:231], v[212:215], v[2:5]
	s_barrier
	ds_read_b128 v[152:155], v137 offset:32768
	ds_read_b128 v[164:167], v137 offset:33792
	ds_read_b128 v[176:179], v137 offset:34816
	ds_read_b128 v[180:183], v137 offset:35840
	ds_read_b128 v[184:187], v136 offset:32768
	ds_read_b128 v[188:191], v136 offset:33792
	ds_read_b128 v[192:195], v136 offset:34816
	ds_read_b128 v[196:199], v136 offset:35840
	ds_read_b128 v[200:203], v136 offset:36864
	ds_read_b128 v[204:207], v136 offset:37888
	ds_read_b128 v[208:211], v136 offset:38912
	ds_read_b128 v[212:215], v136 offset:39936
	s_mov_b64 s[78:79], 0x17460100
	v_readfirstlane_b32 s25, v144
	v_lshl_add_u64 v[216:217], v[168:169], 0, s[78:79]
	s_mov_b32 m0, s25
	s_mov_b64 s[78:79], 0x17510100
	v_readfirstlane_b32 s25, v145
	global_load_lds_dwordx4 v[216:217], off
	v_lshl_add_u64 v[216:217], v[168:169], 0, s[78:79]
	s_mov_b32 m0, s25
	s_nop 0
	global_load_lds_dwordx4 v[216:217], off
	s_waitcnt lgkmcnt(8)
	s_barrier
	s_waitcnt lgkmcnt(0)
	s_waitcnt lgkmcnt(0)
	v_mfma_f32_16x16x32_bf16 v[126:129], v[152:155], v[184:187], v[126:129]
	v_mfma_f32_16x16x32_bf16 v[122:125], v[176:179], v[184:187], v[122:125]
	v_mfma_f32_16x16x32_bf16 v[118:121], v[152:155], v[192:195], v[118:121]
	v_mfma_f32_16x16x32_bf16 v[114:117], v[176:179], v[192:195], v[114:117]
	v_mfma_f32_16x16x32_bf16 v[110:113], v[152:155], v[200:203], v[110:113]
	v_mfma_f32_16x16x32_bf16 v[106:109], v[176:179], v[200:203], v[106:109]
	v_mfma_f32_16x16x32_bf16 v[102:105], v[152:155], v[208:211], v[102:105]
	v_mfma_f32_16x16x32_bf16 v[98:101], v[176:179], v[208:211], v[98:101]
	v_mfma_f32_16x16x32_bf16 v[126:129], v[164:167], v[188:191], v[126:129]
	v_mfma_f32_16x16x32_bf16 v[122:125], v[180:183], v[188:191], v[122:125]
	v_mfma_f32_16x16x32_bf16 v[118:121], v[164:167], v[196:199], v[118:121]
	v_mfma_f32_16x16x32_bf16 v[114:117], v[180:183], v[196:199], v[114:117]
	v_mfma_f32_16x16x32_bf16 v[110:113], v[164:167], v[204:207], v[110:113]
	v_mfma_f32_16x16x32_bf16 v[106:109], v[180:183], v[204:207], v[106:109]
	v_mfma_f32_16x16x32_bf16 v[102:105], v[164:167], v[212:215], v[102:105]
	v_mfma_f32_16x16x32_bf16 v[98:101], v[180:183], v[212:215], v[98:101]
	s_barrier
	ds_read_b128 v[216:219], v137 offset:49152
	ds_read_b128 v[220:223], v137 offset:50176
	ds_read_b128 v[224:227], v137 offset:51200
	ds_read_b128 v[228:231], v137 offset:52224
	s_mov_b64 s[78:79], 0x6c00180
	v_readfirstlane_b32 s25, v146
	v_lshl_add_u64 v[234:235], v[232:233], 0, s[78:79]
	s_mov_b32 m0, s25
	s_mov_b64 s[78:79], 0x6cb0180
	v_readfirstlane_b32 s25, v147
	global_load_lds_dwordx4 v[234:235], off
	v_lshl_add_u64 v[234:235], v[232:233], 0, s[78:79]
	s_mov_b32 m0, s25
	s_nop 0
	global_load_lds_dwordx4 v[234:235], off
	s_barrier
	s_waitcnt lgkmcnt(0)
	s_waitcnt lgkmcnt(0)
	v_mfma_f32_16x16x32_bf16 v[94:97], v[216:219], v[184:187], v[94:97]
	v_mfma_f32_16x16x32_bf16 v[90:93], v[224:227], v[184:187], v[90:93]
	v_mfma_f32_16x16x32_bf16 v[86:89], v[216:219], v[192:195], v[86:89]
	v_mfma_f32_16x16x32_bf16 v[82:85], v[224:227], v[192:195], v[82:85]
	v_mfma_f32_16x16x32_bf16 v[78:81], v[216:219], v[200:203], v[78:81]
	v_mfma_f32_16x16x32_bf16 v[74:77], v[224:227], v[200:203], v[74:77]
	v_mfma_f32_16x16x32_bf16 v[70:73], v[216:219], v[208:211], v[70:73]
	v_mfma_f32_16x16x32_bf16 v[66:69], v[224:227], v[208:211], v[66:69]
	v_mfma_f32_16x16x32_bf16 v[94:97], v[220:223], v[188:191], v[94:97]
	v_mfma_f32_16x16x32_bf16 v[90:93], v[228:231], v[188:191], v[90:93]
	v_mfma_f32_16x16x32_bf16 v[86:89], v[220:223], v[196:199], v[86:89]
	v_mfma_f32_16x16x32_bf16 v[82:85], v[228:231], v[196:199], v[82:85]
	v_mfma_f32_16x16x32_bf16 v[78:81], v[220:223], v[204:207], v[78:81]
	v_mfma_f32_16x16x32_bf16 v[74:77], v[228:231], v[204:207], v[74:77]
	v_mfma_f32_16x16x32_bf16 v[70:73], v[220:223], v[212:215], v[70:73]
	v_mfma_f32_16x16x32_bf16 v[66:69], v[228:231], v[212:215], v[66:69]
	v_readfirstlane_b32 s25, v148
	v_lshl_add_u64 v[234:235], v[168:169], 0, s[16:17]
	s_mov_b32 m0, s25
	s_mov_b64 s[78:79], 0x173b0180
	v_readfirstlane_b32 s25, v149
	s_barrier
; #define WAIT_V(n) asm volatile("s_waitcnt vmcnt(%0)" ::"n"(n) : "memory")
; #define WAIT_L(n) asm volatile("s_waitcnt lgkmcnt(%0)" ::"n"(n) : "memory")
; #define SBAR() __builtin_amdgcn_sched_barrier(0)
; #define LDA8(dst, b, h) _Pragma("unroll") for (int m = 0; m < 4; ++m) _Pragma("unroll") for (int k = 0; k < 2; ++k) \
;     dst[m][k] = *(const bf16x8*)(abase + SAo(b, h) + m * 2048 + k * 1024)
; #define LDB8(dst, b, h) _Pragma("unroll") for (int n = 0; n < 2; ++n) _Pragma("unroll") for (int k = 0; k < 2; ++k) \
;     dst[n][k] = *(const bf16x8*)(bbase + SAo(b, h) + n * 2048 + k * 1024)
; #define BAR8 __builtin_amdgcn_s_barrier()
; __device__ __forceinline__ void gemm_main8(const u16* __restrict__ Ab, int lda, const u16* __restrict__ Bb, int ldb, int K,
;                                            char* shm, f32x4 (&acc)[2][2][4][2]) {
;     ...
;     LDA8(At, 1, 1); STG_A(1, 0, t + 3);
;     BAR8; WAIT_L(0); MMA8(1, 0, At, B0); BAR8; SBAR();
;     STG_B(1, 1, t + 3);
;     WAIT_V(6); BAR8; MMA8(1, 1, At, B1); BAR8;
;   }
;   { LDB8(B0, 0, 0); LDA8(At, 0, 0); STG_A(1, 1, nt - 1);
;     BAR8; WAIT_L(0); MMA8(0, 0, At, B0); BAR8;
;     LDB8(B1, 0, 1); BAR8; WAIT_L(0); MMA8(0, 1, At, B1); BAR8;
	ds_read_b128 v[184:187], v136 offset:49152
	ds_read_b128 v[188:191], v136 offset:50176
	ds_read_b128 v[192:195], v136 offset:51200
	ds_read_b128 v[196:199], v136 offset:52224
	ds_read_b128 v[200:203], v136 offset:53248
	ds_read_b128 v[204:207], v136 offset:54272
	ds_read_b128 v[208:211], v136 offset:55296
	ds_read_b128 v[212:215], v136 offset:56320
	global_load_lds_dwordx4 v[234:235], off
	v_lshl_add_u64 v[168:169], v[168:169], 0, s[78:79]
	s_mov_b32 m0, s25
	s_nop 0
	global_load_lds_dwordx4 v[168:169], off
	s_barrier
	s_waitcnt lgkmcnt(0)
	s_waitcnt lgkmcnt(0)
	v_mfma_f32_16x16x32_bf16 v[62:65], v[152:155], v[184:187], v[62:65]
	v_mfma_f32_16x16x32_bf16 v[58:61], v[176:179], v[184:187], v[58:61]
	v_mfma_f32_16x16x32_bf16 v[54:57], v[152:155], v[192:195], v[54:57]
	v_mfma_f32_16x16x32_bf16 v[50:53], v[176:179], v[192:195], v[50:53]
	v_mfma_f32_16x16x32_bf16 v[46:49], v[152:155], v[200:203], v[46:49]
	v_mfma_f32_16x16x32_bf16 v[42:45], v[176:179], v[200:203], v[42:45]
	v_mfma_f32_16x16x32_bf16 v[38:41], v[152:155], v[208:211], v[38:41]
	v_mfma_f32_16x16x32_bf16 v[34:37], v[176:179], v[208:211], v[34:37]
	v_mfma_f32_16x16x32_bf16 v[62:65], v[164:167], v[188:191], v[62:65]
	v_mfma_f32_16x16x32_bf16 v[58:61], v[180:183], v[188:191], v[58:61]
	v_mfma_f32_16x16x32_bf16 v[54:57], v[164:167], v[196:199], v[54:57]
	v_mfma_f32_16x16x32_bf16 v[50:53], v[180:183], v[196:199], v[50:53]
	v_mfma_f32_16x16x32_bf16 v[46:49], v[164:167], v[204:207], v[46:49]
	v_mfma_f32_16x16x32_bf16 v[42:45], v[180:183], v[204:207], v[42:45]
	v_mfma_f32_16x16x32_bf16 v[38:41], v[164:167], v[212:215], v[38:41]
	v_mfma_f32_16x16x32_bf16 v[34:37], v[180:183], v[212:215], v[34:37]
	s_barrier
	s_mov_b64 s[78:79], 0x6d60180
	v_readfirstlane_b32 s25, v171
	v_lshl_add_u64 v[152:153], v[232:233], 0, s[78:79]
	s_mov_b32 m0, s25
	s_mov_b64 s[78:79], 0x6e10180
	v_readfirstlane_b32 s25, v172
	global_load_lds_dwordx4 v[152:153], off
	v_lshl_add_u64 v[152:153], v[232:233], 0, s[78:79]
	s_mov_b32 m0, s25
	s_nop 0
	global_load_lds_dwordx4 v[152:153], off
	s_waitcnt vmcnt(6)
	s_barrier
	v_mfma_f32_16x16x32_bf16 v[30:33], v[216:219], v[184:187], v[30:33]
	v_mfma_f32_16x16x32_bf16 v[26:29], v[224:227], v[184:187], v[26:29]
	v_mfma_f32_16x16x32_bf16 v[22:25], v[216:219], v[192:195], v[22:25]
	v_mfma_f32_16x16x32_bf16 v[18:21], v[224:227], v[192:195], v[18:21]
	v_mfma_f32_16x16x32_bf16 v[14:17], v[216:219], v[200:203], v[14:17]
	v_mfma_f32_16x16x32_bf16 v[10:13], v[224:227], v[200:203], v[10:13]
	v_mfma_f32_16x16x32_bf16 v[6:9], v[216:219], v[208:211], v[6:9]
	v_mfma_f32_16x16x32_bf16 v[2:5], v[224:227], v[208:211], v[2:5]
	v_mfma_f32_16x16x32_bf16 v[30:33], v[220:223], v[188:191], v[30:33]
	v_mfma_f32_16x16x32_bf16 v[26:29], v[228:231], v[188:191], v[26:29]
	v_mfma_f32_16x16x32_bf16 v[22:25], v[220:223], v[196:199], v[22:25]
	v_mfma_f32_16x16x32_bf16 v[18:21], v[228:231], v[196:199], v[18:21]
	v_mfma_f32_16x16x32_bf16 v[14:17], v[220:223], v[204:207], v[14:17]
	v_mfma_f32_16x16x32_bf16 v[10:13], v[228:231], v[204:207], v[10:13]
	v_mfma_f32_16x16x32_bf16 v[6:9], v[220:223], v[212:215], v[6:9]
	v_mfma_f32_16x16x32_bf16 v[2:5], v[228:231], v[212:215], v[2:5]
	s_add_i32 s24, s24, 2
	s_add_u32 s18, s18, 0x100
	s_addc_u32 s19, s19, 0
	s_add_u32 s20, s20, 0x100
	s_addc_u32 s21, s21, 0
	s_cmpk_lt_u32 s24, 0x54
	s_barrier
	s_cbranch_scc1 .LBB0_951
	s_mov_b64 s[18:19], 0x162b80
	v_lshl_add_u64 v[200:201], v[130:131], 0, s[18:19]
	v_readfirstlane_b32 s18, v173
	s_mov_b32 m0, s18
	s_mov_b64 s[18:19], 0x212b80
	v_lshl_add_u64 v[130:131], v[130:131], 0, s[18:19]
	v_readfirstlane_b32 s18, v174
	ds_read_b128 v[138:141], v137
	ds_read_b128 v[142:145], v137 offset:1024
	ds_read_b128 v[146:149], v137 offset:2048
	ds_read_b128 v[152:155], v137 offset:3072
	ds_read_b128 v[164:167], v136
	ds_read_b128 v[168:171], v136 offset:1024
	ds_read_b128 v[176:179], v136 offset:2048
	ds_read_b128 v[180:183], v136 offset:3072
	ds_read_b128 v[184:187], v136 offset:4096
	ds_read_b128 v[188:191], v136 offset:5120
	ds_read_b128 v[192:195], v136 offset:6144
	ds_read_b128 v[196:199], v136 offset:7168
	global_load_lds_dwordx4 v[200:201], off
	s_mov_b32 m0, s18
	s_nop 0
	global_load_lds_dwordx4 v[130:131], off
	s_barrier
	s_waitcnt lgkmcnt(0)
	s_waitcnt lgkmcnt(0)
	v_mfma_f32_16x16x32_bf16 v[126:129], v[138:141], v[164:167], v[126:129]
	v_mfma_f32_16x16x32_bf16 v[118:121], v[138:141], v[176:179], v[118:121]
	v_mfma_f32_16x16x32_bf16 v[110:113], v[138:141], v[184:187], v[110:113]
	v_mfma_f32_16x16x32_bf16 v[102:105], v[138:141], v[192:195], v[102:105]
	v_mfma_f32_16x16x32_bf16 v[126:129], v[142:145], v[168:171], v[126:129]
	v_mfma_f32_16x16x32_bf16 v[122:125], v[146:149], v[164:167], v[122:125]
	v_mfma_f32_16x16x32_bf16 v[118:121], v[142:145], v[180:183], v[118:121]
	v_mfma_f32_16x16x32_bf16 v[114:117], v[146:149], v[176:179], v[114:117]
	v_mfma_f32_16x16x32_bf16 v[110:113], v[142:145], v[188:191], v[110:113]
	v_mfma_f32_16x16x32_bf16 v[106:109], v[146:149], v[184:187], v[106:109]
	v_mfma_f32_16x16x32_bf16 v[102:105], v[142:145], v[196:199], v[102:105]
	v_mfma_f32_16x16x32_bf16 v[98:101], v[146:149], v[192:195], v[98:101]
	v_mfma_f32_16x16x32_bf16 v[172:175], v[152:155], v[168:171], v[122:125]
	v_mfma_f32_16x16x32_bf16 v[200:203], v[152:155], v[180:183], v[114:117]
	v_mfma_f32_16x16x32_bf16 v[204:207], v[152:155], v[188:191], v[106:109]
	v_mfma_f32_16x16x32_bf16 v[208:211], v[152:155], v[196:199], v[98:101]
	s_barrier
	s_nop 1
	ds_read_b128 v[98:101], v137 offset:16384
	ds_read_b128 v[106:109], v137 offset:17408
	ds_read_b128 v[114:117], v137 offset:18432
	ds_read_b128 v[122:125], v137 offset:19456
	s_barrier
; #define WAIT_V(n) asm volatile("s_waitcnt vmcnt(%0)" ::"n"(n) : "memory")
; #define WAIT_L(n) asm volatile("s_waitcnt lgkmcnt(%0)" ::"n"(n) : "memory")
; #define LDA8(dst, b, h) _Pragma("unroll") for (int m = 0; m < 4; ++m) _Pragma("unroll") for (int k = 0; k < 2; ++k) \
;     dst[m][k] = *(const bf16x8*)(abase + SAo(b, h) + m * 2048 + k * 1024)
; #define LDB8(dst, b, h) _Pragma("unroll") for (int n = 0; n < 2; ++n) _Pragma("unroll") for (int k = 0; k < 2; ++k) \
;     dst[n][k] = *(const bf16x8*)(bbase + SAo(b, h) + n * 2048 + k * 1024)
; #define BAR8 __builtin_amdgcn_s_barrier()
; __device__ __forceinline__ void gemm_main8(const u16* __restrict__ Ab, int lda, const u16* __restrict__ Bb, int ldb, int K,
;                                            char* shm, f32x4 (&acc)[2][2][4][2]) {
;     ...
;     LDB8(B1, 0, 1); BAR8; WAIT_L(0); MMA8(0, 1, At, B1); BAR8;
;     LDA8(At, 0, 1); WAIT_V(4); BAR8; WAIT_L(0); MMA8(1, 0, At, B0); MMA8(1, 1, At, B1); BAR8; }
;   { LDB8(B0, 1, 0); LDA8(At, 1, 0); WAIT_V(2); BAR8; WAIT_L(0); MMA8(0, 0, At, B0); BAR8;
	s_waitcnt lgkmcnt(0)
	s_waitcnt lgkmcnt(0)
	v_mfma_f32_16x16x32_bf16 v[94:97], v[98:101], v[164:167], v[94:97]
	v_mfma_f32_16x16x32_bf16 v[86:89], v[98:101], v[176:179], v[86:89]
	v_mfma_f32_16x16x32_bf16 v[78:81], v[98:101], v[184:187], v[78:81]
	v_mfma_f32_16x16x32_bf16 v[70:73], v[98:101], v[192:195], v[70:73]
	v_mfma_f32_16x16x32_bf16 v[94:97], v[106:109], v[168:171], v[94:97]
	v_mfma_f32_16x16x32_bf16 v[90:93], v[114:117], v[164:167], v[90:93]
	v_mfma_f32_16x16x32_bf16 v[86:89], v[106:109], v[180:183], v[86:89]
	v_mfma_f32_16x16x32_bf16 v[82:85], v[114:117], v[176:179], v[82:85]
	v_mfma_f32_16x16x32_bf16 v[78:81], v[106:109], v[188:191], v[78:81]
	v_mfma_f32_16x16x32_bf16 v[74:77], v[114:117], v[184:187], v[74:77]
	v_mfma_f32_16x16x32_bf16 v[70:73], v[106:109], v[196:199], v[70:73]
	v_mfma_f32_16x16x32_bf16 v[66:69], v[114:117], v[192:195], v[66:69]
	v_mfma_f32_16x16x32_bf16 v[164:167], v[122:125], v[168:171], v[90:93]
	v_mfma_f32_16x16x32_bf16 v[168:171], v[122:125], v[180:183], v[82:85]
	v_mfma_f32_16x16x32_bf16 v[176:179], v[122:125], v[188:191], v[74:77]
	v_mfma_f32_16x16x32_bf16 v[180:183], v[122:125], v[196:199], v[66:69]
	s_barrier
	s_nop 1
	ds_read_b128 v[66:69], v136 offset:16384
	ds_read_b128 v[74:77], v136 offset:17408
	ds_read_b128 v[82:85], v136 offset:18432
	ds_read_b128 v[90:93], v136 offset:19456
	ds_read_b128 v[184:187], v136 offset:20480
	ds_read_b128 v[188:191], v136 offset:21504
	ds_read_b128 v[192:195], v136 offset:22528
	ds_read_b128 v[196:199], v136 offset:23552
	s_waitcnt vmcnt(4)
	s_barrier
	s_waitcnt lgkmcnt(0)
	s_waitcnt lgkmcnt(0)
	v_mfma_f32_16x16x32_bf16 v[62:65], v[138:141], v[66:69], v[62:65]
	v_mfma_f32_16x16x32_bf16 v[58:61], v[146:149], v[66:69], v[58:61]
	v_mfma_f32_16x16x32_bf16 v[50:53], v[146:149], v[82:85], v[50:53]
	v_mfma_f32_16x16x32_bf16 v[42:45], v[146:149], v[184:187], v[42:45]
	v_mfma_f32_16x16x32_bf16 v[34:37], v[146:149], v[192:195], v[34:37]
	v_mfma_f32_16x16x32_bf16 v[62:65], v[142:145], v[74:77], v[62:65]
	v_mfma_f32_16x16x32_bf16 v[58:61], v[152:155], v[74:77], v[58:61]
	v_mfma_f32_16x16x32_bf16 v[54:57], v[138:141], v[82:85], v[54:57]
	v_mfma_f32_16x16x32_bf16 v[50:53], v[152:155], v[90:93], v[50:53]
	v_mfma_f32_16x16x32_bf16 v[46:49], v[138:141], v[184:187], v[46:49]
	v_mfma_f32_16x16x32_bf16 v[42:45], v[152:155], v[188:191], v[42:45]
	v_mfma_f32_16x16x32_bf16 v[38:41], v[138:141], v[192:195], v[38:41]
	v_mfma_f32_16x16x32_bf16 v[34:37], v[152:155], v[196:199], v[34:37]
	v_mfma_f32_16x16x32_bf16 v[212:215], v[142:145], v[90:93], v[54:57]
	v_mfma_f32_16x16x32_bf16 v[216:219], v[142:145], v[188:191], v[46:49]
	v_mfma_f32_16x16x32_bf16 v[138:141], v[142:145], v[196:199], v[38:41]
	v_mfma_f32_16x16x32_bf16 v[26:29], v[114:117], v[66:69], v[26:29]
	v_mfma_f32_16x16x32_bf16 v[18:21], v[114:117], v[82:85], v[18:21]
	v_mfma_f32_16x16x32_bf16 v[10:13], v[114:117], v[184:187], v[10:13]
	v_mfma_f32_16x16x32_bf16 v[2:5], v[114:117], v[192:195], v[2:5]
	v_mfma_f32_16x16x32_bf16 v[30:33], v[98:101], v[66:69], v[30:33]
	v_mfma_f32_16x16x32_bf16 v[26:29], v[122:125], v[74:77], v[26:29]
	v_mfma_f32_16x16x32_bf16 v[22:25], v[98:101], v[82:85], v[22:25]
	v_mfma_f32_16x16x32_bf16 v[18:21], v[122:125], v[90:93], v[18:21]
	v_mfma_f32_16x16x32_bf16 v[14:17], v[98:101], v[184:187], v[14:17]
	v_mfma_f32_16x16x32_bf16 v[10:13], v[122:125], v[188:191], v[10:13]
	v_mfma_f32_16x16x32_bf16 v[6:9], v[98:101], v[192:195], v[6:9]
	v_mfma_f32_16x16x32_bf16 v[2:5], v[122:125], v[196:199], v[2:5]
	v_mfma_f32_16x16x32_bf16 v[142:145], v[106:109], v[74:77], v[30:33]
	v_mfma_f32_16x16x32_bf16 v[146:149], v[106:109], v[90:93], v[22:25]
	v_mfma_f32_16x16x32_bf16 v[152:155], v[106:109], v[188:191], v[14:17]
	v_mfma_f32_16x16x32_bf16 v[184:187], v[106:109], v[196:199], v[6:9]
	s_barrier
	s_nop 0
	ds_read_b128 v[6:9], v137 offset:32768
	ds_read_b128 v[14:17], v137 offset:33792
	ds_read_b128 v[188:191], v137 offset:34816
	ds_read_b128 v[192:195], v137 offset:35840
	ds_read_b128 v[22:25], v136 offset:32768
	ds_read_b128 v[30:33], v136 offset:33792
	ds_read_b128 v[38:41], v136 offset:34816
	ds_read_b128 v[46:49], v136 offset:35840
	ds_read_b128 v[54:57], v136 offset:36864
	ds_read_b128 v[196:199], v136 offset:37888
	ds_read_b128 v[220:223], v136 offset:38912
	ds_read_b128 v[224:227], v136 offset:39936
	s_waitcnt vmcnt(2)
	s_barrier
; #define WAIT_V(n) asm volatile("s_waitcnt vmcnt(%0)" ::"n"(n) : "memory")
; #define WAIT_L(n) asm volatile("s_waitcnt lgkmcnt(%0)" ::"n"(n) : "memory")
; #define LDA8(dst, b, h) _Pragma("unroll") for (int m = 0; m < 4; ++m) _Pragma("unroll") for (int k = 0; k < 2; ++k) \
;     dst[m][k] = *(const bf16x8*)(abase + SAo(b, h) + m * 2048 + k * 1024)
; #define LDB8(dst, b, h) _Pragma("unroll") for (int n = 0; n < 2; ++n) _Pragma("unroll") for (int k = 0; k < 2; ++k) \
;     dst[n][k] = *(const bf16x8*)(bbase + SAo(b, h) + n * 2048 + k * 1024)
; #define BAR8 __builtin_amdgcn_s_barrier()
; __device__ __forceinline__ void gemm_main8(const u16* __restrict__ Ab, int lda, const u16* __restrict__ Bb, int ldb, int K,
;                                            char* shm, f32x4 (&acc)[2][2][4][2]) {
;     ...
;   { LDB8(B0, 1, 0); LDA8(At, 1, 0); WAIT_V(2); BAR8; WAIT_L(0); MMA8(0, 0, At, B0); BAR8;
;     LDB8(B1, 1, 1); WAIT_V(0); BAR8; WAIT_L(0); MMA8(0, 1, At, B1); BAR8;
;     LDA8(At, 1, 1); BAR8; WAIT_L(0); MMA8(1, 0, At, B0); MMA8(1, 1, At, B1); BAR8; }
;   if (wr == 0) BAR8;
	s_waitcnt lgkmcnt(0)
	s_waitcnt lgkmcnt(0)
	v_mfma_f32_16x16x32_bf16 v[66:69], v[6:9], v[22:25], v[126:129]
	v_mfma_f32_16x16x32_bf16 v[122:125], v[14:17], v[30:33], v[66:69]
	v_mfma_f32_16x16x32_bf16 v[66:69], v[188:191], v[22:25], v[172:175]
	v_mfma_f32_16x16x32_bf16 v[114:117], v[192:195], v[30:33], v[66:69]
	v_mfma_f32_16x16x32_bf16 v[66:69], v[6:9], v[38:41], v[118:121]
	v_mfma_f32_16x16x32_bf16 v[106:109], v[14:17], v[46:49], v[66:69]
	v_mfma_f32_16x16x32_bf16 v[66:69], v[188:191], v[38:41], v[200:203]
	v_mfma_f32_16x16x32_bf16 v[98:101], v[192:195], v[46:49], v[66:69]
	v_mfma_f32_16x16x32_bf16 v[66:69], v[6:9], v[54:57], v[110:113]
	v_mfma_f32_16x16x32_bf16 v[90:93], v[14:17], v[196:199], v[66:69]
	v_mfma_f32_16x16x32_bf16 v[66:69], v[188:191], v[54:57], v[204:207]
	v_mfma_f32_16x16x32_bf16 v[82:85], v[192:195], v[196:199], v[66:69]
	v_mfma_f32_16x16x32_bf16 v[66:69], v[6:9], v[220:223], v[102:105]
	v_mfma_f32_16x16x32_bf16 v[74:77], v[14:17], v[224:227], v[66:69]
	v_mfma_f32_16x16x32_bf16 v[66:69], v[188:191], v[220:223], v[208:211]
	v_mfma_f32_16x16x32_bf16 v[66:69], v[192:195], v[224:227], v[66:69]
	s_barrier
	ds_read_b128 v[172:175], v137 offset:49152
	ds_read_b128 v[200:203], v137 offset:50176
	ds_read_b128 v[204:207], v137 offset:51200
	ds_read_b128 v[208:211], v137 offset:52224
	s_waitcnt vmcnt(0)
	s_barrier
	s_waitcnt lgkmcnt(0)
	s_waitcnt lgkmcnt(0)
	v_mfma_f32_16x16x32_bf16 v[94:97], v[172:175], v[22:25], v[94:97]
	v_mfma_f32_16x16x32_bf16 v[22:25], v[204:207], v[22:25], v[164:167]
	v_mfma_f32_16x16x32_bf16 v[118:121], v[208:211], v[30:33], v[22:25]
	v_mfma_f32_16x16x32_bf16 v[22:25], v[172:175], v[38:41], v[86:89]
	v_mfma_f32_16x16x32_bf16 v[110:113], v[200:203], v[46:49], v[22:25]
	v_mfma_f32_16x16x32_bf16 v[22:25], v[204:207], v[38:41], v[168:171]
	v_mfma_f32_16x16x32_bf16 v[102:105], v[208:211], v[46:49], v[22:25]
	v_mfma_f32_16x16x32_bf16 v[22:25], v[172:175], v[54:57], v[78:81]
	v_mfma_f32_16x16x32_bf16 v[126:129], v[200:203], v[30:33], v[94:97]
	v_mfma_f32_16x16x32_bf16 v[94:97], v[200:203], v[196:199], v[22:25]
	v_mfma_f32_16x16x32_bf16 v[22:25], v[204:207], v[54:57], v[176:179]
	v_mfma_f32_16x16x32_bf16 v[86:89], v[208:211], v[196:199], v[22:25]
	v_mfma_f32_16x16x32_bf16 v[22:25], v[172:175], v[220:223], v[70:73]
	v_mfma_f32_16x16x32_bf16 v[78:81], v[200:203], v[224:227], v[22:25]
	v_mfma_f32_16x16x32_bf16 v[22:25], v[204:207], v[220:223], v[180:183]
	v_mfma_f32_16x16x32_bf16 v[70:73], v[208:211], v[224:227], v[22:25]
	s_barrier
	ds_read_b128 v[164:167], v136 offset:49152
	ds_read_b128 v[168:171], v136 offset:50176
	ds_read_b128 v[176:179], v136 offset:51200
	ds_read_b128 v[180:183], v136 offset:52224
	ds_read_b128 v[196:199], v136 offset:53248
	ds_read_b128 v[220:223], v136 offset:54272
	ds_read_b128 v[224:227], v136 offset:55296
	ds_read_b128 v[228:231], v136 offset:56320
	s_barrier
	s_waitcnt lgkmcnt(0)
	s_waitcnt lgkmcnt(0)
	v_mfma_f32_16x16x32_bf16 v[22:25], v[6:9], v[164:167], v[62:65]
	v_mfma_f32_16x16x32_bf16 v[62:65], v[14:17], v[168:171], v[22:25]
	v_mfma_f32_16x16x32_bf16 v[22:25], v[188:191], v[164:167], v[58:61]
	v_mfma_f32_16x16x32_bf16 v[54:57], v[192:195], v[168:171], v[22:25]
	v_mfma_f32_16x16x32_bf16 v[22:25], v[6:9], v[176:179], v[212:215]
	v_mfma_f32_16x16x32_bf16 v[46:49], v[14:17], v[180:183], v[22:25]
	v_mfma_f32_16x16x32_bf16 v[22:25], v[188:191], v[176:179], v[50:53]
	v_mfma_f32_16x16x32_bf16 v[38:41], v[192:195], v[180:183], v[22:25]
	v_mfma_f32_16x16x32_bf16 v[22:25], v[6:9], v[196:199], v[216:219]
	v_mfma_f32_16x16x32_bf16 v[6:9], v[6:9], v[224:227], v[138:141]
	v_mfma_f32_16x16x32_bf16 v[30:33], v[14:17], v[220:223], v[22:25]
	v_mfma_f32_16x16x32_bf16 v[22:25], v[188:191], v[196:199], v[42:45]
	v_mfma_f32_16x16x32_bf16 v[14:17], v[14:17], v[228:231], v[6:9]
	v_mfma_f32_16x16x32_bf16 v[6:9], v[188:191], v[224:227], v[34:37]
	v_mfma_f32_16x16x32_bf16 v[22:25], v[192:195], v[220:223], v[22:25]
	v_mfma_f32_16x16x32_bf16 v[6:9], v[192:195], v[228:231], v[6:9]
	v_mfma_f32_16x16x32_bf16 v[34:37], v[172:175], v[164:167], v[142:145]
	v_mfma_f32_16x16x32_bf16 v[26:29], v[204:207], v[164:167], v[26:29]
	v_mfma_f32_16x16x32_bf16 v[18:21], v[204:207], v[176:179], v[18:21]
	v_mfma_f32_16x16x32_bf16 v[58:61], v[200:203], v[168:171], v[34:37]
	v_mfma_f32_16x16x32_bf16 v[50:53], v[208:211], v[168:171], v[26:29]
	v_mfma_f32_16x16x32_bf16 v[26:29], v[172:175], v[176:179], v[146:149]
	v_mfma_f32_16x16x32_bf16 v[34:37], v[208:211], v[180:183], v[18:21]
	v_mfma_f32_16x16x32_bf16 v[18:21], v[172:175], v[196:199], v[152:155]
	v_mfma_f32_16x16x32_bf16 v[10:13], v[204:207], v[196:199], v[10:13]
	v_mfma_f32_16x16x32_bf16 v[42:45], v[200:203], v[180:183], v[26:29]
	v_mfma_f32_16x16x32_bf16 v[26:29], v[200:203], v[220:223], v[18:21]
	v_mfma_f32_16x16x32_bf16 v[18:21], v[208:211], v[220:223], v[10:13]
	v_mfma_f32_16x16x32_bf16 v[10:13], v[172:175], v[224:227], v[184:187]
	v_mfma_f32_16x16x32_bf16 v[2:5], v[204:207], v[224:227], v[2:5]
	v_mfma_f32_16x16x32_bf16 v[10:13], v[200:203], v[228:231], v[10:13]
	v_mfma_f32_16x16x32_bf16 v[2:5], v[208:211], v[228:231], v[2:5]
	v_cmp_gt_u32_e32 vcc, s97, v135
	s_barrier
	s_and_saveexec_b64 s[18:19], vcc
	s_cbranch_execz .LBB0_947
	s_barrier
	s_branch .LBB0_947
